# write-through (sc0 sc1) on the scattered 64-byte-piece stores: G1 epilogue PX stores and mixer MIX output stores
# speedup vs baseline: 1.0139x; 1.0139x over previous
; #define LAS __attribute__((address_space(3)))
; __device__ __forceinline__ unsigned f2bf(float f) { unsigned u = __builtin_bit_cast(unsigned, f); return (u + 0x7fffu + ((u >> 16) & 1u)) >> 16; }
; __device__ __forceinline__ unsigned pk2(float lo, float hi) { return f2bf(lo) | (f2bf(hi) << 16); }
; __device__ __forceinline__ float frcp(float x) { return __builtin_amdgcn_rcpf(x); }
; template <int WIN>
; __device__ __forceinline__ void pool_p_run(const LAS unsigned* Zu, LAS bf16_t* P, int g, int cpi, int run, const Tile& T) {
;     ...
;         const float inv = frcp((float)(min(tg + HI + 1, T.seqlen) - max(tg - LO, 0)));
;         const unsigned cv = z[tt + LO];
;         *(LAS unsigned*)(P + t * CXS + 2 * cp) = pk2(s0 * inv - bf2f(cv & 0xffffu), s1 * inv - __builtin_bit_cast(float, cv & 0xffff0000u));
; __device__ __forceinline__ void pool_unit(const Args& a, LAS unsigned char* lds, int l, int tt) {
;     ...
;     for (int mm = 0; mm < 4; ++mm) {
;         const int m = mh * 4 + mm;
;         bf16x8 Af[2];
; #pragma unroll
;         for (int ks = 0; ks < 2; ++ks) Af[ks] = *(const LAS bf16x8*)(P + (m * 16 + fr) * CXS + 64 * g + 32 * ks + 8 * fq);
; #pragma unroll
;         for (int nt = 0; nt < 4; ++nt) {
;             f32x4 acc = (f32x4){0.f, 0.f, 0.f, 0.f};
; #pragma unroll
;             for (int ks = 0; ks < 2; ++ks) acc = __builtin_amdgcn_mfma_f32_16x16x32_bf16(Af[ks], Bw[nt][ks], acc, 0, 0, 0);
; #pragma unroll
;             for (int reg = 0; reg < 4; ++reg) Z[(m * 16 + 4 * fq + reg) * CXS + 64 * g + 16 * nt + fr] = (bf16_t)f2bf(acc[reg] * sc[nt]);
;         }
.LBB0_451:
	v_or_b32_e32 v39, 31, v136
	v_or_b32_e32 v38, s39, v39
	v_add_u32_e32 v40, s4, v38
	v_min_u32_e32 v40, s42, v40
	v_sub_u32_e32 v38, s4, v38
	v_add_u32_e32 v38, v38, v40
	v_cvt_f32_i32_e32 v38, v38
	v_mad_i32_i24 v39, v39, s55, v137
	s_lshl_b32 s0, s41, 7
	s_add_i32 s1, s0, 0
	v_rcp_iflag_f32_e32 v38, v38
	s_add_i32 s0, s1, 0x12000
	s_add_i32 s39, s39, s38
	s_mov_b32 s28, 0x3fff0
	v_pk_fma_f32 v[34:35], v[36:37], v[38:39], v[34:35] op_sel_hi:[1,0,1] neg_lo:[0,0,1] neg_hi:[0,0,1]
	s_movk_i32 s29, 0x1e0
	v_and_b32_sdwa v37, v34, v1 dst_sel:DWORD dst_unused:UNUSED_PAD src0_sel:WORD_1 src1_sel:DWORD
	v_and_b32_sdwa v36, v35, v1 dst_sel:DWORD dst_unused:UNUSED_PAD src0_sel:WORD_1 src1_sel:DWORD
	v_add3_u32 v34, v34, v37, s27
	v_add3_u32 v35, v35, v36, s27
	v_lshrrev_b32_e32 v34, 16, v34
	v_and_or_b32 v34, v35, s6, v34
	ds_write_b32 v39, v34
	v_lshl_add_u32 v34, v135, 4, s0
	s_ashr_i32 s0, s40, 2
	s_andn2_b32 s0, s0, 63
	v_or_b32_e32 v35, s0, v131
	v_mad_u64_u32 v[36:37], s[4:5], v35, s55, v[34:35]
	s_waitcnt lgkmcnt(0)
	s_barrier
	ds_read_b128 v[38:41], v36
	ds_read_b128 v[42:45], v36 offset:64
	s_waitcnt lgkmcnt(1)
	v_mfma_f32_16x16x32_bf16 v[46:49], v[38:41], v[30:33], 0
	v_lshlrev_b32_e32 v37, 2, v135
	v_lshl_add_u32 v36, v131, 1, s1
	v_or_b32_e32 v35, s0, v37
	s_waitcnt lgkmcnt(0)
	v_mfma_f32_16x16x32_bf16 v[46:49], v[42:45], v[26:29], v[46:49]
	s_or_b32 s1, s0, 16
	s_nop 6
	v_mul_f32_e32 v46, v134, v46
	v_bfe_u32 v50, v46, 16, 1
	v_add3_u32 v46, v46, v50, s27
	v_mad_u64_u32 v[50:51], s[4:5], v35, s55, v[36:37]
	v_mul_f32_e32 v35, v134, v47
	ds_write_b16_d16_hi v50, v46
	v_bfe_u32 v46, v35, 16, 1
	v_add3_u32 v35, v35, v46, s27
	ds_write_b16_d16_hi v50, v35 offset:528
	v_mul_f32_e32 v35, v134, v48
	v_bfe_u32 v46, v35, 16, 1
	v_add3_u32 v35, v35, v46, s27
	ds_write_b16_d16_hi v50, v35 offset:1056
	v_mul_f32_e32 v35, v134, v49
	v_mfma_f32_16x16x32_bf16 v[46:49], v[38:41], v[22:25], 0
	v_bfe_u32 v51, v35, 16, 1
	v_add3_u32 v35, v35, v51, s27
	ds_write_b16_d16_hi v50, v35 offset:1584
	v_mfma_f32_16x16x32_bf16 v[46:49], v[42:45], v[18:21], v[46:49]
	s_nop 7
	v_mul_f32_e32 v35, v133, v46
	v_bfe_u32 v46, v35, 16, 1
	v_add3_u32 v35, v35, v46, s27
	ds_write_b16_d16_hi v50, v35 offset:32
	v_mul_f32_e32 v35, v133, v47
	v_bfe_u32 v46, v35, 16, 1
	v_add3_u32 v35, v35, v46, s27
	ds_write_b16_d16_hi v50, v35 offset:560
	v_mul_f32_e32 v35, v133, v48
	v_bfe_u32 v46, v35, 16, 1
	v_add3_u32 v35, v35, v46, s27
	ds_write_b16_d16_hi v50, v35 offset:1088
	v_mul_f32_e32 v35, v133, v49
	v_mfma_f32_16x16x32_bf16 v[46:49], v[38:41], v[14:17], 0
	v_bfe_u32 v51, v35, 16, 1
	v_add3_u32 v35, v35, v51, s27
	ds_write_b16_d16_hi v50, v35 offset:1616
	v_mfma_f32_16x16x32_bf16 v[46:49], v[42:45], v[10:13], v[46:49]
	v_mfma_f32_16x16x32_bf16 v[38:41], v[38:41], v[6:9], 0
	v_mfma_f32_16x16x32_bf16 v[38:41], v[42:45], v[2:5], v[38:41]
	s_nop 5
	v_mul_f32_e32 v35, v132, v46
	v_bfe_u32 v46, v35, 16, 1
	v_add3_u32 v35, v35, v46, s27
	ds_write_b16_d16_hi v50, v35 offset:64
	v_mul_f32_e32 v35, v132, v47
	v_bfe_u32 v46, v35, 16, 1
	v_add3_u32 v35, v35, v46, s27
	ds_write_b16_d16_hi v50, v35 offset:592
	v_mul_f32_e32 v35, v132, v48
	v_bfe_u32 v46, v35, 16, 1
	v_add3_u32 v35, v35, v46, s27
	ds_write_b16_d16_hi v50, v35 offset:1120
	v_mul_f32_e32 v35, v132, v49
	v_bfe_u32 v46, v35, 16, 1
	v_add3_u32 v35, v35, v46, s27
	ds_write_b16_d16_hi v50, v35 offset:1648
	v_mul_f32_e32 v35, v130, v38
	v_bfe_u32 v38, v35, 16, 1
	v_add3_u32 v35, v35, v38, s27
	ds_write_b16_d16_hi v50, v35 offset:96
	v_mul_f32_e32 v35, v130, v39
	v_bfe_u32 v38, v35, 16, 1
	v_add3_u32 v35, v35, v38, s27
	ds_write_b16_d16_hi v50, v35 offset:624
	v_mul_f32_e32 v35, v130, v40
	v_bfe_u32 v38, v35, 16, 1
	v_add3_u32 v35, v35, v38, s27
	ds_write_b16_d16_hi v50, v35 offset:1152
	v_mul_f32_e32 v35, v130, v41
	v_bfe_u32 v38, v35, 16, 1
	v_add3_u32 v35, v35, v38, s27
	ds_write_b16_d16_hi v50, v35 offset:1680
	v_or_b32_e32 v35, s1, v131
	v_mad_u64_u32 v[42:43], s[4:5], v35, s55, v[34:35]
	ds_read_b128 v[38:41], v42
	ds_read_b128 v[42:45], v42 offset:64
	s_waitcnt lgkmcnt(1)
	v_mfma_f32_16x16x32_bf16 v[46:49], v[38:41], v[30:33], 0
	v_or_b32_e32 v35, s1, v37
	s_or_b32 s1, s0, 32
	s_waitcnt lgkmcnt(0)
	v_mfma_f32_16x16x32_bf16 v[46:49], v[42:45], v[26:29], v[46:49]
	s_nop 7
	v_mul_f32_e32 v46, v134, v46
	v_bfe_u32 v50, v46, 16, 1
	v_add3_u32 v46, v46, v50, s27
	v_mad_u64_u32 v[50:51], s[4:5], v35, s55, v[36:37]
	v_mul_f32_e32 v35, v134, v47
	ds_write_b16_d16_hi v50, v46
	v_bfe_u32 v46, v35, 16, 1
	v_add3_u32 v35, v35, v46, s27
	ds_write_b16_d16_hi v50, v35 offset:528
	v_mul_f32_e32 v35, v134, v48
	v_bfe_u32 v46, v35, 16, 1
	v_add3_u32 v35, v35, v46, s27
	ds_write_b16_d16_hi v50, v35 offset:1056
	v_mul_f32_e32 v35, v134, v49
	v_mfma_f32_16x16x32_bf16 v[46:49], v[38:41], v[22:25], 0
	v_bfe_u32 v51, v35, 16, 1
	v_add3_u32 v35, v35, v51, s27
	ds_write_b16_d16_hi v50, v35 offset:1584
	v_mfma_f32_16x16x32_bf16 v[46:49], v[42:45], v[18:21], v[46:49]
	s_nop 7
	v_mul_f32_e32 v35, v133, v46
	v_bfe_u32 v46, v35, 16, 1
	v_add3_u32 v35, v35, v46, s27
	ds_write_b16_d16_hi v50, v35 offset:32
	v_mul_f32_e32 v35, v133, v47
	v_bfe_u32 v46, v35, 16, 1
	v_add3_u32 v35, v35, v46, s27
	ds_write_b16_d16_hi v50, v35 offset:560
	v_mul_f32_e32 v35, v133, v48
	v_bfe_u32 v46, v35, 16, 1
	v_add3_u32 v35, v35, v46, s27
	ds_write_b16_d16_hi v50, v35 offset:1088
	v_mul_f32_e32 v35, v133, v49
	v_mfma_f32_16x16x32_bf16 v[46:49], v[38:41], v[14:17], 0
	v_bfe_u32 v51, v35, 16, 1
	v_add3_u32 v35, v35, v51, s27
	ds_write_b16_d16_hi v50, v35 offset:1616
	v_mfma_f32_16x16x32_bf16 v[46:49], v[42:45], v[10:13], v[46:49]
	v_mfma_f32_16x16x32_bf16 v[38:41], v[38:41], v[6:9], 0
	v_mfma_f32_16x16x32_bf16 v[38:41], v[42:45], v[2:5], v[38:41]
	s_nop 5
	v_mul_f32_e32 v35, v132, v46
	v_bfe_u32 v46, v35, 16, 1
	v_add3_u32 v35, v35, v46, s27
	ds_write_b16_d16_hi v50, v35 offset:64
	v_mul_f32_e32 v35, v132, v47
	v_bfe_u32 v46, v35, 16, 1
	v_add3_u32 v35, v35, v46, s27
	ds_write_b16_d16_hi v50, v35 offset:592
	v_mul_f32_e32 v35, v132, v48
	v_bfe_u32 v46, v35, 16, 1
	v_add3_u32 v35, v35, v46, s27
	ds_write_b16_d16_hi v50, v35 offset:1120
	v_mul_f32_e32 v35, v132, v49
	v_bfe_u32 v46, v35, 16, 1
	v_add3_u32 v35, v35, v46, s27
	ds_write_b16_d16_hi v50, v35 offset:1648
	v_mul_f32_e32 v35, v130, v38
	v_bfe_u32 v38, v35, 16, 1
	v_add3_u32 v35, v35, v38, s27
	ds_write_b16_d16_hi v50, v35 offset:96
	v_mul_f32_e32 v35, v130, v39
	v_bfe_u32 v38, v35, 16, 1
	v_add3_u32 v35, v35, v38, s27
	ds_write_b16_d16_hi v50, v35 offset:624
	v_mul_f32_e32 v35, v130, v40
	v_bfe_u32 v38, v35, 16, 1
	v_add3_u32 v35, v35, v38, s27
	ds_write_b16_d16_hi v50, v35 offset:1152
	v_mul_f32_e32 v35, v130, v41
	v_bfe_u32 v38, v35, 16, 1
	v_add3_u32 v35, v35, v38, s27
	ds_write_b16_d16_hi v50, v35 offset:1680
	v_or_b32_e32 v35, s1, v131
	v_mad_u64_u32 v[42:43], s[4:5], v35, s55, v[34:35]
	ds_read_b128 v[38:41], v42
	ds_read_b128 v[42:45], v42 offset:64
	s_waitcnt lgkmcnt(1)
; #define LAS __attribute__((address_space(3)))
; __device__ __forceinline__ unsigned f2bf(float f) { unsigned u = __builtin_bit_cast(unsigned, f); return (u + 0x7fffu + ((u >> 16) & 1u)) >> 16; }
; __device__ __forceinline__ void pool_unit(const Args& a, LAS unsigned char* lds, int l, int tt) {
;     ...
;     for (int mm = 0; mm < 4; ++mm) {
;         const int m = mh * 4 + mm;
;         bf16x8 Af[2];
; #pragma unroll
;         for (int ks = 0; ks < 2; ++ks) Af[ks] = *(const LAS bf16x8*)(P + (m * 16 + fr) * CXS + 64 * g + 32 * ks + 8 * fq);
; #pragma unroll
;         for (int nt = 0; nt < 4; ++nt) {
;             f32x4 acc = (f32x4){0.f, 0.f, 0.f, 0.f};
; #pragma unroll
;             for (int ks = 0; ks < 2; ++ks) acc = __builtin_amdgcn_mfma_f32_16x16x32_bf16(Af[ks], Bw[nt][ks], acc, 0, 0, 0);
; #pragma unroll
;             for (int reg = 0; reg < 4; ++reg) Z[(m * 16 + 4 * fq + reg) * CXS + 64 * g + 16 * nt + fr] = (bf16_t)f2bf(acc[reg] * sc[nt]);
;         }
;     }
;     __syncthreads();
	v_mfma_f32_16x16x32_bf16 v[46:49], v[38:41], v[30:33], 0
	v_or_b32_e32 v35, s1, v37
	s_waitcnt lgkmcnt(0)
	v_mfma_f32_16x16x32_bf16 v[46:49], v[42:45], v[26:29], v[46:49]
	s_nop 7
	v_mul_f32_e32 v46, v134, v46
	v_bfe_u32 v50, v46, 16, 1
	v_add3_u32 v46, v46, v50, s27
	v_mad_u64_u32 v[50:51], s[4:5], v35, s55, v[36:37]
	v_mul_f32_e32 v35, v134, v47
	ds_write_b16_d16_hi v50, v46
	v_bfe_u32 v46, v35, 16, 1
	v_add3_u32 v35, v35, v46, s27
	ds_write_b16_d16_hi v50, v35 offset:528
	v_mul_f32_e32 v35, v134, v48
	v_bfe_u32 v46, v35, 16, 1
	v_add3_u32 v35, v35, v46, s27
	ds_write_b16_d16_hi v50, v35 offset:1056
	v_mul_f32_e32 v35, v134, v49
	v_mfma_f32_16x16x32_bf16 v[46:49], v[38:41], v[22:25], 0
	v_bfe_u32 v51, v35, 16, 1
	v_add3_u32 v35, v35, v51, s27
	ds_write_b16_d16_hi v50, v35 offset:1584
	v_mfma_f32_16x16x32_bf16 v[46:49], v[42:45], v[18:21], v[46:49]
	s_or_b32 s4, s0, 48
	s_nop 6
	v_mul_f32_e32 v35, v133, v46
	v_bfe_u32 v46, v35, 16, 1
	v_add3_u32 v35, v35, v46, s27
	ds_write_b16_d16_hi v50, v35 offset:32
	v_mul_f32_e32 v35, v133, v47
	v_bfe_u32 v46, v35, 16, 1
	v_add3_u32 v35, v35, v46, s27
	ds_write_b16_d16_hi v50, v35 offset:560
	v_mul_f32_e32 v35, v133, v48
	v_bfe_u32 v46, v35, 16, 1
	v_add3_u32 v35, v35, v46, s27
	ds_write_b16_d16_hi v50, v35 offset:1088
	v_mul_f32_e32 v35, v133, v49
	v_mfma_f32_16x16x32_bf16 v[46:49], v[38:41], v[14:17], 0
	v_bfe_u32 v51, v35, 16, 1
	v_add3_u32 v35, v35, v51, s27
	ds_write_b16_d16_hi v50, v35 offset:1616
	v_mfma_f32_16x16x32_bf16 v[46:49], v[42:45], v[10:13], v[46:49]
	v_mfma_f32_16x16x32_bf16 v[38:41], v[38:41], v[6:9], 0
	v_mfma_f32_16x16x32_bf16 v[38:41], v[42:45], v[2:5], v[38:41]
	s_nop 5
	v_mul_f32_e32 v35, v132, v46
	v_bfe_u32 v46, v35, 16, 1
	v_add3_u32 v35, v35, v46, s27
	ds_write_b16_d16_hi v50, v35 offset:64
	v_mul_f32_e32 v35, v132, v47
	v_bfe_u32 v46, v35, 16, 1
	v_add3_u32 v35, v35, v46, s27
	ds_write_b16_d16_hi v50, v35 offset:592
	v_mul_f32_e32 v35, v132, v48
	v_bfe_u32 v46, v35, 16, 1
	v_add3_u32 v35, v35, v46, s27
	ds_write_b16_d16_hi v50, v35 offset:1120
	v_mul_f32_e32 v35, v132, v49
	v_bfe_u32 v46, v35, 16, 1
	v_add3_u32 v35, v35, v46, s27
	ds_write_b16_d16_hi v50, v35 offset:1648
	v_mul_f32_e32 v35, v130, v38
	v_bfe_u32 v38, v35, 16, 1
	v_add3_u32 v35, v35, v38, s27
	ds_write_b16_d16_hi v50, v35 offset:96
	v_mul_f32_e32 v35, v130, v39
	v_bfe_u32 v38, v35, 16, 1
	v_add3_u32 v35, v35, v38, s27
	ds_write_b16_d16_hi v50, v35 offset:624
	v_mul_f32_e32 v35, v130, v40
	v_bfe_u32 v38, v35, 16, 1
	v_add3_u32 v35, v35, v38, s27
	ds_write_b16_d16_hi v50, v35 offset:1152
	v_mul_f32_e32 v35, v130, v41
	v_bfe_u32 v38, v35, 16, 1
	v_add3_u32 v35, v35, v38, s27
	ds_write_b16_d16_hi v50, v35 offset:1680
	v_or_b32_e32 v35, s4, v131
	v_mad_u64_u32 v[34:35], s[0:1], v35, s55, v[34:35]
	ds_read_b128 v[38:41], v34
	ds_read_b128 v[42:45], v34 offset:64
	s_waitcnt lgkmcnt(1)
	v_mfma_f32_16x16x32_bf16 v[30:33], v[38:41], v[30:33], 0
	v_or_b32_e32 v34, s4, v37
	v_readlane_b32 s4, v253, 18
	v_readlane_b32 s5, v253, 19
	v_mfma_f32_16x16x32_bf16 v[22:25], v[38:41], v[22:25], 0
	v_mfma_f32_16x16x32_bf16 v[14:17], v[38:41], v[14:17], 0
	v_mfma_f32_16x16x32_bf16 v[6:9], v[38:41], v[6:9], 0
	s_waitcnt lgkmcnt(0)
	v_mfma_f32_16x16x32_bf16 v[26:29], v[42:45], v[26:29], v[30:33]
	v_mfma_f32_16x16x32_bf16 v[18:21], v[42:45], v[18:21], v[22:25]
	v_mfma_f32_16x16x32_bf16 v[10:13], v[42:45], v[10:13], v[14:17]
	s_nop 5
	v_mul_f32_e32 v26, v134, v26
	v_mul_f32_e32 v18, v133, v18
	v_bfe_u32 v30, v26, 16, 1
	v_mfma_f32_16x16x32_bf16 v[2:5], v[42:45], v[2:5], v[6:9]
	v_bfe_u32 v22, v18, 16, 1
	v_mul_f32_e32 v10, v132, v10
	v_bfe_u32 v14, v10, 16, 1
	v_add3_u32 v26, v26, v30, s27
	v_mad_u64_u32 v[30:31], s[0:1], v34, s55, v[36:37]
	s_nop 2
	v_mul_f32_e32 v2, v130, v2
	v_bfe_u32 v6, v2, 16, 1
	v_add3_u32 v18, v18, v22, s27
	v_add3_u32 v10, v10, v14, s27
	v_add3_u32 v2, v2, v6, s27
	ds_write_b16_d16_hi v30, v26
	v_mul_f32_e32 v26, v134, v27
	ds_write_b16_d16_hi v30, v18 offset:32
	v_mul_f32_e32 v18, v133, v19
	ds_write_b16_d16_hi v30, v10 offset:64
	v_mul_f32_e32 v10, v132, v11
	ds_write_b16_d16_hi v30, v2 offset:96
	v_mul_f32_e32 v2, v130, v3
	v_bfe_u32 v27, v26, 16, 1
	v_bfe_u32 v19, v18, 16, 1
	v_bfe_u32 v11, v10, 16, 1
	v_bfe_u32 v3, v2, 16, 1
	v_add3_u32 v26, v26, v27, s27
	v_add3_u32 v18, v18, v19, s27
	v_add3_u32 v10, v10, v11, s27
	v_add3_u32 v2, v2, v3, s27
	ds_write_b16_d16_hi v30, v26 offset:528
	v_mul_f32_e32 v26, v134, v28
	ds_write_b16_d16_hi v30, v18 offset:560
	v_mul_f32_e32 v18, v133, v20
	ds_write_b16_d16_hi v30, v10 offset:592
	v_mul_f32_e32 v10, v132, v12
	ds_write_b16_d16_hi v30, v2 offset:624
	v_mul_f32_e32 v2, v130, v4
	v_bfe_u32 v27, v26, 16, 1
	v_bfe_u32 v19, v18, 16, 1
	v_bfe_u32 v11, v10, 16, 1
	v_bfe_u32 v3, v2, 16, 1
	v_add3_u32 v26, v26, v27, s27
	v_add3_u32 v18, v18, v19, s27
	v_add3_u32 v10, v10, v11, s27
	v_add3_u32 v2, v2, v3, s27
	ds_write_b16_d16_hi v30, v26 offset:1056
	v_mul_f32_e32 v26, v134, v29
	ds_write_b16_d16_hi v30, v18 offset:1088
	v_mul_f32_e32 v18, v133, v21
	ds_write_b16_d16_hi v30, v10 offset:1120
	v_mul_f32_e32 v10, v132, v13
	ds_write_b16_d16_hi v30, v2 offset:1152
	v_mul_f32_e32 v2, v130, v5
	v_bfe_u32 v27, v26, 16, 1
	v_bfe_u32 v19, v18, 16, 1
	v_bfe_u32 v11, v10, 16, 1
	v_bfe_u32 v3, v2, 16, 1
	v_add3_u32 v26, v26, v27, s27
	v_add3_u32 v18, v18, v19, s27
	v_add3_u32 v10, v10, v11, s27
	v_add3_u32 v2, v2, v3, s27
	v_mov_b32_e32 v11, v0
	ds_write_b16_d16_hi v30, v26 offset:1584
	ds_write_b16_d16_hi v30, v18 offset:1616
	ds_write_b16_d16_hi v30, v10 offset:1648
	ds_write_b16_d16_hi v30, v2 offset:1680
	s_waitcnt lgkmcnt(0)
	s_barrier
; #define LAS __attribute__((address_space(3)))
; __host__ __device__ __forceinline__ unsigned img_off(unsigned row, unsigned col, unsigned KT) { return (((row >> 8) * KT + (col >> 6)) << 14) + (((row >> 7) & 1u) << 13) + hl_off(row & 127u, col & 63u); }
; __device__ __forceinline__ int opaque_tid() { int t = threadIdx.x; asm volatile("" : "+v"(t)); return t; }
; __device__ __forceinline__ void flush_tile(const LAS bf16_t* src, bf16_t* MIX, const Tile& T, int col) {
;     const int tid = opaque_tid();
; #pragma unroll
;     for (int it = 0; it < 8; ++it) {
;         const int idx = tid + NTHREADS * it, r = idx >> 5, vec = idx & 31;
;         *(u32x4*)(MIX + img_off((unsigned)(T.rowbase + T.t0 + r), (unsigned)(col + vec * 8), 16u)) = *(const LAS u32x4*)(src + r * CXS + vec * 8);
;     }
; }
	s_nop 0
	v_lshlrev_b32_e32 v2, 3, v11
	v_and_b32_e32 v3, 0xf8, v2
	v_lshl_add_u32 v10, v3, 1, 0
	v_bfe_u32 v3, v2, 6, 2
	v_ashrrev_i32_e32 v6, 5, v11
	v_or_b32_e32 v14, 4, v3
	v_bfe_u32 v15, v11, 2, 1
	v_and_b32_e32 v16, 24, v2
	v_mad_u64_u32 v[2:3], s[0:1], v6, s55, v[10:11]
	v_add_u32_e32 v7, s39, v6
	v_lshrrev_b32_e32 v9, 3, v6
	ds_read_b128 v[2:5], v2
	v_lshrrev_b32_e32 v8, 4, v7
	v_and_or_b32 v9, v9, 14, v15
	v_lshlrev_b32_e32 v6, 1, v6
	v_and_or_b32 v8, v8, s28, v14
	v_lshlrev_b32_e32 v7, 6, v7
	v_and_or_b32 v12, v11, s29, v16
	v_lshlrev_b32_e32 v9, 9, v9
	v_and_b32_e32 v6, 16, v6
	v_lshlrev_b32_e32 v8, 14, v8
	v_and_b32_e32 v7, 0x2000, v7
	v_bitop3_b32 v6, v12, v9, v6 bitop3:0xde
	v_add_u32_e32 v17, 0x200, v11
	v_or3_b32 v206, v8, v7, v6
	v_ashrrev_i32_e32 v18, 5, v17
	v_lshl_add_u64 v[12:13], v[206:207], 1, s[4:5]
	v_mad_u64_u32 v[6:7], s[0:1], v18, s55, v[10:11]
	ds_read_b128 v[6:9], v6
	s_waitcnt lgkmcnt(1)
	global_store_dwordx4 v[12:13], v[2:5], off sc0 sc1
	v_lshlrev_b32_e32 v12, 1, v18
	v_and_b32_e32 v12, 16, v12
	v_add_u32_e32 v2, s39, v18
	v_lshrrev_b32_e32 v4, 3, v18
	v_lshrrev_b32_e32 v3, 4, v2
	v_and_or_b32 v4, v4, 14, v15
	v_and_or_b32 v3, v3, s28, v14
	v_lshlrev_b32_e32 v2, 6, v2
	v_and_or_b32 v5, v17, s29, v16
	v_lshlrev_b32_e32 v4, 9, v4
	v_lshlrev_b32_e32 v3, 14, v3
	v_and_b32_e32 v2, 0x2000, v2
	v_bitop3_b32 v4, v5, v4, v12 bitop3:0xde
	v_or3_b32 v206, v3, v2, v4
	v_lshl_add_u64 v[2:3], v[206:207], 1, s[4:5]
	s_waitcnt lgkmcnt(0)
	global_store_dwordx4 v[2:3], v[6:9], off sc0 sc1
	v_add_u32_e32 v17, 0x600, v11
	v_ashrrev_i32_e32 v18, 5, v17
	v_add_u32_e32 v6, 0x400, v11
	v_ashrrev_i32_e32 v7, 5, v6
	v_mad_u64_u32 v[2:3], s[0:1], v7, s55, v[10:11]
	v_add_u32_e32 v8, s39, v7
	v_lshrrev_b32_e32 v12, 3, v7
	ds_read_b128 v[2:5], v2
	v_lshrrev_b32_e32 v9, 4, v8
	v_and_or_b32 v12, v12, 14, v15
	v_lshlrev_b32_e32 v7, 1, v7
	v_and_or_b32 v9, v9, s28, v14
	v_lshlrev_b32_e32 v8, 6, v8
	v_and_or_b32 v6, v6, s29, v16
	v_lshlrev_b32_e32 v12, 9, v12
	v_and_b32_e32 v7, 16, v7
	v_lshlrev_b32_e32 v9, 14, v9
	v_and_b32_e32 v8, 0x2000, v8
	v_bitop3_b32 v6, v6, v12, v7 bitop3:0xde
	v_or3_b32 v206, v9, v8, v6
	v_lshl_add_u64 v[12:13], v[206:207], 1, s[4:5]
	v_mad_u64_u32 v[6:7], s[0:1], v18, s55, v[10:11]
	ds_read_b128 v[6:9], v6
	s_waitcnt lgkmcnt(1)
	global_store_dwordx4 v[12:13], v[2:5], off sc0 sc1
	v_lshlrev_b32_e32 v12, 1, v18
	v_and_b32_e32 v12, 16, v12
	v_add_u32_e32 v2, s39, v18
	v_lshrrev_b32_e32 v4, 3, v18
	v_lshrrev_b32_e32 v3, 4, v2
	v_and_or_b32 v4, v4, 14, v15
	v_and_or_b32 v3, v3, s28, v14
	v_lshlrev_b32_e32 v2, 6, v2
	v_and_or_b32 v5, v17, s29, v16
	v_lshlrev_b32_e32 v4, 9, v4
	v_lshlrev_b32_e32 v3, 14, v3
	v_and_b32_e32 v2, 0x2000, v2
	v_bitop3_b32 v4, v5, v4, v12 bitop3:0xde
	v_or3_b32 v206, v3, v2, v4
	v_lshl_add_u64 v[2:3], v[206:207], 1, s[4:5]
	s_waitcnt lgkmcnt(0)
	global_store_dwordx4 v[2:3], v[6:9], off sc0 sc1
	v_add_u32_e32 v17, 0xa00, v11
	v_ashrrev_i32_e32 v18, 5, v17
	v_add_u32_e32 v6, 0x800, v11
	v_ashrrev_i32_e32 v7, 5, v6
	v_mad_u64_u32 v[2:3], s[0:1], v7, s55, v[10:11]
	v_add_u32_e32 v8, s39, v7
	v_lshrrev_b32_e32 v12, 3, v7
	ds_read_b128 v[2:5], v2
	v_lshrrev_b32_e32 v9, 4, v8
	v_and_or_b32 v12, v12, 14, v15
	v_lshlrev_b32_e32 v7, 1, v7
	v_and_or_b32 v9, v9, s28, v14
	v_lshlrev_b32_e32 v8, 6, v8
	v_and_or_b32 v6, v6, s29, v16
	v_lshlrev_b32_e32 v12, 9, v12
	v_and_b32_e32 v7, 16, v7
	v_lshlrev_b32_e32 v9, 14, v9
	v_and_b32_e32 v8, 0x2000, v8
	v_bitop3_b32 v6, v6, v12, v7 bitop3:0xde
	v_or3_b32 v206, v9, v8, v6
	v_lshl_add_u64 v[12:13], v[206:207], 1, s[4:5]
	v_mad_u64_u32 v[6:7], s[0:1], v18, s55, v[10:11]
	ds_read_b128 v[6:9], v6
	s_waitcnt lgkmcnt(1)
	global_store_dwordx4 v[12:13], v[2:5], off sc0 sc1
	v_lshlrev_b32_e32 v12, 1, v18
	v_and_b32_e32 v12, 16, v12
	v_add_u32_e32 v2, s39, v18
	v_lshrrev_b32_e32 v4, 3, v18
	v_lshrrev_b32_e32 v3, 4, v2
	v_and_or_b32 v4, v4, 14, v15
	v_and_or_b32 v3, v3, s28, v14
	v_lshlrev_b32_e32 v2, 6, v2
	v_and_or_b32 v5, v17, s29, v16
	v_lshlrev_b32_e32 v4, 9, v4
	v_lshlrev_b32_e32 v3, 14, v3
	v_and_b32_e32 v2, 0x2000, v2
	v_bitop3_b32 v4, v5, v4, v12 bitop3:0xde
	v_or3_b32 v206, v3, v2, v4
	v_lshl_add_u64 v[2:3], v[206:207], 1, s[4:5]
	s_waitcnt lgkmcnt(0)
	global_store_dwordx4 v[2:3], v[6:9], off sc0 sc1
	s_nop 1
	v_add_u32_e32 v6, 0xc00, v11
	v_ashrrev_i32_e32 v7, 5, v6
	v_mad_u64_u32 v[2:3], s[0:1], v7, s55, v[10:11]
	v_add_u32_e32 v8, s39, v7
	v_lshrrev_b32_e32 v12, 3, v7
	ds_read_b128 v[2:5], v2
	v_lshrrev_b32_e32 v9, 4, v8
	v_and_or_b32 v12, v12, 14, v15
	v_lshlrev_b32_e32 v7, 1, v7
	v_and_or_b32 v9, v9, s28, v14
	v_lshlrev_b32_e32 v8, 6, v8
	v_and_or_b32 v6, v6, s29, v16
	v_lshlrev_b32_e32 v12, 9, v12
	v_and_b32_e32 v7, 16, v7
	v_lshlrev_b32_e32 v9, 14, v9
	v_and_b32_e32 v8, 0x2000, v8
	v_bitop3_b32 v6, v6, v12, v7 bitop3:0xde
	v_add_u32_e32 v11, 0xe00, v11
	v_or3_b32 v206, v9, v8, v6
	v_ashrrev_i32_e32 v17, 5, v11
	v_lshl_add_u64 v[12:13], v[206:207], 1, s[4:5]
	v_mad_u64_u32 v[6:7], s[0:1], v17, s55, v[10:11]
	ds_read_b128 v[6:9], v6
	s_waitcnt lgkmcnt(1)
	global_store_dwordx4 v[12:13], v[2:5], off sc0 sc1
	v_lshlrev_b32_e32 v10, 1, v17
	v_and_b32_e32 v10, 16, v10
	v_add_u32_e32 v2, s39, v17
	v_lshrrev_b32_e32 v4, 3, v17
	v_lshrrev_b32_e32 v3, 4, v2
	v_and_or_b32 v4, v4, 14, v15
	v_and_or_b32 v3, v3, s28, v14
	v_lshlrev_b32_e32 v2, 6, v2
	v_and_or_b32 v5, v11, s29, v16
	v_lshlrev_b32_e32 v4, 9, v4
	v_lshlrev_b32_e32 v3, 14, v3
	v_and_b32_e32 v2, 0x2000, v2
	v_bitop3_b32 v4, v5, v4, v10 bitop3:0xde
	v_or3_b32 v206, v3, v2, v4
	v_lshl_add_u64 v[2:3], v[206:207], 1, s[4:5]
	s_waitcnt lgkmcnt(0)
	global_store_dwordx4 v[2:3], v[6:9], off sc0 sc1
	s_barrier
	s_mov_b64 s[0:1], 0

; __device__ __forceinline__ u32x4 pack8(const float (&f)[8]) { u32x4 o; o.x = pk2(f[0], f[1]); o.y = pk2(f[2], f[3]); o.z = pk2(f[4], f[5]); o.w = pk2(f[6], f[7]); return o; }
; __device__ __forceinline__ void sgu_unit(const Args& a, LAS unsigned char* lds, int l, int tt) {
;     ...
;     {
;         const int c = tid & 255, q0 = (tid >> 8) * 64;
;         const float lg = a.in[18][l * 256 + c], lb = a.in[19][l * 256 + c];
;         u32x4 pk[8];
; #pragma unroll
;         for (int j = 0; j < 8; ++j) {
;             float y[8];
; #pragma unroll
;             for (int e = 0; e < 8; ++e) { const int q = q0 + 8 * j + e; const f32x2 st = stats[q]; y[e] = (bf2f(Vb[q * CXS + c]) - st[0]) * st[1] * lg + lb; }
;             pk[j] = pack8(y);
;         }
.LBB0_487:
	s_or_b64 exec, exec, s[4:5]
	v_and_b32_e32 v105, 0xff, v113
	v_or_b32_e32 v82, s78, v105
	v_ashrrev_i32_e32 v83, 31, v82
	v_readlane_b32 s8, v254, 39
	v_lshlrev_b64 v[82:83], 2, v[82:83]
	v_readlane_b32 s12, v254, 43
	v_readlane_b32 s13, v254, 44
	v_readlane_b32 s14, v254, 45
	v_readlane_b32 s15, v254, 46
	s_waitcnt lgkmcnt(0)
	v_lshl_add_u64 v[84:85], s[12:13], 0, v[82:83]
	v_lshl_add_u64 v[82:83], s[14:15], 0, v[82:83]
	s_barrier
	global_load_dword v102, v[84:85], off
	global_load_dword v104, v[82:83], off
	v_and_b32_e32 v107, 0xffffffc0, v103
	s_add_i32 s4, 0, 0x21800
	v_lshl_add_u32 v110, v107, 3, s4
	v_lshl_add_u32 v106, v105, 1, 0
	ds_read_b128 v[82:85], v110
	ds_read_b128 v[86:89], v110 offset:16
	ds_read_b128 v[90:93], v110 offset:32
	ds_read_b128 v[94:97], v110 offset:48
	v_mad_u64_u32 v[108:109], s[34:35], v107, s55, v[106:107]
	ds_read_b128 v[98:101], v110 offset:64
	ds_read_b128 v[114:117], v110 offset:80
	ds_read_b128 v[118:121], v110 offset:96
	ds_read_b128 v[122:125], v110 offset:112
	ds_read_u16 v109, v108
	ds_read_u16 v113, v108 offset:528
	ds_read_u16 v128, v108 offset:1056
	ds_read_u16 v129, v108 offset:1584
	ds_read_u16 v130, v108 offset:2112
	ds_read_u16 v132, v108 offset:2640
	ds_read_u16 v131, v108 offset:3168
	ds_read_u16 v133, v108 offset:3696
	s_waitcnt lgkmcnt(14)
	v_mov_b32_e32 v126, v82
	v_mov_b32_e32 v127, v86
	v_mov_b32_e32 v86, v83
	v_mov_b32_e32 v82, v84
	v_mov_b32_e32 v83, v88
	v_mov_b32_e32 v88, v85
	s_waitcnt lgkmcnt(13)
	v_mov_b32_e32 v84, v90
	s_waitcnt lgkmcnt(12)
	v_mov_b32_e32 v85, v94
	v_mov_b32_e32 v94, v91
	v_mov_b32_e32 v90, v92
	v_mov_b32_e32 v91, v96
	v_mov_b32_e32 v96, v93
	s_waitcnt lgkmcnt(5)
	v_lshlrev_b32_e32 v93, 16, v128
	v_lshlrev_b32_e32 v92, 16, v109
	s_waitcnt lgkmcnt(4)
	v_lshlrev_b32_e32 v129, 16, v129
	v_lshlrev_b32_e32 v128, 16, v113
	v_pk_add_f32 v[92:93], v[92:93], v[126:127] neg_lo:[0,1] neg_hi:[0,1]
	s_waitcnt lgkmcnt(1)
	v_lshlrev_b32_e32 v131, 16, v131
	v_lshlrev_b32_e32 v130, 16, v130
	s_waitcnt lgkmcnt(0)
	v_lshlrev_b32_e32 v133, 16, v133
	v_lshlrev_b32_e32 v132, 16, v132
	v_pk_add_f32 v[82:83], v[128:129], v[82:83] neg_lo:[0,1] neg_hi:[0,1]
	v_pk_mul_f32 v[86:87], v[86:87], v[92:93]
	v_pk_add_f32 v[84:85], v[130:131], v[84:85] neg_lo:[0,1] neg_hi:[0,1]
	v_pk_add_f32 v[90:91], v[132:133], v[90:91] neg_lo:[0,1] neg_hi:[0,1]
	v_pk_mul_f32 v[82:83], v[88:89], v[82:83]
	v_pk_mul_f32 v[84:85], v[94:95], v[84:85]
	v_pk_mul_f32 v[88:89], v[96:97], v[90:91]
	s_movk_i32 s34, 0x1e0
	v_readlane_b32 s28, v253, 18
	v_readlane_b32 s29, v253, 19
	v_readlane_b32 s9, v254, 40
	v_readlane_b32 s10, v254, 41
	v_readlane_b32 s11, v254, 42
	v_readlane_b32 s16, v254, 47
	v_readlane_b32 s17, v254, 48
	v_readlane_b32 s18, v254, 49
	v_readlane_b32 s19, v254, 50
	v_readlane_b32 s20, v254, 51
	v_readlane_b32 s21, v254, 52
	v_readlane_b32 s22, v254, 53
	v_readlane_b32 s23, v254, 54
	s_waitcnt vmcnt(0)
	v_pk_fma_f32 v[86:87], v[102:103], v[86:87], v[104:105] op_sel_hi:[0,1,0]
	v_pk_fma_f32 v[82:83], v[102:103], v[82:83], v[104:105] op_sel_hi:[0,1,0]
	v_bfe_u32 v94, v86, 16, 1
	v_bfe_u32 v95, v87, 16, 1
	v_pk_fma_f32 v[84:85], v[102:103], v[84:85], v[104:105] op_sel_hi:[0,1,0]
	v_pk_fma_f32 v[88:89], v[102:103], v[88:89], v[104:105] op_sel_hi:[0,1,0]
	v_bfe_u32 v92, v83, 16, 1
	v_bfe_u32 v93, v82, 16, 1
	v_add3_u32 v87, v87, v95, s27
	v_add3_u32 v86, v86, v94, s27
	v_bfe_u32 v90, v89, 16, 1
	v_bfe_u32 v91, v88, 16, 1
	v_bfe_u32 v96, v84, 16, 1
	v_bfe_u32 v97, v85, 16, 1
	v_add3_u32 v82, v82, v93, s27
	v_add3_u32 v83, v83, v92, s27
	v_lshrrev_b32_e32 v86, 16, v86
	v_lshrrev_b32_e32 v87, 16, v87
	v_add3_u32 v88, v88, v91, s27
	v_add3_u32 v89, v89, v90, s27
	v_add3_u32 v85, v85, v97, s27
	v_add3_u32 v84, v84, v96, s27
	v_and_or_b32 v83, v83, s6, v87
	v_and_or_b32 v82, v82, s6, v86
	ds_read_u16 v86, v108 offset:4224
	ds_read_u16 v90, v108 offset:4752
	ds_read_u16 v87, v108 offset:5280
	ds_read_u16 v91, v108 offset:5808
	ds_read_u16 v92, v108 offset:6336
	ds_read_u16 v94, v108 offset:6864
	ds_read_u16 v93, v108 offset:7392
	ds_read_u16 v95, v108 offset:7920
	v_lshrrev_b32_e32 v84, 16, v84
	v_lshrrev_b32_e32 v85, 16, v85
	v_and_or_b32 v85, v89, s6, v85
	v_and_or_b32 v84, v88, s6, v84
	s_waitcnt lgkmcnt(5)
	v_lshlrev_b32_e32 v87, 16, v87
	v_lshlrev_b32_e32 v86, 16, v86
	v_mov_b32_e32 v88, v98
	v_mov_b32_e32 v89, v114
	v_pk_add_f32 v[86:87], v[86:87], v[88:89] neg_lo:[0,1] neg_hi:[0,1]
	s_waitcnt lgkmcnt(4)
	v_lshlrev_b32_e32 v89, 16, v91
	v_lshlrev_b32_e32 v88, 16, v90
	v_mov_b32_e32 v90, v100
	v_mov_b32_e32 v91, v116
	v_pk_add_f32 v[88:89], v[88:89], v[90:91] neg_lo:[0,1] neg_hi:[0,1]
	s_waitcnt lgkmcnt(1)
	v_lshlrev_b32_e32 v91, 16, v93
	v_lshlrev_b32_e32 v90, 16, v92
	v_mov_b32_e32 v92, v118
	v_mov_b32_e32 v93, v122
	v_pk_add_f32 v[90:91], v[90:91], v[92:93] neg_lo:[0,1] neg_hi:[0,1]
	s_waitcnt lgkmcnt(0)
; __device__ __forceinline__ u32x4 pack8(const float (&f)[8]) { u32x4 o; o.x = pk2(f[0], f[1]); o.y = pk2(f[2], f[3]); o.z = pk2(f[4], f[5]); o.w = pk2(f[6], f[7]); return o; }
; __device__ __forceinline__ void sgu_unit(const Args& a, LAS unsigned char* lds, int l, int tt) {
;     ...
;         for (int j = 0; j < 8; ++j) {
;             float y[8];
; #pragma unroll
;             for (int e = 0; e < 8; ++e) { const int q = q0 + 8 * j + e; const f32x2 st = stats[q]; y[e] = (bf2f(Vb[q * CXS + c]) - st[0]) * st[1] * lg + lb; }
;             pk[j] = pack8(y);
;         }
	v_lshlrev_b32_e32 v93, 16, v95
	v_lshlrev_b32_e32 v92, 16, v94
	v_mov_b32_e32 v94, v120
	v_mov_b32_e32 v95, v124
	v_mov_b32_e32 v116, v101
	v_pk_add_f32 v[92:93], v[92:93], v[94:95] neg_lo:[0,1] neg_hi:[0,1]
	v_mov_b32_e32 v124, v121
	v_mov_b32_e32 v114, v99
	v_pk_mul_f32 v[88:89], v[116:117], v[88:89]
	v_mov_b32_e32 v122, v119
	v_pk_mul_f32 v[92:93], v[124:125], v[92:93]
	v_pk_mul_f32 v[86:87], v[114:115], v[86:87]
	v_pk_fma_f32 v[88:89], v[102:103], v[88:89], v[104:105] op_sel_hi:[0,1,0]
	v_pk_mul_f32 v[90:91], v[122:123], v[90:91]
	v_pk_fma_f32 v[92:93], v[102:103], v[92:93], v[104:105] op_sel_hi:[0,1,0]
	v_pk_fma_f32 v[86:87], v[102:103], v[86:87], v[104:105] op_sel_hi:[0,1,0]
	v_pk_fma_f32 v[90:91], v[102:103], v[90:91], v[104:105] op_sel_hi:[0,1,0]
	v_bfe_u32 v94, v93, 16, 1
	v_bfe_u32 v95, v92, 16, 1
	v_bfe_u32 v96, v89, 16, 1
	v_bfe_u32 v97, v88, 16, 1
	v_add3_u32 v97, v88, v97, s27
	v_add3_u32 v96, v89, v96, s27
	v_add3_u32 v88, v92, v95, s27
	v_add3_u32 v89, v93, v94, s27
	v_bfe_u32 v92, v86, 16, 1
	v_bfe_u32 v93, v87, 16, 1
	v_bfe_u32 v94, v90, 16, 1
	v_bfe_u32 v95, v91, 16, 1
	v_add3_u32 v91, v91, v95, s27
	v_add3_u32 v90, v90, v94, s27
	v_add3_u32 v87, v87, v93, s27
	v_add3_u32 v86, v86, v92, s27
	v_lshrrev_b32_e32 v86, 16, v86
	v_lshrrev_b32_e32 v87, 16, v87
	v_lshrrev_b32_e32 v90, 16, v90
	v_lshrrev_b32_e32 v91, 16, v91
	v_and_or_b32 v89, v89, s6, v91
	v_and_or_b32 v88, v88, s6, v90
	v_and_or_b32 v87, v96, s6, v87
	v_and_or_b32 v86, v97, s6, v86
	ds_read_b128 v[90:93], v110 offset:128
	ds_read_b128 v[94:97], v110 offset:144
	ds_read_b128 v[98:101], v110 offset:160
	ds_read_b128 v[114:117], v110 offset:176
	ds_read_u16 v109, v108 offset:8448
	ds_read_u16 v113, v108 offset:8976
	ds_read_u16 v118, v108 offset:9504
	ds_read_u16 v122, v108 offset:10032
	ds_read_u16 v123, v108 offset:10560
	ds_read_u16 v124, v108 offset:11088
	ds_read_u16 v125, v108 offset:11616
	ds_read_u16 v126, v108 offset:12144
	s_waitcnt lgkmcnt(5)
	v_lshlrev_b32_e32 v119, 16, v118
	v_lshlrev_b32_e32 v118, 16, v109
	v_mov_b32_e32 v120, v90
	v_mov_b32_e32 v121, v94
	v_pk_add_f32 v[118:119], v[118:119], v[120:121] neg_lo:[0,1] neg_hi:[0,1]
	v_mov_b32_e32 v94, v91
	v_pk_mul_f32 v[90:91], v[94:95], v[118:119]
	s_waitcnt lgkmcnt(4)
	v_lshlrev_b32_e32 v95, 16, v122
	v_lshlrev_b32_e32 v94, 16, v113
	v_mov_b32_e32 v118, v92
	v_mov_b32_e32 v119, v96
	v_pk_add_f32 v[94:95], v[94:95], v[118:119] neg_lo:[0,1] neg_hi:[0,1]
	v_mov_b32_e32 v96, v93
	v_pk_mul_f32 v[92:93], v[96:97], v[94:95]
	s_waitcnt lgkmcnt(1)
	v_lshlrev_b32_e32 v95, 16, v125
	v_lshlrev_b32_e32 v94, 16, v123
	v_mov_b32_e32 v96, v98
	v_mov_b32_e32 v97, v114
	v_pk_add_f32 v[94:95], v[94:95], v[96:97] neg_lo:[0,1] neg_hi:[0,1]
	v_mov_b32_e32 v114, v99
	s_waitcnt lgkmcnt(0)
	v_lshlrev_b32_e32 v97, 16, v126
	v_lshlrev_b32_e32 v96, 16, v124
	v_mov_b32_e32 v98, v100
	v_mov_b32_e32 v99, v116
	v_pk_add_f32 v[96:97], v[96:97], v[98:99] neg_lo:[0,1] neg_hi:[0,1]
	v_mov_b32_e32 v116, v101
	v_pk_mul_f32 v[96:97], v[116:117], v[96:97]
	v_pk_fma_f32 v[92:93], v[102:103], v[92:93], v[104:105] op_sel_hi:[0,1,0]
	v_pk_mul_f32 v[94:95], v[114:115], v[94:95]
	v_pk_fma_f32 v[96:97], v[102:103], v[96:97], v[104:105] op_sel_hi:[0,1,0]
	v_pk_fma_f32 v[90:91], v[102:103], v[90:91], v[104:105] op_sel_hi:[0,1,0]
	v_pk_fma_f32 v[94:95], v[102:103], v[94:95], v[104:105] op_sel_hi:[0,1,0]
	v_bfe_u32 v98, v97, 16, 1
	v_bfe_u32 v99, v96, 16, 1
	v_bfe_u32 v100, v93, 16, 1
	v_bfe_u32 v101, v92, 16, 1
	v_add3_u32 v101, v92, v101, s27
	v_add3_u32 v100, v93, v100, s27
	v_add3_u32 v92, v96, v99, s27
	v_add3_u32 v93, v97, v98, s27
	v_bfe_u32 v96, v90, 16, 1
	v_bfe_u32 v97, v91, 16, 1
	v_bfe_u32 v98, v94, 16, 1
	v_bfe_u32 v99, v95, 16, 1
	v_add3_u32 v95, v95, v99, s27
	v_add3_u32 v94, v94, v98, s27
	v_add3_u32 v91, v91, v97, s27
	v_add3_u32 v90, v90, v96, s27
	v_lshrrev_b32_e32 v90, 16, v90
	v_lshrrev_b32_e32 v91, 16, v91
	v_lshrrev_b32_e32 v94, 16, v94
	v_lshrrev_b32_e32 v95, 16, v95
	v_and_or_b32 v93, v93, s6, v95
	v_and_or_b32 v92, v92, s6, v94
	v_and_or_b32 v91, v100, s6, v91
	v_and_or_b32 v90, v101, s6, v90
	ds_read_b128 v[94:97], v110 offset:192
	ds_read_b128 v[98:101], v110 offset:208
	ds_read_b128 v[114:117], v110 offset:224
	ds_read_b128 v[118:121], v110 offset:240
	ds_read_u16 v109, v108 offset:12672
	ds_read_u16 v113, v108 offset:13200
	ds_read_u16 v122, v108 offset:13728
	ds_read_u16 v126, v108 offset:14256
	ds_read_u16 v127, v108 offset:14784
	ds_read_u16 v128, v108 offset:15312
	ds_read_u16 v129, v108 offset:15840
	ds_read_u16 v130, v108 offset:16368
	s_waitcnt lgkmcnt(5)
	v_lshlrev_b32_e32 v123, 16, v122
	v_lshlrev_b32_e32 v122, 16, v109
	v_mov_b32_e32 v124, v94
	v_mov_b32_e32 v125, v98
	v_pk_add_f32 v[122:123], v[122:123], v[124:125] neg_lo:[0,1] neg_hi:[0,1]
	v_mov_b32_e32 v98, v95
	v_pk_mul_f32 v[94:95], v[98:99], v[122:123]
	s_waitcnt lgkmcnt(4)
	v_lshlrev_b32_e32 v99, 16, v126
	v_lshlrev_b32_e32 v98, 16, v113
	v_mov_b32_e32 v122, v96
	v_mov_b32_e32 v123, v100
	v_pk_add_f32 v[98:99], v[98:99], v[122:123] neg_lo:[0,1] neg_hi:[0,1]
	v_mov_b32_e32 v100, v97
	v_pk_mul_f32 v[96:97], v[100:101], v[98:99]
	s_waitcnt lgkmcnt(1)
	v_lshlrev_b32_e32 v99, 16, v129
	v_lshlrev_b32_e32 v98, 16, v127
	v_mov_b32_e32 v100, v114
	v_mov_b32_e32 v101, v118
	v_pk_add_f32 v[98:99], v[98:99], v[100:101] neg_lo:[0,1] neg_hi:[0,1]
	v_mov_b32_e32 v118, v115
	s_waitcnt lgkmcnt(0)
; __device__ __forceinline__ u32x4 pack8(const float (&f)[8]) { u32x4 o; o.x = pk2(f[0], f[1]); o.y = pk2(f[2], f[3]); o.z = pk2(f[4], f[5]); o.w = pk2(f[6], f[7]); return o; }
; __device__ __forceinline__ void sgu_unit(const Args& a, LAS unsigned char* lds, int l, int tt) {
;     ...
;         for (int j = 0; j < 8; ++j) {
;             float y[8];
; #pragma unroll
;             for (int e = 0; e < 8; ++e) { const int q = q0 + 8 * j + e; const f32x2 st = stats[q]; y[e] = (bf2f(Vb[q * CXS + c]) - st[0]) * st[1] * lg + lb; }
;             pk[j] = pack8(y);
;         }
	v_lshlrev_b32_e32 v101, 16, v130
	v_lshlrev_b32_e32 v100, 16, v128
	v_mov_b32_e32 v114, v116
	v_mov_b32_e32 v115, v120
	v_pk_add_f32 v[100:101], v[100:101], v[114:115] neg_lo:[0,1] neg_hi:[0,1]
	v_mov_b32_e32 v120, v117
	v_pk_mul_f32 v[100:101], v[120:121], v[100:101]
	v_pk_fma_f32 v[96:97], v[102:103], v[96:97], v[104:105] op_sel_hi:[0,1,0]
	v_pk_mul_f32 v[98:99], v[118:119], v[98:99]
	v_pk_fma_f32 v[100:101], v[102:103], v[100:101], v[104:105] op_sel_hi:[0,1,0]
	v_pk_fma_f32 v[94:95], v[102:103], v[94:95], v[104:105] op_sel_hi:[0,1,0]
	v_pk_fma_f32 v[98:99], v[102:103], v[98:99], v[104:105] op_sel_hi:[0,1,0]
	v_bfe_u32 v109, v101, 16, 1
	v_bfe_u32 v113, v100, 16, 1
	v_bfe_u32 v114, v97, 16, 1
	v_bfe_u32 v115, v96, 16, 1
	v_add3_u32 v115, v96, v115, s27
	v_add3_u32 v114, v97, v114, s27
	v_add3_u32 v96, v100, v113, s27
	v_add3_u32 v97, v101, v109, s27
	v_bfe_u32 v100, v94, 16, 1
	v_bfe_u32 v101, v95, 16, 1
	v_bfe_u32 v109, v98, 16, 1
	v_bfe_u32 v113, v99, 16, 1
	v_add3_u32 v99, v99, v113, s27
	v_add3_u32 v98, v98, v109, s27
	v_add3_u32 v95, v95, v101, s27
	v_add3_u32 v94, v94, v100, s27
	v_lshrrev_b32_e32 v94, 16, v94
	v_lshrrev_b32_e32 v95, 16, v95
	v_lshrrev_b32_e32 v98, 16, v98
	v_lshrrev_b32_e32 v99, 16, v99
	v_and_or_b32 v97, v97, s6, v99
	v_and_or_b32 v96, v96, s6, v98
	v_and_or_b32 v95, v114, s6, v95
	v_and_or_b32 v94, v115, s6, v94
	ds_read_b128 v[98:101], v110 offset:256
	ds_read_b128 v[114:117], v110 offset:272
	ds_read_b128 v[118:121], v110 offset:288
	ds_read_b128 v[122:125], v110 offset:304
	ds_read_u16 v109, v108 offset:16896
	ds_read_u16 v113, v108 offset:17424
	ds_read_u16 v126, v108 offset:17952
	ds_read_u16 v130, v108 offset:18480
	ds_read_u16 v131, v108 offset:19008
	ds_read_u16 v132, v108 offset:19536
	ds_read_u16 v133, v108 offset:20064
	ds_read_u16 v134, v108 offset:20592
	s_waitcnt lgkmcnt(5)
	v_lshlrev_b32_e32 v127, 16, v126
	v_lshlrev_b32_e32 v126, 16, v109
	v_mov_b32_e32 v128, v98
	v_mov_b32_e32 v129, v114
	v_pk_add_f32 v[126:127], v[126:127], v[128:129] neg_lo:[0,1] neg_hi:[0,1]
	v_mov_b32_e32 v114, v99
	v_pk_mul_f32 v[98:99], v[114:115], v[126:127]
	s_waitcnt lgkmcnt(4)
	v_lshlrev_b32_e32 v115, 16, v130
	v_lshlrev_b32_e32 v114, 16, v113
	v_mov_b32_e32 v126, v100
	v_mov_b32_e32 v127, v116
	v_pk_add_f32 v[114:115], v[114:115], v[126:127] neg_lo:[0,1] neg_hi:[0,1]
	v_mov_b32_e32 v116, v101
	v_pk_mul_f32 v[100:101], v[116:117], v[114:115]
	s_waitcnt lgkmcnt(1)
	v_lshlrev_b32_e32 v115, 16, v133
	v_lshlrev_b32_e32 v114, 16, v131
	v_mov_b32_e32 v116, v118
	v_mov_b32_e32 v117, v122
	v_pk_add_f32 v[114:115], v[114:115], v[116:117] neg_lo:[0,1] neg_hi:[0,1]
	v_mov_b32_e32 v122, v119
	s_waitcnt lgkmcnt(0)
	v_lshlrev_b32_e32 v117, 16, v134
	v_lshlrev_b32_e32 v116, 16, v132
	v_mov_b32_e32 v118, v120
	v_mov_b32_e32 v119, v124
	v_pk_add_f32 v[116:117], v[116:117], v[118:119] neg_lo:[0,1] neg_hi:[0,1]
	v_mov_b32_e32 v124, v121
	v_pk_mul_f32 v[116:117], v[124:125], v[116:117]
	v_pk_fma_f32 v[100:101], v[102:103], v[100:101], v[104:105] op_sel_hi:[0,1,0]
	v_pk_mul_f32 v[114:115], v[122:123], v[114:115]
	v_pk_fma_f32 v[116:117], v[102:103], v[116:117], v[104:105] op_sel_hi:[0,1,0]
	v_pk_fma_f32 v[98:99], v[102:103], v[98:99], v[104:105] op_sel_hi:[0,1,0]
	v_pk_fma_f32 v[114:115], v[102:103], v[114:115], v[104:105] op_sel_hi:[0,1,0]
	v_bfe_u32 v109, v117, 16, 1
	v_bfe_u32 v113, v116, 16, 1
	v_bfe_u32 v118, v101, 16, 1
	v_bfe_u32 v119, v100, 16, 1
	v_add3_u32 v119, v100, v119, s27
	v_add3_u32 v118, v101, v118, s27
	v_add3_u32 v100, v116, v113, s27
	v_add3_u32 v101, v117, v109, s27
	v_bfe_u32 v109, v98, 16, 1
	v_bfe_u32 v113, v99, 16, 1
	v_bfe_u32 v116, v114, 16, 1
	v_bfe_u32 v117, v115, 16, 1
	v_add3_u32 v115, v115, v117, s27
	v_add3_u32 v114, v114, v116, s27
	v_add3_u32 v99, v99, v113, s27
	v_add3_u32 v98, v98, v109, s27
	v_lshrrev_b32_e32 v98, 16, v98
	v_lshrrev_b32_e32 v99, 16, v99
	v_lshrrev_b32_e32 v109, 16, v114
	v_lshrrev_b32_e32 v113, 16, v115
	v_and_or_b32 v101, v101, s6, v113
	v_and_or_b32 v100, v100, s6, v109
	v_and_or_b32 v99, v118, s6, v99
	v_and_or_b32 v98, v119, s6, v98
	ds_read_b128 v[114:117], v110 offset:320
	ds_read_b128 v[118:121], v110 offset:336
	ds_read_b128 v[122:125], v110 offset:352
	ds_read_b128 v[126:129], v110 offset:368
	ds_read_u16 v109, v108 offset:21120
	ds_read_u16 v113, v108 offset:21648
	ds_read_u16 v130, v108 offset:22176
	ds_read_u16 v134, v108 offset:22704
	ds_read_u16 v135, v108 offset:23232
	ds_read_u16 v136, v108 offset:23760
	ds_read_u16 v137, v108 offset:24288
	ds_read_u16 v138, v108 offset:24816
	s_waitcnt lgkmcnt(5)
	v_lshlrev_b32_e32 v131, 16, v130
	v_lshlrev_b32_e32 v130, 16, v109
	v_mov_b32_e32 v132, v114
	v_mov_b32_e32 v133, v118
	v_pk_add_f32 v[130:131], v[130:131], v[132:133] neg_lo:[0,1] neg_hi:[0,1]
	v_mov_b32_e32 v118, v115
	v_pk_mul_f32 v[114:115], v[118:119], v[130:131]
	s_waitcnt lgkmcnt(4)
	v_lshlrev_b32_e32 v119, 16, v134
	v_lshlrev_b32_e32 v118, 16, v113
	v_mov_b32_e32 v130, v116
	v_mov_b32_e32 v131, v120
	v_pk_add_f32 v[118:119], v[118:119], v[130:131] neg_lo:[0,1] neg_hi:[0,1]
	v_mov_b32_e32 v120, v117
	v_pk_mul_f32 v[116:117], v[120:121], v[118:119]
	s_waitcnt lgkmcnt(1)
	v_lshlrev_b32_e32 v119, 16, v137
	v_lshlrev_b32_e32 v118, 16, v135
	v_mov_b32_e32 v120, v122
	v_mov_b32_e32 v121, v126
	v_pk_add_f32 v[118:119], v[118:119], v[120:121] neg_lo:[0,1] neg_hi:[0,1]
	v_mov_b32_e32 v126, v123
	s_waitcnt lgkmcnt(0)
; __device__ __forceinline__ u32x4 pack8(const float (&f)[8]) { u32x4 o; o.x = pk2(f[0], f[1]); o.y = pk2(f[2], f[3]); o.z = pk2(f[4], f[5]); o.w = pk2(f[6], f[7]); return o; }
; __device__ __forceinline__ void sgu_unit(const Args& a, LAS unsigned char* lds, int l, int tt) {
;     ...
;         for (int j = 0; j < 8; ++j) {
;             float y[8];
; #pragma unroll
;             for (int e = 0; e < 8; ++e) { const int q = q0 + 8 * j + e; const f32x2 st = stats[q]; y[e] = (bf2f(Vb[q * CXS + c]) - st[0]) * st[1] * lg + lb; }
;             pk[j] = pack8(y);
;         }
	v_lshlrev_b32_e32 v121, 16, v138
	v_lshlrev_b32_e32 v120, 16, v136
	v_mov_b32_e32 v122, v124
	v_mov_b32_e32 v123, v128
	v_pk_add_f32 v[120:121], v[120:121], v[122:123] neg_lo:[0,1] neg_hi:[0,1]
	v_mov_b32_e32 v128, v125
	v_pk_mul_f32 v[120:121], v[128:129], v[120:121]
	v_pk_fma_f32 v[116:117], v[102:103], v[116:117], v[104:105] op_sel_hi:[0,1,0]
	v_pk_mul_f32 v[118:119], v[126:127], v[118:119]
	v_pk_fma_f32 v[120:121], v[102:103], v[120:121], v[104:105] op_sel_hi:[0,1,0]
	v_pk_fma_f32 v[114:115], v[102:103], v[114:115], v[104:105] op_sel_hi:[0,1,0]
	v_pk_fma_f32 v[118:119], v[102:103], v[118:119], v[104:105] op_sel_hi:[0,1,0]
	v_bfe_u32 v109, v121, 16, 1
	v_bfe_u32 v113, v120, 16, 1
	v_bfe_u32 v122, v117, 16, 1
	v_bfe_u32 v123, v116, 16, 1
	v_add3_u32 v123, v116, v123, s27
	v_add3_u32 v122, v117, v122, s27
	v_add3_u32 v113, v120, v113, s27
	v_add3_u32 v109, v121, v109, s27
	v_bfe_u32 v116, v114, 16, 1
	v_bfe_u32 v117, v115, 16, 1
	v_bfe_u32 v120, v118, 16, 1
	v_bfe_u32 v121, v119, 16, 1
	v_add3_u32 v119, v119, v121, s27
	v_add3_u32 v118, v118, v120, s27
	v_add3_u32 v115, v115, v117, s27
	v_add3_u32 v114, v114, v116, s27
	v_lshrrev_b32_e32 v114, 16, v114
	v_lshrrev_b32_e32 v115, 16, v115
	v_lshrrev_b32_e32 v116, 16, v118
	v_lshrrev_b32_e32 v117, 16, v119
	v_and_or_b32 v117, v109, s6, v117
	v_and_or_b32 v116, v113, s6, v116
	v_and_or_b32 v115, v122, s6, v115
	v_and_or_b32 v114, v123, s6, v114
	ds_read_b128 v[118:121], v110 offset:384
	ds_read_b128 v[122:125], v110 offset:400
	ds_read_b128 v[126:129], v110 offset:416
	ds_read_b128 v[130:133], v110 offset:432
	ds_read_u16 v109, v108 offset:25344
	ds_read_u16 v113, v108 offset:25872
	ds_read_u16 v134, v108 offset:26400
	ds_read_u16 v138, v108 offset:26928
	ds_read_u16 v139, v108 offset:27456
	ds_read_u16 v140, v108 offset:27984
	ds_read_u16 v141, v108 offset:28512
	ds_read_u16 v142, v108 offset:29040
	s_waitcnt lgkmcnt(5)
	v_lshlrev_b32_e32 v135, 16, v134
	v_lshlrev_b32_e32 v134, 16, v109
	v_mov_b32_e32 v136, v118
	v_mov_b32_e32 v137, v122
	v_pk_add_f32 v[134:135], v[134:135], v[136:137] neg_lo:[0,1] neg_hi:[0,1]
	v_mov_b32_e32 v122, v119
	v_pk_mul_f32 v[118:119], v[122:123], v[134:135]
	s_waitcnt lgkmcnt(4)
	v_lshlrev_b32_e32 v123, 16, v138
	v_lshlrev_b32_e32 v122, 16, v113
	v_mov_b32_e32 v134, v120
	v_mov_b32_e32 v135, v124
	v_pk_add_f32 v[122:123], v[122:123], v[134:135] neg_lo:[0,1] neg_hi:[0,1]
	v_mov_b32_e32 v124, v121
	v_pk_mul_f32 v[120:121], v[124:125], v[122:123]
	s_waitcnt lgkmcnt(1)
	v_lshlrev_b32_e32 v123, 16, v141
	v_lshlrev_b32_e32 v122, 16, v139
	v_mov_b32_e32 v124, v126
	v_mov_b32_e32 v125, v130
	v_pk_add_f32 v[122:123], v[122:123], v[124:125] neg_lo:[0,1] neg_hi:[0,1]
	v_mov_b32_e32 v130, v127
	s_waitcnt lgkmcnt(0)
	v_lshlrev_b32_e32 v125, 16, v142
	v_lshlrev_b32_e32 v124, 16, v140
	v_mov_b32_e32 v126, v128
	v_mov_b32_e32 v127, v132
	v_pk_add_f32 v[124:125], v[124:125], v[126:127] neg_lo:[0,1] neg_hi:[0,1]
	v_mov_b32_e32 v132, v129
	v_pk_fma_f32 v[120:121], v[102:103], v[120:121], v[104:105] op_sel_hi:[0,1,0]
	v_pk_mul_f32 v[124:125], v[132:133], v[124:125]
	v_pk_fma_f32 v[118:119], v[102:103], v[118:119], v[104:105] op_sel_hi:[0,1,0]
	v_pk_mul_f32 v[122:123], v[130:131], v[122:123]
	v_pk_fma_f32 v[124:125], v[102:103], v[124:125], v[104:105] op_sel_hi:[0,1,0]
	v_bfe_u32 v126, v121, 16, 1
	v_bfe_u32 v127, v120, 16, 1
	v_pk_fma_f32 v[122:123], v[102:103], v[122:123], v[104:105] op_sel_hi:[0,1,0]
	v_bfe_u32 v109, v125, 16, 1
	v_bfe_u32 v113, v124, 16, 1
	v_add3_u32 v127, v120, v127, s27
	v_add3_u32 v126, v121, v126, s27
	v_bfe_u32 v120, v118, 16, 1
	v_bfe_u32 v121, v119, 16, 1
	v_add3_u32 v113, v124, v113, s27
	v_add3_u32 v109, v125, v109, s27
	v_bfe_u32 v124, v122, 16, 1
	v_bfe_u32 v125, v123, 16, 1
	v_add3_u32 v119, v119, v121, s27
	v_add3_u32 v118, v118, v120, s27
	v_add3_u32 v123, v123, v125, s27
	v_add3_u32 v122, v122, v124, s27
	v_lshrrev_b32_e32 v118, 16, v118
	v_lshrrev_b32_e32 v119, 16, v119
	v_lshrrev_b32_e32 v120, 16, v122
	v_lshrrev_b32_e32 v121, 16, v123
	v_and_or_b32 v119, v126, s6, v119
	v_and_or_b32 v118, v127, s6, v118
	ds_read_b128 v[122:125], v110 offset:448
	ds_read_b128 v[126:129], v110 offset:464
	ds_read_b128 v[130:133], v110 offset:480
	ds_read_b64 v[134:135], v110 offset:496
	v_or_b32_e32 v103, 63, v103
	v_and_or_b32 v121, v109, s6, v121
	v_lshl_add_u32 v109, v103, 3, s4
	v_and_or_b32 v120, v113, s6, v120
	ds_read_u16 v110, v108 offset:29568
	ds_read_u16 v113, v108 offset:30096
	ds_read_u16 v138, v108 offset:30624
	ds_read_u16 v140, v108 offset:31152
	ds_read_u16 v141, v108 offset:31680
	ds_read_u16 v142, v108 offset:32208
	ds_read_u16 v143, v108 offset:32736
	ds_read_b64 v[108:109], v109
	v_mad_u64_u32 v[136:137], s[4:5], v103, s55, v[106:107]
	ds_read_u16 v103, v136
	s_waitcnt lgkmcnt(6)
	v_lshlrev_b32_e32 v137, 16, v138
	v_lshlrev_b32_e32 v136, 16, v110
	v_mov_b32_e32 v138, v122
	v_mov_b32_e32 v139, v126
	v_pk_add_f32 v[136:137], v[136:137], v[138:139] neg_lo:[0,1] neg_hi:[0,1]
	v_mov_b32_e32 v126, v123
	v_pk_mul_f32 v[122:123], v[126:127], v[136:137]
	s_waitcnt lgkmcnt(5)
	v_lshlrev_b32_e32 v127, 16, v140
	v_lshlrev_b32_e32 v126, 16, v113
	v_mov_b32_e32 v136, v124
	v_mov_b32_e32 v137, v128
	v_pk_add_f32 v[126:127], v[126:127], v[136:137] neg_lo:[0,1] neg_hi:[0,1]
	v_mov_b32_e32 v128, v125
	v_pk_mul_f32 v[124:125], v[128:129], v[126:127]
	s_waitcnt lgkmcnt(2)
	v_lshlrev_b32_e32 v127, 16, v143
	v_lshlrev_b32_e32 v126, 16, v141
	v_mov_b32_e32 v128, v130
	v_mov_b32_e32 v129, v134
	v_pk_add_f32 v[126:127], v[126:127], v[128:129] neg_lo:[0,1] neg_hi:[0,1]
	v_mov_b32_e32 v134, v131
	s_waitcnt lgkmcnt(0)
; #define LAS __attribute__((address_space(3)))
; __device__ __forceinline__ unsigned f2bf(float f) { unsigned u = __builtin_bit_cast(unsigned, f); return (u + 0x7fffu + ((u >> 16) & 1u)) >> 16; }
; __device__ __forceinline__ u32x4 pack8(const float (&f)[8]) { u32x4 o; o.x = pk2(f[0], f[1]); o.y = pk2(f[2], f[3]); o.z = pk2(f[4], f[5]); o.w = pk2(f[6], f[7]); return o; }
; __device__ __forceinline__ void sgu_unit(const Args& a, LAS unsigned char* lds, int l, int tt) {
;     ...
;             for (int e = 0; e < 8; ++e) { const int q = q0 + 8 * j + e; const f32x2 st = stats[q]; y[e] = (bf2f(Vb[q * CXS + c]) - st[0]) * st[1] * lg + lb; }
;             pk[j] = pack8(y);
;         }
;         __syncthreads();
; #pragma unroll
;         for (int j = 0; j < 8; ++j) *(LAS u32x4*)(vnT + c * VTS + q0 + 8 * j) = pk[j];
;     }
;     __syncthreads();
; #pragma unroll
;     for (int nt = 0; nt < 4; ++nt) {
;         const int c = 64 * h + 16 * nt + fr;
;         bf16x8 Bf[4];
; #pragma unroll
;         for (int ks = 0; ks < 4; ++ks) Bf[ks] = *(const LAS bf16x8*)(vnT + c * VTS + 32 * ks + 8 * fq);
; #pragma unroll
;         for (int mm = 0; mm < 4; ++mm) {
;             f32x4 acc = (f32x4){0.f, 0.f, 0.f, 0.f};
; #pragma unroll
;             for (int ks = 0; ks < 4; ++ks) acc = __builtin_amdgcn_mfma_f32_16x16x32_bf16(Aw[mm][ks], Bf[ks], acc, 0, 0, 0);
; #pragma unroll
;             for (int reg = 0; reg < 4; ++reg) { LAS bf16_t* up = Ub + ((mh * 4 + mm) * 16 + 4 * fq + reg) * CXS + c;
;                 *up = (bf16_t)f2bf(bf2f(*up) * (acc[reg] + bsv[mm][reg])); }
;         }
;     }
	v_lshlrev_b32_e32 v129, 16, v103
	v_lshlrev_b32_e32 v128, 16, v142
	v_mov_b32_e32 v130, v132
	v_mov_b32_e32 v131, v108
	v_pk_mul_f32 v[126:127], v[134:135], v[126:127]
	v_pk_add_f32 v[128:129], v[128:129], v[130:131] neg_lo:[0,1] neg_hi:[0,1]
	v_mov_b32_e32 v108, v133
	v_pk_fma_f32 v[126:127], v[102:103], v[126:127], v[104:105] op_sel_hi:[0,1,0]
	v_pk_mul_f32 v[108:109], v[108:109], v[128:129]
	v_pk_fma_f32 v[122:123], v[102:103], v[122:123], v[104:105] op_sel_hi:[0,1,0]
	v_pk_fma_f32 v[124:125], v[102:103], v[124:125], v[104:105] op_sel_hi:[0,1,0]
	v_pk_fma_f32 v[102:103], v[102:103], v[108:109], v[104:105] op_sel_hi:[0,1,0]
	v_bfe_u32 v110, v126, 16, 1
	v_bfe_u32 v113, v127, 16, 1
	v_bfe_u32 v108, v103, 16, 1
	v_bfe_u32 v109, v102, 16, 1
	v_add3_u32 v113, v127, v113, s27
	v_add3_u32 v110, v126, v110, s27
	v_bfe_u32 v104, v125, 16, 1
	v_bfe_u32 v106, v124, 16, 1
	v_add3_u32 v102, v102, v109, s27
	v_add3_u32 v103, v103, v108, s27
	v_bfe_u32 v108, v122, 16, 1
	v_bfe_u32 v109, v123, 16, 1
	v_lshrrev_b32_e32 v110, 16, v110
	v_lshrrev_b32_e32 v113, 16, v113
	v_add3_u32 v106, v124, v106, s27
	v_add3_u32 v104, v125, v104, s27
	v_add3_u32 v109, v123, v109, s27
	v_add3_u32 v108, v122, v108, s27
	v_and_or_b32 v125, v103, s6, v113
	v_and_or_b32 v124, v102, s6, v110
	v_mul_u32_u24_e32 v102, 0x110, v105
	v_lshlrev_b32_e32 v103, 1, v107
	v_lshrrev_b32_e32 v108, 16, v108
	v_lshrrev_b32_e32 v109, 16, v109
	v_add3_u32 v102, 0, v102, v103
	v_and_or_b32 v123, v104, s6, v109
	v_and_or_b32 v122, v106, s6, v108
	s_barrier
	ds_write_b128 v102, v[82:85]
	ds_write_b128 v102, v[86:89] offset:16
	ds_write_b128 v102, v[90:93] offset:32
	ds_write_b128 v102, v[94:97] offset:48
	ds_write_b128 v102, v[98:101] offset:64
	ds_write_b128 v102, v[114:117] offset:80
	ds_write_b128 v102, v[118:121] offset:96
	ds_write_b128 v102, v[122:125] offset:112
	v_lshl_or_b32 v84, s38, 6, v112
	v_lshl_add_u32 v83, v111, 4, 0
	s_movk_i32 s4, 0x110
	v_mad_u32_u24 v82, v84, s4, v83
	s_waitcnt lgkmcnt(0)
	s_barrier
	ds_read_b128 v[86:89], v82
	ds_read_b128 v[90:93], v82 offset:64
	s_waitcnt lgkmcnt(1)
	v_mfma_f32_16x16x32_bf16 v[94:97], v[78:81], v[86:89], 0
	ds_read_b128 v[98:101], v82 offset:128
	ds_read_b128 v[102:105], v82 offset:192
	v_lshlrev_b32_e32 v82, 2, v111
	v_or_b32_e32 v82, s0, v82
	s_waitcnt lgkmcnt(2)
	v_mfma_f32_16x16x32_bf16 v[94:97], v[74:77], v[90:93], v[94:97]
	v_mul_lo_u32 v82, v82, s55
	v_add_u32_e32 v85, s37, v82
	v_lshl_add_u32 v110, v84, 1, v85
	s_waitcnt lgkmcnt(1)
	v_mfma_f32_16x16x32_bf16 v[94:97], v[70:73], v[98:101], v[94:97]
	ds_read_u16 v106, v110
	ds_read_u16 v107, v110 offset:528
	ds_read_u16 v108, v110 offset:1056
	ds_read_u16 v111, v110 offset:1584
	ds_read_u16 v112, v110 offset:8448
	ds_read_u16 v113, v110 offset:8976
	ds_read_u16 v114, v110 offset:9504
	ds_read_u16 v115, v110 offset:10032
	s_waitcnt lgkmcnt(7)
	v_lshlrev_b32_e32 v106, 16, v106
	v_mfma_f32_16x16x32_bf16 v[94:97], v[66:69], v[102:105], v[94:97]
	s_nop 7
	v_add_f32_e32 v94, v46, v94
	v_mul_f32_e32 v94, v94, v106
	v_bfe_u32 v106, v94, 16, 1
	v_add3_u32 v94, v94, v106, s27
	ds_write_b16_d16_hi v110, v94
	s_waitcnt lgkmcnt(7)
	v_lshlrev_b32_e32 v94, 16, v107
	v_add_f32_e32 v95, v47, v95
	v_mul_f32_e32 v94, v95, v94
	v_bfe_u32 v95, v94, 16, 1
	v_add3_u32 v94, v94, v95, s27
	ds_write_b16_d16_hi v110, v94 offset:528
	s_waitcnt lgkmcnt(7)
	v_lshlrev_b32_e32 v94, 16, v108
	v_mfma_f32_16x16x32_bf16 v[106:109], v[62:65], v[86:89], 0
	v_add_f32_e32 v95, v48, v96
	v_mul_f32_e32 v94, v95, v94
	v_bfe_u32 v95, v94, 16, 1
	v_mfma_f32_16x16x32_bf16 v[106:109], v[58:61], v[90:93], v[106:109]
	v_add3_u32 v94, v94, v95, s27
	ds_write_b16_d16_hi v110, v94 offset:1056
	s_waitcnt lgkmcnt(7)
	v_lshlrev_b32_e32 v94, 16, v111
	v_add_f32_e32 v95, v49, v97
	v_mul_f32_e32 v111, v95, v94
	v_mfma_f32_16x16x32_bf16 v[94:97], v[54:57], v[98:101], v[106:109]
	v_mfma_f32_16x16x32_bf16 v[94:97], v[50:53], v[102:105], v[94:97]
	s_nop 1
	v_bfe_u32 v106, v111, 16, 1
	v_add3_u32 v106, v111, v106, s27
	ds_write_b16_d16_hi v110, v106 offset:1584
	s_waitcnt lgkmcnt(7)
	v_lshlrev_b32_e32 v106, 16, v112
	s_nop 0
	v_add_f32_e32 v94, v26, v94
	v_mul_f32_e32 v94, v94, v106
	v_bfe_u32 v106, v94, 16, 1
	v_add3_u32 v94, v94, v106, s27
	ds_write_b16_d16_hi v110, v94 offset:8448
	s_waitcnt lgkmcnt(7)
	v_lshlrev_b32_e32 v94, 16, v113
	v_add_f32_e32 v95, v27, v95
	v_mul_f32_e32 v94, v95, v94
	v_mfma_f32_16x16x32_bf16 v[106:109], v[42:45], v[86:89], 0
	v_bfe_u32 v95, v94, 16, 1
	v_add3_u32 v94, v94, v95, s27
	ds_write_b16_d16_hi v110, v94 offset:8976
	s_waitcnt lgkmcnt(7)
	v_lshlrev_b32_e32 v94, 16, v114
	v_add_f32_e32 v95, v28, v96
	v_mul_f32_e32 v94, v95, v94
	v_mfma_f32_16x16x32_bf16 v[106:109], v[38:41], v[90:93], v[106:109]
	v_bfe_u32 v95, v94, 16, 1
	v_add3_u32 v94, v94, v95, s27
	ds_write_b16_d16_hi v110, v94 offset:9504
	v_mfma_f32_16x16x32_bf16 v[86:89], v[22:25], v[86:89], 0
	s_waitcnt lgkmcnt(7)
	v_lshlrev_b32_e32 v94, 16, v115
	v_add_f32_e32 v95, v29, v97
	v_mul_f32_e32 v111, v95, v94
	v_mfma_f32_16x16x32_bf16 v[94:97], v[34:37], v[98:101], v[106:109]
	v_mfma_f32_16x16x32_bf16 v[86:89], v[18:21], v[90:93], v[86:89]
	s_nop 1
	v_bfe_u32 v106, v111, 16, 1
	v_add3_u32 v106, v111, v106, s27
	ds_write_b16_d16_hi v110, v106 offset:10032
	v_mfma_f32_16x16x32_bf16 v[94:97], v[30:33], v[102:105], v[94:97]
	ds_read_u16 v106, v110 offset:16896
	ds_read_u16 v107, v110 offset:17424
	ds_read_u16 v108, v110 offset:17952
	ds_read_u16 v109, v110 offset:18480
	ds_read_u16 v111, v110 offset:25344
	ds_read_u16 v112, v110 offset:25872
	ds_read_u16 v113, v110 offset:26400
	ds_read_u16 v114, v110 offset:26928
	s_waitcnt lgkmcnt(4)
; #define LAS __attribute__((address_space(3)))
; __device__ __forceinline__ unsigned f2bf(float f) { unsigned u = __builtin_bit_cast(unsigned, f); return (u + 0x7fffu + ((u >> 16) & 1u)) >> 16; }
; __device__ __forceinline__ void sgu_unit(const Args& a, LAS unsigned char* lds, int l, int tt) {
;     ...
;     for (int nt = 0; nt < 4; ++nt) {
;         const int c = 64 * h + 16 * nt + fr;
;         bf16x8 Bf[4];
; #pragma unroll
;         for (int ks = 0; ks < 4; ++ks) Bf[ks] = *(const LAS bf16x8*)(vnT + c * VTS + 32 * ks + 8 * fq);
; #pragma unroll
;         for (int mm = 0; mm < 4; ++mm) {
;             f32x4 acc = (f32x4){0.f, 0.f, 0.f, 0.f};
; #pragma unroll
;             for (int ks = 0; ks < 4; ++ks) acc = __builtin_amdgcn_mfma_f32_16x16x32_bf16(Aw[mm][ks], Bf[ks], acc, 0, 0, 0);
; #pragma unroll
;             for (int reg = 0; reg < 4; ++reg) { LAS bf16_t* up = Ub + ((mh * 4 + mm) * 16 + 4 * fq + reg) * CXS + c;
;                 *up = (bf16_t)f2bf(bf2f(*up) * (acc[reg] + bsv[mm][reg])); }
;         }
;     }
	v_lshlrev_b32_e32 v90, 16, v109
	v_lshlrev_b32_e32 v106, 16, v106
	v_mfma_f32_16x16x32_bf16 v[86:89], v[14:17], v[98:101], v[86:89]
	v_add_f32_e32 v91, v9, v97
	v_mul_f32_e32 v90, v91, v90
	v_bfe_u32 v91, v90, 16, 1
	v_mfma_f32_16x16x32_bf16 v[86:89], v[10:13], v[102:105], v[86:89]
	v_add3_u32 v90, v90, v91, s27
	ds_write_b16_d16_hi v110, v90 offset:18480
	s_waitcnt lgkmcnt(4)
	v_lshlrev_b32_e32 v90, 16, v111
	v_add_f32_e32 v94, v6, v94
	v_mul_f32_e32 v94, v94, v106
	s_nop 1
	v_add_f32_e32 v86, v2, v86
	v_mul_f32_e32 v86, v86, v90
	v_bfe_u32 v90, v86, 16, 1
	v_add3_u32 v86, v86, v90, s27
	ds_write_b16_d16_hi v110, v86 offset:25344
	s_waitcnt lgkmcnt(4)
	v_lshlrev_b32_e32 v86, 16, v112
	v_add_f32_e32 v87, v3, v87
	v_mul_f32_e32 v86, v87, v86
	v_bfe_u32 v106, v94, 16, 1
	v_bfe_u32 v87, v86, 16, 1
	v_add3_u32 v94, v94, v106, s27
	v_add3_u32 v86, v86, v87, s27
	ds_write_b16_d16_hi v110, v94 offset:16896
	v_lshlrev_b32_e32 v94, 16, v107
	v_add_f32_e32 v95, v7, v95
	ds_write_b16_d16_hi v110, v86 offset:25872
	s_waitcnt lgkmcnt(5)
	v_lshlrev_b32_e32 v86, 16, v113
	v_add_f32_e32 v87, v4, v88
	v_mul_f32_e32 v94, v95, v94
	v_mul_f32_e32 v86, v87, v86
	v_bfe_u32 v95, v94, 16, 1
	v_bfe_u32 v87, v86, 16, 1
	v_add3_u32 v94, v94, v95, s27
	v_add3_u32 v86, v86, v87, s27
	ds_write_b16_d16_hi v110, v94 offset:17424
	v_lshlrev_b32_e32 v94, 16, v108
	v_add_f32_e32 v95, v8, v96
	ds_write_b16_d16_hi v110, v86 offset:26400
	s_waitcnt lgkmcnt(6)
	v_lshlrev_b32_e32 v86, 16, v114
	v_add_f32_e32 v87, v5, v89
	v_mul_f32_e32 v94, v95, v94
	v_mul_f32_e32 v86, v87, v86
	v_bfe_u32 v95, v94, 16, 1
	v_bfe_u32 v87, v86, 16, 1
	v_add3_u32 v94, v94, v95, s27
	v_add3_u32 v86, v86, v87, s27
	v_or_b32_e32 v106, 16, v84
	ds_write_b16_d16_hi v110, v94 offset:17952
	ds_write_b16_d16_hi v110, v86 offset:26928
	v_mad_u32_u24 v102, v106, s4, v83
	ds_read_b128 v[86:89], v102
	ds_read_b128 v[90:93], v102 offset:64
	s_waitcnt lgkmcnt(1)
	v_mfma_f32_16x16x32_bf16 v[94:97], v[78:81], v[86:89], 0
	ds_read_b128 v[98:101], v102 offset:128
	ds_read_b128 v[102:105], v102 offset:192
	v_lshlrev_b32_e32 v106, 1, v106
	v_add_u32_e32 v107, v85, v106
	s_waitcnt lgkmcnt(2)
	v_mfma_f32_16x16x32_bf16 v[94:97], v[74:77], v[90:93], v[94:97]
	v_add3_u32 v110, s37, v106, v82
	ds_read_u16 v106, v107
	ds_read_u16 v108, v110 offset:528
	ds_read_u16 v109, v110 offset:1056
	ds_read_u16 v111, v110 offset:1584
	ds_read_u16 v112, v110 offset:8448
	ds_read_u16 v113, v110 offset:8976
	ds_read_u16 v114, v110 offset:9504
	ds_read_u16 v115, v110 offset:10032
	s_waitcnt lgkmcnt(7)
	v_lshlrev_b32_e32 v106, 16, v106
	v_mfma_f32_16x16x32_bf16 v[94:97], v[70:73], v[98:101], v[94:97]
	v_mfma_f32_16x16x32_bf16 v[94:97], v[66:69], v[102:105], v[94:97]
	s_nop 7
	v_add_f32_e32 v94, v46, v94
	v_mul_f32_e32 v94, v94, v106
	v_bfe_u32 v106, v94, 16, 1
	v_add3_u32 v94, v94, v106, s27
	ds_write_b16_d16_hi v107, v94
	s_waitcnt lgkmcnt(7)
	v_lshlrev_b32_e32 v94, 16, v108
	v_add_f32_e32 v95, v47, v95
	v_mul_f32_e32 v94, v95, v94
	v_bfe_u32 v95, v94, 16, 1
	v_add3_u32 v94, v94, v95, s27
	ds_write_b16_d16_hi v110, v94 offset:528
	s_waitcnt lgkmcnt(7)
	v_lshlrev_b32_e32 v94, 16, v109
	v_mfma_f32_16x16x32_bf16 v[106:109], v[62:65], v[86:89], 0
	v_add_f32_e32 v95, v48, v96
	v_mul_f32_e32 v94, v95, v94
	v_bfe_u32 v95, v94, 16, 1
	v_mfma_f32_16x16x32_bf16 v[106:109], v[58:61], v[90:93], v[106:109]
	v_add3_u32 v94, v94, v95, s27
	ds_write_b16_d16_hi v110, v94 offset:1056
	s_waitcnt lgkmcnt(7)
	v_lshlrev_b32_e32 v94, 16, v111
	v_add_f32_e32 v95, v49, v97
	v_mul_f32_e32 v111, v95, v94
	v_mfma_f32_16x16x32_bf16 v[94:97], v[54:57], v[98:101], v[106:109]
	v_mfma_f32_16x16x32_bf16 v[94:97], v[50:53], v[102:105], v[94:97]
	s_nop 1
	v_bfe_u32 v106, v111, 16, 1
	v_add3_u32 v106, v111, v106, s27
	ds_write_b16_d16_hi v110, v106 offset:1584
	s_waitcnt lgkmcnt(7)
	v_lshlrev_b32_e32 v106, 16, v112
	s_nop 0
	v_add_f32_e32 v94, v26, v94
	v_mul_f32_e32 v94, v94, v106
	v_bfe_u32 v106, v94, 16, 1
	v_add3_u32 v94, v94, v106, s27
	ds_write_b16_d16_hi v110, v94 offset:8448
	s_waitcnt lgkmcnt(7)
	v_lshlrev_b32_e32 v94, 16, v113
	v_add_f32_e32 v95, v27, v95
	v_mul_f32_e32 v94, v95, v94
	v_mfma_f32_16x16x32_bf16 v[106:109], v[42:45], v[86:89], 0
	v_bfe_u32 v95, v94, 16, 1
	v_add3_u32 v94, v94, v95, s27
	ds_write_b16_d16_hi v110, v94 offset:8976
	s_waitcnt lgkmcnt(7)
	v_lshlrev_b32_e32 v94, 16, v114
	v_add_f32_e32 v95, v28, v96
	v_mul_f32_e32 v94, v95, v94
	v_mfma_f32_16x16x32_bf16 v[106:109], v[38:41], v[90:93], v[106:109]
	v_bfe_u32 v95, v94, 16, 1
	v_add3_u32 v94, v94, v95, s27
	ds_write_b16_d16_hi v110, v94 offset:9504
	v_mfma_f32_16x16x32_bf16 v[86:89], v[22:25], v[86:89], 0
	s_waitcnt lgkmcnt(7)
	v_lshlrev_b32_e32 v94, 16, v115
	v_add_f32_e32 v95, v29, v97
	v_mul_f32_e32 v111, v95, v94
	v_mfma_f32_16x16x32_bf16 v[94:97], v[34:37], v[98:101], v[106:109]
	v_mfma_f32_16x16x32_bf16 v[86:89], v[18:21], v[90:93], v[86:89]
	s_nop 1
	v_bfe_u32 v106, v111, 16, 1
	v_add3_u32 v106, v111, v106, s27
	ds_write_b16_d16_hi v110, v106 offset:10032
	v_mfma_f32_16x16x32_bf16 v[94:97], v[30:33], v[102:105], v[94:97]
	ds_read_u16 v106, v110 offset:16896
	ds_read_u16 v107, v110 offset:17424
	ds_read_u16 v108, v110 offset:17952
	ds_read_u16 v109, v110 offset:18480
	ds_read_u16 v111, v110 offset:25344
	ds_read_u16 v112, v110 offset:25872
	ds_read_u16 v113, v110 offset:26400
	ds_read_u16 v114, v110 offset:26928
	s_waitcnt lgkmcnt(4)
	v_lshlrev_b32_e32 v90, 16, v109
	v_lshlrev_b32_e32 v106, 16, v106
	v_mfma_f32_16x16x32_bf16 v[86:89], v[14:17], v[98:101], v[86:89]
	v_add_f32_e32 v91, v9, v97
	v_mul_f32_e32 v90, v91, v90
	v_bfe_u32 v91, v90, 16, 1
	v_mfma_f32_16x16x32_bf16 v[86:89], v[10:13], v[102:105], v[86:89]
	v_add3_u32 v90, v90, v91, s27
	ds_write_b16_d16_hi v110, v90 offset:18480
	s_waitcnt lgkmcnt(4)
; #define LAS __attribute__((address_space(3)))
; __device__ __forceinline__ unsigned f2bf(float f) { unsigned u = __builtin_bit_cast(unsigned, f); return (u + 0x7fffu + ((u >> 16) & 1u)) >> 16; }
; __device__ __forceinline__ void sgu_unit(const Args& a, LAS unsigned char* lds, int l, int tt) {
;     ...
;     for (int nt = 0; nt < 4; ++nt) {
;         const int c = 64 * h + 16 * nt + fr;
;         bf16x8 Bf[4];
; #pragma unroll
;         for (int ks = 0; ks < 4; ++ks) Bf[ks] = *(const LAS bf16x8*)(vnT + c * VTS + 32 * ks + 8 * fq);
; #pragma unroll
;         for (int mm = 0; mm < 4; ++mm) {
;             f32x4 acc = (f32x4){0.f, 0.f, 0.f, 0.f};
; #pragma unroll
;             for (int ks = 0; ks < 4; ++ks) acc = __builtin_amdgcn_mfma_f32_16x16x32_bf16(Aw[mm][ks], Bf[ks], acc, 0, 0, 0);
; #pragma unroll
;             for (int reg = 0; reg < 4; ++reg) { LAS bf16_t* up = Ub + ((mh * 4 + mm) * 16 + 4 * fq + reg) * CXS + c;
;                 *up = (bf16_t)f2bf(bf2f(*up) * (acc[reg] + bsv[mm][reg])); }
;         }
;     }
	v_lshlrev_b32_e32 v90, 16, v111
	v_add_f32_e32 v94, v6, v94
	v_mul_f32_e32 v94, v94, v106
	s_nop 1
	v_add_f32_e32 v86, v2, v86
	v_mul_f32_e32 v86, v86, v90
	v_bfe_u32 v90, v86, 16, 1
	v_add3_u32 v86, v86, v90, s27
	ds_write_b16_d16_hi v110, v86 offset:25344
	s_waitcnt lgkmcnt(4)
	v_lshlrev_b32_e32 v86, 16, v112
	v_add_f32_e32 v87, v3, v87
	v_mul_f32_e32 v86, v87, v86
	v_bfe_u32 v106, v94, 16, 1
	v_bfe_u32 v87, v86, 16, 1
	v_add3_u32 v94, v94, v106, s27
	v_add3_u32 v86, v86, v87, s27
	ds_write_b16_d16_hi v110, v94 offset:16896
	v_lshlrev_b32_e32 v94, 16, v107
	v_add_f32_e32 v95, v7, v95
	ds_write_b16_d16_hi v110, v86 offset:25872
	s_waitcnt lgkmcnt(5)
	v_lshlrev_b32_e32 v86, 16, v113
	v_add_f32_e32 v87, v4, v88
	v_mul_f32_e32 v94, v95, v94
	v_mul_f32_e32 v86, v87, v86
	v_bfe_u32 v95, v94, 16, 1
	v_bfe_u32 v87, v86, 16, 1
	v_add3_u32 v94, v94, v95, s27
	v_add3_u32 v86, v86, v87, s27
	ds_write_b16_d16_hi v110, v94 offset:17424
	v_lshlrev_b32_e32 v94, 16, v108
	v_add_f32_e32 v95, v8, v96
	ds_write_b16_d16_hi v110, v86 offset:26400
	s_waitcnt lgkmcnt(6)
	v_lshlrev_b32_e32 v86, 16, v114
	v_add_f32_e32 v87, v5, v89
	v_mul_f32_e32 v94, v95, v94
	v_mul_f32_e32 v86, v87, v86
	v_bfe_u32 v95, v94, 16, 1
	v_bfe_u32 v87, v86, 16, 1
	v_add3_u32 v94, v94, v95, s27
	v_add3_u32 v86, v86, v87, s27
	v_or_b32_e32 v106, 32, v84
	ds_write_b16_d16_hi v110, v94 offset:17952
	ds_write_b16_d16_hi v110, v86 offset:26928
	v_mad_u32_u24 v102, v106, s4, v83
	ds_read_b128 v[86:89], v102
	ds_read_b128 v[90:93], v102 offset:64
	s_waitcnt lgkmcnt(1)
	v_mfma_f32_16x16x32_bf16 v[94:97], v[78:81], v[86:89], 0
	ds_read_b128 v[98:101], v102 offset:128
	ds_read_b128 v[102:105], v102 offset:192
	v_lshlrev_b32_e32 v106, 1, v106
	v_add_u32_e32 v107, v85, v106
	s_waitcnt lgkmcnt(2)
	v_mfma_f32_16x16x32_bf16 v[94:97], v[74:77], v[90:93], v[94:97]
	v_add3_u32 v110, s37, v106, v82
	ds_read_u16 v106, v107
	ds_read_u16 v108, v110 offset:528
	ds_read_u16 v109, v110 offset:1056
	ds_read_u16 v111, v110 offset:1584
	ds_read_u16 v112, v110 offset:8448
	ds_read_u16 v113, v110 offset:8976
	ds_read_u16 v114, v110 offset:9504
	ds_read_u16 v115, v110 offset:10032
	s_waitcnt lgkmcnt(7)
	v_lshlrev_b32_e32 v106, 16, v106
	v_mfma_f32_16x16x32_bf16 v[94:97], v[70:73], v[98:101], v[94:97]
	v_or_b32_e32 v84, 48, v84
	v_mad_u32_u24 v83, v84, s4, v83
	v_mfma_f32_16x16x32_bf16 v[94:97], v[66:69], v[102:105], v[94:97]
	s_nop 7
	v_add_f32_e32 v94, v46, v94
	v_mul_f32_e32 v94, v94, v106
	v_bfe_u32 v106, v94, 16, 1
	v_add3_u32 v94, v94, v106, s27
	ds_write_b16_d16_hi v107, v94
	s_waitcnt lgkmcnt(7)
	v_lshlrev_b32_e32 v94, 16, v108
	v_add_f32_e32 v95, v47, v95
	v_mul_f32_e32 v94, v95, v94
	v_bfe_u32 v95, v94, 16, 1
	v_add3_u32 v94, v94, v95, s27
	ds_write_b16_d16_hi v110, v94 offset:528
	s_waitcnt lgkmcnt(7)
	v_lshlrev_b32_e32 v94, 16, v109
	v_mfma_f32_16x16x32_bf16 v[106:109], v[62:65], v[86:89], 0
	v_add_f32_e32 v95, v48, v96
	v_mul_f32_e32 v94, v95, v94
	v_bfe_u32 v95, v94, 16, 1
	v_mfma_f32_16x16x32_bf16 v[106:109], v[58:61], v[90:93], v[106:109]
	v_add3_u32 v94, v94, v95, s27
	ds_write_b16_d16_hi v110, v94 offset:1056
	s_waitcnt lgkmcnt(7)
	v_lshlrev_b32_e32 v94, 16, v111
	v_add_f32_e32 v95, v49, v97
	v_mul_f32_e32 v111, v95, v94
	v_mfma_f32_16x16x32_bf16 v[94:97], v[54:57], v[98:101], v[106:109]
	v_mfma_f32_16x16x32_bf16 v[94:97], v[50:53], v[102:105], v[94:97]
	s_nop 1
	v_bfe_u32 v106, v111, 16, 1
	v_add3_u32 v106, v111, v106, s27
	ds_write_b16_d16_hi v110, v106 offset:1584
	s_waitcnt lgkmcnt(7)
	v_lshlrev_b32_e32 v106, 16, v112
	s_nop 0
	v_add_f32_e32 v94, v26, v94
	v_mul_f32_e32 v94, v94, v106
	v_bfe_u32 v106, v94, 16, 1
	v_add3_u32 v94, v94, v106, s27
	ds_write_b16_d16_hi v110, v94 offset:8448
	s_waitcnt lgkmcnt(7)
	v_lshlrev_b32_e32 v94, 16, v113
	v_add_f32_e32 v95, v27, v95
	v_mul_f32_e32 v94, v95, v94
	v_mfma_f32_16x16x32_bf16 v[106:109], v[42:45], v[86:89], 0
	v_bfe_u32 v95, v94, 16, 1
	v_add3_u32 v94, v94, v95, s27
	ds_write_b16_d16_hi v110, v94 offset:8976
	s_waitcnt lgkmcnt(7)
	v_lshlrev_b32_e32 v94, 16, v114
	v_add_f32_e32 v95, v28, v96
	v_mul_f32_e32 v94, v95, v94
	v_mfma_f32_16x16x32_bf16 v[106:109], v[38:41], v[90:93], v[106:109]
	v_bfe_u32 v95, v94, 16, 1
	v_add3_u32 v94, v94, v95, s27
	ds_write_b16_d16_hi v110, v94 offset:9504
	v_mfma_f32_16x16x32_bf16 v[86:89], v[22:25], v[86:89], 0
	s_waitcnt lgkmcnt(7)
	v_lshlrev_b32_e32 v94, 16, v115
	v_add_f32_e32 v95, v29, v97
	v_mul_f32_e32 v111, v95, v94
	v_mfma_f32_16x16x32_bf16 v[94:97], v[34:37], v[98:101], v[106:109]
	v_mfma_f32_16x16x32_bf16 v[86:89], v[18:21], v[90:93], v[86:89]
	s_nop 1
	v_bfe_u32 v106, v111, 16, 1
	v_add3_u32 v106, v111, v106, s27
	ds_write_b16_d16_hi v110, v106 offset:10032
	v_mfma_f32_16x16x32_bf16 v[94:97], v[30:33], v[102:105], v[94:97]
	ds_read_u16 v106, v110 offset:16896
	ds_read_u16 v107, v110 offset:17424
	ds_read_u16 v108, v110 offset:17952
	ds_read_u16 v109, v110 offset:18480
	ds_read_u16 v111, v110 offset:25344
	ds_read_u16 v112, v110 offset:25872
	ds_read_u16 v113, v110 offset:26400
	ds_read_u16 v114, v110 offset:26928
	s_waitcnt lgkmcnt(4)
	v_lshlrev_b32_e32 v90, 16, v109
	v_lshlrev_b32_e32 v106, 16, v106
	v_mfma_f32_16x16x32_bf16 v[86:89], v[14:17], v[98:101], v[86:89]
	v_add_f32_e32 v91, v9, v97
	v_mul_f32_e32 v90, v91, v90
	v_bfe_u32 v91, v90, 16, 1
	v_mfma_f32_16x16x32_bf16 v[86:89], v[10:13], v[102:105], v[86:89]
	v_add3_u32 v90, v90, v91, s27
	ds_write_b16_d16_hi v110, v90 offset:18480
	s_waitcnt lgkmcnt(4)
	v_lshlrev_b32_e32 v90, 16, v111
	v_add_f32_e32 v94, v6, v94
	v_mul_f32_e32 v94, v94, v106
	s_nop 1
	v_add_f32_e32 v86, v2, v86
	v_mul_f32_e32 v86, v86, v90
	v_bfe_u32 v90, v86, 16, 1
	v_add3_u32 v86, v86, v90, s27
	ds_write_b16_d16_hi v110, v86 offset:25344
	s_waitcnt lgkmcnt(4)
; #define LAS __attribute__((address_space(3)))
; __device__ __forceinline__ unsigned f2bf(float f) { unsigned u = __builtin_bit_cast(unsigned, f); return (u + 0x7fffu + ((u >> 16) & 1u)) >> 16; }
; __device__ __forceinline__ void sgu_unit(const Args& a, LAS unsigned char* lds, int l, int tt) {
;     ...
;     for (int nt = 0; nt < 4; ++nt) {
;         const int c = 64 * h + 16 * nt + fr;
;         bf16x8 Bf[4];
; #pragma unroll
;         for (int ks = 0; ks < 4; ++ks) Bf[ks] = *(const LAS bf16x8*)(vnT + c * VTS + 32 * ks + 8 * fq);
; #pragma unroll
;         for (int mm = 0; mm < 4; ++mm) {
;             f32x4 acc = (f32x4){0.f, 0.f, 0.f, 0.f};
; #pragma unroll
;             for (int ks = 0; ks < 4; ++ks) acc = __builtin_amdgcn_mfma_f32_16x16x32_bf16(Aw[mm][ks], Bf[ks], acc, 0, 0, 0);
; #pragma unroll
;             for (int reg = 0; reg < 4; ++reg) { LAS bf16_t* up = Ub + ((mh * 4 + mm) * 16 + 4 * fq + reg) * CXS + c;
;                 *up = (bf16_t)f2bf(bf2f(*up) * (acc[reg] + bsv[mm][reg])); }
;         }
;     }
;     __syncthreads();
	v_lshlrev_b32_e32 v86, 16, v112
	v_add_f32_e32 v87, v3, v87
	v_mul_f32_e32 v86, v87, v86
	v_bfe_u32 v106, v94, 16, 1
	v_bfe_u32 v87, v86, 16, 1
	v_add3_u32 v94, v94, v106, s27
	v_add3_u32 v86, v86, v87, s27
	ds_write_b16_d16_hi v110, v94 offset:16896
	v_lshlrev_b32_e32 v94, 16, v107
	v_add_f32_e32 v95, v7, v95
	ds_write_b16_d16_hi v110, v86 offset:25872
	s_waitcnt lgkmcnt(5)
	v_lshlrev_b32_e32 v86, 16, v113
	v_add_f32_e32 v87, v4, v88
	v_mul_f32_e32 v94, v95, v94
	v_mul_f32_e32 v86, v87, v86
	v_bfe_u32 v95, v94, 16, 1
	v_bfe_u32 v87, v86, 16, 1
	v_add3_u32 v94, v94, v95, s27
	v_add3_u32 v86, v86, v87, s27
	ds_write_b16_d16_hi v110, v94 offset:17424
	v_lshlrev_b32_e32 v94, 16, v108
	v_add_f32_e32 v95, v8, v96
	ds_write_b16_d16_hi v110, v86 offset:26400
	s_waitcnt lgkmcnt(6)
	v_lshlrev_b32_e32 v86, 16, v114
	v_add_f32_e32 v87, v5, v89
	v_mul_f32_e32 v94, v95, v94
	v_mul_f32_e32 v86, v87, v86
	v_bfe_u32 v95, v94, 16, 1
	v_bfe_u32 v87, v86, 16, 1
	v_add3_u32 v94, v94, v95, s27
	v_add3_u32 v86, v86, v87, s27
	ds_write_b16_d16_hi v110, v94 offset:17952
	ds_write_b16_d16_hi v110, v86 offset:26928
	ds_read_b128 v[86:89], v83
	ds_read_b128 v[90:93], v83 offset:64
	s_waitcnt lgkmcnt(1)
	v_mfma_f32_16x16x32_bf16 v[78:81], v[78:81], v[86:89], 0
	s_waitcnt lgkmcnt(0)
	v_mfma_f32_16x16x32_bf16 v[74:77], v[74:77], v[90:93], v[78:81]
	s_nop 5
	ds_read_b128 v[78:81], v83 offset:128
	ds_read_b128 v[94:97], v83 offset:192
	s_waitcnt lgkmcnt(1)
	v_mfma_f32_16x16x32_bf16 v[70:73], v[70:73], v[78:81], v[74:77]
	s_nop 2
	v_lshlrev_b32_e32 v74, 1, v84
	s_waitcnt lgkmcnt(0)
	v_mfma_f32_16x16x32_bf16 v[66:69], v[66:69], v[94:97], v[70:73]
	s_nop 2
	v_add_u32_e32 v70, v85, v74
	v_add3_u32 v71, s37, v74, v82
	ds_read_u16 v72, v70
	ds_read_u16 v73, v71 offset:528
	ds_read_u16 v74, v71 offset:1056
	ds_read_u16 v75, v71 offset:1584
	ds_read_u16 v76, v71 offset:8448
	ds_read_u16 v77, v71 offset:8976
	ds_read_u16 v82, v71 offset:9504
	ds_read_u16 v83, v71 offset:10032
	s_waitcnt lgkmcnt(7)
	v_lshlrev_b32_e32 v72, 16, v72
	v_add_f32_e32 v46, v46, v66
	v_mul_f32_e32 v46, v46, v72
	v_bfe_u32 v66, v46, 16, 1
	v_add3_u32 v46, v46, v66, s27
	ds_write_b16_d16_hi v70, v46
	s_waitcnt lgkmcnt(7)
	v_lshlrev_b32_e32 v46, 16, v73
	v_add_f32_e32 v47, v47, v67
	v_mul_f32_e32 v46, v47, v46
	v_mfma_f32_16x16x32_bf16 v[62:65], v[62:65], v[86:89], 0
	v_bfe_u32 v47, v46, 16, 1
	v_add3_u32 v46, v46, v47, s27
	ds_write_b16_d16_hi v71, v46 offset:528
	s_waitcnt lgkmcnt(7)
	v_lshlrev_b32_e32 v46, 16, v74
	v_add_f32_e32 v47, v48, v68
	v_mul_f32_e32 v46, v47, v46
	v_mfma_f32_16x16x32_bf16 v[58:61], v[58:61], v[90:93], v[62:65]
	v_bfe_u32 v47, v46, 16, 1
	v_add3_u32 v46, v46, v47, s27
	ds_write_b16_d16_hi v71, v46 offset:1056
	s_waitcnt lgkmcnt(7)
	v_lshlrev_b32_e32 v46, 16, v75
	v_add_f32_e32 v47, v49, v69
	v_mul_f32_e32 v62, v47, v46
	v_mfma_f32_16x16x32_bf16 v[46:49], v[54:57], v[78:81], v[58:61]
	v_bfe_u32 v54, v62, 16, 1
	v_add3_u32 v54, v62, v54, s27
	ds_write_b16_d16_hi v71, v54 offset:1584
	v_mfma_f32_16x16x32_bf16 v[46:49], v[50:53], v[94:97], v[46:49]
	s_waitcnt lgkmcnt(7)
	v_lshlrev_b32_e32 v50, 16, v76
	v_mfma_f32_16x16x32_bf16 v[42:45], v[42:45], v[86:89], 0
	v_mfma_f32_16x16x32_bf16 v[38:41], v[38:41], v[90:93], v[42:45]
	s_nop 3
	v_add_f32_e32 v26, v26, v46
	v_mul_f32_e32 v26, v26, v50
	v_bfe_u32 v46, v26, 16, 1
	v_add3_u32 v26, v26, v46, s27
	ds_write_b16_d16_hi v71, v26 offset:8448
	s_waitcnt lgkmcnt(7)
	v_lshlrev_b32_e32 v26, 16, v77
	v_add_f32_e32 v27, v27, v47
	v_mul_f32_e32 v26, v27, v26
	v_bfe_u32 v27, v26, 16, 1
	v_add3_u32 v26, v26, v27, s27
	ds_write_b16_d16_hi v71, v26 offset:8976
	s_waitcnt lgkmcnt(7)
	v_lshlrev_b32_e32 v26, 16, v82
	v_add_f32_e32 v27, v28, v48
	v_mul_f32_e32 v26, v27, v26
	v_bfe_u32 v27, v26, 16, 1
	v_add3_u32 v26, v26, v27, s27
	ds_write_b16_d16_hi v71, v26 offset:9504
	s_waitcnt lgkmcnt(7)
	v_lshlrev_b32_e32 v26, 16, v83
	v_add_f32_e32 v27, v29, v49
	v_mul_f32_e32 v42, v27, v26
	v_mfma_f32_16x16x32_bf16 v[26:29], v[34:37], v[78:81], v[38:41]
	v_bfe_u32 v34, v42, 16, 1
	v_add3_u32 v34, v42, v34, s27
	ds_write_b16_d16_hi v71, v34 offset:10032
	v_mfma_f32_16x16x32_bf16 v[26:29], v[30:33], v[94:97], v[26:29]
	ds_read_u16 v30, v71 offset:16896
	ds_read_u16 v31, v71 offset:17424
	ds_read_u16 v32, v71 offset:17952
	ds_read_u16 v33, v71 offset:18480
	ds_read_u16 v34, v71 offset:25344
	ds_read_u16 v35, v71 offset:25872
	ds_read_u16 v36, v71 offset:26400
	ds_read_u16 v37, v71 offset:26928
	s_waitcnt lgkmcnt(7)
	v_lshlrev_b32_e32 v30, 16, v30
	v_add_f32_e32 v6, v6, v26
	v_mul_f32_e32 v6, v6, v30
	v_bfe_u32 v26, v6, 16, 1
	v_add3_u32 v6, v6, v26, s27
	ds_write_b16_d16_hi v71, v6 offset:16896
	s_waitcnt lgkmcnt(7)
	v_lshlrev_b32_e32 v6, 16, v31
	v_add_f32_e32 v7, v7, v27
	v_mul_f32_e32 v6, v7, v6
	v_mfma_f32_16x16x32_bf16 v[22:25], v[22:25], v[86:89], 0
	v_bfe_u32 v7, v6, 16, 1
	v_add3_u32 v6, v6, v7, s27
	ds_write_b16_d16_hi v71, v6 offset:17424
	s_waitcnt lgkmcnt(7)
	v_lshlrev_b32_e32 v6, 16, v32
	v_add_f32_e32 v7, v8, v28
	v_mul_f32_e32 v6, v7, v6
	v_mfma_f32_16x16x32_bf16 v[18:21], v[18:21], v[90:93], v[22:25]
	v_bfe_u32 v7, v6, 16, 1
	v_add3_u32 v6, v6, v7, s27
	ds_write_b16_d16_hi v71, v6 offset:17952
	s_waitcnt lgkmcnt(7)
	v_lshlrev_b32_e32 v6, 16, v33
	v_add_f32_e32 v7, v9, v29
	v_mul_f32_e32 v22, v7, v6
	v_mfma_f32_16x16x32_bf16 v[6:9], v[14:17], v[78:81], v[18:21]
	v_bfe_u32 v14, v22, 16, 1
	v_add3_u32 v14, v22, v14, s27
	ds_write_b16_d16_hi v71, v14 offset:18480
	v_mfma_f32_16x16x32_bf16 v[6:9], v[10:13], v[94:97], v[6:9]
	s_waitcnt lgkmcnt(7)
	v_lshlrev_b32_e32 v10, 16, v34
	v_mov_b32_e32 v11, v0
	s_nop 4
	v_add_f32_e32 v2, v2, v6
	v_mul_f32_e32 v2, v2, v10
	v_bfe_u32 v6, v2, 16, 1
	v_add3_u32 v2, v2, v6, s27
	ds_write_b16_d16_hi v71, v2 offset:25344
	s_waitcnt lgkmcnt(7)
	v_lshlrev_b32_e32 v2, 16, v35
	v_add_f32_e32 v3, v3, v7
	v_mul_f32_e32 v2, v3, v2
	v_bfe_u32 v3, v2, 16, 1
	v_add3_u32 v2, v2, v3, s27
	ds_write_b16_d16_hi v71, v2 offset:25872
	s_waitcnt lgkmcnt(7)
	v_lshlrev_b32_e32 v2, 16, v36
	v_add_f32_e32 v3, v4, v8
	v_mul_f32_e32 v2, v3, v2
	v_bfe_u32 v3, v2, 16, 1
	v_add3_u32 v2, v2, v3, s27
	ds_write_b16_d16_hi v71, v2 offset:26400
	s_waitcnt lgkmcnt(7)
	v_lshlrev_b32_e32 v2, 16, v37
	v_add_f32_e32 v3, v5, v9
	v_mul_f32_e32 v2, v3, v2
	v_bfe_u32 v3, v2, 16, 1
	v_add3_u32 v2, v2, v3, s27
	ds_write_b16_d16_hi v71, v2 offset:26928
	s_waitcnt lgkmcnt(0)
	s_barrier
; #define LAS __attribute__((address_space(3)))
; __host__ __device__ __forceinline__ unsigned img_off(unsigned row, unsigned col, unsigned KT) { return (((row >> 8) * KT + (col >> 6)) << 14) + (((row >> 7) & 1u) << 13) + hl_off(row & 127u, col & 63u); }
; __device__ __forceinline__ int opaque_tid() { int t = threadIdx.x; asm volatile("" : "+v"(t)); return t; }
; __device__ __forceinline__ void flush_tile(const LAS bf16_t* src, bf16_t* MIX, const Tile& T, int col) {
;     const int tid = opaque_tid();
; #pragma unroll
;     for (int it = 0; it < 8; ++it) {
;         const int idx = tid + NTHREADS * it, r = idx >> 5, vec = idx & 31;
;         *(u32x4*)(MIX + img_off((unsigned)(T.rowbase + T.t0 + r), (unsigned)(col + vec * 8), 16u)) = *(const LAS u32x4*)(src + r * CXS + vec * 8);
;     }
; }
	s_nop 0
	v_lshlrev_b32_e32 v2, 3, v11
	v_and_b32_e32 v3, 0xf8, v2
	v_lshl_add_u32 v10, v3, 1, s37
	v_bfe_u32 v3, v2, 6, 2
	v_ashrrev_i32_e32 v6, 5, v11
	v_or_b32_e32 v14, 8, v3
	v_and_b32_e32 v16, 24, v2
	v_mad_u64_u32 v[2:3], s[4:5], v6, s55, v[10:11]
	s_add_i32 s4, s1, s36
	v_bfe_u32 v15, v11, 2, 1
	v_add_u32_e32 v7, s4, v6
	v_lshrrev_b32_e32 v9, 3, v6
	ds_read_b128 v[2:5], v2
	v_lshrrev_b32_e32 v8, 4, v7
	s_mov_b32 s5, 0x3fff0
	v_and_or_b32 v9, v9, 14, v15
	v_lshlrev_b32_e32 v6, 1, v6
	v_and_or_b32 v8, v8, s5, v14
	v_lshlrev_b32_e32 v7, 6, v7
	v_and_or_b32 v12, v11, s34, v16
	v_lshlrev_b32_e32 v9, 9, v9
	v_and_b32_e32 v6, 16, v6
	v_lshlrev_b32_e32 v8, 14, v8
	v_and_b32_e32 v7, 0x2000, v7
	v_bitop3_b32 v6, v12, v9, v6 bitop3:0xde
	v_add_u32_e32 v17, 0x200, v11
	v_or3_b32 v206, v8, v7, v6
	v_ashrrev_i32_e32 v18, 5, v17
	v_lshl_add_u64 v[12:13], v[206:207], 1, s[28:29]
	v_mad_u64_u32 v[6:7], s[0:1], v18, s55, v[10:11]
	ds_read_b128 v[6:9], v6
	s_waitcnt lgkmcnt(1)
	global_store_dwordx4 v[12:13], v[2:5], off sc0 sc1
	v_lshlrev_b32_e32 v12, 1, v18
	v_and_b32_e32 v12, 16, v12
	v_add_u32_e32 v2, s4, v18
	v_lshrrev_b32_e32 v4, 3, v18
	v_lshrrev_b32_e32 v3, 4, v2
	v_and_or_b32 v4, v4, 14, v15
	v_and_or_b32 v3, v3, s5, v14
	v_lshlrev_b32_e32 v2, 6, v2
	v_and_or_b32 v5, v17, s34, v16
	v_lshlrev_b32_e32 v4, 9, v4
	v_lshlrev_b32_e32 v3, 14, v3
	v_and_b32_e32 v2, 0x2000, v2
	v_bitop3_b32 v4, v5, v4, v12 bitop3:0xde
	v_or3_b32 v206, v3, v2, v4
	v_lshl_add_u64 v[2:3], v[206:207], 1, s[28:29]
	s_waitcnt lgkmcnt(0)
	global_store_dwordx4 v[2:3], v[6:9], off sc0 sc1
	v_add_u32_e32 v17, 0x600, v11
	v_ashrrev_i32_e32 v18, 5, v17
	v_add_u32_e32 v6, 0x400, v11
	v_ashrrev_i32_e32 v7, 5, v6
	v_mad_u64_u32 v[2:3], s[0:1], v7, s55, v[10:11]
	v_add_u32_e32 v8, s4, v7
	v_lshrrev_b32_e32 v12, 3, v7
	ds_read_b128 v[2:5], v2
	v_lshrrev_b32_e32 v9, 4, v8
	v_and_or_b32 v12, v12, 14, v15
	v_lshlrev_b32_e32 v7, 1, v7
	v_and_or_b32 v9, v9, s5, v14
	v_lshlrev_b32_e32 v8, 6, v8
	v_and_or_b32 v6, v6, s34, v16
	v_lshlrev_b32_e32 v12, 9, v12
	v_and_b32_e32 v7, 16, v7
	v_lshlrev_b32_e32 v9, 14, v9
	v_and_b32_e32 v8, 0x2000, v8
	v_bitop3_b32 v6, v6, v12, v7 bitop3:0xde
	v_or3_b32 v206, v9, v8, v6
	v_lshl_add_u64 v[12:13], v[206:207], 1, s[28:29]
	v_mad_u64_u32 v[6:7], s[0:1], v18, s55, v[10:11]
	ds_read_b128 v[6:9], v6
	s_waitcnt lgkmcnt(1)
	global_store_dwordx4 v[12:13], v[2:5], off sc0 sc1
	v_lshlrev_b32_e32 v12, 1, v18
	v_and_b32_e32 v12, 16, v12
	v_add_u32_e32 v2, s4, v18
	v_lshrrev_b32_e32 v4, 3, v18
	v_lshrrev_b32_e32 v3, 4, v2
	v_and_or_b32 v4, v4, 14, v15
	v_and_or_b32 v3, v3, s5, v14
	v_lshlrev_b32_e32 v2, 6, v2
	v_and_or_b32 v5, v17, s34, v16
	v_lshlrev_b32_e32 v4, 9, v4
	v_lshlrev_b32_e32 v3, 14, v3
	v_and_b32_e32 v2, 0x2000, v2
	v_bitop3_b32 v4, v5, v4, v12 bitop3:0xde
	v_or3_b32 v206, v3, v2, v4
	v_lshl_add_u64 v[2:3], v[206:207], 1, s[28:29]
	s_waitcnt lgkmcnt(0)
	global_store_dwordx4 v[2:3], v[6:9], off sc0 sc1
	v_add_u32_e32 v17, 0xa00, v11
	v_ashrrev_i32_e32 v18, 5, v17
	v_add_u32_e32 v6, 0x800, v11
	v_ashrrev_i32_e32 v7, 5, v6
	v_mad_u64_u32 v[2:3], s[0:1], v7, s55, v[10:11]
	v_add_u32_e32 v8, s4, v7
	v_lshrrev_b32_e32 v12, 3, v7
	ds_read_b128 v[2:5], v2
	v_lshrrev_b32_e32 v9, 4, v8
	v_and_or_b32 v12, v12, 14, v15
	v_lshlrev_b32_e32 v7, 1, v7
	v_and_or_b32 v9, v9, s5, v14
	v_lshlrev_b32_e32 v8, 6, v8
	v_and_or_b32 v6, v6, s34, v16
	v_lshlrev_b32_e32 v12, 9, v12
	v_and_b32_e32 v7, 16, v7
	v_lshlrev_b32_e32 v9, 14, v9
	v_and_b32_e32 v8, 0x2000, v8
	v_bitop3_b32 v6, v6, v12, v7 bitop3:0xde
	v_or3_b32 v206, v9, v8, v6
	v_lshl_add_u64 v[12:13], v[206:207], 1, s[28:29]
	v_mad_u64_u32 v[6:7], s[0:1], v18, s55, v[10:11]
	ds_read_b128 v[6:9], v6
	s_waitcnt lgkmcnt(1)
	global_store_dwordx4 v[12:13], v[2:5], off sc0 sc1
	v_lshlrev_b32_e32 v12, 1, v18
	v_and_b32_e32 v12, 16, v12
	v_add_u32_e32 v2, s4, v18
	v_lshrrev_b32_e32 v4, 3, v18
	v_lshrrev_b32_e32 v3, 4, v2
	v_and_or_b32 v4, v4, 14, v15
	v_and_or_b32 v3, v3, s5, v14
	v_lshlrev_b32_e32 v2, 6, v2
	v_and_or_b32 v5, v17, s34, v16
	v_lshlrev_b32_e32 v4, 9, v4
	v_lshlrev_b32_e32 v3, 14, v3
	v_and_b32_e32 v2, 0x2000, v2
	v_bitop3_b32 v4, v5, v4, v12 bitop3:0xde
	v_or3_b32 v206, v3, v2, v4
	v_lshl_add_u64 v[2:3], v[206:207], 1, s[28:29]
	s_waitcnt lgkmcnt(0)
	global_store_dwordx4 v[2:3], v[6:9], off sc0 sc1
	s_nop 1
	v_add_u32_e32 v6, 0xc00, v11
	v_ashrrev_i32_e32 v7, 5, v6
	v_mad_u64_u32 v[2:3], s[0:1], v7, s55, v[10:11]
	v_add_u32_e32 v8, s4, v7
	v_lshrrev_b32_e32 v12, 3, v7
	ds_read_b128 v[2:5], v2
	v_lshrrev_b32_e32 v9, 4, v8
	v_and_or_b32 v12, v12, 14, v15
	v_lshlrev_b32_e32 v7, 1, v7
	v_and_or_b32 v9, v9, s5, v14
	v_lshlrev_b32_e32 v8, 6, v8
	v_and_or_b32 v6, v6, s34, v16
	v_lshlrev_b32_e32 v12, 9, v12
	v_and_b32_e32 v7, 16, v7
	v_lshlrev_b32_e32 v9, 14, v9
	v_and_b32_e32 v8, 0x2000, v8
	v_bitop3_b32 v6, v6, v12, v7 bitop3:0xde
	v_add_u32_e32 v11, 0xe00, v11
	v_or3_b32 v206, v9, v8, v6
	v_ashrrev_i32_e32 v17, 5, v11
	v_lshl_add_u64 v[12:13], v[206:207], 1, s[28:29]
	v_mad_u64_u32 v[6:7], s[0:1], v17, s55, v[10:11]
	ds_read_b128 v[6:9], v6
	s_waitcnt lgkmcnt(1)
	global_store_dwordx4 v[12:13], v[2:5], off sc0 sc1
	v_lshlrev_b32_e32 v10, 1, v17
	v_and_b32_e32 v10, 16, v10
	v_add_u32_e32 v2, s4, v17
	v_lshrrev_b32_e32 v4, 3, v17
	v_lshrrev_b32_e32 v3, 4, v2
	v_and_or_b32 v4, v4, 14, v15
	v_and_or_b32 v3, v3, s5, v14
	v_lshlrev_b32_e32 v2, 6, v2
	v_and_or_b32 v5, v11, s34, v16
	v_lshlrev_b32_e32 v4, 9, v4
	v_lshlrev_b32_e32 v3, 14, v3
	v_and_b32_e32 v2, 0x2000, v2
	v_bitop3_b32 v4, v5, v4, v10 bitop3:0xde
	v_or3_b32 v206, v3, v2, v4
	v_lshl_add_u64 v[2:3], v[206:207], 1, s[28:29]
	s_waitcnt lgkmcnt(0)
	global_store_dwordx4 v[2:3], v[6:9], off sc0 sc1
	s_barrier
	s_mov_b64 s[0:1], 0

; __device__ __forceinline__ void conv_unit(const Args& a, LAS unsigned char* lds, int l, int tt) {
;     ...
;         for (int half = 0; half < 2; ++half) {
;             const int tb = (tg4 + 4 * half) * 16;
;             float a0[16], a1[16];
; #pragma unroll
;             for (int t = 0; t < 16; ++t) { a0[t] = cb[0]; a1[t] = cb[1]; }
; #pragma unroll
;             for (int r = 0; r < 46; ++r) {
;                 const unsigned wv = Yu[(tb + r) * 128 + cp];
;                 const float x0 = bf2f(wv & 0xffffu), x1 = __builtin_bit_cast(float, wv & 0xffff0000u);
; #pragma unroll
;                 for (int t = 0; t < 16; ++t) { const int k = r - t; if (k >= 0 && k <= 30) { a0[t] += w0[k] * x0; a1[t] += w1[k] * x1; } }
.LBB0_512:
	v_add_u32_e32 v69, s4, v67
	v_lshl_add_u32 v78, v69, 9, v68
	ds_read2st64_b32 v[72:73], v78 offset1:2
	ds_read2st64_b32 v[76:77], v78 offset0:4 offset1:6
	ds_read2st64_b32 v[80:81], v78 offset0:8 offset1:10
	ds_read2st64_b32 v[84:85], v78 offset0:12 offset1:14
	ds_read2st64_b32 v[88:89], v78 offset0:16 offset1:18
	s_waitcnt lgkmcnt(4)
	v_and_b32_e32 v70, 0xffff0000, v72
	v_lshlrev_b32_e32 v71, 16, v72
	s_waitcnt vmcnt(0)
	v_fma_f32 v74, v2, v71, v64
	v_fma_f32 v71, v3, v70, v65
	v_lshlrev_b32_e32 v70, 16, v73
	v_and_b32_e32 v73, 0xffff0000, v73
	v_fmac_f32_e32 v74, v4, v70
	v_fmac_f32_e32 v71, v5, v73
	v_fma_f32 v72, v2, v70, v64
	v_fma_f32 v70, v3, v73, v65
	s_waitcnt lgkmcnt(3)
	v_lshlrev_b32_e32 v73, 16, v76
	v_and_b32_e32 v76, 0xffff0000, v76
	v_fmac_f32_e32 v74, v6, v73
	v_fmac_f32_e32 v71, v7, v76
	v_fmac_f32_e32 v72, v4, v73
	v_fmac_f32_e32 v70, v5, v76
	v_fma_f32 v75, v2, v73, v64
	v_fma_f32 v73, v3, v76, v65
	v_lshlrev_b32_e32 v76, 16, v77
	v_and_b32_e32 v79, 0xffff0000, v77
	v_fmac_f32_e32 v74, v8, v76
	v_fmac_f32_e32 v71, v9, v79
	v_fmac_f32_e32 v72, v6, v76
	v_fmac_f32_e32 v70, v7, v79
	v_fmac_f32_e32 v75, v4, v76
	v_fmac_f32_e32 v73, v5, v79
	v_fma_f32 v77, v2, v76, v64
	v_fma_f32 v76, v3, v79, v65
	s_waitcnt lgkmcnt(2)
	v_lshlrev_b32_e32 v79, 16, v80
	v_and_b32_e32 v82, 0xffff0000, v80
	v_fmac_f32_e32 v74, v10, v79
	v_fmac_f32_e32 v71, v11, v82
	v_fmac_f32_e32 v72, v8, v79
	v_fmac_f32_e32 v70, v9, v82
	v_fmac_f32_e32 v75, v6, v79
	v_fmac_f32_e32 v73, v7, v82
	v_fmac_f32_e32 v77, v4, v79
	v_fmac_f32_e32 v76, v5, v82
	v_fma_f32 v80, v2, v79, v64
	v_fma_f32 v79, v3, v82, v65
	v_lshlrev_b32_e32 v82, 16, v81
	v_and_b32_e32 v81, 0xffff0000, v81
	ds_read2st64_b32 v[92:93], v78 offset0:20 offset1:22
	v_fmac_f32_e32 v74, v18, v82
	v_fmac_f32_e32 v71, v19, v81
	v_fmac_f32_e32 v72, v10, v82
	v_fmac_f32_e32 v70, v11, v81
	v_fmac_f32_e32 v75, v8, v82
	v_fmac_f32_e32 v73, v9, v81
	v_fmac_f32_e32 v77, v6, v82
	v_fmac_f32_e32 v76, v7, v81
	v_fmac_f32_e32 v80, v4, v82
	v_fmac_f32_e32 v79, v5, v81
	v_fma_f32 v82, v2, v82, v64
	v_fma_f32 v81, v3, v81, v65
	s_waitcnt lgkmcnt(2)
	v_lshlrev_b32_e32 v83, 16, v84
	v_and_b32_e32 v86, 0xffff0000, v84
	v_fmac_f32_e32 v74, v20, v83
	v_fmac_f32_e32 v71, v21, v86
	v_fmac_f32_e32 v72, v18, v83
	v_fmac_f32_e32 v70, v19, v86
	v_fmac_f32_e32 v75, v10, v83
	v_fmac_f32_e32 v73, v11, v86
	v_fmac_f32_e32 v77, v8, v83
	v_fmac_f32_e32 v76, v9, v86
	v_fmac_f32_e32 v80, v6, v83
	v_fmac_f32_e32 v79, v7, v86
	v_fmac_f32_e32 v82, v4, v83
	v_fmac_f32_e32 v81, v5, v86
	v_fma_f32 v84, v2, v83, v64
	v_fma_f32 v83, v3, v86, v65
	v_lshlrev_b32_e32 v86, 16, v85
	v_and_b32_e32 v85, 0xffff0000, v85
	ds_read2st64_b32 v[98:99], v78 offset0:24 offset1:26
	v_fmac_f32_e32 v74, v22, v86
	v_fmac_f32_e32 v71, v23, v85
	v_fmac_f32_e32 v72, v20, v86
	v_fmac_f32_e32 v70, v21, v85
	v_fmac_f32_e32 v75, v18, v86
	v_fmac_f32_e32 v73, v19, v85
	v_fmac_f32_e32 v77, v10, v86
	v_fmac_f32_e32 v76, v11, v85
	v_fmac_f32_e32 v80, v8, v86
	v_fmac_f32_e32 v79, v9, v85
	v_fmac_f32_e32 v82, v6, v86
	v_fmac_f32_e32 v81, v7, v85
	v_fmac_f32_e32 v84, v4, v86
	v_fmac_f32_e32 v83, v5, v85
	v_fma_f32 v86, v2, v86, v64
	v_fma_f32 v85, v3, v85, v65
	s_waitcnt lgkmcnt(2)
	v_lshlrev_b32_e32 v87, 16, v88
	v_and_b32_e32 v90, 0xffff0000, v88
	v_fmac_f32_e32 v74, v12, v87
	v_fmac_f32_e32 v71, v13, v90
	v_fmac_f32_e32 v72, v22, v87
	v_fmac_f32_e32 v70, v23, v90
	v_fmac_f32_e32 v75, v20, v87
	v_fmac_f32_e32 v73, v21, v90
	v_fmac_f32_e32 v77, v18, v87
	v_fmac_f32_e32 v76, v19, v90
	v_fmac_f32_e32 v80, v10, v87
	v_fmac_f32_e32 v79, v11, v90
	v_fmac_f32_e32 v82, v8, v87
	v_fmac_f32_e32 v81, v9, v90
	v_fmac_f32_e32 v84, v6, v87
	v_fmac_f32_e32 v83, v7, v90
	v_fmac_f32_e32 v86, v4, v87
	v_fmac_f32_e32 v85, v5, v90
	v_fma_f32 v88, v2, v87, v64
	v_fma_f32 v87, v3, v90, v65
	v_lshlrev_b32_e32 v90, 16, v89
	v_and_b32_e32 v89, 0xffff0000, v89
	ds_read2st64_b32 v[102:103], v78 offset0:28 offset1:30
	v_fmac_f32_e32 v74, v14, v90
	v_fmac_f32_e32 v71, v15, v89
	v_fmac_f32_e32 v72, v12, v90
	v_fmac_f32_e32 v70, v13, v89
	v_fmac_f32_e32 v75, v22, v90
	v_fmac_f32_e32 v73, v23, v89
	v_fmac_f32_e32 v77, v20, v90
	v_fmac_f32_e32 v76, v21, v89
	v_fmac_f32_e32 v80, v18, v90
	v_fmac_f32_e32 v79, v19, v89
	v_fmac_f32_e32 v82, v10, v90
	v_fmac_f32_e32 v81, v11, v89
	v_fmac_f32_e32 v84, v8, v90
	v_fmac_f32_e32 v83, v9, v89
	v_fmac_f32_e32 v86, v6, v90
	v_fmac_f32_e32 v85, v7, v89
	v_fmac_f32_e32 v88, v4, v90
	v_fmac_f32_e32 v87, v5, v89
	v_fma_f32 v90, v2, v90, v64
	v_fma_f32 v89, v3, v89, v65
	s_waitcnt lgkmcnt(2)
	v_lshlrev_b32_e32 v91, 16, v92
	v_and_b32_e32 v94, 0xffff0000, v92
	v_fmac_f32_e32 v74, v16, v91
	v_fmac_f32_e32 v71, v17, v94
	v_fmac_f32_e32 v72, v14, v91
	v_fmac_f32_e32 v70, v15, v94
	v_fmac_f32_e32 v75, v12, v91
	v_fmac_f32_e32 v73, v13, v94
	v_fmac_f32_e32 v77, v22, v91
	v_fmac_f32_e32 v76, v23, v94
	v_fmac_f32_e32 v80, v20, v91
	v_fmac_f32_e32 v79, v21, v94
	v_fmac_f32_e32 v82, v18, v91
	v_fmac_f32_e32 v81, v19, v94
	v_fmac_f32_e32 v84, v10, v91
	v_fmac_f32_e32 v83, v11, v94
	v_fmac_f32_e32 v86, v8, v91
	v_fmac_f32_e32 v85, v9, v94
	v_fmac_f32_e32 v88, v6, v91
	v_fmac_f32_e32 v87, v7, v94
	v_fmac_f32_e32 v90, v4, v91
	v_fmac_f32_e32 v89, v5, v94
	v_fma_f32 v92, v2, v91, v64
	v_fma_f32 v91, v3, v94, v65
	v_lshlrev_b32_e32 v94, 16, v93
	v_and_b32_e32 v93, 0xffff0000, v93
	v_fmac_f32_e32 v74, v26, v94
	v_fmac_f32_e32 v71, v27, v93
	v_fmac_f32_e32 v72, v16, v94
	v_fmac_f32_e32 v70, v17, v93
	v_fmac_f32_e32 v75, v14, v94
	v_fmac_f32_e32 v73, v15, v93
	v_fmac_f32_e32 v77, v12, v94
	v_fmac_f32_e32 v76, v13, v93
	v_fmac_f32_e32 v80, v22, v94
	v_fmac_f32_e32 v79, v23, v93
	v_fmac_f32_e32 v82, v20, v94
	v_fmac_f32_e32 v81, v21, v93
	v_fmac_f32_e32 v84, v18, v94
	v_fmac_f32_e32 v83, v19, v93
	v_fmac_f32_e32 v86, v10, v94
	v_fmac_f32_e32 v85, v11, v93
	v_fmac_f32_e32 v88, v8, v94
	v_fmac_f32_e32 v87, v9, v93
	v_fmac_f32_e32 v90, v6, v94
	v_fmac_f32_e32 v89, v7, v93
	v_fmac_f32_e32 v92, v4, v94
	v_fmac_f32_e32 v91, v5, v93
	v_fma_f32 v94, v2, v94, v64
	v_fma_f32 v93, v3, v93, v65
	s_waitcnt lgkmcnt(1)
; __device__ __forceinline__ void conv_unit(const Args& a, LAS unsigned char* lds, int l, int tt) {
;     ...
;             for (int r = 0; r < 46; ++r) {
;                 const unsigned wv = Yu[(tb + r) * 128 + cp];
;                 const float x0 = bf2f(wv & 0xffffu), x1 = __builtin_bit_cast(float, wv & 0xffff0000u);
; #pragma unroll
;                 for (int t = 0; t < 16; ++t) { const int k = r - t; if (k >= 0 && k <= 30) { a0[t] += w0[k] * x0; a1[t] += w1[k] * x1; } }
	v_lshlrev_b32_e32 v96, 16, v98
	v_and_b32_e32 v98, 0xffff0000, v98
	v_fmac_f32_e32 v74, v28, v96
	v_fmac_f32_e32 v71, v29, v98
	v_fmac_f32_e32 v72, v26, v96
	v_fmac_f32_e32 v70, v27, v98
	v_fmac_f32_e32 v75, v16, v96
	v_fmac_f32_e32 v73, v17, v98
	v_fmac_f32_e32 v77, v14, v96
	v_fmac_f32_e32 v76, v15, v98
	v_fmac_f32_e32 v80, v12, v96
	v_fmac_f32_e32 v79, v13, v98
	v_fmac_f32_e32 v82, v22, v96
	v_fmac_f32_e32 v81, v23, v98
	v_fmac_f32_e32 v84, v20, v96
	v_fmac_f32_e32 v83, v21, v98
	v_fmac_f32_e32 v86, v18, v96
	v_fmac_f32_e32 v85, v19, v98
	v_fmac_f32_e32 v88, v10, v96
	v_fmac_f32_e32 v87, v11, v98
	v_fmac_f32_e32 v90, v8, v96
	v_fmac_f32_e32 v89, v9, v98
	v_fmac_f32_e32 v92, v6, v96
	v_fmac_f32_e32 v91, v7, v98
	v_fmac_f32_e32 v94, v4, v96
	v_fmac_f32_e32 v93, v5, v98
	v_fma_f32 v97, v2, v96, v64
	v_fma_f32 v96, v3, v98, v65
	v_lshlrev_b32_e32 v98, 16, v99
	v_and_b32_e32 v100, 0xffff0000, v99
	v_fmac_f32_e32 v74, v24, v98
	v_fmac_f32_e32 v71, v25, v100
	v_fmac_f32_e32 v72, v28, v98
	v_fmac_f32_e32 v70, v29, v100
	v_fmac_f32_e32 v75, v26, v98
	v_fmac_f32_e32 v73, v27, v100
	v_fmac_f32_e32 v77, v16, v98
	v_fmac_f32_e32 v76, v17, v100
	v_fmac_f32_e32 v80, v14, v98
	v_fmac_f32_e32 v79, v15, v100
	v_fmac_f32_e32 v82, v12, v98
	v_fmac_f32_e32 v81, v13, v100
	v_fmac_f32_e32 v84, v22, v98
	v_fmac_f32_e32 v83, v23, v100
	v_fmac_f32_e32 v86, v20, v98
	v_fmac_f32_e32 v85, v21, v100
	v_fmac_f32_e32 v88, v18, v98
	v_fmac_f32_e32 v87, v19, v100
	v_fmac_f32_e32 v90, v10, v98
	v_fmac_f32_e32 v89, v11, v100
	v_fmac_f32_e32 v92, v8, v98
	v_fmac_f32_e32 v91, v9, v100
	v_fmac_f32_e32 v94, v6, v98
	v_fmac_f32_e32 v93, v7, v100
	v_fmac_f32_e32 v97, v4, v98
	v_fmac_f32_e32 v96, v5, v100
	v_fma_f32 v99, v2, v98, v64
	v_fma_f32 v98, v3, v100, v65
	s_waitcnt lgkmcnt(0)
	v_lshlrev_b32_e32 v100, 16, v102
	v_and_b32_e32 v102, 0xffff0000, v102
	v_fmac_f32_e32 v74, v34, v100
	v_fmac_f32_e32 v71, v35, v102
	v_fmac_f32_e32 v72, v24, v100
	v_fmac_f32_e32 v70, v25, v102
	v_fmac_f32_e32 v75, v28, v100
	v_fmac_f32_e32 v73, v29, v102
	v_fmac_f32_e32 v77, v26, v100
	v_fmac_f32_e32 v76, v27, v102
	v_fmac_f32_e32 v80, v16, v100
	v_fmac_f32_e32 v79, v17, v102
	v_fmac_f32_e32 v82, v14, v100
	v_fmac_f32_e32 v81, v15, v102
	v_fmac_f32_e32 v84, v12, v100
	v_fmac_f32_e32 v83, v13, v102
	v_fmac_f32_e32 v86, v22, v100
	v_fmac_f32_e32 v85, v23, v102
	v_fmac_f32_e32 v88, v20, v100
	v_fmac_f32_e32 v87, v21, v102
	v_fmac_f32_e32 v90, v18, v100
	v_fmac_f32_e32 v89, v19, v102
	v_fmac_f32_e32 v92, v10, v100
	v_fmac_f32_e32 v91, v11, v102
	v_fmac_f32_e32 v94, v8, v100
	v_fmac_f32_e32 v93, v9, v102
	v_fmac_f32_e32 v97, v6, v100
	v_fmac_f32_e32 v96, v7, v102
	v_fmac_f32_e32 v99, v4, v100
	v_fmac_f32_e32 v98, v5, v102
	v_fma_f32 v101, v2, v100, v64
	v_fma_f32 v100, v3, v102, v65
	v_lshlrev_b32_e32 v102, 16, v103
	v_and_b32_e32 v104, 0xffff0000, v103
	v_fmac_f32_e32 v74, v36, v102
	v_fmac_f32_e32 v71, v37, v104
	v_fmac_f32_e32 v72, v34, v102
	v_fmac_f32_e32 v70, v35, v104
	v_fmac_f32_e32 v75, v24, v102
	v_fmac_f32_e32 v73, v25, v104
	v_fmac_f32_e32 v77, v28, v102
	v_fmac_f32_e32 v76, v29, v104
	v_fmac_f32_e32 v80, v26, v102
	v_fmac_f32_e32 v79, v27, v104
	v_fmac_f32_e32 v82, v16, v102
	v_fmac_f32_e32 v81, v17, v104
	v_fmac_f32_e32 v84, v14, v102
	v_fmac_f32_e32 v83, v15, v104
	v_fmac_f32_e32 v86, v12, v102
	v_fmac_f32_e32 v85, v13, v104
	v_fmac_f32_e32 v88, v22, v102
	v_fmac_f32_e32 v87, v23, v104
	v_fmac_f32_e32 v90, v20, v102
	v_fmac_f32_e32 v89, v21, v104
	v_fmac_f32_e32 v92, v18, v102
	v_fmac_f32_e32 v91, v19, v104
	v_fmac_f32_e32 v94, v10, v102
	v_fmac_f32_e32 v93, v11, v104
	v_fmac_f32_e32 v97, v8, v102
	v_fmac_f32_e32 v96, v9, v104
	v_fmac_f32_e32 v99, v6, v102
	v_fmac_f32_e32 v98, v7, v104
	v_fmac_f32_e32 v101, v4, v102
	v_fmac_f32_e32 v100, v5, v104
	v_fma_f32 v103, v2, v102, v64
	v_fma_f32 v102, v3, v104, v65
	ds_read2st64_b32 v[104:105], v78 offset0:32 offset1:34
	s_and_b64 vcc, exec, s[0:1]
	s_mov_b64 s[0:1], 0
	s_waitcnt lgkmcnt(0)
	v_lshlrev_b32_e32 v106, 16, v104
	v_and_b32_e32 v104, 0xffff0000, v104
	v_fmac_f32_e32 v74, v30, v106
	v_fmac_f32_e32 v71, v31, v104
	v_fmac_f32_e32 v72, v36, v106
	v_fmac_f32_e32 v70, v37, v104
	v_fmac_f32_e32 v75, v34, v106
	v_fmac_f32_e32 v73, v35, v104
	v_fmac_f32_e32 v77, v24, v106
	v_fmac_f32_e32 v76, v25, v104
	v_fmac_f32_e32 v80, v28, v106
	v_fmac_f32_e32 v79, v29, v104
	v_fmac_f32_e32 v82, v26, v106
	v_fmac_f32_e32 v81, v27, v104
	v_fmac_f32_e32 v84, v16, v106
	v_fmac_f32_e32 v83, v17, v104
	v_fmac_f32_e32 v86, v14, v106
	v_fmac_f32_e32 v85, v15, v104
	v_fmac_f32_e32 v88, v12, v106
	v_fmac_f32_e32 v87, v13, v104
	v_fmac_f32_e32 v90, v22, v106
	v_fmac_f32_e32 v89, v23, v104
	v_fmac_f32_e32 v92, v20, v106
	v_fmac_f32_e32 v91, v21, v104
	v_fmac_f32_e32 v94, v18, v106
	v_fmac_f32_e32 v93, v19, v104
	v_fmac_f32_e32 v97, v10, v106
	v_fmac_f32_e32 v96, v11, v104
	v_fmac_f32_e32 v99, v8, v106
	v_fmac_f32_e32 v98, v9, v104
	v_fmac_f32_e32 v101, v6, v106
	v_fmac_f32_e32 v100, v7, v104
	v_fmac_f32_e32 v103, v4, v106
	v_fmac_f32_e32 v102, v5, v104
	v_lshlrev_b32_e32 v104, 16, v105
	v_and_b32_e32 v105, 0xffff0000, v105
	v_fmac_f32_e32 v74, v32, v104
	v_fmac_f32_e32 v71, v33, v105
	v_fmac_f32_e32 v72, v30, v104
	v_fmac_f32_e32 v70, v31, v105
	v_fmac_f32_e32 v75, v36, v104
	v_fmac_f32_e32 v73, v37, v105
	v_fmac_f32_e32 v77, v34, v104
	v_fmac_f32_e32 v76, v35, v105
	v_fmac_f32_e32 v80, v24, v104
	v_fmac_f32_e32 v79, v25, v105
	v_fmac_f32_e32 v82, v28, v104
	v_fmac_f32_e32 v81, v29, v105
	v_fmac_f32_e32 v84, v26, v104
	v_fmac_f32_e32 v83, v27, v105
	v_fmac_f32_e32 v86, v16, v104
	v_fmac_f32_e32 v85, v17, v105
	v_fmac_f32_e32 v88, v14, v104
	v_fmac_f32_e32 v87, v15, v105
	v_fmac_f32_e32 v90, v12, v104
	v_fmac_f32_e32 v89, v13, v105
	v_fmac_f32_e32 v92, v22, v104
	v_fmac_f32_e32 v91, v23, v105
	v_fmac_f32_e32 v94, v20, v104
	v_fmac_f32_e32 v93, v21, v105
	v_fmac_f32_e32 v97, v18, v104
	v_fmac_f32_e32 v96, v19, v105
	v_fmac_f32_e32 v99, v10, v104
	v_fmac_f32_e32 v98, v11, v105
	v_fmac_f32_e32 v101, v8, v104
	v_fmac_f32_e32 v100, v9, v105
	v_fmac_f32_e32 v103, v6, v104
	v_fmac_f32_e32 v102, v7, v105
	ds_read2st64_b32 v[104:105], v78 offset0:36 offset1:38
	s_waitcnt lgkmcnt(0)
; __device__ __forceinline__ void conv_unit(const Args& a, LAS unsigned char* lds, int l, int tt) {
;     ...
;             for (int r = 0; r < 46; ++r) {
;                 const unsigned wv = Yu[(tb + r) * 128 + cp];
;                 const float x0 = bf2f(wv & 0xffffu), x1 = __builtin_bit_cast(float, wv & 0xffff0000u);
; #pragma unroll
;                 for (int t = 0; t < 16; ++t) { const int k = r - t; if (k >= 0 && k <= 30) { a0[t] += w0[k] * x0; a1[t] += w1[k] * x1; } }
	v_lshlrev_b32_e32 v106, 16, v104
	v_and_b32_e32 v104, 0xffff0000, v104
	v_fmac_f32_e32 v74, v42, v106
	v_fmac_f32_e32 v71, v43, v104
	v_fmac_f32_e32 v72, v32, v106
	v_fmac_f32_e32 v70, v33, v104
	v_fmac_f32_e32 v75, v30, v106
	v_fmac_f32_e32 v73, v31, v104
	v_fmac_f32_e32 v77, v36, v106
	v_fmac_f32_e32 v76, v37, v104
	v_fmac_f32_e32 v80, v34, v106
	v_fmac_f32_e32 v79, v35, v104
	v_fmac_f32_e32 v82, v24, v106
	v_fmac_f32_e32 v81, v25, v104
	v_fmac_f32_e32 v84, v28, v106
	v_fmac_f32_e32 v83, v29, v104
	v_fmac_f32_e32 v86, v26, v106
	v_fmac_f32_e32 v85, v27, v104
	v_fmac_f32_e32 v88, v16, v106
	v_fmac_f32_e32 v87, v17, v104
	v_fmac_f32_e32 v90, v14, v106
	v_fmac_f32_e32 v89, v15, v104
	v_fmac_f32_e32 v92, v12, v106
	v_fmac_f32_e32 v91, v13, v104
	v_fmac_f32_e32 v94, v22, v106
	v_fmac_f32_e32 v93, v23, v104
	v_fmac_f32_e32 v97, v20, v106
	v_fmac_f32_e32 v96, v21, v104
	v_fmac_f32_e32 v99, v18, v106
	v_fmac_f32_e32 v98, v19, v104
	v_fmac_f32_e32 v101, v10, v106
	v_fmac_f32_e32 v100, v11, v104
	v_fmac_f32_e32 v103, v8, v106
	v_fmac_f32_e32 v102, v9, v104
	v_lshlrev_b32_e32 v104, 16, v105
	v_and_b32_e32 v105, 0xffff0000, v105
	v_fmac_f32_e32 v74, v44, v104
	v_fmac_f32_e32 v71, v45, v105
	v_fmac_f32_e32 v72, v42, v104
	v_fmac_f32_e32 v70, v43, v105
	v_fmac_f32_e32 v75, v32, v104
	v_fmac_f32_e32 v73, v33, v105
	v_fmac_f32_e32 v77, v30, v104
	v_fmac_f32_e32 v76, v31, v105
	v_fmac_f32_e32 v80, v36, v104
	v_fmac_f32_e32 v79, v37, v105
	v_fmac_f32_e32 v82, v34, v104
	v_fmac_f32_e32 v81, v35, v105
	v_fmac_f32_e32 v84, v24, v104
	v_fmac_f32_e32 v83, v25, v105
	v_fmac_f32_e32 v86, v28, v104
	v_fmac_f32_e32 v85, v29, v105
	v_fmac_f32_e32 v88, v26, v104
	v_fmac_f32_e32 v87, v27, v105
	v_fmac_f32_e32 v90, v16, v104
	v_fmac_f32_e32 v89, v17, v105
	v_fmac_f32_e32 v92, v14, v104
	v_fmac_f32_e32 v91, v15, v105
	v_fmac_f32_e32 v94, v12, v104
	v_fmac_f32_e32 v93, v13, v105
	v_fmac_f32_e32 v97, v22, v104
	v_fmac_f32_e32 v96, v23, v105
	v_fmac_f32_e32 v99, v20, v104
	v_fmac_f32_e32 v98, v21, v105
	v_fmac_f32_e32 v101, v18, v104
	v_fmac_f32_e32 v100, v19, v105
	v_fmac_f32_e32 v103, v10, v104
	v_fmac_f32_e32 v102, v11, v105
	ds_read2st64_b32 v[104:105], v78 offset0:40 offset1:42
	s_waitcnt lgkmcnt(0)
	v_lshlrev_b32_e32 v106, 16, v104
	v_and_b32_e32 v104, 0xffff0000, v104
	v_fmac_f32_e32 v74, v46, v106
	v_fmac_f32_e32 v71, v47, v104
	v_fmac_f32_e32 v72, v44, v106
	v_fmac_f32_e32 v70, v45, v104
	v_fmac_f32_e32 v75, v42, v106
	v_fmac_f32_e32 v73, v43, v104
	v_fmac_f32_e32 v77, v32, v106
	v_fmac_f32_e32 v76, v33, v104
	v_fmac_f32_e32 v80, v30, v106
	v_fmac_f32_e32 v79, v31, v104
	v_fmac_f32_e32 v82, v36, v106
	v_fmac_f32_e32 v81, v37, v104
	v_fmac_f32_e32 v84, v34, v106
	v_fmac_f32_e32 v83, v35, v104
	v_fmac_f32_e32 v86, v24, v106
	v_fmac_f32_e32 v85, v25, v104
	v_fmac_f32_e32 v88, v28, v106
	v_fmac_f32_e32 v87, v29, v104
	v_fmac_f32_e32 v90, v26, v106
	v_fmac_f32_e32 v89, v27, v104
	v_fmac_f32_e32 v92, v16, v106
	v_fmac_f32_e32 v91, v17, v104
	v_fmac_f32_e32 v94, v14, v106
	v_fmac_f32_e32 v93, v15, v104
	v_fmac_f32_e32 v97, v12, v106
	v_fmac_f32_e32 v96, v13, v104
	v_fmac_f32_e32 v99, v22, v106
	v_fmac_f32_e32 v98, v23, v104
	v_fmac_f32_e32 v101, v20, v106
	v_fmac_f32_e32 v100, v21, v104
	v_fmac_f32_e32 v103, v18, v106
	v_fmac_f32_e32 v102, v19, v104
	v_lshlrev_b32_e32 v104, 16, v105
	v_and_b32_e32 v105, 0xffff0000, v105
	v_fmac_f32_e32 v74, v38, v104
	v_fmac_f32_e32 v71, v39, v105
	v_fmac_f32_e32 v72, v46, v104
	v_fmac_f32_e32 v70, v47, v105
	v_fmac_f32_e32 v75, v44, v104
	v_fmac_f32_e32 v73, v45, v105
	v_fmac_f32_e32 v77, v42, v104
	v_fmac_f32_e32 v76, v43, v105
	v_fmac_f32_e32 v80, v32, v104
	v_fmac_f32_e32 v79, v33, v105
	v_fmac_f32_e32 v82, v30, v104
	v_fmac_f32_e32 v81, v31, v105
	v_fmac_f32_e32 v84, v36, v104
	v_fmac_f32_e32 v83, v37, v105
	v_fmac_f32_e32 v86, v34, v104
	v_fmac_f32_e32 v85, v35, v105
	v_fmac_f32_e32 v88, v24, v104
	v_fmac_f32_e32 v87, v25, v105
	v_fmac_f32_e32 v90, v28, v104
	v_fmac_f32_e32 v89, v29, v105
	v_fmac_f32_e32 v92, v26, v104
	v_fmac_f32_e32 v91, v27, v105
	v_fmac_f32_e32 v94, v16, v104
	v_fmac_f32_e32 v93, v17, v105
	v_fmac_f32_e32 v97, v14, v104
	v_fmac_f32_e32 v96, v15, v105
	v_fmac_f32_e32 v99, v12, v104
	v_fmac_f32_e32 v98, v13, v105
	v_fmac_f32_e32 v101, v22, v104
	v_fmac_f32_e32 v100, v23, v105
	v_fmac_f32_e32 v103, v20, v104
	v_fmac_f32_e32 v102, v21, v105
	ds_read2st64_b32 v[104:105], v78 offset0:44 offset1:46
	s_waitcnt lgkmcnt(0)
	v_lshlrev_b32_e32 v106, 16, v104
	v_and_b32_e32 v104, 0xffff0000, v104
	v_fmac_f32_e32 v74, v40, v106
	v_fmac_f32_e32 v71, v41, v104
	v_fmac_f32_e32 v72, v38, v106
	v_fmac_f32_e32 v70, v39, v104
	v_fmac_f32_e32 v75, v46, v106
	v_fmac_f32_e32 v73, v47, v104
	v_fmac_f32_e32 v77, v44, v106
	v_fmac_f32_e32 v76, v45, v104
	v_fmac_f32_e32 v80, v42, v106
	v_fmac_f32_e32 v79, v43, v104
	v_fmac_f32_e32 v82, v32, v106
	v_fmac_f32_e32 v81, v33, v104
	v_fmac_f32_e32 v84, v30, v106
	v_fmac_f32_e32 v83, v31, v104
	v_fmac_f32_e32 v86, v36, v106
	v_fmac_f32_e32 v85, v37, v104
	v_fmac_f32_e32 v88, v34, v106
	v_fmac_f32_e32 v87, v35, v104
	v_fmac_f32_e32 v90, v24, v106
	v_fmac_f32_e32 v89, v25, v104
	v_fmac_f32_e32 v92, v28, v106
	v_fmac_f32_e32 v91, v29, v104
	v_fmac_f32_e32 v94, v26, v106
	v_fmac_f32_e32 v93, v27, v104
	v_fmac_f32_e32 v97, v16, v106
	v_fmac_f32_e32 v96, v17, v104
	v_fmac_f32_e32 v99, v14, v106
	v_fmac_f32_e32 v98, v15, v104
	v_fmac_f32_e32 v101, v12, v106
	v_fmac_f32_e32 v100, v13, v104
	v_fmac_f32_e32 v103, v22, v106
	v_fmac_f32_e32 v102, v23, v104
	v_lshlrev_b32_e32 v104, 16, v105
	v_and_b32_e32 v105, 0xffff0000, v105
	v_fmac_f32_e32 v74, v56, v104
	v_fmac_f32_e32 v71, v57, v105
	v_fmac_f32_e32 v72, v40, v104
	v_fmac_f32_e32 v70, v41, v105
	v_fmac_f32_e32 v75, v38, v104
	v_fmac_f32_e32 v73, v39, v105
	v_fmac_f32_e32 v77, v46, v104
	v_fmac_f32_e32 v76, v47, v105
	v_fmac_f32_e32 v80, v44, v104
	v_fmac_f32_e32 v79, v45, v105
	v_fmac_f32_e32 v82, v42, v104
	v_fmac_f32_e32 v81, v43, v105
	v_fmac_f32_e32 v84, v32, v104
	v_fmac_f32_e32 v83, v33, v105
	v_fmac_f32_e32 v86, v30, v104
	v_fmac_f32_e32 v85, v31, v105
	v_fmac_f32_e32 v88, v36, v104
	v_fmac_f32_e32 v87, v37, v105
	v_fmac_f32_e32 v90, v34, v104
	v_fmac_f32_e32 v89, v35, v105
	v_fmac_f32_e32 v92, v24, v104
	v_fmac_f32_e32 v91, v25, v105
	v_fmac_f32_e32 v94, v28, v104
	v_fmac_f32_e32 v93, v29, v105
	v_fmac_f32_e32 v97, v26, v104
	v_fmac_f32_e32 v96, v27, v105
	v_fmac_f32_e32 v99, v16, v104
	v_fmac_f32_e32 v98, v17, v105
	v_fmac_f32_e32 v101, v14, v104
	v_fmac_f32_e32 v100, v15, v105
	v_fmac_f32_e32 v103, v12, v104
	v_fmac_f32_e32 v102, v13, v105
	ds_read2st64_b32 v[104:105], v78 offset0:48 offset1:50
	s_waitcnt lgkmcnt(0)
; __device__ __forceinline__ void conv_unit(const Args& a, LAS unsigned char* lds, int l, int tt) {
;     ...
;             for (int r = 0; r < 46; ++r) {
;                 const unsigned wv = Yu[(tb + r) * 128 + cp];
;                 const float x0 = bf2f(wv & 0xffffu), x1 = __builtin_bit_cast(float, wv & 0xffff0000u);
; #pragma unroll
;                 for (int t = 0; t < 16; ++t) { const int k = r - t; if (k >= 0 && k <= 30) { a0[t] += w0[k] * x0; a1[t] += w1[k] * x1; } }
	v_lshlrev_b32_e32 v106, 16, v104
	v_and_b32_e32 v104, 0xffff0000, v104
	v_fmac_f32_e32 v74, v48, v106
	v_fmac_f32_e32 v71, v49, v104
	v_fmac_f32_e32 v72, v56, v106
	v_fmac_f32_e32 v70, v57, v104
	v_fmac_f32_e32 v75, v40, v106
	v_fmac_f32_e32 v73, v41, v104
	v_fmac_f32_e32 v77, v38, v106
	v_fmac_f32_e32 v76, v39, v104
	v_fmac_f32_e32 v80, v46, v106
	v_fmac_f32_e32 v79, v47, v104
	v_fmac_f32_e32 v82, v44, v106
	v_fmac_f32_e32 v81, v45, v104
	v_fmac_f32_e32 v84, v42, v106
	v_fmac_f32_e32 v83, v43, v104
	v_fmac_f32_e32 v86, v32, v106
	v_fmac_f32_e32 v85, v33, v104
	v_fmac_f32_e32 v88, v30, v106
	v_fmac_f32_e32 v87, v31, v104
	v_fmac_f32_e32 v90, v36, v106
	v_fmac_f32_e32 v89, v37, v104
	v_fmac_f32_e32 v92, v34, v106
	v_fmac_f32_e32 v91, v35, v104
	v_fmac_f32_e32 v94, v24, v106
	v_fmac_f32_e32 v93, v25, v104
	v_fmac_f32_e32 v97, v28, v106
	v_fmac_f32_e32 v96, v29, v104
	v_fmac_f32_e32 v99, v26, v106
	v_fmac_f32_e32 v98, v27, v104
	v_fmac_f32_e32 v101, v16, v106
	v_fmac_f32_e32 v100, v17, v104
	v_fmac_f32_e32 v103, v14, v106
	v_fmac_f32_e32 v102, v15, v104
	v_lshlrev_b32_e32 v104, 16, v105
	v_and_b32_e32 v105, 0xffff0000, v105
	v_fmac_f32_e32 v74, v50, v104
	v_fmac_f32_e32 v71, v51, v105
	v_fmac_f32_e32 v72, v48, v104
	v_fmac_f32_e32 v70, v49, v105
	v_fmac_f32_e32 v75, v56, v104
	v_fmac_f32_e32 v73, v57, v105
	v_fmac_f32_e32 v77, v40, v104
	v_fmac_f32_e32 v76, v41, v105
	v_fmac_f32_e32 v80, v38, v104
	v_fmac_f32_e32 v79, v39, v105
	v_fmac_f32_e32 v82, v46, v104
	v_fmac_f32_e32 v81, v47, v105
	v_fmac_f32_e32 v84, v44, v104
	v_fmac_f32_e32 v83, v45, v105
	v_fmac_f32_e32 v86, v42, v104
	v_fmac_f32_e32 v85, v43, v105
	v_fmac_f32_e32 v88, v32, v104
	v_fmac_f32_e32 v87, v33, v105
	v_fmac_f32_e32 v90, v30, v104
	v_fmac_f32_e32 v89, v31, v105
	v_fmac_f32_e32 v92, v36, v104
	v_fmac_f32_e32 v91, v37, v105
	v_fmac_f32_e32 v94, v34, v104
	v_fmac_f32_e32 v93, v35, v105
	v_fmac_f32_e32 v97, v24, v104
	v_fmac_f32_e32 v96, v25, v105
	v_fmac_f32_e32 v99, v28, v104
	v_fmac_f32_e32 v98, v29, v105
	v_fmac_f32_e32 v101, v26, v104
	v_fmac_f32_e32 v100, v27, v105
	v_fmac_f32_e32 v103, v16, v104
	v_fmac_f32_e32 v102, v17, v105
	ds_read2st64_b32 v[104:105], v78 offset0:52 offset1:54
	s_waitcnt lgkmcnt(0)
	v_lshlrev_b32_e32 v106, 16, v104
	v_and_b32_e32 v104, 0xffff0000, v104
	v_fmac_f32_e32 v74, v52, v106
	v_fmac_f32_e32 v71, v53, v104
	v_fmac_f32_e32 v72, v50, v106
	v_fmac_f32_e32 v70, v51, v104
	v_fmac_f32_e32 v75, v48, v106
	v_fmac_f32_e32 v73, v49, v104
	v_fmac_f32_e32 v77, v56, v106
	v_fmac_f32_e32 v76, v57, v104
	v_fmac_f32_e32 v80, v40, v106
	v_fmac_f32_e32 v79, v41, v104
	v_fmac_f32_e32 v82, v38, v106
	v_fmac_f32_e32 v81, v39, v104
	v_fmac_f32_e32 v84, v46, v106
	v_fmac_f32_e32 v83, v47, v104
	v_fmac_f32_e32 v86, v44, v106
	v_fmac_f32_e32 v85, v45, v104
	v_fmac_f32_e32 v88, v42, v106
	v_fmac_f32_e32 v87, v43, v104
	v_fmac_f32_e32 v90, v32, v106
	v_fmac_f32_e32 v89, v33, v104
	v_fmac_f32_e32 v92, v30, v106
	v_fmac_f32_e32 v91, v31, v104
	v_fmac_f32_e32 v94, v36, v106
	v_fmac_f32_e32 v93, v37, v104
	v_fmac_f32_e32 v97, v34, v106
	v_fmac_f32_e32 v96, v35, v104
	v_fmac_f32_e32 v99, v24, v106
	v_fmac_f32_e32 v98, v25, v104
	v_fmac_f32_e32 v101, v28, v106
	v_fmac_f32_e32 v100, v29, v104
	v_fmac_f32_e32 v103, v26, v106
	v_fmac_f32_e32 v102, v27, v104
	v_lshlrev_b32_e32 v104, 16, v105
	v_and_b32_e32 v105, 0xffff0000, v105
	v_fmac_f32_e32 v74, v54, v104
	v_fmac_f32_e32 v71, v55, v105
	v_fmac_f32_e32 v72, v52, v104
	v_fmac_f32_e32 v70, v53, v105
	v_fmac_f32_e32 v75, v50, v104
	v_fmac_f32_e32 v73, v51, v105
	v_fmac_f32_e32 v77, v48, v104
	v_fmac_f32_e32 v76, v49, v105
	v_fmac_f32_e32 v80, v56, v104
	v_fmac_f32_e32 v79, v57, v105
	v_fmac_f32_e32 v82, v40, v104
	v_fmac_f32_e32 v81, v41, v105
	v_fmac_f32_e32 v84, v38, v104
	v_fmac_f32_e32 v83, v39, v105
	v_fmac_f32_e32 v86, v46, v104
	v_fmac_f32_e32 v85, v47, v105
	v_fmac_f32_e32 v88, v44, v104
	v_fmac_f32_e32 v87, v45, v105
	v_fmac_f32_e32 v90, v42, v104
	v_fmac_f32_e32 v89, v43, v105
	v_fmac_f32_e32 v92, v32, v104
	v_fmac_f32_e32 v91, v33, v105
	v_fmac_f32_e32 v94, v30, v104
	v_fmac_f32_e32 v93, v31, v105
	v_fmac_f32_e32 v97, v36, v104
	v_fmac_f32_e32 v96, v37, v105
	v_fmac_f32_e32 v99, v34, v104
	v_fmac_f32_e32 v98, v35, v105
	v_fmac_f32_e32 v101, v24, v104
	v_fmac_f32_e32 v100, v25, v105
	v_fmac_f32_e32 v103, v28, v104
	v_fmac_f32_e32 v102, v29, v105
	ds_read2st64_b32 v[104:105], v78 offset0:56 offset1:58
	s_waitcnt lgkmcnt(0)
	v_lshlrev_b32_e32 v106, 16, v104
	v_and_b32_e32 v104, 0xffff0000, v104
	v_fmac_f32_e32 v74, v58, v106
	v_fmac_f32_e32 v71, v59, v104
	v_fmac_f32_e32 v72, v54, v106
	v_fmac_f32_e32 v70, v55, v104
	v_fmac_f32_e32 v75, v52, v106
	v_fmac_f32_e32 v73, v53, v104
	v_fmac_f32_e32 v77, v50, v106
	v_fmac_f32_e32 v76, v51, v104
	v_fmac_f32_e32 v80, v48, v106
	v_fmac_f32_e32 v79, v49, v104
	v_fmac_f32_e32 v82, v56, v106
	v_fmac_f32_e32 v81, v57, v104
	v_fmac_f32_e32 v84, v40, v106
	v_fmac_f32_e32 v83, v41, v104
	v_fmac_f32_e32 v86, v38, v106
	v_fmac_f32_e32 v85, v39, v104
	v_fmac_f32_e32 v88, v46, v106
	v_fmac_f32_e32 v87, v47, v104
	v_fmac_f32_e32 v90, v44, v106
	v_fmac_f32_e32 v89, v45, v104
	v_fmac_f32_e32 v92, v42, v106
	v_fmac_f32_e32 v91, v43, v104
	v_fmac_f32_e32 v94, v32, v106
	v_fmac_f32_e32 v93, v33, v104
	v_fmac_f32_e32 v97, v30, v106
	v_fmac_f32_e32 v96, v31, v104
	v_fmac_f32_e32 v99, v36, v106
	v_fmac_f32_e32 v98, v37, v104
	v_fmac_f32_e32 v101, v34, v106
	v_fmac_f32_e32 v100, v35, v104
	v_fmac_f32_e32 v103, v24, v106
	v_fmac_f32_e32 v102, v25, v104
	v_lshlrev_b32_e32 v104, 16, v105
	v_and_b32_e32 v105, 0xffff0000, v105
	v_fmac_f32_e32 v74, v60, v104
	v_fmac_f32_e32 v71, v61, v105
	v_fmac_f32_e32 v72, v58, v104
	v_fmac_f32_e32 v70, v59, v105
	v_fmac_f32_e32 v75, v54, v104
	v_fmac_f32_e32 v73, v55, v105
	v_fmac_f32_e32 v77, v52, v104
	v_fmac_f32_e32 v76, v53, v105
	v_fmac_f32_e32 v80, v50, v104
	v_fmac_f32_e32 v79, v51, v105
	v_fmac_f32_e32 v82, v48, v104
	v_fmac_f32_e32 v81, v49, v105
	v_fmac_f32_e32 v84, v56, v104
	v_fmac_f32_e32 v83, v57, v105
	v_fmac_f32_e32 v86, v40, v104
	v_fmac_f32_e32 v85, v41, v105
	v_fmac_f32_e32 v88, v38, v104
	v_fmac_f32_e32 v87, v39, v105
	v_fmac_f32_e32 v90, v46, v104
	v_fmac_f32_e32 v89, v47, v105
	v_fmac_f32_e32 v92, v44, v104
	v_fmac_f32_e32 v91, v45, v105
	v_fmac_f32_e32 v94, v42, v104
	v_fmac_f32_e32 v93, v43, v105
	v_fmac_f32_e32 v97, v32, v104
	v_fmac_f32_e32 v96, v33, v105
	v_fmac_f32_e32 v99, v30, v104
	v_fmac_f32_e32 v98, v31, v105
	v_fmac_f32_e32 v101, v36, v104
	v_fmac_f32_e32 v100, v37, v105
	v_fmac_f32_e32 v103, v34, v104
	v_fmac_f32_e32 v102, v35, v105
	ds_read2st64_b32 v[104:105], v78 offset0:60 offset1:62
	s_waitcnt lgkmcnt(0)
; __device__ __forceinline__ void conv_unit(const Args& a, LAS unsigned char* lds, int l, int tt) {
;     ...
;             for (int r = 0; r < 46; ++r) {
;                 const unsigned wv = Yu[(tb + r) * 128 + cp];
;                 const float x0 = bf2f(wv & 0xffffu), x1 = __builtin_bit_cast(float, wv & 0xffff0000u);
; #pragma unroll
;                 for (int t = 0; t < 16; ++t) { const int k = r - t; if (k >= 0 && k <= 30) { a0[t] += w0[k] * x0; a1[t] += w1[k] * x1; } }
	v_lshlrev_b32_e32 v106, 16, v104
	v_and_b32_e32 v104, 0xffff0000, v104
	v_fmac_f32_e32 v71, v63, v104
	v_fmac_f32_e32 v72, v60, v106
	v_fmac_f32_e32 v70, v61, v104
	v_fmac_f32_e32 v75, v58, v106
	v_fmac_f32_e32 v73, v59, v104
	v_fmac_f32_e32 v77, v54, v106
	v_fmac_f32_e32 v76, v55, v104
	v_fmac_f32_e32 v80, v52, v106
	v_fmac_f32_e32 v79, v53, v104
	v_fmac_f32_e32 v82, v50, v106
	v_fmac_f32_e32 v81, v51, v104
	v_fmac_f32_e32 v84, v48, v106
	v_fmac_f32_e32 v83, v49, v104
	v_fmac_f32_e32 v86, v56, v106
	v_fmac_f32_e32 v85, v57, v104
	v_fmac_f32_e32 v88, v40, v106
	v_fmac_f32_e32 v87, v41, v104
	v_fmac_f32_e32 v90, v38, v106
	v_fmac_f32_e32 v89, v39, v104
	v_fmac_f32_e32 v92, v46, v106
	v_fmac_f32_e32 v91, v47, v104
	v_fmac_f32_e32 v94, v44, v106
	v_fmac_f32_e32 v93, v45, v104
	v_fmac_f32_e32 v97, v42, v106
	v_fmac_f32_e32 v96, v43, v104
	v_fmac_f32_e32 v99, v32, v106
	v_fmac_f32_e32 v98, v33, v104
	v_fmac_f32_e32 v101, v30, v106
	v_fmac_f32_e32 v100, v31, v104
	v_fmac_f32_e32 v103, v36, v106
	v_fmac_f32_e32 v102, v37, v104
	v_lshlrev_b32_e32 v104, 16, v105
	v_and_b32_e32 v105, 0xffff0000, v105
	v_fmac_f32_e32 v72, v62, v104
	v_fmac_f32_e32 v70, v63, v105
	v_fmac_f32_e32 v75, v60, v104
	v_fmac_f32_e32 v73, v61, v105
	v_fmac_f32_e32 v77, v58, v104
	v_fmac_f32_e32 v76, v59, v105
	v_fmac_f32_e32 v80, v54, v104
	v_fmac_f32_e32 v79, v55, v105
	v_fmac_f32_e32 v82, v52, v104
	v_fmac_f32_e32 v81, v53, v105
	v_fmac_f32_e32 v84, v50, v104
	v_fmac_f32_e32 v83, v51, v105
	v_fmac_f32_e32 v86, v48, v104
	v_fmac_f32_e32 v85, v49, v105
	v_fmac_f32_e32 v88, v56, v104
	v_fmac_f32_e32 v87, v57, v105
	v_fmac_f32_e32 v90, v40, v104
	v_fmac_f32_e32 v89, v41, v105
	v_fmac_f32_e32 v92, v38, v104
	v_fmac_f32_e32 v91, v39, v105
	v_fmac_f32_e32 v94, v46, v104
	v_fmac_f32_e32 v93, v47, v105
	v_fmac_f32_e32 v97, v44, v104
	v_fmac_f32_e32 v96, v45, v105
	v_fmac_f32_e32 v99, v42, v104
	v_fmac_f32_e32 v98, v43, v105
	v_fmac_f32_e32 v101, v32, v104
	v_fmac_f32_e32 v100, v33, v105
	v_fmac_f32_e32 v103, v30, v104
	v_fmac_f32_e32 v102, v31, v105
	ds_read2st64_b32 v[104:105], v78 offset0:64 offset1:66
	v_fmac_f32_e32 v74, v62, v106
	s_waitcnt lgkmcnt(0)
	v_lshlrev_b32_e32 v106, 16, v104
	v_and_b32_e32 v104, 0xffff0000, v104
	v_fmac_f32_e32 v73, v63, v104
	v_fmac_f32_e32 v77, v60, v106
	v_fmac_f32_e32 v76, v61, v104
	v_fmac_f32_e32 v80, v58, v106
	v_fmac_f32_e32 v79, v59, v104
	v_fmac_f32_e32 v82, v54, v106
	v_fmac_f32_e32 v81, v55, v104
	v_fmac_f32_e32 v84, v52, v106
	v_fmac_f32_e32 v83, v53, v104
	v_fmac_f32_e32 v86, v50, v106
	v_fmac_f32_e32 v85, v51, v104
	v_fmac_f32_e32 v88, v48, v106
	v_fmac_f32_e32 v87, v49, v104
	v_fmac_f32_e32 v90, v56, v106
	v_fmac_f32_e32 v89, v57, v104
	v_fmac_f32_e32 v92, v40, v106
	v_fmac_f32_e32 v91, v41, v104
	v_fmac_f32_e32 v94, v38, v106
	v_fmac_f32_e32 v93, v39, v104
	v_fmac_f32_e32 v97, v46, v106
	v_fmac_f32_e32 v96, v47, v104
	v_fmac_f32_e32 v99, v44, v106
	v_fmac_f32_e32 v98, v45, v104
	v_fmac_f32_e32 v101, v42, v106
	v_fmac_f32_e32 v100, v43, v104
	v_fmac_f32_e32 v103, v32, v106
	v_fmac_f32_e32 v102, v33, v104
	v_lshlrev_b32_e32 v104, 16, v105
	v_and_b32_e32 v105, 0xffff0000, v105
	v_fmac_f32_e32 v77, v62, v104
	v_fmac_f32_e32 v76, v63, v105
	v_fmac_f32_e32 v80, v60, v104
	v_fmac_f32_e32 v79, v61, v105
	v_fmac_f32_e32 v82, v58, v104
	v_fmac_f32_e32 v81, v59, v105
	v_fmac_f32_e32 v84, v54, v104
	v_fmac_f32_e32 v83, v55, v105
	v_fmac_f32_e32 v86, v52, v104
	v_fmac_f32_e32 v85, v53, v105
	v_fmac_f32_e32 v88, v50, v104
	v_fmac_f32_e32 v87, v51, v105
	v_fmac_f32_e32 v90, v48, v104
	v_fmac_f32_e32 v89, v49, v105
	v_fmac_f32_e32 v92, v56, v104
	v_fmac_f32_e32 v91, v57, v105
	v_fmac_f32_e32 v94, v40, v104
	v_fmac_f32_e32 v93, v41, v105
	v_fmac_f32_e32 v97, v38, v104
	v_fmac_f32_e32 v96, v39, v105
	v_fmac_f32_e32 v99, v46, v104
	v_fmac_f32_e32 v98, v47, v105
	v_fmac_f32_e32 v101, v44, v104
	v_fmac_f32_e32 v100, v45, v105
	v_fmac_f32_e32 v103, v42, v104
	v_fmac_f32_e32 v102, v43, v105
	ds_read2st64_b32 v[104:105], v78 offset0:68 offset1:70
	v_fmac_f32_e32 v75, v62, v106
	s_waitcnt lgkmcnt(0)
	v_lshlrev_b32_e32 v106, 16, v104
	v_and_b32_e32 v104, 0xffff0000, v104
	v_fmac_f32_e32 v79, v63, v104
	v_fmac_f32_e32 v82, v60, v106
	v_fmac_f32_e32 v81, v61, v104
	v_fmac_f32_e32 v84, v58, v106
	v_fmac_f32_e32 v83, v59, v104
	v_fmac_f32_e32 v86, v54, v106
	v_fmac_f32_e32 v85, v55, v104
	v_fmac_f32_e32 v88, v52, v106
	v_fmac_f32_e32 v87, v53, v104
	v_fmac_f32_e32 v90, v50, v106
	v_fmac_f32_e32 v89, v51, v104
	v_fmac_f32_e32 v92, v48, v106
	v_fmac_f32_e32 v91, v49, v104
	v_fmac_f32_e32 v94, v56, v106
	v_fmac_f32_e32 v93, v57, v104
	v_fmac_f32_e32 v97, v40, v106
	v_fmac_f32_e32 v96, v41, v104
	v_fmac_f32_e32 v99, v38, v106
	v_fmac_f32_e32 v98, v39, v104
	v_fmac_f32_e32 v101, v46, v106
	v_fmac_f32_e32 v100, v47, v104
	v_fmac_f32_e32 v103, v44, v106
	v_fmac_f32_e32 v102, v45, v104
	v_lshlrev_b32_e32 v104, 16, v105
	v_and_b32_e32 v105, 0xffff0000, v105
	v_fmac_f32_e32 v82, v62, v104
	v_fmac_f32_e32 v81, v63, v105
	v_fmac_f32_e32 v84, v60, v104
	v_fmac_f32_e32 v83, v61, v105
	v_fmac_f32_e32 v86, v58, v104
	v_fmac_f32_e32 v85, v59, v105
	v_fmac_f32_e32 v88, v54, v104
	v_fmac_f32_e32 v87, v55, v105
	v_fmac_f32_e32 v90, v52, v104
	v_fmac_f32_e32 v89, v53, v105
	v_fmac_f32_e32 v92, v50, v104
	v_fmac_f32_e32 v91, v51, v105
	v_fmac_f32_e32 v94, v48, v104
	v_fmac_f32_e32 v93, v49, v105
	v_fmac_f32_e32 v97, v56, v104
	v_fmac_f32_e32 v96, v57, v105
	v_fmac_f32_e32 v99, v40, v104
	v_fmac_f32_e32 v98, v41, v105
	v_fmac_f32_e32 v101, v38, v104
	v_fmac_f32_e32 v100, v39, v105
	v_fmac_f32_e32 v103, v46, v104
	v_fmac_f32_e32 v102, v47, v105
	ds_read2st64_b32 v[104:105], v78 offset0:72 offset1:74
	v_fmac_f32_e32 v80, v62, v106
	s_waitcnt lgkmcnt(0)
; #define LAS __attribute__((address_space(3)))
; __device__ __forceinline__ unsigned pk2(float lo, float hi) { return f2bf(lo) | (f2bf(hi) << 16); }
; __device__ __forceinline__ void conv_unit(const Args& a, LAS unsigned char* lds, int l, int tt) {
;     ...
;             for (int r = 0; r < 46; ++r) {
;                 const unsigned wv = Yu[(tb + r) * 128 + cp];
;                 const float x0 = bf2f(wv & 0xffffu), x1 = __builtin_bit_cast(float, wv & 0xffff0000u);
; #pragma unroll
;                 for (int t = 0; t < 16; ++t) { const int k = r - t; if (k >= 0 && k <= 30) { a0[t] += w0[k] * x0; a1[t] += w1[k] * x1; } }
;             }
; #pragma unroll
;             for (int t = 0; t < 16; ++t) *(LAS unsigned*)(O + (tb + t) * CXS + 2 * cp) = pk2(a0[t], a1[t]);
	v_lshlrev_b32_e32 v106, 16, v104
	v_and_b32_e32 v104, 0xffff0000, v104
	v_fmac_f32_e32 v83, v63, v104
	v_fmac_f32_e32 v86, v60, v106
	v_fmac_f32_e32 v85, v61, v104
	v_fmac_f32_e32 v88, v58, v106
	v_fmac_f32_e32 v87, v59, v104
	v_fmac_f32_e32 v90, v54, v106
	v_fmac_f32_e32 v89, v55, v104
	v_fmac_f32_e32 v92, v52, v106
	v_fmac_f32_e32 v91, v53, v104
	v_fmac_f32_e32 v94, v50, v106
	v_fmac_f32_e32 v93, v51, v104
	v_fmac_f32_e32 v97, v48, v106
	v_fmac_f32_e32 v96, v49, v104
	v_fmac_f32_e32 v99, v56, v106
	v_fmac_f32_e32 v98, v57, v104
	v_fmac_f32_e32 v101, v40, v106
	v_fmac_f32_e32 v100, v41, v104
	v_fmac_f32_e32 v103, v38, v106
	v_fmac_f32_e32 v102, v39, v104
	v_lshlrev_b32_e32 v104, 16, v105
	v_and_b32_e32 v105, 0xffff0000, v105
	v_fmac_f32_e32 v86, v62, v104
	v_fmac_f32_e32 v85, v63, v105
	v_fmac_f32_e32 v88, v60, v104
	v_fmac_f32_e32 v87, v61, v105
	v_fmac_f32_e32 v90, v58, v104
	v_fmac_f32_e32 v89, v59, v105
	v_fmac_f32_e32 v92, v54, v104
	v_fmac_f32_e32 v91, v55, v105
	v_fmac_f32_e32 v94, v52, v104
	v_fmac_f32_e32 v93, v53, v105
	v_fmac_f32_e32 v97, v50, v104
	v_fmac_f32_e32 v96, v51, v105
	v_fmac_f32_e32 v99, v48, v104
	v_fmac_f32_e32 v98, v49, v105
	v_fmac_f32_e32 v101, v56, v104
	v_fmac_f32_e32 v100, v57, v105
	v_fmac_f32_e32 v103, v40, v104
	v_fmac_f32_e32 v102, v41, v105
	ds_read2st64_b32 v[104:105], v78 offset0:76 offset1:78
	v_fmac_f32_e32 v84, v62, v106
	s_waitcnt lgkmcnt(0)
	v_lshlrev_b32_e32 v106, 16, v104
	v_and_b32_e32 v104, 0xffff0000, v104
	v_fmac_f32_e32 v87, v63, v104
	v_fmac_f32_e32 v90, v60, v106
	v_fmac_f32_e32 v89, v61, v104
	v_fmac_f32_e32 v92, v58, v106
	v_fmac_f32_e32 v91, v59, v104
	v_fmac_f32_e32 v94, v54, v106
	v_fmac_f32_e32 v93, v55, v104
	v_fmac_f32_e32 v97, v52, v106
	v_fmac_f32_e32 v96, v53, v104
	v_fmac_f32_e32 v99, v50, v106
	v_fmac_f32_e32 v98, v51, v104
	v_fmac_f32_e32 v101, v48, v106
	v_fmac_f32_e32 v100, v49, v104
	v_fmac_f32_e32 v103, v56, v106
	v_fmac_f32_e32 v102, v57, v104
	v_lshlrev_b32_e32 v104, 16, v105
	v_and_b32_e32 v105, 0xffff0000, v105
	v_fmac_f32_e32 v90, v62, v104
	v_fmac_f32_e32 v89, v63, v105
	v_fmac_f32_e32 v92, v60, v104
	v_fmac_f32_e32 v91, v61, v105
	v_fmac_f32_e32 v94, v58, v104
	v_fmac_f32_e32 v93, v59, v105
	v_fmac_f32_e32 v97, v54, v104
	v_fmac_f32_e32 v96, v55, v105
	v_fmac_f32_e32 v99, v52, v104
	v_fmac_f32_e32 v98, v53, v105
	v_fmac_f32_e32 v101, v50, v104
	v_fmac_f32_e32 v100, v51, v105
	v_fmac_f32_e32 v103, v48, v104
	v_fmac_f32_e32 v102, v49, v105
	ds_read2st64_b32 v[104:105], v78 offset0:80 offset1:82
	v_fmac_f32_e32 v88, v62, v106
	s_waitcnt lgkmcnt(0)
	v_lshlrev_b32_e32 v106, 16, v104
	v_and_b32_e32 v104, 0xffff0000, v104
	v_fmac_f32_e32 v91, v63, v104
	v_fmac_f32_e32 v94, v60, v106
	v_fmac_f32_e32 v93, v61, v104
	v_fmac_f32_e32 v97, v58, v106
	v_fmac_f32_e32 v96, v59, v104
	v_fmac_f32_e32 v99, v54, v106
	v_fmac_f32_e32 v98, v55, v104
	v_fmac_f32_e32 v101, v52, v106
	v_fmac_f32_e32 v100, v53, v104
	v_fmac_f32_e32 v103, v50, v106
	v_fmac_f32_e32 v102, v51, v104
	v_lshlrev_b32_e32 v104, 16, v105
	v_and_b32_e32 v105, 0xffff0000, v105
	v_fmac_f32_e32 v94, v62, v104
	v_fmac_f32_e32 v93, v63, v105
	v_fmac_f32_e32 v97, v60, v104
	v_fmac_f32_e32 v96, v61, v105
	v_fmac_f32_e32 v99, v58, v104
	v_fmac_f32_e32 v98, v59, v105
	v_fmac_f32_e32 v101, v54, v104
	v_fmac_f32_e32 v100, v55, v105
	v_fmac_f32_e32 v103, v52, v104
	v_fmac_f32_e32 v102, v53, v105
	ds_read2st64_b32 v[104:105], v78 offset0:84 offset1:86
	v_fmac_f32_e32 v92, v62, v106
	s_waitcnt lgkmcnt(0)
	v_lshlrev_b32_e32 v106, 16, v104
	v_and_b32_e32 v104, 0xffff0000, v104
	v_fmac_f32_e32 v96, v63, v104
	v_fmac_f32_e32 v99, v60, v106
	v_fmac_f32_e32 v98, v61, v104
	v_fmac_f32_e32 v101, v58, v106
	v_fmac_f32_e32 v100, v59, v104
	v_fmac_f32_e32 v103, v54, v106
	v_fmac_f32_e32 v102, v55, v104
	v_lshlrev_b32_e32 v104, 16, v105
	v_and_b32_e32 v105, 0xffff0000, v105
	v_fmac_f32_e32 v99, v62, v104
	v_fmac_f32_e32 v98, v63, v105
	v_fmac_f32_e32 v101, v60, v104
	v_fmac_f32_e32 v100, v61, v105
	v_fmac_f32_e32 v103, v58, v104
	v_fmac_f32_e32 v102, v59, v105
	ds_read2st64_b32 v[104:105], v78 offset0:88 offset1:90
	v_fmac_f32_e32 v97, v62, v106
	s_waitcnt lgkmcnt(0)
	v_lshlrev_b32_e32 v78, 16, v104
	v_and_b32_e32 v104, 0xffff0000, v104
	v_fmac_f32_e32 v101, v62, v78
	v_fmac_f32_e32 v100, v63, v104
	v_fmac_f32_e32 v103, v60, v78
	v_fmac_f32_e32 v102, v61, v104
	v_lshlrev_b32_e32 v78, 16, v105
	v_and_b32_e32 v104, 0xffff0000, v105
	v_fmac_f32_e32 v102, v63, v104
	v_fmac_f32_e32 v103, v62, v78
	v_bfe_u32 v78, v74, 16, 1
	v_mad_u64_u32 v[104:105], s[4:5], v69, s55, v[66:67]
	v_bfe_u32 v69, v72, 16, 1
	v_add3_u32 v74, v74, v78, s27
	v_bfe_u32 v78, v71, 16, 1
	v_add3_u32 v69, v72, v69, s27
	v_bfe_u32 v72, v70, 16, 1
	v_lshrrev_b32_e32 v74, 16, v74
	v_add3_u32 v71, v71, v78, s27
	v_lshrrev_b32_e32 v69, 16, v69
	v_add3_u32 v70, v70, v72, s27
	v_and_or_b32 v71, v71, s6, v74
	v_and_or_b32 v69, v70, s6, v69
	ds_write2_b32 v104, v71, v69 offset1:132
	v_bfe_u32 v69, v75, 16, 1
	v_add3_u32 v69, v75, v69, s27
	v_bfe_u32 v70, v73, 16, 1
	v_lshrrev_b32_e32 v69, 16, v69
	v_add3_u32 v70, v73, v70, s27
	v_and_or_b32 v69, v70, s6, v69
	v_bfe_u32 v70, v77, 16, 1
	v_add3_u32 v70, v77, v70, s27
	v_bfe_u32 v71, v76, 16, 1
	v_lshrrev_b32_e32 v70, 16, v70
	v_add3_u32 v71, v76, v71, s27
	v_and_or_b32 v70, v71, s6, v70
	v_add_u32_e32 v71, 0x400, v104
	ds_write2_b32 v71, v69, v70 offset0:8 offset1:140
	v_bfe_u32 v69, v80, 16, 1
	v_add3_u32 v69, v80, v69, s27
	v_bfe_u32 v70, v79, 16, 1
	v_lshrrev_b32_e32 v69, 16, v69
	v_add3_u32 v70, v79, v70, s27
	v_and_or_b32 v69, v70, s6, v69
	v_bfe_u32 v70, v82, 16, 1
	v_add3_u32 v70, v82, v70, s27
	v_bfe_u32 v71, v81, 16, 1
; #define LAS __attribute__((address_space(3)))
; __device__ __forceinline__ unsigned pk2(float lo, float hi) { return f2bf(lo) | (f2bf(hi) << 16); }
; __device__ __forceinline__ float sum8sq(const float (&d)[8]) { return (d[0] * d[0] + d[1] * d[1]) + (d[2] * d[2] + d[3] * d[3]) + (d[4] * d[4] + d[5] * d[5]) + (d[6] * d[6] + d[7] * d[7]); }
; __host__ __device__ __forceinline__ unsigned hl_off(unsigned r, unsigned c) { const unsigned st = (r >> 4) * 2u + (c >> 5), ob = (r & 15u) * 64u + (c & 31u) * 2u; return (st * 1024u + (ob ^ (((ob >> 9) & 1u) << 5))) >> 1; }
; __host__ __device__ __forceinline__ unsigned img_off(unsigned row, unsigned col, unsigned KT) { return (((row >> 8) * KT + (col >> 6)) << 14) + (((row >> 7) & 1u) << 13) + hl_off(row & 127u, col & 63u); }
; __device__ __forceinline__ void conv_unit(const Args& a, LAS unsigned char* lds, int l, int tt) {
;     ...
;             for (int t = 0; t < 16; ++t) *(LAS unsigned*)(O + (tb + t) * CXS + 2 * cp) = pk2(a0[t], a1[t]);
;         }
;     }
;     __syncthreads();
;     {
;         const int row = tid >> 2, seg = tid & 3;
;         float v[8][8]; float s = 0.f;
; #pragma unroll
;         for (int j = 0; j < 8; ++j) { unpack8(*(const LAS u32x4*)(O + row * CXS + 64 * seg + 8 * j), v[j]);
; #pragma unroll
;             for (int e = 0; e < 8; ++e) s += v[j][e]; }
;         s += __shfl_xor(s, 1); s += __shfl_xor(s, 2);
;         const float mu = s * (1.0f / 256.0f);
;         float q = 0.f;
; #pragma unroll
;         for (int j = 0; j < 8; ++j) {
; #pragma unroll
;             for (int e = 0; e < 8; ++e) v[j][e] -= mu;
;             q += sum8sq(v[j]); }
;         q += __shfl_xor(q, 1); q += __shfl_xor(q, 2);
;         const float rstd = __builtin_amdgcn_rsqf(q * (1.0f / 256.0f) + EPS);
;         const LAS float* lgp = lnp + 64 * seg; const LAS float* lbp = lnp + 256 + 64 * seg;
;         bf16_t* dst = MIX + img_off((unsigned)(T.rowbase + T.t0 + row), (unsigned)(768 + 64 * seg), 16u);
;         const unsigned rl_ = (unsigned)((T.t0 + row) & 127), h0_ = hl_off(rl_, 0u);
	v_lshrrev_b32_e32 v70, 16, v70
	v_add3_u32 v71, v81, v71, s27
	v_and_or_b32 v70, v71, s6, v70
	v_add_u32_e32 v71, 0x800, v104
	ds_write2_b32 v71, v69, v70 offset0:16 offset1:148
	v_bfe_u32 v69, v84, 16, 1
	v_add3_u32 v69, v84, v69, s27
	v_bfe_u32 v70, v83, 16, 1
	v_lshrrev_b32_e32 v69, 16, v69
	v_add3_u32 v70, v83, v70, s27
	v_and_or_b32 v69, v70, s6, v69
	v_bfe_u32 v70, v86, 16, 1
	v_add3_u32 v70, v86, v70, s27
	v_bfe_u32 v71, v85, 16, 1
	v_lshrrev_b32_e32 v70, 16, v70
	v_add3_u32 v71, v85, v71, s27
	v_and_or_b32 v70, v71, s6, v70
	v_add_u32_e32 v71, 0xc00, v104
	ds_write2_b32 v71, v69, v70 offset0:24 offset1:156
	v_bfe_u32 v69, v88, 16, 1
	v_add3_u32 v69, v88, v69, s27
	v_bfe_u32 v70, v87, 16, 1
	v_lshrrev_b32_e32 v69, 16, v69
	v_add3_u32 v70, v87, v70, s27
	v_and_or_b32 v69, v70, s6, v69
	v_bfe_u32 v70, v90, 16, 1
	v_add3_u32 v70, v90, v70, s27
	v_bfe_u32 v71, v89, 16, 1
	v_lshrrev_b32_e32 v70, 16, v70
	v_add3_u32 v71, v89, v71, s27
	v_and_or_b32 v70, v71, s6, v70
	v_add_u32_e32 v71, 0x1000, v104
	ds_write2_b32 v71, v69, v70 offset0:32 offset1:164
	v_bfe_u32 v69, v92, 16, 1
	v_add3_u32 v69, v92, v69, s27
	v_bfe_u32 v70, v91, 16, 1
	v_lshrrev_b32_e32 v69, 16, v69
	v_add3_u32 v70, v91, v70, s27
	v_and_or_b32 v69, v70, s6, v69
	v_bfe_u32 v70, v94, 16, 1
	v_add3_u32 v70, v94, v70, s27
	v_bfe_u32 v71, v93, 16, 1
	v_lshrrev_b32_e32 v70, 16, v70
	v_add3_u32 v71, v93, v71, s27
	v_and_or_b32 v70, v71, s6, v70
	v_add_u32_e32 v71, 0x1400, v104
	ds_write2_b32 v71, v69, v70 offset0:40 offset1:172
	v_bfe_u32 v69, v97, 16, 1
	v_add3_u32 v69, v97, v69, s27
	v_bfe_u32 v70, v96, 16, 1
	v_lshrrev_b32_e32 v69, 16, v69
	v_add3_u32 v70, v96, v70, s27
	v_and_or_b32 v69, v70, s6, v69
	v_bfe_u32 v70, v99, 16, 1
	v_add3_u32 v70, v99, v70, s27
	v_bfe_u32 v71, v98, 16, 1
	v_lshrrev_b32_e32 v70, 16, v70
	v_add3_u32 v71, v98, v71, s27
	v_and_or_b32 v70, v71, s6, v70
	v_add_u32_e32 v71, 0x1800, v104
	ds_write2_b32 v71, v69, v70 offset0:48 offset1:180
	v_bfe_u32 v69, v101, 16, 1
	v_add3_u32 v69, v101, v69, s27
	v_bfe_u32 v70, v100, 16, 1
	v_lshrrev_b32_e32 v69, 16, v69
	v_add3_u32 v70, v100, v70, s27
	v_and_or_b32 v69, v70, s6, v69
	v_bfe_u32 v70, v103, 16, 1
	v_add3_u32 v70, v103, v70, s27
	v_bfe_u32 v71, v102, 16, 1
	v_lshrrev_b32_e32 v70, 16, v70
	v_add3_u32 v71, v102, v71, s27
	v_and_or_b32 v70, v71, s6, v70
	v_add_u32_e32 v71, 0x1c00, v104
	s_mov_b32 s4, 64
	ds_write2_b32 v71, v69, v70 offset0:56 offset1:188
	s_cbranch_vccnz .LBB0_512
	v_ashrrev_i32_e32 v30, 2, v95
	v_and_b32_e32 v31, 3, v95
	v_mul_lo_u32 v2, v30, s55
	v_lshlrev_b32_e32 v3, 7, v31
	v_readlane_b32 s0, v254, 6
	s_waitcnt lgkmcnt(0)
	s_barrier
	v_add3_u32 v26, s0, v2, v3
	ds_read_b128 v[2:5], v26
	ds_read_b128 v[6:9], v26 offset:16
	ds_read_b128 v[10:13], v26 offset:32
	ds_read_b128 v[14:17], v26 offset:48
	s_add_i32 s38, s38, s39
	s_waitcnt lgkmcnt(3)
	v_lshlrev_b32_e32 v144, 16, v2
	s_waitcnt lgkmcnt(2)
	v_lshlrev_b32_e32 v212, 16, v9
	v_and_b32_e32 v211, 0xffff0000, v9
	v_xor_b32_e32 v9, 1, v227
	v_cmp_lt_i32_e32 vcc, v9, v229
	v_and_b32_e32 v142, 0xffff0000, v2
	v_lshlrev_b32_e32 v145, 16, v3
	v_cndmask_b32_e32 v9, v227, v9, vcc
	v_and_b32_e32 v143, 0xffff0000, v3
	v_lshlrev_b32_e32 v150, 16, v4
	v_and_b32_e32 v148, 0xffff0000, v4
	v_lshlrev_b32_e32 v151, 16, v5
	v_and_b32_e32 v149, 0xffff0000, v5
	ds_read_b128 v[2:5], v26 offset:64
	ds_read_b128 v[18:21], v26 offset:80
	v_lshlrev_b32_e32 v214, 2, v9
	v_xor_b32_e32 v9, 2, v227
	v_cmp_lt_i32_e32 vcc, v9, v229
	s_waitcnt lgkmcnt(2)
	v_lshlrev_b32_e32 v210, 16, v15
	v_and_b32_e32 v100, 0xffff0000, v15
	v_cndmask_b32_e32 v9, v227, v9, vcc
	v_lshlrev_b32_e32 v213, 2, v9
	v_lshl_add_u32 v9, v31, 8, 0
	v_add_u32_e32 v203, 0x24400, v9
	v_add_u32_e32 v202, 0x24800, v9
	v_add_u32_e32 v9, s38, v30
	v_lshlrev_b32_e32 v15, 6, v30
	v_lshlrev_b32_e32 v140, 16, v10
	v_and_b32_e32 v130, 0xffff0000, v10
	v_lshlrev_b32_e32 v141, 16, v11
	v_and_b32_e32 v131, 0xffff0000, v11
	v_lshlrev_b32_e32 v120, 16, v17
	v_and_b32_e32 v116, 0xffff0000, v17
	s_waitcnt lgkmcnt(0)
	v_lshlrev_b32_e32 v208, 16, v21
	v_and_b32_e32 v205, 0xffff0000, v21
	v_lshrrev_b32_e32 v10, 4, v9
	s_mov_b32 s0, 0x3fff0
	v_lshlrev_b32_e32 v9, 6, v9
	v_lshlrev_b32_e32 v11, 5, v30
	v_and_b32_e32 v17, 0x1c00, v15
	v_lshlrev_b32_e32 v21, 1, v30
	v_and_or_b32 v10, v10, s0, v31
	v_and_b32_e32 v9, 0x2000, v9
	v_and_b32_e32 v11, 0x1e0, v11
	v_and_or_b32 v17, v21, 16, v17
	v_lshlrev_b32_e32 v10, 14, v10
	v_or3_b32 v9, v17, v11, v9
	s_mov_b32 s0, 0x30000
	v_or3_b32 v206, v10, v9, s0
	v_and_b32_e32 v9, 0x3c0, v15
	v_lshlrev_b32_e32 v10, 7, v30
	v_and_b32_e32 v11, 32, v95
	v_and_b32_e32 v10, 0x3800, v10
	v_or_b32_e32 v15, v9, v11
	v_or_b32_e32 v17, v15, v10
	v_lshrrev_b32_e32 v200, 1, v17
	v_add_f32_e32 v17, 0, v144
	v_add_f32_e32 v17, v17, v142
	v_add_f32_e32 v17, v17, v145
	v_add_f32_e32 v17, v17, v143
	v_add_f32_e32 v17, v17, v150
	v_add_f32_e32 v17, v17, v148
	v_add_f32_e32 v17, v17, v151
	v_add_f32_e32 v17, v17, v149
	v_lshlrev_b32_e32 v165, 16, v6
	v_lshlrev_b32_e32 v177, 16, v2
	v_and_b32_e32 v181, 0xffff0000, v2
	v_and_b32_e32 v167, 0xffff0000, v6
	v_add_f32_e32 v2, v17, v165
	v_add_f32_e32 v2, v2, v167
	v_lshlrev_b32_e32 v188, 16, v7
	v_and_b32_e32 v189, 0xffff0000, v7
	v_add_f32_e32 v2, v2, v188
	v_lshlrev_b32_e32 v164, 16, v8
	v_add_f32_e32 v2, v2, v189
	v_and_b32_e32 v166, 0xffff0000, v8
	v_add_f32_e32 v2, v2, v164
	v_add_f32_e32 v2, v2, v166
	v_add_f32_e32 v2, v2, v212
	v_or_b32_e32 v215, 16, v15
	v_lshlrev_b32_e32 v176, 16, v4
	v_and_b32_e32 v180, 0xffff0000, v4
	v_add_f32_e32 v4, v2, v211
	v_or_b32_e32 v2, v215, v10
	v_readlane_b32 s0, v253, 18
	v_lshrrev_b32_e32 v2, 1, v2
	v_readlane_b32 s1, v253, 19
; #define LAS __attribute__((address_space(3)))
; __device__ __forceinline__ float sum8sq(const float (&d)[8]) { return (d[0] * d[0] + d[1] * d[1]) + (d[2] * d[2] + d[3] * d[3]) + (d[4] * d[4] + d[5] * d[5]) + (d[6] * d[6] + d[7] * d[7]); }
; __host__ __device__ __forceinline__ unsigned hl_off(unsigned r, unsigned c) { const unsigned st = (r >> 4) * 2u + (c >> 5), ob = (r & 15u) * 64u + (c & 31u) * 2u; return (st * 1024u + (ob ^ (((ob >> 9) & 1u) << 5))) >> 1; }
; __host__ __device__ __forceinline__ unsigned img_off(unsigned row, unsigned col, unsigned KT) { return (((row >> 8) * KT + (col >> 6)) << 14) + (((row >> 7) & 1u) << 13) + hl_off(row & 127u, col & 63u); }
; __device__ __forceinline__ void conv_unit(const Args& a, LAS unsigned char* lds, int l, int tt) {
;     ...
;         const int row = tid >> 2, seg = tid & 3;
;         float v[8][8]; float s = 0.f;
; #pragma unroll
;         for (int j = 0; j < 8; ++j) { unpack8(*(const LAS u32x4*)(O + row * CXS + 64 * seg + 8 * j), v[j]);
; #pragma unroll
;             for (int e = 0; e < 8; ++e) s += v[j][e]; }
;         s += __shfl_xor(s, 1); s += __shfl_xor(s, 2);
;         const float mu = s * (1.0f / 256.0f);
;         float q = 0.f;
; #pragma unroll
;         for (int j = 0; j < 8; ++j) {
; #pragma unroll
;             for (int e = 0; e < 8; ++e) v[j][e] -= mu;
;             q += sum8sq(v[j]); }
;         q += __shfl_xor(q, 1); q += __shfl_xor(q, 2);
;         const float rstd = __builtin_amdgcn_rsqf(q * (1.0f / 256.0f) + EPS);
;         const LAS float* lgp = lnp + 64 * seg; const LAS float* lbp = lnp + 256 + 64 * seg;
;         bf16_t* dst = MIX + img_off((unsigned)(T.rowbase + T.t0 + row), (unsigned)(768 + 64 * seg), 16u);
;         const unsigned rl_ = (unsigned)((T.t0 + row) & 127), h0_ = hl_off(rl_, 0u);
; #pragma unroll
;         for (int j = 0; j < 8; ++j) {
;             const f32x4 g0 = *(const LAS f32x4*)(lgp + 8 * j), g1 = *(const LAS f32x4*)(lgp + 8 * j + 4), b0 = *(const LAS f32x4*)(lbp + 8 * j), b1 = *(const LAS f32x4*)(lbp + 8 * j + 4);
	v_sub_u32_e32 v2, v2, v200
	v_lshlrev_b32_e32 v184, 16, v3
	v_lshl_add_u64 v[96:97], v[206:207], 1, s[0:1]
	v_and_b32_e32 v185, 0xffff0000, v3
	v_ashrrev_i32_e32 v3, 31, v2
	v_lshl_add_u64 v[114:115], v[2:3], 1, v[96:97]
	v_add_f32_e32 v2, v4, v140
	v_add_f32_e32 v2, v2, v130
	v_add_f32_e32 v2, v2, v141
	v_lshlrev_b32_e32 v155, 16, v12
	v_add_f32_e32 v2, v2, v131
	v_and_b32_e32 v157, 0xffff0000, v12
	v_add_f32_e32 v2, v2, v155
	v_lshlrev_b32_e32 v163, 16, v13
	v_add_f32_e32 v2, v2, v157
	v_and_b32_e32 v187, 0xffff0000, v13
	v_add_f32_e32 v2, v2, v163
	v_lshlrev_b32_e32 v154, 16, v14
	v_add_f32_e32 v2, v2, v187
	v_and_b32_e32 v156, 0xffff0000, v14
	v_add_f32_e32 v2, v2, v154
	v_add_f32_e32 v2, v2, v156
	v_add_f32_e32 v2, v2, v210
	v_lshlrev_b32_e32 v162, 16, v16
	v_add_f32_e32 v2, v2, v100
	v_and_b32_e32 v186, 0xffff0000, v16
	v_add_f32_e32 v2, v2, v162
	v_add_f32_e32 v2, v2, v186
	v_add_f32_e32 v2, v2, v120
	v_add_f32_e32 v2, v2, v116
	v_add_f32_e32 v2, v2, v177
	v_add_f32_e32 v2, v2, v181
	v_add_f32_e32 v2, v2, v184
	v_add_f32_e32 v2, v2, v185
	v_add_f32_e32 v2, v2, v176
	v_lshlrev_b32_e32 v174, 16, v5
	v_add_f32_e32 v2, v2, v180
	v_and_b32_e32 v175, 0xffff0000, v5
	v_add_f32_e32 v2, v2, v174
	v_lshlrev_b32_e32 v169, 16, v18
	v_add_f32_e32 v2, v2, v175
	v_and_b32_e32 v171, 0xffff0000, v18
	v_add_f32_e32 v2, v2, v169
	v_lshlrev_b32_e32 v172, 16, v19
	v_add_f32_e32 v2, v2, v171
	v_and_b32_e32 v173, 0xffff0000, v19
	v_add_f32_e32 v2, v2, v172
	v_lshlrev_b32_e32 v168, 16, v20
	v_add_f32_e32 v2, v2, v173
	v_and_b32_e32 v170, 0xffff0000, v20
	v_add_f32_e32 v2, v2, v168
	v_add_f32_e32 v2, v2, v170
	v_add_f32_e32 v2, v2, v208
	v_bitop3_b32 v209, v9, v95, 32 bitop3:0x72
	v_add_f32_e32 v12, v2, v205
	v_or_b32_e32 v2, v209, v10
	v_lshrrev_b32_e32 v2, 1, v2
	v_sub_u32_e32 v2, v2, v200
	ds_read_b128 v[22:25], v26 offset:96
	ds_read_b128 v[76:79], v203
	ds_read_b128 v[26:29], v26 offset:112
	ds_read_b128 v[80:83], v203 offset:16
	ds_read_b128 v[44:47], v203 offset:32
	ds_read_b128 v[30:33], v203 offset:48
	ds_read_b128 v[88:91], v202
	ds_read_b128 v[84:87], v202 offset:16
	ds_read_b128 v[48:51], v202 offset:32
	ds_read_b128 v[34:37], v202 offset:48
	ds_read_b128 v[66:69], v203 offset:64
	ds_read_b128 v[52:55], v203 offset:80
	ds_read_b128 v[70:73], v202 offset:64
	ds_read_b128 v[56:59], v202 offset:80
	v_ashrrev_i32_e32 v3, 31, v2
	ds_read_b128 v[60:63], v203 offset:96
	v_bitop3_b32 v204, v9, v11, 48 bitop3:0x36
	v_lshl_add_u64 v[106:107], v[2:3], 1, v[96:97]
	v_or_b32_e32 v2, v204, v10
	v_lshrrev_b32_e32 v2, 1, v2
	v_sub_u32_e32 v2, v2, v200
	v_ashrrev_i32_e32 v3, 31, v2
	s_waitcnt lgkmcnt(14)
	v_lshlrev_b32_e32 v108, 16, v22
	v_and_b32_e32 v104, 0xffff0000, v22
	v_lshlrev_b32_e32 v109, 16, v23
	v_and_b32_e32 v105, 0xffff0000, v23
	s_waitcnt lgkmcnt(10)
	v_mov_b32_e32 v134, v44
	v_mov_b32_e32 v135, v46
	v_mov_b32_e32 v46, v45
	s_waitcnt lgkmcnt(4)
	v_mov_b32_e32 v124, v66
	v_mov_b32_e32 v125, v68
	v_mov_b32_e32 v68, v67
	ds_read_b128 v[64:67], v202 offset:96
	ds_read_b128 v[38:41], v203 offset:112
	ds_read_b128 v[42:45], v202 offset:112
	s_waitcnt lgkmcnt(3)
	v_mov_b32_e32 v110, v60
	v_mov_b32_e32 v111, v62
	v_mov_b32_e32 v62, v61
	ds_read_b128 v[16:19], v203 offset:128
	v_lshl_add_u64 v[60:61], v[2:3], 1, v[96:97]
	ds_read_b128 v[20:23], v202 offset:128
	ds_read_b128 v[2:5], v203 offset:144
	ds_read_b128 v[6:9], v202 offset:144
	v_mov_b32_e32 v137, v50
	v_mov_b32_e32 v50, v49
	v_mov_b32_e32 v75, v78
	s_waitcnt lgkmcnt(1)
	v_mov_b32_e32 v49, v4
	v_mov_b32_e32 v4, v3
	v_add_f32_e32 v3, v12, v108
	v_add_f32_e32 v3, v3, v104
	v_add_f32_e32 v3, v3, v109
	v_mov_b32_e32 v78, v77
	v_lshlrev_b32_e32 v77, 16, v24
	v_add_f32_e32 v3, v3, v105
	v_and_b32_e32 v159, 0xffff0000, v24
	v_add_f32_e32 v3, v3, v77
	v_lshlrev_b32_e32 v147, 16, v25
	v_add_f32_e32 v3, v3, v159
	v_and_b32_e32 v161, 0xffff0000, v25
	v_add_f32_e32 v3, v3, v147
	v_mov_b32_e32 v74, v76
	v_lshlrev_b32_e32 v76, 16, v26
	v_add_f32_e32 v3, v3, v161
	v_and_b32_e32 v158, 0xffff0000, v26
	v_add_f32_e32 v3, v3, v76
	v_lshlrev_b32_e32 v201, 16, v27
	v_add_f32_e32 v3, v3, v158
	v_and_b32_e32 v98, 0xffff0000, v27
	v_add_f32_e32 v3, v3, v201
	v_lshlrev_b32_e32 v146, 16, v28
	v_add_f32_e32 v3, v3, v98
	v_and_b32_e32 v160, 0xffff0000, v28
	v_add_f32_e32 v3, v3, v146
	v_lshlrev_b32_e32 v138, 16, v29
	v_add_f32_e32 v3, v3, v160
	v_and_b32_e32 v94, 0xffff0000, v29
	v_add_f32_e32 v3, v3, v138
	v_mov_b32_e32 v122, v56
	s_waitcnt lgkmcnt(0)
	v_mov_b32_e32 v56, v6
	v_add_f32_e32 v6, v3, v94
	v_mov_b32_e32 v123, v58
	v_mov_b32_e32 v58, v57
	v_mov_b32_e32 v57, v8
	v_mov_b32_e32 v8, v7
	v_or_b32_e32 v206, 0x400, v10
	ds_bpermute_b32 v7, v214, v6
	v_mov_b32_e32 v136, v48
	v_mov_b32_e32 v48, v2
	v_or_b32_e32 v2, v15, v206
	v_lshrrev_b32_e32 v2, 1, v2
	v_sub_u32_e32 v2, v2, v200
	v_ashrrev_i32_e32 v3, 31, v2
	v_mov_b32_e32 v118, v52
	v_mov_b32_e32 v119, v54
	v_mov_b32_e32 v54, v53
	v_lshl_add_u64 v[52:53], v[2:3], 1, v[96:97]
	s_waitcnt lgkmcnt(0)
	v_add_f32_e32 v2, v6, v7
	ds_bpermute_b32 v3, v213, v2
	v_mov_b32_e32 v92, v88
	v_mov_b32_e32 v93, v90
	v_mov_b32_e32 v90, v89
	v_mov_b32_e32 v88, v80
	s_waitcnt lgkmcnt(0)
; #define LAS __attribute__((address_space(3)))
; __device__ __forceinline__ float sum8sq(const float (&d)[8]) { return (d[0] * d[0] + d[1] * d[1]) + (d[2] * d[2] + d[3] * d[3]) + (d[4] * d[4] + d[5] * d[5]) + (d[6] * d[6] + d[7] * d[7]); }
; __host__ __device__ __forceinline__ unsigned hl_off(unsigned r, unsigned c) { const unsigned st = (r >> 4) * 2u + (c >> 5), ob = (r & 15u) * 64u + (c & 31u) * 2u; return (st * 1024u + (ob ^ (((ob >> 9) & 1u) << 5))) >> 1; }
; __host__ __device__ __forceinline__ unsigned img_off(unsigned row, unsigned col, unsigned KT) { return (((row >> 8) * KT + (col >> 6)) << 14) + (((row >> 7) & 1u) << 13) + hl_off(row & 127u, col & 63u); }
; __device__ __forceinline__ void conv_unit(const Args& a, LAS unsigned char* lds, int l, int tt) {
;     ...
;             for (int e = 0; e < 8; ++e) s += v[j][e]; }
;         s += __shfl_xor(s, 1); s += __shfl_xor(s, 2);
;         const float mu = s * (1.0f / 256.0f);
;         float q = 0.f;
; #pragma unroll
;         for (int j = 0; j < 8; ++j) {
; #pragma unroll
;             for (int e = 0; e < 8; ++e) v[j][e] -= mu;
;             q += sum8sq(v[j]); }
;         q += __shfl_xor(q, 1); q += __shfl_xor(q, 2);
;         const float rstd = __builtin_amdgcn_rsqf(q * (1.0f / 256.0f) + EPS);
;         const LAS float* lgp = lnp + 64 * seg; const LAS float* lbp = lnp + 256 + 64 * seg;
;         bf16_t* dst = MIX + img_off((unsigned)(T.rowbase + T.t0 + row), (unsigned)(768 + 64 * seg), 16u);
;         const unsigned rl_ = (unsigned)((T.t0 + row) & 127), h0_ = hl_off(rl_, 0u);
; #pragma unroll
;         for (int j = 0; j < 8; ++j) {
;             const f32x4 g0 = *(const LAS f32x4*)(lgp + 8 * j), g1 = *(const LAS f32x4*)(lgp + 8 * j + 4), b0 = *(const LAS f32x4*)(lbp + 8 * j), b1 = *(const LAS f32x4*)(lbp + 8 * j + 4);
	v_add_f32_e32 v218, v2, v3
	v_mul_f32_e32 v216, 0x3b800000, v218
	v_mov_b32_e32 v89, v82
	v_mov_b32_e32 v82, v81
	v_pk_add_f32 v[80:81], v[142:143], v[216:217] op_sel_hi:[1,0] neg_lo:[0,1] neg_hi:[0,1]
	v_pk_add_f32 v[194:195], v[148:149], v[216:217] op_sel_hi:[1,0] neg_lo:[0,1] neg_hi:[0,1]
	v_mov_b32_e32 v126, v70
	v_mov_b32_e32 v127, v72
	v_mov_b32_e32 v72, v71
	v_mov_b32_e32 v70, v20
	v_mov_b32_e32 v71, v22
	v_mov_b32_e32 v22, v21
	v_pk_add_f32 v[198:199], v[144:145], v[216:217] op_sel_hi:[1,0] neg_lo:[0,1] neg_hi:[0,1]
	v_pk_add_f32 v[196:197], v[150:151], v[216:217] op_sel_hi:[1,0] neg_lo:[0,1] neg_hi:[0,1]
	v_mov_b32_e32 v20, v194
	v_mov_b32_e32 v21, v80
	v_mov_b32_e32 v6, v196
	v_mov_b32_e32 v7, v198
	v_pk_mul_f32 v[20:21], v[20:21], v[20:21]
	v_pk_add_f32 v[182:183], v[140:141], v[216:217] op_sel_hi:[1,0] neg_lo:[0,1] neg_hi:[0,1]
	v_pk_add_f32 v[178:179], v[130:131], v[216:217] op_sel_hi:[1,0] neg_lo:[0,1] neg_hi:[0,1]
	v_mov_b32_e32 v152, v84
	v_mov_b32_e32 v153, v86
	v_mov_b32_e32 v86, v85
	v_mov_b32_e32 v132, v34
	v_mov_b32_e32 v133, v36
	v_mov_b32_e32 v36, v35
	v_mov_b32_e32 v84, v38
	v_mov_b32_e32 v85, v40
	v_mov_b32_e32 v40, v39
	v_pk_fma_f32 v[6:7], v[6:7], v[6:7], v[20:21]
	v_pk_mul_f32 v[20:21], v[196:197], v[196:197]
	v_pk_mul_f32 v[34:35], v[182:183], v[182:183]
	v_pk_mul_f32 v[38:39], v[178:179], v[178:179]
	v_fmac_f32_e32 v100, 0xbb800000, v218
	v_mov_b32_e32 v121, v21
	v_add_f32_e32 v21, v34, v38
	v_mov_b32_e32 v101, v35
	v_mov_b32_e32 v34, v100
	v_mov_b32_e32 v35, v39
	v_pk_mul_f32 v[34:35], v[100:101], v[34:35]
	v_pk_fma_f32 v[38:39], v[182:183], v[182:183], v[38:39]
	v_fmac_f32_e32 v210, 0xbb800000, v218
	v_mov_b32_e32 v35, v39
	v_pk_add_f32 v[190:191], v[164:165], v[216:217] op_sel_hi:[1,0] neg_lo:[0,1] neg_hi:[0,1]
	v_pk_add_f32 v[164:165], v[156:157], v[216:217] op_sel_hi:[1,0] neg_lo:[0,1] neg_hi:[0,1]
	v_mul_f32_e32 v20, v210, v210
	v_pk_add_f32 v[192:193], v[188:189], v[216:217] op_sel_hi:[1,0] neg_lo:[0,1] neg_hi:[0,1]
	v_pk_add_f32 v[188:189], v[166:167], v[216:217] op_sel_hi:[1,0] neg_lo:[0,1] neg_hi:[0,1]
	v_pk_add_f32 v[166:167], v[154:155], v[216:217] op_sel_hi:[1,0] neg_lo:[0,1] neg_hi:[0,1]
	v_pk_add_f32 v[20:21], v[20:21], v[34:35]
	v_pk_mul_f32 v[34:35], v[164:165], v[164:165]
	v_mov_b32_e32 v2, v199
	v_mov_b32_e32 v3, v81
	v_pk_add_f32 v[150:151], v[186:187], v[216:217] op_sel_hi:[1,0] neg_lo:[0,1] neg_hi:[0,1]
	v_pk_fma_f32 v[34:35], v[166:167], v[166:167], v[34:35]
	v_pk_mul_f32 v[2:3], v[2:3], v[2:3]
	v_pk_add_f32 v[154:155], v[162:163], v[216:217] op_sel_hi:[1,0] neg_lo:[0,1] neg_hi:[0,1]
	v_pk_add_f32 v[20:21], v[34:35], v[20:21]
	v_pk_mul_f32 v[34:35], v[150:151], v[150:151]
	v_pk_mul_f32 v[38:39], v[194:195], v[194:195]
	v_fmac_f32_e32 v211, 0xbb800000, v218
	v_pk_fma_f32 v[34:35], v[154:155], v[154:155], v[34:35]
	v_add_f32_e32 v2, v2, v3
	v_pk_add_f32 v[20:21], v[34:35], v[20:21]
	v_mul_f32_e32 v34, v211, v211
	v_mov_b32_e32 v217, v39
	v_add_f32_e32 v2, v7, v2
	v_pk_add_f32 v[156:157], v[120:121], v[216:217] neg_lo:[0,1] neg_hi:[0,1]
	v_mov_b32_e32 v217, v34
	v_pk_mul_f32 v[34:35], v[192:193], v[192:193]
	v_add_f32_e32 v2, v6, v2
	v_pk_mul_f32 v[6:7], v[188:189], v[188:189]
	v_fmac_f32_e32 v212, 0xbb800000, v218
	v_pk_fma_f32 v[6:7], v[190:191], v[190:191], v[6:7]
	v_pk_fma_f32 v[38:39], v[196:197], v[196:197], v[38:39]
	v_add_f32_e32 v34, v34, v35
	v_mul_f32_e32 v117, v212, v212
	v_pk_add_f32 v[2:3], v[38:39], v[2:3] op_sel_hi:[1,0]
	v_pk_mul_f32 v[38:39], v[156:157], v[156:157]
	v_add_f32_e32 v7, v7, v34
	v_mov_b32_e32 v39, v3
	v_pk_add_f32 v[162:163], v[116:117], v[216:217] neg_lo:[0,1] neg_hi:[0,1]
	v_pk_add_f32 v[2:3], v[116:117], v[216:217]
	v_add_f32_e32 v6, v6, v7
	v_pk_mul_f32 v[34:35], v[162:163], v[162:163]
	v_pk_add_f32 v[2:3], v[2:3], v[6:7] op_sel_hi:[1,0]
	v_fmac_f32_e32 v205, 0xbb800000, v218
	v_mov_b32_e32 v35, v3
	v_pk_add_f32 v[2:3], v[38:39], v[34:35]
	v_pk_add_f32 v[148:149], v[184:185], v[216:217] op_sel_hi:[1,0] neg_lo:[0,1] neg_hi:[0,1]
	v_pk_add_f32 v[144:145], v[176:177], v[216:217] op_sel_hi:[1,0] neg_lo:[0,1] neg_hi:[0,1]
	v_pk_add_f32 v[140:141], v[180:181], v[216:217] op_sel_hi:[1,0] neg_lo:[0,1] neg_hi:[0,1]
	v_pk_add_f32 v[142:143], v[174:175], v[216:217] op_sel_hi:[1,0] neg_lo:[0,1] neg_hi:[0,1]
	v_pk_add_f32 v[130:131], v[172:173], v[216:217] op_sel_hi:[1,0] neg_lo:[0,1] neg_hi:[0,1]
	v_pk_add_f32 v[120:121], v[168:169], v[216:217] op_sel_hi:[1,0] neg_lo:[0,1] neg_hi:[0,1]
	v_pk_add_f32 v[116:117], v[170:171], v[216:217] op_sel_hi:[1,0] neg_lo:[0,1] neg_hi:[0,1]
	v_fmac_f32_e32 v208, 0xbb800000, v218
	v_mul_f32_e32 v217, v205, v205
	v_pk_add_f32 v[186:187], v[20:21], v[2:3]
	v_mul_f32_e32 v2, v149, v149
	v_pk_mul_f32 v[6:7], v[140:141], v[140:141]
	v_mul_f32_e32 v139, v208, v208
	v_pk_add_f32 v[108:109], v[108:109], v[216:217] op_sel_hi:[1,0] neg_lo:[0,1] neg_hi:[0,1]
	v_pk_add_f32 v[104:105], v[104:105], v[216:217] op_sel_hi:[1,0] neg_lo:[0,1] neg_hi:[0,1]
	v_mov_b32_e32 v102, v42
	v_mov_b32_e32 v103, v44
	v_mov_b32_e32 v44, v43
	v_pk_fma_f32 v[2:3], v[148:149], v[148:149], v[2:3] op_sel_hi:[1,1,0]
	v_pk_fma_f32 v[6:7], v[144:145], v[144:145], v[6:7]
	v_pk_mul_f32 v[168:169], v[108:109], v[108:109]
	v_pk_add_f32 v[42:43], v[76:77], v[216:217] op_sel_hi:[1,0] neg_lo:[0,1] neg_hi:[0,1]
	v_fmac_f32_e32 v98, 0xbb800000, v218
	v_pk_add_f32 v[34:35], v[138:139], v[216:217] neg_lo:[0,1] neg_hi:[0,1]
	v_pk_add_f32 v[76:77], v[138:139], v[216:217]
	v_pk_mul_f32 v[138:139], v[104:105], v[104:105]
	v_pk_add_f32 v[2:3], v[6:7], v[2:3] op_sel:[1,0] op_sel_hi:[0,1]
	v_pk_add_f32 v[38:39], v[158:159], v[216:217] op_sel_hi:[1,0] neg_lo:[0,1] neg_hi:[0,1]
	v_mov_b32_e32 v99, v169
	v_mov_b32_e32 v158, v98
	v_mov_b32_e32 v159, v139
	v_pk_add_f32 v[20:21], v[6:7], v[2:3]
	v_pk_add_f32 v[6:7], v[146:147], v[216:217] op_sel_hi:[1,0] neg_lo:[0,1] neg_hi:[0,1]
	v_add_f32_e32 v147, v168, v138
	v_pk_mul_f32 v[158:159], v[98:99], v[158:159]
	v_pk_fma_f32 v[138:139], v[108:109], v[108:109], v[138:139]
	v_fmac_f32_e32 v201, 0xbb800000, v218
	v_mov_b32_e32 v159, v139
	v_mul_f32_e32 v146, v201, v201
	v_mul_f32_e32 v2, v142, v142
	v_pk_add_f32 v[146:147], v[146:147], v[158:159]
	v_pk_mul_f32 v[158:159], v[38:39], v[38:39]
	v_pk_fma_f32 v[174:175], v[142:143], v[142:143], v[2:3] op_sel_hi:[1,1,0]
	v_pk_add_f32 v[2:3], v[160:161], v[216:217] op_sel_hi:[1,0] neg_lo:[0,1] neg_hi:[0,1]
	v_pk_fma_f32 v[158:159], v[42:43], v[42:43], v[158:159]
	v_mov_b32_e32 v128, v30
	v_pk_add_f32 v[146:147], v[158:159], v[146:147]
	v_pk_mul_f32 v[158:159], v[2:3], v[2:3]
	v_mov_b32_e32 v129, v32
	v_mov_b32_e32 v32, v31
	v_mov_b32_e32 v112, v64
	v_mov_b32_e32 v113, v66
	v_mov_b32_e32 v66, v65
	v_mov_b32_e32 v64, v16
	v_mov_b32_e32 v65, v18
	v_mov_b32_e32 v18, v17
	ds_read_b128 v[24:27], v203 offset:160
	ds_read_b128 v[10:13], v203 offset:176
	ds_read_b128 v[28:31], v202 offset:160
	ds_read_b128 v[14:17], v202 offset:176
	v_pk_fma_f32 v[158:159], v[6:7], v[6:7], v[158:159]
	s_waitcnt lgkmcnt(3)
; #define LAS __attribute__((address_space(3)))
; __device__ __forceinline__ u32x4 pack8(const float (&f)[8]) { u32x4 o; o.x = pk2(f[0], f[1]); o.y = pk2(f[2], f[3]); o.z = pk2(f[4], f[5]); o.w = pk2(f[6], f[7]); return o; }
; __host__ __device__ __forceinline__ unsigned hl_off(unsigned r, unsigned c) { const unsigned st = (r >> 4) * 2u + (c >> 5), ob = (r & 15u) * 64u + (c & 31u) * 2u; return (st * 1024u + (ob ^ (((ob >> 9) & 1u) << 5))) >> 1; }
; __host__ __device__ __forceinline__ unsigned img_off(unsigned row, unsigned col, unsigned KT) { return (((row >> 8) * KT + (col >> 6)) << 14) + (((row >> 7) & 1u) << 13) + hl_off(row & 127u, col & 63u); }
; __device__ __forceinline__ float fsig(float x) { return frcp(1.0f + __expf(-x)); }
; __device__ __forceinline__ void conv_unit(const Args& a, LAS unsigned char* lds, int l, int tt) {
;     ...
;         q += __shfl_xor(q, 1); q += __shfl_xor(q, 2);
;         const float rstd = __builtin_amdgcn_rsqf(q * (1.0f / 256.0f) + EPS);
;         const LAS float* lgp = lnp + 64 * seg; const LAS float* lbp = lnp + 256 + 64 * seg;
;         bf16_t* dst = MIX + img_off((unsigned)(T.rowbase + T.t0 + row), (unsigned)(768 + 64 * seg), 16u);
;         const unsigned rl_ = (unsigned)((T.t0 + row) & 127), h0_ = hl_off(rl_, 0u);
; #pragma unroll
;         for (int j = 0; j < 8; ++j) {
;             const f32x4 g0 = *(const LAS f32x4*)(lgp + 8 * j), g1 = *(const LAS f32x4*)(lgp + 8 * j + 4), b0 = *(const LAS f32x4*)(lbp + 8 * j), b1 = *(const LAS f32x4*)(lbp + 8 * j + 4);
;             float y[8];
; #pragma unroll
;             for (int e = 0; e < 4; ++e) { y[e] = v[j][e] * rstd * g0[e] + b0[e]; y[4 + e] = v[j][4 + e] * rstd * g1[e] + b1[e]; }
; #pragma unroll
;             for (int e = 0; e < 8; ++e) y[e] = y[e] * fsig(y[e]);
;             *(u32x4*)(dst + ((int)hl_off(rl_, 8u * j) - (int)h0_)) = pack8(y);
	v_mov_b32_e32 v138, v24
	v_pk_add_f32 v[158:159], v[158:159], v[146:147]
	v_pk_mul_f32 v[146:147], v[130:131], v[130:131]
	v_mov_b32_e32 v217, v20
	v_add_f32_e32 v24, v146, v147
	v_pk_mul_f32 v[146:147], v[116:117], v[116:117]
	v_mov_b32_e32 v95, v175
	v_pk_fma_f32 v[146:147], v[120:121], v[120:121], v[146:147]
	v_pk_add_f32 v[20:21], v[94:95], v[216:217] neg_lo:[0,1] neg_hi:[0,1]
	v_add_f32_e32 v24, v147, v24
	v_add_f32_e32 v24, v146, v24
	v_pk_add_f32 v[94:95], v[174:175], v[216:217]
	v_mov_b32_e32 v139, v26
	v_pk_add_f32 v[76:77], v[76:77], v[24:25] op_sel_hi:[1,0]
	v_mov_b32_e32 v26, v25
	v_pk_add_f32 v[24:25], v[186:187], v[186:187] op_sel_hi:[0,1]
	v_pk_mul_f32 v[160:161], v[34:35], v[34:35]
	s_waitcnt lgkmcnt(1)
	v_mov_b32_e32 v146, v28
	v_mov_b32_e32 v147, v30
	v_mov_b32_e32 v30, v29
	v_pk_add_f32 v[24:25], v[94:95], v[24:25]
	v_pk_mul_f32 v[28:29], v[20:21], v[20:21]
	v_mov_b32_e32 v161, v77
	v_mov_b32_e32 v29, v25
	v_pk_add_f32 v[24:25], v[160:161], v[28:29]
	s_waitcnt lgkmcnt(0)
	v_mov_b32_e32 v28, v14
	v_pk_add_f32 v[24:25], v[158:159], v[24:25]
	v_mov_b32_e32 v29, v16
	v_add_f32_e32 v21, v24, v25
	ds_bpermute_b32 v35, v214, v21
	v_mov_b32_e32 v24, v10
	v_mov_b32_e32 v25, v12
	v_mov_b32_e32 v12, v11
	v_or_b32_e32 v11, v215, v206
	s_waitcnt lgkmcnt(0)
	v_add_f32_e32 v10, v21, v35
	ds_bpermute_b32 v14, v213, v10
	v_lshrrev_b32_e32 v11, 1, v11
	v_mov_b32_e32 v16, v15
	s_waitcnt lgkmcnt(0)
	v_add_f32_e32 v10, v10, v14
	v_fmamk_f32 v10, v10, 0x3b800000, v222
	v_rsq_f32_e32 v10, v10
	v_sub_u32_e32 v14, v11, v200
	v_ashrrev_i32_e32 v15, 31, v14
	v_lshl_add_u64 v[14:15], v[14:15], 1, v[96:97]
	v_pk_mul_f32 v[76:77], v[198:199], v[10:11] op_sel_hi:[1,0]
	v_pk_mul_f32 v[160:161], v[196:197], v[10:11] op_sel_hi:[1,0]
	v_pk_fma_f32 v[158:159], v[74:75], v[76:77], v[92:93]
	v_pk_mul_f32 v[80:81], v[80:81], v[10:11] op_sel_hi:[1,0]
	v_pk_fma_f32 v[152:153], v[88:89], v[160:161], v[152:153]
	v_pk_fma_f32 v[160:161], v[78:79], v[80:81], v[90:91]
	v_pk_mul_f32 v[168:169], v[194:195], v[10:11] op_sel_hi:[1,0]
	v_mul_f32_e32 v11, 0xbfb8aa3b, v158
	v_exp_f32_e32 v11, v11
	v_mul_f32_e32 v21, 0xbfb8aa3b, v160
	v_exp_f32_e32 v21, v21
	v_pk_fma_f32 v[82:83], v[82:83], v[168:169], v[86:87]
	v_add_f32_e32 v11, 1.0, v11
	v_rcp_f32_e32 v86, v11
	v_add_f32_e32 v11, 1.0, v21
	v_mul_f32_e32 v21, 0xbfb8aa3b, v159
	v_exp_f32_e32 v21, v21
	v_mul_f32_e32 v35, 0xbfb8aa3b, v161
	v_exp_f32_e32 v35, v35
	v_rcp_f32_e32 v168, v11
	v_add_f32_e32 v11, 1.0, v21
	v_mul_f32_e32 v21, 0xbfb8aa3b, v152
	v_rcp_f32_e32 v87, v11
	v_add_f32_e32 v11, 1.0, v35
	v_exp_f32_e32 v21, v21
	v_mul_f32_e32 v35, 0xbfb8aa3b, v82
	v_exp_f32_e32 v35, v35
	v_rcp_f32_e32 v169, v11
	v_add_f32_e32 v11, 1.0, v21
	v_mul_f32_e32 v21, 0xbfb8aa3b, v153
	v_rcp_f32_e32 v170, v11
	v_add_f32_e32 v11, 1.0, v35
	v_exp_f32_e32 v21, v21
	v_mul_f32_e32 v35, 0xbfb8aa3b, v83
	v_exp_f32_e32 v35, v35
	v_rcp_f32_e32 v172, v11
	v_add_f32_e32 v11, 1.0, v21
	v_rcp_f32_e32 v171, v11
	v_add_f32_e32 v11, 1.0, v35
	v_rcp_f32_e32 v173, v11
	v_pk_mul_f32 v[86:87], v[158:159], v[86:87]
	v_pk_mul_f32 v[158:159], v[160:161], v[168:169]
	v_pk_mul_f32 v[152:153], v[152:153], v[170:171]
	v_pk_mul_f32 v[82:83], v[82:83], v[172:173]
	v_bfe_u32 v35, v159, 16, 1
	v_bfe_u32 v11, v83, 16, 1
	v_bfe_u32 v21, v82, 16, 1
	v_add3_u32 v21, v82, v21, s27
	v_add3_u32 v11, v83, v11, s27
	v_bfe_u32 v82, v86, 16, 1
	v_bfe_u32 v83, v87, 16, 1
	v_bfe_u32 v99, v158, 16, 1
	v_add3_u32 v83, v87, v83, s27
	v_add3_u32 v82, v86, v82, s27
	v_add3_u32 v99, v158, v99, s27
	v_add3_u32 v35, v159, v35, s27
	v_bfe_u32 v101, v152, 16, 1
	v_bfe_u32 v157, v153, 16, 1
	v_lshrrev_b32_e32 v82, 16, v82
	v_lshrrev_b32_e32 v83, 16, v83
	v_add3_u32 v153, v153, v157, s27
	v_add3_u32 v101, v152, v101, s27
	v_and_or_b32 v159, v35, s6, v83
	v_and_or_b32 v158, v99, s6, v82
	v_pk_mov_b32 v[82:83], v[190:191], v[192:193] op_sel:[1,0]
	v_lshrrev_b32_e32 v86, 16, v101
	v_lshrrev_b32_e32 v87, 16, v153
	v_pk_mul_f32 v[82:83], v[82:83], v[10:11] op_sel_hi:[1,0]
	v_mov_b32_e32 v192, v189
	v_and_or_b32 v161, v11, s6, v87
	v_and_or_b32 v160, v21, s6, v86
	v_pk_fma_f32 v[82:83], v[134:135], v[82:83], v[136:137]
	v_pk_mul_f32 v[86:87], v[192:193], v[10:11] op_sel_hi:[1,0]
	v_mul_f32_e32 v11, 0xbfb8aa3b, v82
	v_pk_fma_f32 v[46:47], v[46:47], v[86:87], v[50:51]
	v_exp_f32_e32 v11, v11
	v_mul_f32_e32 v21, 0xbfb8aa3b, v46
	v_exp_f32_e32 v21, v21
	v_mul_f32_e32 v35, 0xbfb8aa3b, v47
	v_add_f32_e32 v11, 1.0, v11
	v_rcp_f32_e32 v50, v11
	v_add_f32_e32 v11, 1.0, v21
	v_mul_f32_e32 v21, 0xbfb8aa3b, v83
	v_exp_f32_e32 v21, v21
	v_exp_f32_e32 v35, v35
	v_rcp_f32_e32 v86, v11
	v_mov_b32_e32 v191, v212
	v_add_f32_e32 v11, 1.0, v21
	v_rcp_f32_e32 v51, v11
	v_add_f32_e32 v11, 1.0, v35
	v_pk_mul_f32 v[134:135], v[190:191], v[10:11] op_sel_hi:[1,0]
	v_mov_b32_e32 v189, v211
	v_pk_fma_f32 v[128:129], v[128:129], v[134:135], v[132:133]
	v_pk_mul_f32 v[132:133], v[188:189], v[10:11] op_sel_hi:[1,0]
	v_mul_f32_e32 v21, 0xbfb8aa3b, v128
	v_pk_fma_f32 v[32:33], v[32:33], v[132:133], v[36:37]
	v_exp_f32_e32 v21, v21
	v_mul_f32_e32 v35, 0xbfb8aa3b, v32
	v_exp_f32_e32 v35, v35
	v_rcp_f32_e32 v87, v11
	v_add_f32_e32 v11, 1.0, v21
	v_mul_f32_e32 v21, 0xbfb8aa3b, v129
	v_rcp_f32_e32 v36, v11
	v_add_f32_e32 v11, 1.0, v35
	v_exp_f32_e32 v21, v21
	v_mul_f32_e32 v35, 0xbfb8aa3b, v33
	v_exp_f32_e32 v35, v35
	v_rcp_f32_e32 v132, v11
	v_add_f32_e32 v11, 1.0, v21
	v_rcp_f32_e32 v37, v11
	v_add_f32_e32 v11, 1.0, v35
	v_rcp_f32_e32 v133, v11
	v_pk_mul_f32 v[50:51], v[82:83], v[50:51]
	v_pk_mul_f32 v[46:47], v[46:47], v[86:87]
	v_pk_mul_f32 v[36:37], v[128:129], v[36:37]
	v_pk_mul_f32 v[32:33], v[32:33], v[132:133]
; #define LAS __attribute__((address_space(3)))
; __device__ __forceinline__ u32x4 pack8(const float (&f)[8]) { u32x4 o; o.x = pk2(f[0], f[1]); o.y = pk2(f[2], f[3]); o.z = pk2(f[4], f[5]); o.w = pk2(f[6], f[7]); return o; }
; __host__ __device__ __forceinline__ unsigned hl_off(unsigned r, unsigned c) { const unsigned st = (r >> 4) * 2u + (c >> 5), ob = (r & 15u) * 64u + (c & 31u) * 2u; return (st * 1024u + (ob ^ (((ob >> 9) & 1u) << 5))) >> 1; }
; __device__ __forceinline__ float fsig(float x) { return frcp(1.0f + __expf(-x)); }
; __device__ __forceinline__ void conv_unit(const Args& a, LAS unsigned char* lds, int l, int tt) {
;     ...
;         for (int j = 0; j < 8; ++j) {
;             const f32x4 g0 = *(const LAS f32x4*)(lgp + 8 * j), g1 = *(const LAS f32x4*)(lgp + 8 * j + 4), b0 = *(const LAS f32x4*)(lbp + 8 * j), b1 = *(const LAS f32x4*)(lbp + 8 * j + 4);
;             float y[8];
; #pragma unroll
;             for (int e = 0; e < 4; ++e) { y[e] = v[j][e] * rstd * g0[e] + b0[e]; y[4 + e] = v[j][4 + e] * rstd * g1[e] + b1[e]; }
; #pragma unroll
;             for (int e = 0; e < 8; ++e) y[e] = y[e] * fsig(y[e]);
;             *(u32x4*)(dst + ((int)hl_off(rl_, 8u * j) - (int)h0_)) = pack8(y);
	v_bfe_u32 v35, v47, 16, 1
	v_bfe_u32 v11, v33, 16, 1
	v_bfe_u32 v21, v32, 16, 1
	v_bfe_u32 v82, v46, 16, 1
	v_add3_u32 v21, v32, v21, s27
	v_add3_u32 v11, v33, v11, s27
	v_bfe_u32 v32, v50, 16, 1
	v_bfe_u32 v33, v51, 16, 1
	v_add3_u32 v46, v46, v82, s27
	v_add3_u32 v35, v47, v35, s27
	v_bfe_u32 v47, v36, 16, 1
	v_bfe_u32 v82, v37, 16, 1
	v_add3_u32 v33, v51, v33, s27
	v_add3_u32 v32, v50, v32, s27
	v_add3_u32 v37, v37, v82, s27
	v_add3_u32 v36, v36, v47, s27
	v_lshrrev_b32_e32 v32, 16, v32
	v_lshrrev_b32_e32 v33, 16, v33
	v_lshrrev_b32_e32 v36, 16, v36
	v_lshrrev_b32_e32 v37, 16, v37
	v_and_or_b32 v133, v35, s6, v33
	v_and_or_b32 v132, v46, s6, v32
	v_pk_mul_f32 v[32:33], v[182:183], v[10:11] op_sel_hi:[1,0]
	v_and_or_b32 v135, v11, s6, v37
	v_and_or_b32 v134, v21, s6, v36
	v_pk_fma_f32 v[32:33], v[124:125], v[32:33], v[126:127]
	v_pk_mul_f32 v[36:37], v[178:179], v[10:11] op_sel_hi:[1,0]
	v_mul_f32_e32 v11, 0xbfb8aa3b, v32
	v_pk_fma_f32 v[36:37], v[68:69], v[36:37], v[72:73]
	v_exp_f32_e32 v11, v11
	v_mul_f32_e32 v21, 0xbfb8aa3b, v36
	v_exp_f32_e32 v21, v21
	v_mul_f32_e32 v35, 0xbfb8aa3b, v37
	v_add_f32_e32 v11, 1.0, v11
	v_rcp_f32_e32 v46, v11
	v_add_f32_e32 v11, 1.0, v21
	v_mul_f32_e32 v21, 0xbfb8aa3b, v33
	v_exp_f32_e32 v21, v21
	v_exp_f32_e32 v35, v35
	v_rcp_f32_e32 v50, v11
	v_mov_b32_e32 v68, v167
	v_add_f32_e32 v11, 1.0, v21
	v_rcp_f32_e32 v47, v11
	v_add_f32_e32 v11, 1.0, v35
	v_mov_b32_e32 v69, v155
	v_pk_mul_f32 v[68:69], v[68:69], v[10:11] op_sel_hi:[1,0]
	v_mov_b32_e32 v72, v165
	v_mov_b32_e32 v73, v151
	v_pk_fma_f32 v[68:69], v[118:119], v[68:69], v[122:123]
	v_pk_mul_f32 v[72:73], v[72:73], v[10:11] op_sel_hi:[1,0]
	v_mul_f32_e32 v21, 0xbfb8aa3b, v68
	v_pk_fma_f32 v[54:55], v[54:55], v[72:73], v[58:59]
	v_exp_f32_e32 v21, v21
	v_mul_f32_e32 v35, 0xbfb8aa3b, v54
	v_exp_f32_e32 v35, v35
	v_rcp_f32_e32 v51, v11
	v_add_f32_e32 v11, 1.0, v21
	v_mul_f32_e32 v21, 0xbfb8aa3b, v69
	v_rcp_f32_e32 v58, v11
	v_add_f32_e32 v11, 1.0, v35
	v_exp_f32_e32 v21, v21
	v_mul_f32_e32 v35, 0xbfb8aa3b, v55
	v_exp_f32_e32 v35, v35
	v_rcp_f32_e32 v72, v11
	v_add_f32_e32 v11, 1.0, v21
	v_rcp_f32_e32 v59, v11
	v_add_f32_e32 v11, 1.0, v35
	v_rcp_f32_e32 v73, v11
	v_pk_mul_f32 v[36:37], v[36:37], v[50:51]
	v_pk_mul_f32 v[32:33], v[32:33], v[46:47]
	v_bfe_u32 v35, v37, 16, 1
	v_pk_mul_f32 v[50:51], v[54:55], v[72:73]
	v_pk_mul_f32 v[46:47], v[68:69], v[58:59]
	v_bfe_u32 v21, v50, 16, 1
	v_bfe_u32 v11, v51, 16, 1
	v_add3_u32 v35, v37, v35, s27
	v_add3_u32 v21, v50, v21, s27
	v_bfe_u32 v37, v32, 16, 1
	v_bfe_u32 v50, v33, 16, 1
	v_bfe_u32 v54, v36, 16, 1
	v_add3_u32 v11, v51, v11, s27
	v_bfe_u32 v51, v46, 16, 1
	v_add3_u32 v33, v33, v50, s27
	v_add3_u32 v32, v32, v37, s27
	v_add3_u32 v36, v36, v54, s27
	v_bfe_u32 v54, v47, 16, 1
	v_add3_u32 v46, v46, v51, s27
	v_lshrrev_b32_e32 v32, 16, v32
	v_lshrrev_b32_e32 v33, 16, v33
	v_mov_b32_e32 v167, v210
	v_add3_u32 v47, v47, v54, s27
	v_lshrrev_b32_e32 v37, 16, v46
	v_and_or_b32 v123, v35, s6, v33
	v_and_or_b32 v122, v36, s6, v32
	v_pk_mul_f32 v[32:33], v[166:167], v[10:11] op_sel_hi:[1,0]
	v_mov_b32_e32 v165, v100
	v_lshrrev_b32_e32 v46, 16, v47
	v_and_or_b32 v124, v21, s6, v37
	v_pk_fma_f32 v[32:33], v[110:111], v[32:33], v[112:113]
	v_pk_mul_f32 v[36:37], v[164:165], v[10:11] op_sel_hi:[1,0]
	v_and_or_b32 v125, v11, s6, v46
	v_pk_fma_f32 v[36:37], v[62:63], v[36:37], v[66:67]
	v_mul_f32_e32 v11, 0xbfb8aa3b, v32
	v_exp_f32_e32 v11, v11
	v_mul_f32_e32 v21, 0xbfb8aa3b, v36
	v_exp_f32_e32 v21, v21
	v_mul_f32_e32 v35, 0xbfb8aa3b, v37
	v_add_f32_e32 v11, 1.0, v11
	v_rcp_f32_e32 v46, v11
	v_add_f32_e32 v11, 1.0, v21
	v_mul_f32_e32 v21, 0xbfb8aa3b, v33
	v_exp_f32_e32 v21, v21
	v_exp_f32_e32 v35, v35
	v_rcp_f32_e32 v50, v11
	v_mov_b32_e32 v155, v156
	v_add_f32_e32 v11, 1.0, v21
	v_rcp_f32_e32 v47, v11
	v_add_f32_e32 v11, 1.0, v35
	v_pk_mul_f32 v[54:55], v[154:155], v[10:11] op_sel_hi:[1,0]
	v_mov_b32_e32 v151, v162
	v_pk_fma_f32 v[54:55], v[84:85], v[54:55], v[102:103]
	v_pk_mul_f32 v[58:59], v[150:151], v[10:11] op_sel_hi:[1,0]
	v_mul_f32_e32 v21, 0xbfb8aa3b, v54
	v_pk_fma_f32 v[40:41], v[40:41], v[58:59], v[44:45]
	v_exp_f32_e32 v21, v21
	v_mul_f32_e32 v35, 0xbfb8aa3b, v40
	v_exp_f32_e32 v35, v35
	v_rcp_f32_e32 v51, v11
	v_add_f32_e32 v11, 1.0, v21
	v_mul_f32_e32 v21, 0xbfb8aa3b, v55
	v_rcp_f32_e32 v44, v11
	v_add_f32_e32 v11, 1.0, v35
	v_exp_f32_e32 v21, v21
	v_mul_f32_e32 v35, 0xbfb8aa3b, v41
	v_exp_f32_e32 v35, v35
	v_rcp_f32_e32 v58, v11
	v_add_f32_e32 v11, 1.0, v21
	v_rcp_f32_e32 v45, v11
	v_add_f32_e32 v11, 1.0, v35
	v_rcp_f32_e32 v59, v11
	v_pk_mul_f32 v[36:37], v[36:37], v[50:51]
	v_pk_mul_f32 v[32:33], v[32:33], v[46:47]
	v_bfe_u32 v35, v37, 16, 1
	v_pk_mul_f32 v[40:41], v[40:41], v[58:59]
	v_pk_mul_f32 v[44:45], v[54:55], v[44:45]
	v_bfe_u32 v21, v40, 16, 1
	v_bfe_u32 v46, v36, 16, 1
	v_add3_u32 v35, v37, v35, s27
	v_add3_u32 v21, v40, v21, s27
	v_bfe_u32 v37, v32, 16, 1
	v_bfe_u32 v40, v33, 16, 1
	v_bfe_u32 v11, v41, 16, 1
	v_add3_u32 v36, v36, v46, s27
	v_bfe_u32 v46, v45, 16, 1
	v_add3_u32 v33, v33, v40, s27
	v_add3_u32 v32, v32, v37, s27
	v_add3_u32 v11, v41, v11, s27
	v_bfe_u32 v41, v44, 16, 1
	v_add3_u32 v45, v45, v46, s27
	v_lshrrev_b32_e32 v32, 16, v32
	v_lshrrev_b32_e32 v33, 16, v33
	v_add3_u32 v41, v44, v41, s27
	v_lshrrev_b32_e32 v40, 16, v45
	v_and_or_b32 v45, v35, s6, v33
	v_and_or_b32 v44, v36, s6, v32
	v_pk_mov_b32 v[32:33], v[144:145], v[148:149] op_sel:[1,0]
	v_lshrrev_b32_e32 v37, 16, v41
	v_pk_mul_f32 v[32:33], v[32:33], v[10:11] op_sel_hi:[1,0]
	v_mov_b32_e32 v148, v141
	v_and_or_b32 v46, v21, s6, v37
	v_pk_fma_f32 v[32:33], v[64:65], v[32:33], v[70:71]
; #define LAS __attribute__((address_space(3)))
; __device__ __forceinline__ u32x4 pack8(const float (&f)[8]) { u32x4 o; o.x = pk2(f[0], f[1]); o.y = pk2(f[2], f[3]); o.z = pk2(f[4], f[5]); o.w = pk2(f[6], f[7]); return o; }
; __host__ __device__ __forceinline__ unsigned hl_off(unsigned r, unsigned c) { const unsigned st = (r >> 4) * 2u + (c >> 5), ob = (r & 15u) * 64u + (c & 31u) * 2u; return (st * 1024u + (ob ^ (((ob >> 9) & 1u) << 5))) >> 1; }
; __device__ __forceinline__ float fsig(float x) { return frcp(1.0f + __expf(-x)); }
; __device__ __forceinline__ void conv_unit(const Args& a, LAS unsigned char* lds, int l, int tt) {
;     ...
;         for (int j = 0; j < 8; ++j) {
;             const f32x4 g0 = *(const LAS f32x4*)(lgp + 8 * j), g1 = *(const LAS f32x4*)(lgp + 8 * j + 4), b0 = *(const LAS f32x4*)(lbp + 8 * j), b1 = *(const LAS f32x4*)(lbp + 8 * j + 4);
;             float y[8];
; #pragma unroll
;             for (int e = 0; e < 4; ++e) { y[e] = v[j][e] * rstd * g0[e] + b0[e]; y[4 + e] = v[j][4 + e] * rstd * g1[e] + b1[e]; }
; #pragma unroll
;             for (int e = 0; e < 8; ++e) y[e] = y[e] * fsig(y[e]);
;             *(u32x4*)(dst + ((int)hl_off(rl_, 8u * j) - (int)h0_)) = pack8(y);
;         }
;     }
;     __syncthreads();
	v_pk_mul_f32 v[36:37], v[148:149], v[10:11] op_sel_hi:[1,0]
	v_and_or_b32 v47, v11, s6, v40
	v_pk_fma_f32 v[18:19], v[18:19], v[36:37], v[22:23]
	v_mul_f32_e32 v11, 0xbfb8aa3b, v32
	v_exp_f32_e32 v11, v11
	v_mul_f32_e32 v21, 0xbfb8aa3b, v18
	v_exp_f32_e32 v21, v21
	v_mul_f32_e32 v23, 0xbfb8aa3b, v19
	v_add_f32_e32 v11, 1.0, v11
	v_rcp_f32_e32 v22, v11
	v_add_f32_e32 v11, 1.0, v21
	v_mul_f32_e32 v21, 0xbfb8aa3b, v33
	v_exp_f32_e32 v21, v21
	v_exp_f32_e32 v35, v23
	v_rcp_f32_e32 v36, v11
	v_mov_b32_e32 v141, v143
	v_add_f32_e32 v11, 1.0, v21
	v_rcp_f32_e32 v23, v11
	v_add_f32_e32 v11, 1.0, v35
	ds_read_b128 v[92:95], v203 offset:192
	ds_read_b128 v[74:77], v203 offset:208
	ds_read_b128 v[88:91], v202 offset:192
	ds_read_b128 v[78:81], v202 offset:208
	global_store_dwordx4 v[96:97], v[158:161], off sc0 sc1
	global_store_dwordx4 v[114:115], v[132:135], off sc0 sc1
	global_store_dwordx4 v[106:107], v[122:125], off sc0 sc1
	global_store_dwordx4 v[60:61], v[44:47], off sc0 sc1
	v_mov_b32_e32 v145, v142
	v_pk_mul_f32 v[40:41], v[144:145], v[10:11] op_sel_hi:[1,0]
	v_pk_mul_f32 v[44:45], v[140:141], v[10:11] op_sel_hi:[1,0]
	v_pk_fma_f32 v[40:41], v[48:49], v[40:41], v[56:57]
	v_pk_fma_f32 v[4:5], v[4:5], v[44:45], v[8:9]
	v_mul_f32_e32 v8, 0xbfb8aa3b, v40
	v_mul_f32_e32 v9, 0xbfb8aa3b, v4
	v_exp_f32_e32 v9, v9
	v_rcp_f32_e32 v37, v11
	v_mul_f32_e32 v11, 0xbfb8aa3b, v41
	v_mul_f32_e32 v21, 0xbfb8aa3b, v5
	v_exp_f32_e32 v8, v8
	v_exp_f32_e32 v11, v11
	v_exp_f32_e32 v21, v21
	v_add_f32_e32 v9, 1.0, v9
	v_add_f32_e32 v8, 1.0, v8
	v_rcp_f32_e32 v44, v9
	v_add_f32_e32 v9, 1.0, v11
	v_add_f32_e32 v11, 1.0, v21
	v_rcp_f32_e32 v8, v8
	v_rcp_f32_e32 v9, v9
	v_rcp_f32_e32 v45, v11
	v_pk_mul_f32 v[18:19], v[18:19], v[36:37]
	v_pk_mul_f32 v[22:23], v[32:33], v[22:23]
	v_pk_mul_f32 v[8:9], v[40:41], v[8:9]
	v_pk_mul_f32 v[4:5], v[4:5], v[44:45]
	v_bfe_u32 v32, v19, 16, 1
	v_bfe_u32 v33, v18, 16, 1
	v_bfe_u32 v11, v5, 16, 1
	v_add3_u32 v18, v18, v33, s27
	v_add3_u32 v19, v19, v32, s27
	v_bfe_u32 v32, v8, 16, 1
	v_bfe_u32 v33, v9, 16, 1
	v_bfe_u32 v21, v4, 16, 1
	v_add3_u32 v5, v5, v11, s27
	v_bfe_u32 v11, v22, 16, 1
	v_add3_u32 v9, v9, v33, s27
	v_add3_u32 v8, v8, v32, s27
	v_add3_u32 v4, v4, v21, s27
	v_add3_u32 v11, v22, v11, s27
	v_lshrrev_b32_e32 v8, 16, v8
	v_lshrrev_b32_e32 v9, 16, v9
	v_lshrrev_b32_e32 v11, 16, v11
	v_and_or_b32 v47, v5, s6, v9
	v_and_or_b32 v46, v4, s6, v8
	v_pk_mov_b32 v[4:5], v[120:121], v[130:131] op_sel:[1,0]
	v_mov_b32_e32 v130, v117
	v_pk_mul_f32 v[4:5], v[4:5], v[10:11] op_sel_hi:[1,0]
	v_bfe_u32 v21, v23, 16, 1
	v_pk_fma_f32 v[4:5], v[138:139], v[4:5], v[146:147]
	v_pk_mul_f32 v[8:9], v[130:131], v[10:11] op_sel_hi:[1,0]
	v_add3_u32 v21, v23, v21, s27
	v_and_or_b32 v44, v18, s6, v11
	v_pk_fma_f32 v[8:9], v[26:27], v[8:9], v[30:31]
	v_mul_f32_e32 v11, 0xbfb8aa3b, v4
	v_lshrrev_b32_e32 v21, 16, v21
	v_exp_f32_e32 v11, v11
	v_mul_f32_e32 v18, 0xbfb8aa3b, v8
	v_and_or_b32 v45, v19, s6, v21
	v_exp_f32_e32 v19, v18
	v_add_f32_e32 v11, 1.0, v11
	v_rcp_f32_e32 v18, v11
	v_mul_f32_e32 v21, 0xbfb8aa3b, v9
	v_add_f32_e32 v11, 1.0, v19
	v_mul_f32_e32 v19, 0xbfb8aa3b, v5
	v_exp_f32_e32 v19, v19
	v_exp_f32_e32 v21, v21
	v_rcp_f32_e32 v22, v11
	v_mov_b32_e32 v121, v208
	v_add_f32_e32 v11, 1.0, v19
	v_rcp_f32_e32 v19, v11
	v_add_f32_e32 v11, 1.0, v21
	v_pk_mul_f32 v[26:27], v[120:121], v[10:11] op_sel_hi:[1,0]
	v_mov_b32_e32 v117, v205
	v_pk_fma_f32 v[24:25], v[24:25], v[26:27], v[28:29]
	v_pk_mul_f32 v[26:27], v[116:117], v[10:11] op_sel_hi:[1,0]
	v_rcp_f32_e32 v23, v11
	v_pk_fma_f32 v[12:13], v[12:13], v[26:27], v[16:17]
	v_mul_f32_e32 v16, 0xbfb8aa3b, v24
	v_exp_f32_e32 v16, v16
	v_mul_f32_e32 v17, 0xbfb8aa3b, v12
	v_exp_f32_e32 v17, v17
	v_mul_f32_e32 v21, 0xbfb8aa3b, v13
	v_add_f32_e32 v11, 1.0, v16
	v_rcp_f32_e32 v16, v11
	v_add_f32_e32 v11, 1.0, v17
	v_mul_f32_e32 v17, 0xbfb8aa3b, v25
	v_exp_f32_e32 v17, v17
	v_exp_f32_e32 v21, v21
	v_rcp_f32_e32 v26, v11
	v_pk_mul_f32 v[8:9], v[8:9], v[22:23]
	v_add_f32_e32 v11, 1.0, v17
	v_rcp_f32_e32 v17, v11
	v_add_f32_e32 v11, 1.0, v21
	v_rcp_f32_e32 v27, v11
	v_pk_mul_f32 v[4:5], v[4:5], v[18:19]
	v_pk_mul_f32 v[16:17], v[24:25], v[16:17]
	v_bfe_u32 v19, v9, 16, 1
	v_pk_mul_f32 v[12:13], v[12:13], v[26:27]
	v_bfe_u32 v21, v8, 16, 1
	v_bfe_u32 v11, v13, 16, 1
	v_bfe_u32 v18, v12, 16, 1
	v_add3_u32 v8, v8, v21, s27
	v_add3_u32 v9, v9, v19, s27
	v_add3_u32 v12, v12, v18, s27
	v_add3_u32 v11, v13, v11, s27
	v_bfe_u32 v13, v4, 16, 1
	v_bfe_u32 v18, v5, 16, 1
	v_bfe_u32 v19, v16, 16, 1
	v_bfe_u32 v21, v17, 16, 1
	v_add3_u32 v17, v17, v21, s27
	v_add3_u32 v16, v16, v19, s27
	v_add3_u32 v5, v5, v18, s27
	v_add3_u32 v4, v4, v13, s27
	v_lshrrev_b32_e32 v4, 16, v4
	v_lshrrev_b32_e32 v5, 16, v5
	v_lshrrev_b32_e32 v13, 16, v16
	v_lshrrev_b32_e32 v16, 16, v17
	v_and_or_b32 v19, v11, s6, v16
	v_and_or_b32 v18, v12, s6, v13
	v_and_or_b32 v17, v9, s6, v5
	v_and_or_b32 v16, v8, s6, v4
	v_pk_mul_f32 v[4:5], v[108:109], v[10:11] op_sel_hi:[1,0]
	s_waitcnt lgkmcnt(3)
	v_mov_b32_e32 v8, v92
	v_mov_b32_e32 v9, v94
	s_waitcnt lgkmcnt(1)
; #define LAS __attribute__((address_space(3)))
; __device__ __forceinline__ u32x4 pack8(const float (&f)[8]) { u32x4 o; o.x = pk2(f[0], f[1]); o.y = pk2(f[2], f[3]); o.z = pk2(f[4], f[5]); o.w = pk2(f[6], f[7]); return o; }
; __host__ __device__ __forceinline__ unsigned hl_off(unsigned r, unsigned c) { const unsigned st = (r >> 4) * 2u + (c >> 5), ob = (r & 15u) * 64u + (c & 31u) * 2u; return (st * 1024u + (ob ^ (((ob >> 9) & 1u) << 5))) >> 1; }
; __device__ __forceinline__ float fsig(float x) { return frcp(1.0f + __expf(-x)); }
; __device__ __forceinline__ void conv_unit(const Args& a, LAS unsigned char* lds, int l, int tt) {
;     ...
;         for (int j = 0; j < 8; ++j) {
;             const f32x4 g0 = *(const LAS f32x4*)(lgp + 8 * j), g1 = *(const LAS f32x4*)(lgp + 8 * j + 4), b0 = *(const LAS f32x4*)(lbp + 8 * j), b1 = *(const LAS f32x4*)(lbp + 8 * j + 4);
;             float y[8];
; #pragma unroll
;             for (int e = 0; e < 4; ++e) { y[e] = v[j][e] * rstd * g0[e] + b0[e]; y[4 + e] = v[j][4 + e] * rstd * g1[e] + b1[e]; }
; #pragma unroll
;             for (int e = 0; e < 8; ++e) y[e] = y[e] * fsig(y[e]);
;             *(u32x4*)(dst + ((int)hl_off(rl_, 8u * j) - (int)h0_)) = pack8(y);
;         }
;     }
;     __syncthreads();
	v_mov_b32_e32 v12, v88
	v_mov_b32_e32 v13, v90
	v_pk_fma_f32 v[4:5], v[8:9], v[4:5], v[12:13]
	v_pk_mul_f32 v[8:9], v[104:105], v[10:11] op_sel_hi:[1,0]
	v_mov_b32_e32 v94, v93
	v_mov_b32_e32 v90, v89
	v_pk_fma_f32 v[8:9], v[94:95], v[8:9], v[90:91]
	v_mul_f32_e32 v11, 0xbfb8aa3b, v4
	v_exp_f32_e32 v11, v11
	v_mul_f32_e32 v12, 0xbfb8aa3b, v8
	v_exp_f32_e32 v13, v12
	global_store_dwordx4 v[52:53], v[44:47], off sc0 sc1
	v_add_f32_e32 v11, 1.0, v11
	v_rcp_f32_e32 v12, v11
	v_add_f32_e32 v11, 1.0, v13
	v_mul_f32_e32 v13, 0xbfb8aa3b, v5
	global_store_dwordx4 v[14:15], v[16:19], off sc0 sc1
	v_exp_f32_e32 v13, v13
	v_mul_f32_e32 v14, 0xbfb8aa3b, v9
	v_exp_f32_e32 v15, v14
	v_rcp_f32_e32 v14, v11
	v_add_f32_e32 v11, 1.0, v13
	v_rcp_f32_e32 v13, v11
	v_add_f32_e32 v11, 1.0, v15
	v_mov_b32_e32 v16, v43
	v_mov_b32_e32 v17, v7
	v_pk_mul_f32 v[16:17], v[16:17], v[10:11] op_sel_hi:[1,0]
	v_mov_b32_e32 v18, v74
	v_mov_b32_e32 v19, v76
	s_waitcnt lgkmcnt(0)
	v_mov_b32_e32 v22, v78
	v_mov_b32_e32 v23, v80
	v_pk_fma_f32 v[16:17], v[18:19], v[16:17], v[22:23]
	v_mov_b32_e32 v18, v39
	v_mov_b32_e32 v19, v3
	v_pk_mul_f32 v[18:19], v[18:19], v[10:11] op_sel_hi:[1,0]
	v_mov_b32_e32 v76, v75
	v_mov_b32_e32 v80, v79
	v_pk_fma_f32 v[18:19], v[76:77], v[18:19], v[80:81]
	v_mul_f32_e32 v3, 0xbfb8aa3b, v16
	v_exp_f32_e32 v3, v3
	v_mul_f32_e32 v7, 0xbfb8aa3b, v18
	v_exp_f32_e32 v7, v7
	v_rcp_f32_e32 v15, v11
	v_add_f32_e32 v3, 1.0, v3
	v_rcp_f32_e32 v22, v3
	v_add_f32_e32 v3, 1.0, v7
	v_mul_f32_e32 v7, 0xbfb8aa3b, v17
	v_exp_f32_e32 v7, v7
	v_mul_f32_e32 v11, 0xbfb8aa3b, v19
	v_exp_f32_e32 v11, v11
	v_rcp_f32_e32 v24, v3
	v_add_f32_e32 v3, 1.0, v7
	v_rcp_f32_e32 v23, v3
	v_add_f32_e32 v3, 1.0, v11
	v_rcp_f32_e32 v25, v3
	v_pk_mul_f32 v[8:9], v[8:9], v[14:15]
	v_pk_mul_f32 v[4:5], v[4:5], v[12:13]
	v_pk_mul_f32 v[12:13], v[16:17], v[22:23]
	v_bfe_u32 v16, v8, 16, 1
	v_pk_mul_f32 v[14:15], v[18:19], v[24:25]
	v_add3_u32 v8, v8, v16, s27
	v_bfe_u32 v16, v13, 16, 1
	v_bfe_u32 v3, v15, 16, 1
	v_bfe_u32 v7, v14, 16, 1
	v_bfe_u32 v11, v9, 16, 1
	v_add3_u32 v13, v13, v16, s27
	ds_read_b128 v[16:19], v203 offset:224
	ds_read_b128 v[22:25], v203 offset:240
	ds_read_b128 v[26:29], v202 offset:224
	ds_read_b128 v[30:33], v202 offset:240
	v_add3_u32 v9, v9, v11, s27
	v_add3_u32 v7, v14, v7, s27
	v_add3_u32 v3, v15, v3, s27
	v_bfe_u32 v11, v4, 16, 1
	v_bfe_u32 v14, v5, 16, 1
	v_bfe_u32 v15, v12, 16, 1
	v_add3_u32 v12, v12, v15, s27
	v_add3_u32 v5, v5, v14, s27
	v_add3_u32 v4, v4, v11, s27
	v_lshrrev_b32_e32 v4, 16, v4
	v_lshrrev_b32_e32 v5, 16, v5
	v_lshrrev_b32_e32 v11, 16, v12
	v_lshrrev_b32_e32 v12, 16, v13
	v_mov_b32_e32 v43, v201
	v_and_or_b32 v15, v3, s6, v12
	v_and_or_b32 v13, v9, s6, v5
	v_and_or_b32 v12, v8, s6, v4
	v_or_b32_e32 v3, v209, v206
	v_pk_mul_f32 v[8:9], v[42:43], v[10:11] op_sel_hi:[1,0]
	s_waitcnt lgkmcnt(3)
	v_mov_b32_e32 v36, v16
	v_mov_b32_e32 v37, v18
	s_waitcnt lgkmcnt(1)
	v_mov_b32_e32 v40, v26
	v_mov_b32_e32 v41, v28
	v_mov_b32_e32 v39, v98
	v_lshrrev_b32_e32 v3, 1, v3
	v_pk_fma_f32 v[8:9], v[36:37], v[8:9], v[40:41]
	v_pk_mul_f32 v[36:37], v[38:39], v[10:11] op_sel_hi:[1,0]
	v_mov_b32_e32 v18, v17
	v_mov_b32_e32 v28, v27
	v_sub_u32_e32 v4, v3, v200
	v_pk_fma_f32 v[16:17], v[18:19], v[36:37], v[28:29]
	v_mul_f32_e32 v3, 0xbfb8aa3b, v8
	v_and_or_b32 v14, v7, s6, v11
	v_exp_f32_e32 v3, v3
	v_mul_f32_e32 v7, 0xbfb8aa3b, v16
	v_exp_f32_e32 v7, v7
	v_ashrrev_i32_e32 v5, 31, v4
	v_lshl_add_u64 v[4:5], v[4:5], 1, v[96:97]
	global_store_dwordx4 v[4:5], v[12:15], off sc0 sc1
	v_add_f32_e32 v3, 1.0, v3
	v_mul_f32_e32 v5, 0xbfb8aa3b, v9
	v_rcp_f32_e32 v4, v3
	v_add_f32_e32 v3, 1.0, v7
	v_exp_f32_e32 v5, v5
	v_mul_f32_e32 v7, 0xbfb8aa3b, v17
	v_exp_f32_e32 v7, v7
	v_rcp_f32_e32 v12, v3
	v_add_f32_e32 v3, 1.0, v5
	v_rcp_f32_e32 v5, v3
	v_add_f32_e32 v11, 1.0, v7
	v_mov_b32_e32 v3, v20
	v_mov_b32_e32 v15, v24
	s_waitcnt lgkmcnt(0)
	v_mov_b32_e32 v19, v32
	v_pk_mul_f32 v[2:3], v[2:3], v[10:11] op_sel_hi:[1,0]
	v_mov_b32_e32 v24, v23
	v_mov_b32_e32 v32, v31
	v_mov_b32_e32 v7, v34
	v_pk_fma_f32 v[2:3], v[24:25], v[2:3], v[32:33]
	v_pk_mul_f32 v[6:7], v[6:7], v[10:11] op_sel_hi:[1,0]
	v_mov_b32_e32 v14, v22
	v_mov_b32_e32 v18, v30
	v_mul_f32_e32 v13, 0xbfb8aa3b, v2
	v_pk_fma_f32 v[6:7], v[14:15], v[6:7], v[18:19]
	v_exp_f32_e32 v14, v13
	v_rcp_f32_e32 v13, v11
	v_mul_f32_e32 v10, 0xbfb8aa3b, v6
	v_exp_f32_e32 v10, v10
	v_add_f32_e32 v11, 1.0, v14
	v_mul_f32_e32 v14, 0xbfb8aa3b, v7
	v_exp_f32_e32 v15, v14
	v_mul_f32_e32 v14, 0xbfb8aa3b, v3
	v_exp_f32_e32 v18, v14
	v_rcp_f32_e32 v14, v11
	v_add_f32_e32 v11, 1.0, v15
	v_add_f32_e32 v10, 1.0, v10
	v_add_f32_e32 v15, 1.0, v18
	v_rcp_f32_e32 v15, v15
	v_rcp_f32_e32 v10, v10
	v_rcp_f32_e32 v11, v11
	v_pk_mul_f32 v[4:5], v[8:9], v[4:5]
	v_pk_mul_f32 v[8:9], v[16:17], v[12:13]
	v_pk_mul_f32 v[2:3], v[2:3], v[14:15]
	v_pk_mul_f32 v[6:7], v[6:7], v[10:11]
	v_bfe_u32 v10, v3, 16, 1
	v_bfe_u32 v12, v9, 16, 1
	v_add3_u32 v9, v9, v12, s27
	v_add3_u32 v3, v3, v10, s27
	v_bfe_u32 v10, v4, 16, 1
	v_bfe_u32 v12, v6, 16, 1
	v_add3_u32 v6, v6, v12, s27
	v_add3_u32 v4, v4, v10, s27
	v_bfe_u32 v11, v2, 16, 1
	v_bfe_u32 v13, v8, 16, 1
	v_lshrrev_b32_e32 v10, 16, v4
	v_lshrrev_b32_e32 v4, 16, v6
	v_or_b32_e32 v6, v204, v206
	v_add3_u32 v8, v8, v13, s27
	v_add3_u32 v2, v2, v11, s27
	v_bfe_u32 v11, v5, 16, 1
	v_bfe_u32 v13, v7, 16, 1
	v_lshrrev_b32_e32 v6, 1, v6
	v_add3_u32 v7, v7, v13, s27
	v_add3_u32 v5, v5, v11, s27
	v_sub_u32_e32 v6, v6, v200
	v_lshrrev_b32_e32 v11, 16, v5
	v_lshrrev_b32_e32 v5, 16, v7
	v_ashrrev_i32_e32 v7, 31, v6
	v_and_or_b32 v5, v3, s6, v5
	v_and_or_b32 v4, v2, s6, v4
	v_and_or_b32 v3, v9, s6, v11
	v_and_or_b32 v2, v8, s6, v10
	v_lshl_add_u64 v[6:7], v[6:7], 1, v[96:97]
	global_store_dwordx4 v[6:7], v[2:5], off sc0 sc1
	s_barrier

; #define LAS __attribute__((address_space(3)))
; __device__ __forceinline__ unsigned f2bf(float f) { unsigned u = __builtin_bit_cast(unsigned, f); return (u + 0x7fffu + ((u >> 16) & 1u)) >> 16; }
; __device__ __forceinline__ float fgelu(float x) { const float u = 0.7978845608028654f * (x + 0.044715f * x * x * x); return 0.5f * x * (2.0f - 2.0f * frcp(__expf(2.0f * u) + 1.0f)); }
; template <int DIR, int MODE>
; __device__ __forceinline__ void lru_pass(const Args& a, const LAS bf16_t* cxb, LAS bf16_t* gyb, const LAS float* carry, const bf16x8 (&Bw)[2][2][2], const float (&prm)[2][3], int l, int tt, float (&hf)[8][2][4]) {
;     ...
;                     const float hv = hl[reg] + cum[reg] * hin;
;                     if (DIR == 0) hf[m][nt][reg] = hv;
;                     else { LAS bf16_t* gp = gyb + (m * 16 + 4 * fq + reg) * CXS + cc[nt];
;                         const float g = bf2f(*gp);
;                         *gp = (bf16_t)f2bf((hf[m][nt][reg] + hv) * fgelu(g)); }
.LBB0_737:
	s_or_b64 exec, exec, s[4:5]
	s_waitcnt lgkmcnt(1)
	v_lshlrev_b32_e32 v6, 1, v53
	v_add3_u32 v6, s38, v50, v6
	v_fmac_f32_e32 v2, v7, v42
	ds_read_u16 v7, v6
	v_fmac_f32_e32 v226, v79, v75
	v_add_f32_e32 v2, v226, v2
	v_fmac_f32_e32 v78, v244, v75
	v_fmac_f32_e32 v3, v12, v42
	s_waitcnt lgkmcnt(0)
	v_lshlrev_b32_e32 v7, 16, v7
	v_mul_f32_e32 v10, 0x3d372713, v7
	v_mul_f32_e32 v10, v10, v7
	v_fma_f32 v10, v10, v7, v7
	v_mul_f32_e32 v10, 0x3f4c422a, v10
	v_add_f32_e32 v10, v10, v10
	v_mul_f32_e32 v10, 0x3fb8aa3b, v10
	v_exp_f32_e32 v10, v10
	v_mul_f32_e32 v7, 0.5, v7
	v_add_f32_e32 v3, v78, v3
	v_fmac_f32_e32 v77, v245, v75
	v_add_f32_e32 v10, 1.0, v10
	v_rcp_f32_e32 v10, v10
	v_fmac_f32_e32 v8, v9, v42
	v_fmac_f32_e32 v76, v237, v75
	v_fmac_f32_e32 v4, v5, v42
	v_fma_f32 v10, v10, -2.0, 2.0
	v_mul_f32_e32 v7, v7, v10
	v_mul_f32_e32 v2, v2, v7
	v_bfe_u32 v7, v2, 16, 1
	v_add3_u32 v2, v2, v7, s27
	ds_write_b16_d16_hi v6, v2
	ds_read_u16 v2, v52 offset:528
	v_mov_b32_e32 v7, v0
	s_mov_b32 s28, 0x3fff0
	v_readlane_b32 s4, v253, 18
	v_readlane_b32 s5, v253, 19
	s_waitcnt lgkmcnt(0)
	v_lshlrev_b32_e32 v2, 16, v2
	v_mul_f32_e32 v6, 0x3d372713, v2
	v_mul_f32_e32 v6, v6, v2
	v_fma_f32 v6, v6, v2, v2
	v_mul_f32_e32 v6, 0x3f4c422a, v6
	v_add_f32_e32 v6, v6, v6
	v_mul_f32_e32 v6, 0x3fb8aa3b, v6
	v_exp_f32_e32 v6, v6
	v_mul_f32_e32 v2, 0.5, v2
	s_movk_i32 s55, 0x210
	v_add_f32_e32 v6, 1.0, v6
	v_rcp_f32_e32 v6, v6
	s_nop 0
	v_fma_f32 v6, v6, -2.0, 2.0
	v_mul_f32_e32 v2, v2, v6
	v_mul_f32_e32 v2, v3, v2
	v_bfe_u32 v3, v2, 16, 1
	v_add3_u32 v2, v2, v3, s27
	ds_write_b16_d16_hi v52, v2 offset:528
	ds_read_u16 v2, v52 offset:1056
	v_add_f32_e32 v3, v77, v8
	s_waitcnt lgkmcnt(0)
	v_lshlrev_b32_e32 v2, 16, v2
	v_mul_f32_e32 v6, 0x3d372713, v2
	v_mul_f32_e32 v6, v6, v2
	v_fma_f32 v6, v6, v2, v2
	v_mul_f32_e32 v6, 0x3f4c422a, v6
	v_add_f32_e32 v6, v6, v6
	v_mul_f32_e32 v6, 0x3fb8aa3b, v6
	v_exp_f32_e32 v6, v6
	v_mul_f32_e32 v2, 0.5, v2
	v_add_f32_e32 v6, 1.0, v6
	v_rcp_f32_e32 v6, v6
	s_nop 0
	v_fma_f32 v6, v6, -2.0, 2.0
	v_mul_f32_e32 v2, v2, v6
	v_mul_f32_e32 v2, v3, v2
	v_bfe_u32 v3, v2, 16, 1
	v_add3_u32 v2, v2, v3, s27
	ds_write_b16_d16_hi v52, v2 offset:1056
	ds_read_u16 v2, v52 offset:1584
	v_add_f32_e32 v3, v76, v4
	s_waitcnt lgkmcnt(0)
	v_lshlrev_b32_e32 v2, 16, v2
	v_mul_f32_e32 v4, 0x3d372713, v2
	v_mul_f32_e32 v4, v4, v2
	v_fma_f32 v4, v4, v2, v2
	v_mul_f32_e32 v4, 0x3f4c422a, v4
	v_add_f32_e32 v4, v4, v4
	v_mul_f32_e32 v4, 0x3fb8aa3b, v4
	v_exp_f32_e32 v4, v4
	v_mul_f32_e32 v2, 0.5, v2
	v_add_f32_e32 v4, 1.0, v4
	v_rcp_f32_e32 v4, v4
	s_nop 0
	v_fma_f32 v4, v4, -2.0, 2.0
	v_mul_f32_e32 v2, v2, v4
	v_mul_f32_e32 v2, v3, v2
	v_bfe_u32 v3, v2, 16, 1
	v_add3_u32 v2, v2, v3, s27
	ds_write_b16_d16_hi v52, v2 offset:1584
	s_waitcnt lgkmcnt(0)
	s_barrier
; #define LAS __attribute__((address_space(3)))
; __host__ __device__ __forceinline__ unsigned img_off(unsigned row, unsigned col, unsigned KT) { return (((row >> 8) * KT + (col >> 6)) << 14) + (((row >> 7) & 1u) << 13) + hl_off(row & 127u, col & 63u); }
; __device__ __forceinline__ int opaque_tid() { int t = threadIdx.x; asm volatile("" : "+v"(t)); return t; }
; __device__ __forceinline__ void flush_tile(const LAS bf16_t* src, bf16_t* MIX, const Tile& T, int col) {
;     const int tid = opaque_tid();
; #pragma unroll
;     for (int it = 0; it < 8; ++it) {
;         const int idx = tid + NTHREADS * it, r = idx >> 5, vec = idx & 31;
;         *(u32x4*)(MIX + img_off((unsigned)(T.rowbase + T.t0 + r), (unsigned)(col + vec * 8), 16u)) = *(const LAS u32x4*)(src + r * CXS + vec * 8);
;     }
; }
	s_nop 0
	v_lshlrev_b32_e32 v2, 3, v7
	v_and_b32_e32 v3, 0xf8, v2
	v_lshl_add_u32 v6, v3, 1, s38
	v_ashrrev_i32_e32 v8, 5, v7
	v_bfe_u32 v10, v2, 6, 2
	v_and_b32_e32 v12, 24, v2
	v_mad_u64_u32 v[2:3], s[0:1], v8, s29, v[6:7]
	v_add_u32_e32 v8, s73, v8
	v_add_u32_e32 v9, s72, v8
	v_lshrrev_b32_e32 v13, 4, v9
	v_lshlrev_b32_e32 v9, 6, v9
	v_and_or_b32 v13, v13, s28, v10
	v_and_b32_e32 v9, 0x2000, v9
	v_bfe_u32 v11, v7, 2, 1
	ds_read_b128 v[2:5], v2
	v_lshl_or_b32 v9, v13, 14, v9
	v_lshrrev_b32_e32 v13, 3, v8
	v_lshlrev_b32_e32 v14, 5, v8
	v_lshlrev_b32_e32 v8, 1, v8
	v_and_or_b32 v13, v13, 14, v11
	v_and_b32_e32 v14, 0x1e0, v14
	v_and_b32_e32 v8, 16, v8
	v_lshlrev_b32_e32 v13, 9, v13
	v_bitop3_b32 v8, v14, v8, v12 bitop3:0x36
	v_or3_b32 v206, v8, v13, v9
	v_lshl_add_u64 v[8:9], v[206:207], 1, s[4:5]
	s_waitcnt lgkmcnt(0)
	global_store_dwordx4 v[8:9], v[2:5], off sc0 sc1
	s_nop 1
	v_add_u32_e32 v2, 0x200, v7
	v_ashrrev_i32_e32 v8, 5, v2
	v_mad_u64_u32 v[2:3], s[0:1], v8, s29, v[6:7]
	v_add_u32_e32 v8, s73, v8
	v_add_u32_e32 v9, s72, v8
	v_lshrrev_b32_e32 v13, 4, v9
	v_lshlrev_b32_e32 v9, 6, v9
	v_and_or_b32 v13, v13, s28, v10
	v_and_b32_e32 v9, 0x2000, v9
	ds_read_b128 v[2:5], v2
	v_lshl_or_b32 v9, v13, 14, v9
	v_lshrrev_b32_e32 v13, 3, v8
	v_lshlrev_b32_e32 v14, 5, v8
	v_lshlrev_b32_e32 v8, 1, v8
	v_and_or_b32 v13, v13, 14, v11
	v_and_b32_e32 v14, 0x1e0, v14
	v_and_b32_e32 v8, 16, v8
	v_lshlrev_b32_e32 v13, 9, v13
	v_bitop3_b32 v8, v14, v8, v12 bitop3:0x36
	v_or3_b32 v206, v8, v13, v9
	v_lshl_add_u64 v[8:9], v[206:207], 1, s[4:5]
	s_waitcnt lgkmcnt(0)
	global_store_dwordx4 v[8:9], v[2:5], off sc0 sc1
	s_nop 1
	v_add_u32_e32 v2, 0x400, v7
	v_ashrrev_i32_e32 v8, 5, v2
	v_mad_u64_u32 v[2:3], s[0:1], v8, s29, v[6:7]
	v_add_u32_e32 v8, s73, v8
	v_add_u32_e32 v9, s72, v8
	v_lshrrev_b32_e32 v13, 4, v9
	v_lshlrev_b32_e32 v9, 6, v9
	v_and_or_b32 v13, v13, s28, v10
	v_and_b32_e32 v9, 0x2000, v9
	ds_read_b128 v[2:5], v2
	v_lshl_or_b32 v9, v13, 14, v9
	v_lshrrev_b32_e32 v13, 3, v8
	v_lshlrev_b32_e32 v14, 5, v8
	v_lshlrev_b32_e32 v8, 1, v8
	v_and_or_b32 v13, v13, 14, v11
	v_and_b32_e32 v14, 0x1e0, v14
	v_and_b32_e32 v8, 16, v8
	v_lshlrev_b32_e32 v13, 9, v13
	v_bitop3_b32 v8, v14, v8, v12 bitop3:0x36
	v_or3_b32 v206, v8, v13, v9
	v_lshl_add_u64 v[8:9], v[206:207], 1, s[4:5]
	s_waitcnt lgkmcnt(0)
	global_store_dwordx4 v[8:9], v[2:5], off sc0 sc1
	s_nop 1
	v_add_u32_e32 v2, 0x600, v7
	v_ashrrev_i32_e32 v8, 5, v2
	v_mad_u64_u32 v[2:3], s[0:1], v8, s29, v[6:7]
	v_add_u32_e32 v8, s73, v8
	v_add_u32_e32 v9, s72, v8
	v_lshrrev_b32_e32 v13, 4, v9
	v_lshlrev_b32_e32 v9, 6, v9
	v_and_or_b32 v13, v13, s28, v10
	v_and_b32_e32 v9, 0x2000, v9
	ds_read_b128 v[2:5], v2
	v_lshl_or_b32 v9, v13, 14, v9
	v_lshrrev_b32_e32 v13, 3, v8
	v_lshlrev_b32_e32 v14, 5, v8
	v_lshlrev_b32_e32 v8, 1, v8
	v_and_or_b32 v13, v13, 14, v11
	v_and_b32_e32 v14, 0x1e0, v14
	v_and_b32_e32 v8, 16, v8
	v_lshlrev_b32_e32 v13, 9, v13
	v_bitop3_b32 v8, v14, v8, v12 bitop3:0x36
	v_or3_b32 v206, v8, v13, v9
	v_lshl_add_u64 v[8:9], v[206:207], 1, s[4:5]
	s_waitcnt lgkmcnt(0)
	global_store_dwordx4 v[8:9], v[2:5], off sc0 sc1
	s_nop 1
	v_add_u32_e32 v2, 0x800, v7
	v_ashrrev_i32_e32 v8, 5, v2
	v_mad_u64_u32 v[2:3], s[0:1], v8, s29, v[6:7]
	v_add_u32_e32 v8, s73, v8
	v_add_u32_e32 v9, s72, v8
	v_lshrrev_b32_e32 v13, 4, v9
	v_lshlrev_b32_e32 v9, 6, v9
	v_and_or_b32 v13, v13, s28, v10
	v_and_b32_e32 v9, 0x2000, v9
	ds_read_b128 v[2:5], v2
	v_lshl_or_b32 v9, v13, 14, v9
	v_lshrrev_b32_e32 v13, 3, v8
	v_lshlrev_b32_e32 v14, 5, v8
	v_lshlrev_b32_e32 v8, 1, v8
	v_and_or_b32 v13, v13, 14, v11
	v_and_b32_e32 v14, 0x1e0, v14
	v_and_b32_e32 v8, 16, v8
	v_lshlrev_b32_e32 v13, 9, v13
	v_bitop3_b32 v8, v14, v8, v12 bitop3:0x36
	v_or3_b32 v206, v8, v13, v9
	v_lshl_add_u64 v[8:9], v[206:207], 1, s[4:5]
	s_waitcnt lgkmcnt(0)
	global_store_dwordx4 v[8:9], v[2:5], off sc0 sc1
	s_nop 1
	v_add_u32_e32 v2, 0xa00, v7
	v_ashrrev_i32_e32 v8, 5, v2
	v_mad_u64_u32 v[2:3], s[0:1], v8, s29, v[6:7]
	v_add_u32_e32 v8, s73, v8
	v_add_u32_e32 v9, s72, v8
	v_lshrrev_b32_e32 v13, 4, v9
	v_lshlrev_b32_e32 v9, 6, v9
	v_and_or_b32 v13, v13, s28, v10
	v_and_b32_e32 v9, 0x2000, v9
	ds_read_b128 v[2:5], v2
	v_lshl_or_b32 v9, v13, 14, v9
	v_lshrrev_b32_e32 v13, 3, v8
	v_lshlrev_b32_e32 v14, 5, v8
	v_lshlrev_b32_e32 v8, 1, v8
	v_and_or_b32 v13, v13, 14, v11
	v_and_b32_e32 v14, 0x1e0, v14
	v_and_b32_e32 v8, 16, v8
	v_lshlrev_b32_e32 v13, 9, v13
	v_bitop3_b32 v8, v14, v8, v12 bitop3:0x36
	v_or3_b32 v206, v8, v13, v9
	v_lshl_add_u64 v[8:9], v[206:207], 1, s[4:5]
	s_waitcnt lgkmcnt(0)
	global_store_dwordx4 v[8:9], v[2:5], off sc0 sc1
	s_nop 1
	v_add_u32_e32 v2, 0xc00, v7
	v_ashrrev_i32_e32 v8, 5, v2
	v_mad_u64_u32 v[2:3], s[0:1], v8, s29, v[6:7]
	v_add_u32_e32 v8, s73, v8
	v_add_u32_e32 v9, s72, v8
	v_lshrrev_b32_e32 v13, 4, v9
	v_lshlrev_b32_e32 v9, 6, v9
	v_and_or_b32 v13, v13, s28, v10
	v_and_b32_e32 v9, 0x2000, v9
	ds_read_b128 v[2:5], v2
	v_lshl_or_b32 v9, v13, 14, v9
	v_lshrrev_b32_e32 v13, 3, v8
	v_lshlrev_b32_e32 v14, 5, v8
	v_lshlrev_b32_e32 v8, 1, v8
	v_and_or_b32 v13, v13, 14, v11
	v_and_b32_e32 v14, 0x1e0, v14
	v_and_b32_e32 v8, 16, v8
	v_lshlrev_b32_e32 v13, 9, v13
	v_bitop3_b32 v8, v14, v8, v12 bitop3:0x36
	v_or3_b32 v206, v8, v13, v9
	v_lshl_add_u64 v[8:9], v[206:207], 1, s[4:5]
	s_waitcnt lgkmcnt(0)
	global_store_dwordx4 v[8:9], v[2:5], off sc0 sc1
	s_nop 1
	v_add_u32_e32 v2, 0xe00, v7
	v_ashrrev_i32_e32 v7, 5, v2
	v_mad_u64_u32 v[2:3], s[0:1], v7, s29, v[6:7]
	v_add_u32_e32 v6, s73, v7
	v_add_u32_e32 v7, s72, v6
	v_lshrrev_b32_e32 v8, 4, v7
	v_lshlrev_b32_e32 v7, 6, v7
	v_and_or_b32 v8, v8, s28, v10
	v_and_b32_e32 v7, 0x2000, v7
	ds_read_b128 v[2:5], v2
	v_lshl_or_b32 v7, v8, 14, v7
	v_lshrrev_b32_e32 v8, 3, v6
	v_lshlrev_b32_e32 v9, 5, v6
	v_lshlrev_b32_e32 v6, 1, v6
	v_and_or_b32 v8, v8, 14, v11
	v_and_b32_e32 v9, 0x1e0, v9
	v_and_b32_e32 v6, 16, v6
	v_lshlrev_b32_e32 v8, 9, v8
	v_bitop3_b32 v6, v9, v6, v12 bitop3:0x36
	v_or3_b32 v206, v6, v8, v7
	v_lshl_add_u64 v[6:7], v[206:207], 1, s[4:5]
	s_waitcnt lgkmcnt(0)
	global_store_dwordx4 v[6:7], v[2:5], off sc0 sc1
	s_barrier

; __device__ __forceinline__ void conv_unit(const Args& a, LAS unsigned char* lds, int l, int tt) {
;     ...
;         for (int half = 0; half < 2; ++half) {
;             const int tb = (tg4 + 4 * half) * 16;
;             float a0[16], a1[16];
; #pragma unroll
;             for (int t = 0; t < 16; ++t) { a0[t] = cb[0]; a1[t] = cb[1]; }
; #pragma unroll
;             for (int r = 0; r < 46; ++r) {
;                 const unsigned wv = Yu[(tb + r) * 128 + cp];
;                 const float x0 = bf2f(wv & 0xffffu), x1 = __builtin_bit_cast(float, wv & 0xffff0000u);
; #pragma unroll
;                 for (int t = 0; t < 16; ++t) { const int k = r - t; if (k >= 0 && k <= 30) { a0[t] += w0[k] * x0; a1[t] += w1[k] * x1; } }
.LBB0_764:
	v_add_u32_e32 v69, s4, v67
	v_lshl_add_u32 v78, v69, 9, v68
	ds_read2st64_b32 v[72:73], v78 offset1:2
	ds_read2st64_b32 v[76:77], v78 offset0:4 offset1:6
	ds_read2st64_b32 v[80:81], v78 offset0:8 offset1:10
	ds_read2st64_b32 v[84:85], v78 offset0:12 offset1:14
	ds_read2st64_b32 v[88:89], v78 offset0:16 offset1:18
	s_waitcnt lgkmcnt(4)
	v_and_b32_e32 v70, 0xffff0000, v72
	v_lshlrev_b32_e32 v71, 16, v72
	s_waitcnt vmcnt(0)
	v_fma_f32 v74, v2, v71, v64
	v_fma_f32 v71, v3, v70, v65
	v_lshlrev_b32_e32 v70, 16, v73
	v_and_b32_e32 v73, 0xffff0000, v73
	v_fmac_f32_e32 v74, v4, v70
	v_fmac_f32_e32 v71, v5, v73
	v_fma_f32 v72, v2, v70, v64
	v_fma_f32 v70, v3, v73, v65
	s_waitcnt lgkmcnt(3)
	v_lshlrev_b32_e32 v73, 16, v76
	v_and_b32_e32 v76, 0xffff0000, v76
	v_fmac_f32_e32 v74, v6, v73
	v_fmac_f32_e32 v71, v7, v76
	v_fmac_f32_e32 v72, v4, v73
	v_fmac_f32_e32 v70, v5, v76
	v_fma_f32 v75, v2, v73, v64
	v_fma_f32 v73, v3, v76, v65
	v_lshlrev_b32_e32 v76, 16, v77
	v_and_b32_e32 v79, 0xffff0000, v77
	v_fmac_f32_e32 v74, v8, v76
	v_fmac_f32_e32 v71, v9, v79
	v_fmac_f32_e32 v72, v6, v76
	v_fmac_f32_e32 v70, v7, v79
	v_fmac_f32_e32 v75, v4, v76
	v_fmac_f32_e32 v73, v5, v79
	v_fma_f32 v77, v2, v76, v64
	v_fma_f32 v76, v3, v79, v65
	s_waitcnt lgkmcnt(2)
	v_lshlrev_b32_e32 v79, 16, v80
	v_and_b32_e32 v82, 0xffff0000, v80
	v_fmac_f32_e32 v74, v10, v79
	v_fmac_f32_e32 v71, v11, v82
	v_fmac_f32_e32 v72, v8, v79
	v_fmac_f32_e32 v70, v9, v82
	v_fmac_f32_e32 v75, v6, v79
	v_fmac_f32_e32 v73, v7, v82
	v_fmac_f32_e32 v77, v4, v79
	v_fmac_f32_e32 v76, v5, v82
	v_fma_f32 v80, v2, v79, v64
	v_fma_f32 v79, v3, v82, v65
	v_lshlrev_b32_e32 v82, 16, v81
	v_and_b32_e32 v81, 0xffff0000, v81
	ds_read2st64_b32 v[92:93], v78 offset0:20 offset1:22
	v_fmac_f32_e32 v74, v18, v82
	v_fmac_f32_e32 v71, v19, v81
	v_fmac_f32_e32 v72, v10, v82
	v_fmac_f32_e32 v70, v11, v81
	v_fmac_f32_e32 v75, v8, v82
	v_fmac_f32_e32 v73, v9, v81
	v_fmac_f32_e32 v77, v6, v82
	v_fmac_f32_e32 v76, v7, v81
	v_fmac_f32_e32 v80, v4, v82
	v_fmac_f32_e32 v79, v5, v81
	v_fma_f32 v82, v2, v82, v64
	v_fma_f32 v81, v3, v81, v65
	s_waitcnt lgkmcnt(2)
	v_lshlrev_b32_e32 v83, 16, v84
	v_and_b32_e32 v86, 0xffff0000, v84
	v_fmac_f32_e32 v74, v20, v83
	v_fmac_f32_e32 v71, v21, v86
	v_fmac_f32_e32 v72, v18, v83
	v_fmac_f32_e32 v70, v19, v86
	v_fmac_f32_e32 v75, v10, v83
	v_fmac_f32_e32 v73, v11, v86
	v_fmac_f32_e32 v77, v8, v83
	v_fmac_f32_e32 v76, v9, v86
	v_fmac_f32_e32 v80, v6, v83
	v_fmac_f32_e32 v79, v7, v86
	v_fmac_f32_e32 v82, v4, v83
	v_fmac_f32_e32 v81, v5, v86
	v_fma_f32 v84, v2, v83, v64
	v_fma_f32 v83, v3, v86, v65
	v_lshlrev_b32_e32 v86, 16, v85
	v_and_b32_e32 v85, 0xffff0000, v85
	ds_read2st64_b32 v[98:99], v78 offset0:24 offset1:26
	v_fmac_f32_e32 v74, v22, v86
	v_fmac_f32_e32 v71, v23, v85
	v_fmac_f32_e32 v72, v20, v86
	v_fmac_f32_e32 v70, v21, v85
	v_fmac_f32_e32 v75, v18, v86
	v_fmac_f32_e32 v73, v19, v85
	v_fmac_f32_e32 v77, v10, v86
	v_fmac_f32_e32 v76, v11, v85
	v_fmac_f32_e32 v80, v8, v86
	v_fmac_f32_e32 v79, v9, v85
	v_fmac_f32_e32 v82, v6, v86
	v_fmac_f32_e32 v81, v7, v85
	v_fmac_f32_e32 v84, v4, v86
	v_fmac_f32_e32 v83, v5, v85
	v_fma_f32 v86, v2, v86, v64
	v_fma_f32 v85, v3, v85, v65
	s_waitcnt lgkmcnt(2)
	v_lshlrev_b32_e32 v87, 16, v88
	v_and_b32_e32 v90, 0xffff0000, v88
	v_fmac_f32_e32 v74, v12, v87
	v_fmac_f32_e32 v71, v13, v90
	v_fmac_f32_e32 v72, v22, v87
	v_fmac_f32_e32 v70, v23, v90
	v_fmac_f32_e32 v75, v20, v87
	v_fmac_f32_e32 v73, v21, v90
	v_fmac_f32_e32 v77, v18, v87
	v_fmac_f32_e32 v76, v19, v90
	v_fmac_f32_e32 v80, v10, v87
	v_fmac_f32_e32 v79, v11, v90
	v_fmac_f32_e32 v82, v8, v87
	v_fmac_f32_e32 v81, v9, v90
	v_fmac_f32_e32 v84, v6, v87
	v_fmac_f32_e32 v83, v7, v90
	v_fmac_f32_e32 v86, v4, v87
	v_fmac_f32_e32 v85, v5, v90
	v_fma_f32 v88, v2, v87, v64
	v_fma_f32 v87, v3, v90, v65
	v_lshlrev_b32_e32 v90, 16, v89
	v_and_b32_e32 v89, 0xffff0000, v89
	ds_read2st64_b32 v[102:103], v78 offset0:28 offset1:30
	v_fmac_f32_e32 v74, v14, v90
	v_fmac_f32_e32 v71, v15, v89
	v_fmac_f32_e32 v72, v12, v90
	v_fmac_f32_e32 v70, v13, v89
	v_fmac_f32_e32 v75, v22, v90
	v_fmac_f32_e32 v73, v23, v89
	v_fmac_f32_e32 v77, v20, v90
	v_fmac_f32_e32 v76, v21, v89
	v_fmac_f32_e32 v80, v18, v90
	v_fmac_f32_e32 v79, v19, v89
	v_fmac_f32_e32 v82, v10, v90
	v_fmac_f32_e32 v81, v11, v89
	v_fmac_f32_e32 v84, v8, v90
	v_fmac_f32_e32 v83, v9, v89
	v_fmac_f32_e32 v86, v6, v90
	v_fmac_f32_e32 v85, v7, v89
	v_fmac_f32_e32 v88, v4, v90
	v_fmac_f32_e32 v87, v5, v89
	v_fma_f32 v90, v2, v90, v64
	v_fma_f32 v89, v3, v89, v65
	s_waitcnt lgkmcnt(2)
	v_lshlrev_b32_e32 v91, 16, v92
	v_and_b32_e32 v94, 0xffff0000, v92
	v_fmac_f32_e32 v74, v16, v91
	v_fmac_f32_e32 v71, v17, v94
	v_fmac_f32_e32 v72, v14, v91
	v_fmac_f32_e32 v70, v15, v94
	v_fmac_f32_e32 v75, v12, v91
	v_fmac_f32_e32 v73, v13, v94
	v_fmac_f32_e32 v77, v22, v91
	v_fmac_f32_e32 v76, v23, v94
	v_fmac_f32_e32 v80, v20, v91
	v_fmac_f32_e32 v79, v21, v94
	v_fmac_f32_e32 v82, v18, v91
	v_fmac_f32_e32 v81, v19, v94
	v_fmac_f32_e32 v84, v10, v91
	v_fmac_f32_e32 v83, v11, v94
	v_fmac_f32_e32 v86, v8, v91
	v_fmac_f32_e32 v85, v9, v94
	v_fmac_f32_e32 v88, v6, v91
	v_fmac_f32_e32 v87, v7, v94
	v_fmac_f32_e32 v90, v4, v91
	v_fmac_f32_e32 v89, v5, v94
	v_fma_f32 v92, v2, v91, v64
	v_fma_f32 v91, v3, v94, v65
	v_lshlrev_b32_e32 v94, 16, v93
	v_and_b32_e32 v93, 0xffff0000, v93
	v_fmac_f32_e32 v74, v26, v94
	v_fmac_f32_e32 v71, v27, v93
	v_fmac_f32_e32 v72, v16, v94
	v_fmac_f32_e32 v70, v17, v93
	v_fmac_f32_e32 v75, v14, v94
	v_fmac_f32_e32 v73, v15, v93
	v_fmac_f32_e32 v77, v12, v94
	v_fmac_f32_e32 v76, v13, v93
	v_fmac_f32_e32 v80, v22, v94
	v_fmac_f32_e32 v79, v23, v93
	v_fmac_f32_e32 v82, v20, v94
	v_fmac_f32_e32 v81, v21, v93
	v_fmac_f32_e32 v84, v18, v94
	v_fmac_f32_e32 v83, v19, v93
	v_fmac_f32_e32 v86, v10, v94
	v_fmac_f32_e32 v85, v11, v93
	v_fmac_f32_e32 v88, v8, v94
	v_fmac_f32_e32 v87, v9, v93
	v_fmac_f32_e32 v90, v6, v94
	v_fmac_f32_e32 v89, v7, v93
	v_fmac_f32_e32 v92, v4, v94
	v_fmac_f32_e32 v91, v5, v93
	v_fma_f32 v94, v2, v94, v64
	v_fma_f32 v93, v3, v93, v65
	s_waitcnt lgkmcnt(1)
; __device__ __forceinline__ void conv_unit(const Args& a, LAS unsigned char* lds, int l, int tt) {
;     ...
; #pragma unroll
;             for (int r = 0; r < 46; ++r) {
;                 const unsigned wv = Yu[(tb + r) * 128 + cp];
;                 const float x0 = bf2f(wv & 0xffffu), x1 = __builtin_bit_cast(float, wv & 0xffff0000u);
; #pragma unroll
;                 for (int t = 0; t < 16; ++t) { const int k = r - t; if (k >= 0 && k <= 30) { a0[t] += w0[k] * x0; a1[t] += w1[k] * x1; } }
	v_lshlrev_b32_e32 v96, 16, v98
	v_and_b32_e32 v98, 0xffff0000, v98
	v_fmac_f32_e32 v74, v28, v96
	v_fmac_f32_e32 v71, v29, v98
	v_fmac_f32_e32 v72, v26, v96
	v_fmac_f32_e32 v70, v27, v98
	v_fmac_f32_e32 v75, v16, v96
	v_fmac_f32_e32 v73, v17, v98
	v_fmac_f32_e32 v77, v14, v96
	v_fmac_f32_e32 v76, v15, v98
	v_fmac_f32_e32 v80, v12, v96
	v_fmac_f32_e32 v79, v13, v98
	v_fmac_f32_e32 v82, v22, v96
	v_fmac_f32_e32 v81, v23, v98
	v_fmac_f32_e32 v84, v20, v96
	v_fmac_f32_e32 v83, v21, v98
	v_fmac_f32_e32 v86, v18, v96
	v_fmac_f32_e32 v85, v19, v98
	v_fmac_f32_e32 v88, v10, v96
	v_fmac_f32_e32 v87, v11, v98
	v_fmac_f32_e32 v90, v8, v96
	v_fmac_f32_e32 v89, v9, v98
	v_fmac_f32_e32 v92, v6, v96
	v_fmac_f32_e32 v91, v7, v98
	v_fmac_f32_e32 v94, v4, v96
	v_fmac_f32_e32 v93, v5, v98
	v_fma_f32 v97, v2, v96, v64
	v_fma_f32 v96, v3, v98, v65
	v_lshlrev_b32_e32 v98, 16, v99
	v_and_b32_e32 v100, 0xffff0000, v99
	v_fmac_f32_e32 v74, v24, v98
	v_fmac_f32_e32 v71, v25, v100
	v_fmac_f32_e32 v72, v28, v98
	v_fmac_f32_e32 v70, v29, v100
	v_fmac_f32_e32 v75, v26, v98
	v_fmac_f32_e32 v73, v27, v100
	v_fmac_f32_e32 v77, v16, v98
	v_fmac_f32_e32 v76, v17, v100
	v_fmac_f32_e32 v80, v14, v98
	v_fmac_f32_e32 v79, v15, v100
	v_fmac_f32_e32 v82, v12, v98
	v_fmac_f32_e32 v81, v13, v100
	v_fmac_f32_e32 v84, v22, v98
	v_fmac_f32_e32 v83, v23, v100
	v_fmac_f32_e32 v86, v20, v98
	v_fmac_f32_e32 v85, v21, v100
	v_fmac_f32_e32 v88, v18, v98
	v_fmac_f32_e32 v87, v19, v100
	v_fmac_f32_e32 v90, v10, v98
	v_fmac_f32_e32 v89, v11, v100
	v_fmac_f32_e32 v92, v8, v98
	v_fmac_f32_e32 v91, v9, v100
	v_fmac_f32_e32 v94, v6, v98
	v_fmac_f32_e32 v93, v7, v100
	v_fmac_f32_e32 v97, v4, v98
	v_fmac_f32_e32 v96, v5, v100
	v_fma_f32 v99, v2, v98, v64
	v_fma_f32 v98, v3, v100, v65
	s_waitcnt lgkmcnt(0)
	v_lshlrev_b32_e32 v100, 16, v102
	v_and_b32_e32 v102, 0xffff0000, v102
	v_fmac_f32_e32 v74, v34, v100
	v_fmac_f32_e32 v71, v35, v102
	v_fmac_f32_e32 v72, v24, v100
	v_fmac_f32_e32 v70, v25, v102
	v_fmac_f32_e32 v75, v28, v100
	v_fmac_f32_e32 v73, v29, v102
	v_fmac_f32_e32 v77, v26, v100
	v_fmac_f32_e32 v76, v27, v102
	v_fmac_f32_e32 v80, v16, v100
	v_fmac_f32_e32 v79, v17, v102
	v_fmac_f32_e32 v82, v14, v100
	v_fmac_f32_e32 v81, v15, v102
	v_fmac_f32_e32 v84, v12, v100
	v_fmac_f32_e32 v83, v13, v102
	v_fmac_f32_e32 v86, v22, v100
	v_fmac_f32_e32 v85, v23, v102
	v_fmac_f32_e32 v88, v20, v100
	v_fmac_f32_e32 v87, v21, v102
	v_fmac_f32_e32 v90, v18, v100
	v_fmac_f32_e32 v89, v19, v102
	v_fmac_f32_e32 v92, v10, v100
	v_fmac_f32_e32 v91, v11, v102
	v_fmac_f32_e32 v94, v8, v100
	v_fmac_f32_e32 v93, v9, v102
	v_fmac_f32_e32 v97, v6, v100
	v_fmac_f32_e32 v96, v7, v102
	v_fmac_f32_e32 v99, v4, v100
	v_fmac_f32_e32 v98, v5, v102
	v_fma_f32 v101, v2, v100, v64
	v_fma_f32 v100, v3, v102, v65
	v_lshlrev_b32_e32 v102, 16, v103
	v_and_b32_e32 v104, 0xffff0000, v103
	v_fmac_f32_e32 v74, v36, v102
	v_fmac_f32_e32 v71, v37, v104
	v_fmac_f32_e32 v72, v34, v102
	v_fmac_f32_e32 v70, v35, v104
	v_fmac_f32_e32 v75, v24, v102
	v_fmac_f32_e32 v73, v25, v104
	v_fmac_f32_e32 v77, v28, v102
	v_fmac_f32_e32 v76, v29, v104
	v_fmac_f32_e32 v80, v26, v102
	v_fmac_f32_e32 v79, v27, v104
	v_fmac_f32_e32 v82, v16, v102
	v_fmac_f32_e32 v81, v17, v104
	v_fmac_f32_e32 v84, v14, v102
	v_fmac_f32_e32 v83, v15, v104
	v_fmac_f32_e32 v86, v12, v102
	v_fmac_f32_e32 v85, v13, v104
	v_fmac_f32_e32 v88, v22, v102
	v_fmac_f32_e32 v87, v23, v104
	v_fmac_f32_e32 v90, v20, v102
	v_fmac_f32_e32 v89, v21, v104
	v_fmac_f32_e32 v92, v18, v102
	v_fmac_f32_e32 v91, v19, v104
	v_fmac_f32_e32 v94, v10, v102
	v_fmac_f32_e32 v93, v11, v104
	v_fmac_f32_e32 v97, v8, v102
	v_fmac_f32_e32 v96, v9, v104
	v_fmac_f32_e32 v99, v6, v102
	v_fmac_f32_e32 v98, v7, v104
	v_fmac_f32_e32 v101, v4, v102
	v_fmac_f32_e32 v100, v5, v104
	v_fma_f32 v103, v2, v102, v64
	v_fma_f32 v102, v3, v104, v65
	ds_read2st64_b32 v[104:105], v78 offset0:32 offset1:34
	s_and_b64 vcc, exec, s[0:1]
	s_mov_b64 s[0:1], 0
	s_waitcnt lgkmcnt(0)
	v_lshlrev_b32_e32 v106, 16, v104
	v_and_b32_e32 v104, 0xffff0000, v104
	v_fmac_f32_e32 v74, v30, v106
	v_fmac_f32_e32 v71, v31, v104
	v_fmac_f32_e32 v72, v36, v106
	v_fmac_f32_e32 v70, v37, v104
	v_fmac_f32_e32 v75, v34, v106
	v_fmac_f32_e32 v73, v35, v104
	v_fmac_f32_e32 v77, v24, v106
	v_fmac_f32_e32 v76, v25, v104
	v_fmac_f32_e32 v80, v28, v106
	v_fmac_f32_e32 v79, v29, v104
	v_fmac_f32_e32 v82, v26, v106
	v_fmac_f32_e32 v81, v27, v104
	v_fmac_f32_e32 v84, v16, v106
	v_fmac_f32_e32 v83, v17, v104
	v_fmac_f32_e32 v86, v14, v106
	v_fmac_f32_e32 v85, v15, v104
	v_fmac_f32_e32 v88, v12, v106
	v_fmac_f32_e32 v87, v13, v104
	v_fmac_f32_e32 v90, v22, v106
	v_fmac_f32_e32 v89, v23, v104
	v_fmac_f32_e32 v92, v20, v106
	v_fmac_f32_e32 v91, v21, v104
	v_fmac_f32_e32 v94, v18, v106
	v_fmac_f32_e32 v93, v19, v104
	v_fmac_f32_e32 v97, v10, v106
	v_fmac_f32_e32 v96, v11, v104
	v_fmac_f32_e32 v99, v8, v106
	v_fmac_f32_e32 v98, v9, v104
	v_fmac_f32_e32 v101, v6, v106
	v_fmac_f32_e32 v100, v7, v104
	v_fmac_f32_e32 v103, v4, v106
	v_fmac_f32_e32 v102, v5, v104
	v_lshlrev_b32_e32 v104, 16, v105
	v_and_b32_e32 v105, 0xffff0000, v105
	v_fmac_f32_e32 v74, v32, v104
	v_fmac_f32_e32 v71, v33, v105
	v_fmac_f32_e32 v72, v30, v104
	v_fmac_f32_e32 v70, v31, v105
	v_fmac_f32_e32 v75, v36, v104
	v_fmac_f32_e32 v73, v37, v105
	v_fmac_f32_e32 v77, v34, v104
	v_fmac_f32_e32 v76, v35, v105
	v_fmac_f32_e32 v80, v24, v104
	v_fmac_f32_e32 v79, v25, v105
	v_fmac_f32_e32 v82, v28, v104
	v_fmac_f32_e32 v81, v29, v105
	v_fmac_f32_e32 v84, v26, v104
	v_fmac_f32_e32 v83, v27, v105
	v_fmac_f32_e32 v86, v16, v104
	v_fmac_f32_e32 v85, v17, v105
	v_fmac_f32_e32 v88, v14, v104
	v_fmac_f32_e32 v87, v15, v105
	v_fmac_f32_e32 v90, v12, v104
	v_fmac_f32_e32 v89, v13, v105
	v_fmac_f32_e32 v92, v22, v104
	v_fmac_f32_e32 v91, v23, v105
	v_fmac_f32_e32 v94, v20, v104
	v_fmac_f32_e32 v93, v21, v105
	v_fmac_f32_e32 v97, v18, v104
	v_fmac_f32_e32 v96, v19, v105
	v_fmac_f32_e32 v99, v10, v104
	v_fmac_f32_e32 v98, v11, v105
	v_fmac_f32_e32 v101, v8, v104
	v_fmac_f32_e32 v100, v9, v105
	v_fmac_f32_e32 v103, v6, v104
	v_fmac_f32_e32 v102, v7, v105
	ds_read2st64_b32 v[104:105], v78 offset0:36 offset1:38
	s_waitcnt lgkmcnt(0)
; __device__ __forceinline__ void conv_unit(const Args& a, LAS unsigned char* lds, int l, int tt) {
;     ...
; #pragma unroll
;             for (int r = 0; r < 46; ++r) {
;                 const unsigned wv = Yu[(tb + r) * 128 + cp];
;                 const float x0 = bf2f(wv & 0xffffu), x1 = __builtin_bit_cast(float, wv & 0xffff0000u);
; #pragma unroll
;                 for (int t = 0; t < 16; ++t) { const int k = r - t; if (k >= 0 && k <= 30) { a0[t] += w0[k] * x0; a1[t] += w1[k] * x1; } }
	v_lshlrev_b32_e32 v106, 16, v104
	v_and_b32_e32 v104, 0xffff0000, v104
	v_fmac_f32_e32 v74, v42, v106
	v_fmac_f32_e32 v71, v43, v104
	v_fmac_f32_e32 v72, v32, v106
	v_fmac_f32_e32 v70, v33, v104
	v_fmac_f32_e32 v75, v30, v106
	v_fmac_f32_e32 v73, v31, v104
	v_fmac_f32_e32 v77, v36, v106
	v_fmac_f32_e32 v76, v37, v104
	v_fmac_f32_e32 v80, v34, v106
	v_fmac_f32_e32 v79, v35, v104
	v_fmac_f32_e32 v82, v24, v106
	v_fmac_f32_e32 v81, v25, v104
	v_fmac_f32_e32 v84, v28, v106
	v_fmac_f32_e32 v83, v29, v104
	v_fmac_f32_e32 v86, v26, v106
	v_fmac_f32_e32 v85, v27, v104
	v_fmac_f32_e32 v88, v16, v106
	v_fmac_f32_e32 v87, v17, v104
	v_fmac_f32_e32 v90, v14, v106
	v_fmac_f32_e32 v89, v15, v104
	v_fmac_f32_e32 v92, v12, v106
	v_fmac_f32_e32 v91, v13, v104
	v_fmac_f32_e32 v94, v22, v106
	v_fmac_f32_e32 v93, v23, v104
	v_fmac_f32_e32 v97, v20, v106
	v_fmac_f32_e32 v96, v21, v104
	v_fmac_f32_e32 v99, v18, v106
	v_fmac_f32_e32 v98, v19, v104
	v_fmac_f32_e32 v101, v10, v106
	v_fmac_f32_e32 v100, v11, v104
	v_fmac_f32_e32 v103, v8, v106
	v_fmac_f32_e32 v102, v9, v104
	v_lshlrev_b32_e32 v104, 16, v105
	v_and_b32_e32 v105, 0xffff0000, v105
	v_fmac_f32_e32 v74, v44, v104
	v_fmac_f32_e32 v71, v45, v105
	v_fmac_f32_e32 v72, v42, v104
	v_fmac_f32_e32 v70, v43, v105
	v_fmac_f32_e32 v75, v32, v104
	v_fmac_f32_e32 v73, v33, v105
	v_fmac_f32_e32 v77, v30, v104
	v_fmac_f32_e32 v76, v31, v105
	v_fmac_f32_e32 v80, v36, v104
	v_fmac_f32_e32 v79, v37, v105
	v_fmac_f32_e32 v82, v34, v104
	v_fmac_f32_e32 v81, v35, v105
	v_fmac_f32_e32 v84, v24, v104
	v_fmac_f32_e32 v83, v25, v105
	v_fmac_f32_e32 v86, v28, v104
	v_fmac_f32_e32 v85, v29, v105
	v_fmac_f32_e32 v88, v26, v104
	v_fmac_f32_e32 v87, v27, v105
	v_fmac_f32_e32 v90, v16, v104
	v_fmac_f32_e32 v89, v17, v105
	v_fmac_f32_e32 v92, v14, v104
	v_fmac_f32_e32 v91, v15, v105
	v_fmac_f32_e32 v94, v12, v104
	v_fmac_f32_e32 v93, v13, v105
	v_fmac_f32_e32 v97, v22, v104
	v_fmac_f32_e32 v96, v23, v105
	v_fmac_f32_e32 v99, v20, v104
	v_fmac_f32_e32 v98, v21, v105
	v_fmac_f32_e32 v101, v18, v104
	v_fmac_f32_e32 v100, v19, v105
	v_fmac_f32_e32 v103, v10, v104
	v_fmac_f32_e32 v102, v11, v105
	ds_read2st64_b32 v[104:105], v78 offset0:40 offset1:42
	s_waitcnt lgkmcnt(0)
	v_lshlrev_b32_e32 v106, 16, v104
	v_and_b32_e32 v104, 0xffff0000, v104
	v_fmac_f32_e32 v74, v46, v106
	v_fmac_f32_e32 v71, v47, v104
	v_fmac_f32_e32 v72, v44, v106
	v_fmac_f32_e32 v70, v45, v104
	v_fmac_f32_e32 v75, v42, v106
	v_fmac_f32_e32 v73, v43, v104
	v_fmac_f32_e32 v77, v32, v106
	v_fmac_f32_e32 v76, v33, v104
	v_fmac_f32_e32 v80, v30, v106
	v_fmac_f32_e32 v79, v31, v104
	v_fmac_f32_e32 v82, v36, v106
	v_fmac_f32_e32 v81, v37, v104
	v_fmac_f32_e32 v84, v34, v106
	v_fmac_f32_e32 v83, v35, v104
	v_fmac_f32_e32 v86, v24, v106
	v_fmac_f32_e32 v85, v25, v104
	v_fmac_f32_e32 v88, v28, v106
	v_fmac_f32_e32 v87, v29, v104
	v_fmac_f32_e32 v90, v26, v106
	v_fmac_f32_e32 v89, v27, v104
	v_fmac_f32_e32 v92, v16, v106
	v_fmac_f32_e32 v91, v17, v104
	v_fmac_f32_e32 v94, v14, v106
	v_fmac_f32_e32 v93, v15, v104
	v_fmac_f32_e32 v97, v12, v106
	v_fmac_f32_e32 v96, v13, v104
	v_fmac_f32_e32 v99, v22, v106
	v_fmac_f32_e32 v98, v23, v104
	v_fmac_f32_e32 v101, v20, v106
	v_fmac_f32_e32 v100, v21, v104
	v_fmac_f32_e32 v103, v18, v106
	v_fmac_f32_e32 v102, v19, v104
	v_lshlrev_b32_e32 v104, 16, v105
	v_and_b32_e32 v105, 0xffff0000, v105
	v_fmac_f32_e32 v74, v38, v104
	v_fmac_f32_e32 v71, v39, v105
	v_fmac_f32_e32 v72, v46, v104
	v_fmac_f32_e32 v70, v47, v105
	v_fmac_f32_e32 v75, v44, v104
	v_fmac_f32_e32 v73, v45, v105
	v_fmac_f32_e32 v77, v42, v104
	v_fmac_f32_e32 v76, v43, v105
	v_fmac_f32_e32 v80, v32, v104
	v_fmac_f32_e32 v79, v33, v105
	v_fmac_f32_e32 v82, v30, v104
	v_fmac_f32_e32 v81, v31, v105
	v_fmac_f32_e32 v84, v36, v104
	v_fmac_f32_e32 v83, v37, v105
	v_fmac_f32_e32 v86, v34, v104
	v_fmac_f32_e32 v85, v35, v105
	v_fmac_f32_e32 v88, v24, v104
	v_fmac_f32_e32 v87, v25, v105
	v_fmac_f32_e32 v90, v28, v104
	v_fmac_f32_e32 v89, v29, v105
	v_fmac_f32_e32 v92, v26, v104
	v_fmac_f32_e32 v91, v27, v105
	v_fmac_f32_e32 v94, v16, v104
	v_fmac_f32_e32 v93, v17, v105
	v_fmac_f32_e32 v97, v14, v104
	v_fmac_f32_e32 v96, v15, v105
	v_fmac_f32_e32 v99, v12, v104
	v_fmac_f32_e32 v98, v13, v105
	v_fmac_f32_e32 v101, v22, v104
	v_fmac_f32_e32 v100, v23, v105
	v_fmac_f32_e32 v103, v20, v104
	v_fmac_f32_e32 v102, v21, v105
	ds_read2st64_b32 v[104:105], v78 offset0:44 offset1:46
	s_waitcnt lgkmcnt(0)
	v_lshlrev_b32_e32 v106, 16, v104
	v_and_b32_e32 v104, 0xffff0000, v104
	v_fmac_f32_e32 v74, v40, v106
	v_fmac_f32_e32 v71, v41, v104
	v_fmac_f32_e32 v72, v38, v106
	v_fmac_f32_e32 v70, v39, v104
	v_fmac_f32_e32 v75, v46, v106
	v_fmac_f32_e32 v73, v47, v104
	v_fmac_f32_e32 v77, v44, v106
	v_fmac_f32_e32 v76, v45, v104
	v_fmac_f32_e32 v80, v42, v106
	v_fmac_f32_e32 v79, v43, v104
	v_fmac_f32_e32 v82, v32, v106
	v_fmac_f32_e32 v81, v33, v104
	v_fmac_f32_e32 v84, v30, v106
	v_fmac_f32_e32 v83, v31, v104
	v_fmac_f32_e32 v86, v36, v106
	v_fmac_f32_e32 v85, v37, v104
	v_fmac_f32_e32 v88, v34, v106
	v_fmac_f32_e32 v87, v35, v104
	v_fmac_f32_e32 v90, v24, v106
	v_fmac_f32_e32 v89, v25, v104
	v_fmac_f32_e32 v92, v28, v106
	v_fmac_f32_e32 v91, v29, v104
	v_fmac_f32_e32 v94, v26, v106
	v_fmac_f32_e32 v93, v27, v104
	v_fmac_f32_e32 v97, v16, v106
	v_fmac_f32_e32 v96, v17, v104
	v_fmac_f32_e32 v99, v14, v106
	v_fmac_f32_e32 v98, v15, v104
	v_fmac_f32_e32 v101, v12, v106
	v_fmac_f32_e32 v100, v13, v104
	v_fmac_f32_e32 v103, v22, v106
	v_fmac_f32_e32 v102, v23, v104
	v_lshlrev_b32_e32 v104, 16, v105
	v_and_b32_e32 v105, 0xffff0000, v105
	v_fmac_f32_e32 v74, v56, v104
	v_fmac_f32_e32 v71, v57, v105
	v_fmac_f32_e32 v72, v40, v104
	v_fmac_f32_e32 v70, v41, v105
	v_fmac_f32_e32 v75, v38, v104
	v_fmac_f32_e32 v73, v39, v105
	v_fmac_f32_e32 v77, v46, v104
	v_fmac_f32_e32 v76, v47, v105
	v_fmac_f32_e32 v80, v44, v104
	v_fmac_f32_e32 v79, v45, v105
	v_fmac_f32_e32 v82, v42, v104
	v_fmac_f32_e32 v81, v43, v105
	v_fmac_f32_e32 v84, v32, v104
	v_fmac_f32_e32 v83, v33, v105
	v_fmac_f32_e32 v86, v30, v104
	v_fmac_f32_e32 v85, v31, v105
	v_fmac_f32_e32 v88, v36, v104
	v_fmac_f32_e32 v87, v37, v105
	v_fmac_f32_e32 v90, v34, v104
	v_fmac_f32_e32 v89, v35, v105
	v_fmac_f32_e32 v92, v24, v104
	v_fmac_f32_e32 v91, v25, v105
	v_fmac_f32_e32 v94, v28, v104
	v_fmac_f32_e32 v93, v29, v105
	v_fmac_f32_e32 v97, v26, v104
	v_fmac_f32_e32 v96, v27, v105
	v_fmac_f32_e32 v99, v16, v104
	v_fmac_f32_e32 v98, v17, v105
	v_fmac_f32_e32 v101, v14, v104
	v_fmac_f32_e32 v100, v15, v105
	v_fmac_f32_e32 v103, v12, v104
	v_fmac_f32_e32 v102, v13, v105
	ds_read2st64_b32 v[104:105], v78 offset0:48 offset1:50
	s_waitcnt lgkmcnt(0)
; __device__ __forceinline__ void conv_unit(const Args& a, LAS unsigned char* lds, int l, int tt) {
;     ...
; #pragma unroll
;             for (int r = 0; r < 46; ++r) {
;                 const unsigned wv = Yu[(tb + r) * 128 + cp];
;                 const float x0 = bf2f(wv & 0xffffu), x1 = __builtin_bit_cast(float, wv & 0xffff0000u);
; #pragma unroll
;                 for (int t = 0; t < 16; ++t) { const int k = r - t; if (k >= 0 && k <= 30) { a0[t] += w0[k] * x0; a1[t] += w1[k] * x1; } }
	v_lshlrev_b32_e32 v106, 16, v104
	v_and_b32_e32 v104, 0xffff0000, v104
	v_fmac_f32_e32 v74, v48, v106
	v_fmac_f32_e32 v71, v49, v104
	v_fmac_f32_e32 v72, v56, v106
	v_fmac_f32_e32 v70, v57, v104
	v_fmac_f32_e32 v75, v40, v106
	v_fmac_f32_e32 v73, v41, v104
	v_fmac_f32_e32 v77, v38, v106
	v_fmac_f32_e32 v76, v39, v104
	v_fmac_f32_e32 v80, v46, v106
	v_fmac_f32_e32 v79, v47, v104
	v_fmac_f32_e32 v82, v44, v106
	v_fmac_f32_e32 v81, v45, v104
	v_fmac_f32_e32 v84, v42, v106
	v_fmac_f32_e32 v83, v43, v104
	v_fmac_f32_e32 v86, v32, v106
	v_fmac_f32_e32 v85, v33, v104
	v_fmac_f32_e32 v88, v30, v106
	v_fmac_f32_e32 v87, v31, v104
	v_fmac_f32_e32 v90, v36, v106
	v_fmac_f32_e32 v89, v37, v104
	v_fmac_f32_e32 v92, v34, v106
	v_fmac_f32_e32 v91, v35, v104
	v_fmac_f32_e32 v94, v24, v106
	v_fmac_f32_e32 v93, v25, v104
	v_fmac_f32_e32 v97, v28, v106
	v_fmac_f32_e32 v96, v29, v104
	v_fmac_f32_e32 v99, v26, v106
	v_fmac_f32_e32 v98, v27, v104
	v_fmac_f32_e32 v101, v16, v106
	v_fmac_f32_e32 v100, v17, v104
	v_fmac_f32_e32 v103, v14, v106
	v_fmac_f32_e32 v102, v15, v104
	v_lshlrev_b32_e32 v104, 16, v105
	v_and_b32_e32 v105, 0xffff0000, v105
	v_fmac_f32_e32 v74, v50, v104
	v_fmac_f32_e32 v71, v51, v105
	v_fmac_f32_e32 v72, v48, v104
	v_fmac_f32_e32 v70, v49, v105
	v_fmac_f32_e32 v75, v56, v104
	v_fmac_f32_e32 v73, v57, v105
	v_fmac_f32_e32 v77, v40, v104
	v_fmac_f32_e32 v76, v41, v105
	v_fmac_f32_e32 v80, v38, v104
	v_fmac_f32_e32 v79, v39, v105
	v_fmac_f32_e32 v82, v46, v104
	v_fmac_f32_e32 v81, v47, v105
	v_fmac_f32_e32 v84, v44, v104
	v_fmac_f32_e32 v83, v45, v105
	v_fmac_f32_e32 v86, v42, v104
	v_fmac_f32_e32 v85, v43, v105
	v_fmac_f32_e32 v88, v32, v104
	v_fmac_f32_e32 v87, v33, v105
	v_fmac_f32_e32 v90, v30, v104
	v_fmac_f32_e32 v89, v31, v105
	v_fmac_f32_e32 v92, v36, v104
	v_fmac_f32_e32 v91, v37, v105
	v_fmac_f32_e32 v94, v34, v104
	v_fmac_f32_e32 v93, v35, v105
	v_fmac_f32_e32 v97, v24, v104
	v_fmac_f32_e32 v96, v25, v105
	v_fmac_f32_e32 v99, v28, v104
	v_fmac_f32_e32 v98, v29, v105
	v_fmac_f32_e32 v101, v26, v104
	v_fmac_f32_e32 v100, v27, v105
	v_fmac_f32_e32 v103, v16, v104
	v_fmac_f32_e32 v102, v17, v105
	ds_read2st64_b32 v[104:105], v78 offset0:52 offset1:54
	s_waitcnt lgkmcnt(0)
	v_lshlrev_b32_e32 v106, 16, v104
	v_and_b32_e32 v104, 0xffff0000, v104
	v_fmac_f32_e32 v74, v52, v106
	v_fmac_f32_e32 v71, v53, v104
	v_fmac_f32_e32 v72, v50, v106
	v_fmac_f32_e32 v70, v51, v104
	v_fmac_f32_e32 v75, v48, v106
	v_fmac_f32_e32 v73, v49, v104
	v_fmac_f32_e32 v77, v56, v106
	v_fmac_f32_e32 v76, v57, v104
	v_fmac_f32_e32 v80, v40, v106
	v_fmac_f32_e32 v79, v41, v104
	v_fmac_f32_e32 v82, v38, v106
	v_fmac_f32_e32 v81, v39, v104
	v_fmac_f32_e32 v84, v46, v106
	v_fmac_f32_e32 v83, v47, v104
	v_fmac_f32_e32 v86, v44, v106
	v_fmac_f32_e32 v85, v45, v104
	v_fmac_f32_e32 v88, v42, v106
	v_fmac_f32_e32 v87, v43, v104
	v_fmac_f32_e32 v90, v32, v106
	v_fmac_f32_e32 v89, v33, v104
	v_fmac_f32_e32 v92, v30, v106
	v_fmac_f32_e32 v91, v31, v104
	v_fmac_f32_e32 v94, v36, v106
	v_fmac_f32_e32 v93, v37, v104
	v_fmac_f32_e32 v97, v34, v106
	v_fmac_f32_e32 v96, v35, v104
	v_fmac_f32_e32 v99, v24, v106
	v_fmac_f32_e32 v98, v25, v104
	v_fmac_f32_e32 v101, v28, v106
	v_fmac_f32_e32 v100, v29, v104
	v_fmac_f32_e32 v103, v26, v106
	v_fmac_f32_e32 v102, v27, v104
	v_lshlrev_b32_e32 v104, 16, v105
	v_and_b32_e32 v105, 0xffff0000, v105
	v_fmac_f32_e32 v74, v54, v104
	v_fmac_f32_e32 v71, v55, v105
	v_fmac_f32_e32 v72, v52, v104
	v_fmac_f32_e32 v70, v53, v105
	v_fmac_f32_e32 v75, v50, v104
	v_fmac_f32_e32 v73, v51, v105
	v_fmac_f32_e32 v77, v48, v104
	v_fmac_f32_e32 v76, v49, v105
	v_fmac_f32_e32 v80, v56, v104
	v_fmac_f32_e32 v79, v57, v105
	v_fmac_f32_e32 v82, v40, v104
	v_fmac_f32_e32 v81, v41, v105
	v_fmac_f32_e32 v84, v38, v104
	v_fmac_f32_e32 v83, v39, v105
	v_fmac_f32_e32 v86, v46, v104
	v_fmac_f32_e32 v85, v47, v105
	v_fmac_f32_e32 v88, v44, v104
	v_fmac_f32_e32 v87, v45, v105
	v_fmac_f32_e32 v90, v42, v104
	v_fmac_f32_e32 v89, v43, v105
	v_fmac_f32_e32 v92, v32, v104
	v_fmac_f32_e32 v91, v33, v105
	v_fmac_f32_e32 v94, v30, v104
	v_fmac_f32_e32 v93, v31, v105
	v_fmac_f32_e32 v97, v36, v104
	v_fmac_f32_e32 v96, v37, v105
	v_fmac_f32_e32 v99, v34, v104
	v_fmac_f32_e32 v98, v35, v105
	v_fmac_f32_e32 v101, v24, v104
	v_fmac_f32_e32 v100, v25, v105
	v_fmac_f32_e32 v103, v28, v104
	v_fmac_f32_e32 v102, v29, v105
	ds_read2st64_b32 v[104:105], v78 offset0:56 offset1:58
	s_waitcnt lgkmcnt(0)
	v_lshlrev_b32_e32 v106, 16, v104
	v_and_b32_e32 v104, 0xffff0000, v104
	v_fmac_f32_e32 v74, v58, v106
	v_fmac_f32_e32 v71, v59, v104
	v_fmac_f32_e32 v72, v54, v106
	v_fmac_f32_e32 v70, v55, v104
	v_fmac_f32_e32 v75, v52, v106
	v_fmac_f32_e32 v73, v53, v104
	v_fmac_f32_e32 v77, v50, v106
	v_fmac_f32_e32 v76, v51, v104
	v_fmac_f32_e32 v80, v48, v106
	v_fmac_f32_e32 v79, v49, v104
	v_fmac_f32_e32 v82, v56, v106
	v_fmac_f32_e32 v81, v57, v104
	v_fmac_f32_e32 v84, v40, v106
	v_fmac_f32_e32 v83, v41, v104
	v_fmac_f32_e32 v86, v38, v106
	v_fmac_f32_e32 v85, v39, v104
	v_fmac_f32_e32 v88, v46, v106
	v_fmac_f32_e32 v87, v47, v104
	v_fmac_f32_e32 v90, v44, v106
	v_fmac_f32_e32 v89, v45, v104
	v_fmac_f32_e32 v92, v42, v106
	v_fmac_f32_e32 v91, v43, v104
	v_fmac_f32_e32 v94, v32, v106
	v_fmac_f32_e32 v93, v33, v104
	v_fmac_f32_e32 v97, v30, v106
	v_fmac_f32_e32 v96, v31, v104
	v_fmac_f32_e32 v99, v36, v106
	v_fmac_f32_e32 v98, v37, v104
	v_fmac_f32_e32 v101, v34, v106
	v_fmac_f32_e32 v100, v35, v104
	v_fmac_f32_e32 v103, v24, v106
	v_fmac_f32_e32 v102, v25, v104
	v_lshlrev_b32_e32 v104, 16, v105
	v_and_b32_e32 v105, 0xffff0000, v105
	v_fmac_f32_e32 v74, v60, v104
	v_fmac_f32_e32 v71, v61, v105
	v_fmac_f32_e32 v72, v58, v104
	v_fmac_f32_e32 v70, v59, v105
	v_fmac_f32_e32 v75, v54, v104
	v_fmac_f32_e32 v73, v55, v105
	v_fmac_f32_e32 v77, v52, v104
	v_fmac_f32_e32 v76, v53, v105
	v_fmac_f32_e32 v80, v50, v104
	v_fmac_f32_e32 v79, v51, v105
	v_fmac_f32_e32 v82, v48, v104
	v_fmac_f32_e32 v81, v49, v105
	v_fmac_f32_e32 v84, v56, v104
	v_fmac_f32_e32 v83, v57, v105
	v_fmac_f32_e32 v86, v40, v104
	v_fmac_f32_e32 v85, v41, v105
	v_fmac_f32_e32 v88, v38, v104
	v_fmac_f32_e32 v87, v39, v105
	v_fmac_f32_e32 v90, v46, v104
	v_fmac_f32_e32 v89, v47, v105
	v_fmac_f32_e32 v92, v44, v104
	v_fmac_f32_e32 v91, v45, v105
	v_fmac_f32_e32 v94, v42, v104
	v_fmac_f32_e32 v93, v43, v105
	v_fmac_f32_e32 v97, v32, v104
	v_fmac_f32_e32 v96, v33, v105
	v_fmac_f32_e32 v99, v30, v104
	v_fmac_f32_e32 v98, v31, v105
	v_fmac_f32_e32 v101, v36, v104
	v_fmac_f32_e32 v100, v37, v105
	v_fmac_f32_e32 v103, v34, v104
	v_fmac_f32_e32 v102, v35, v105
	ds_read2st64_b32 v[104:105], v78 offset0:60 offset1:62
	s_waitcnt lgkmcnt(0)
; __device__ __forceinline__ void conv_unit(const Args& a, LAS unsigned char* lds, int l, int tt) {
;     ...
; #pragma unroll
;             for (int r = 0; r < 46; ++r) {
;                 const unsigned wv = Yu[(tb + r) * 128 + cp];
;                 const float x0 = bf2f(wv & 0xffffu), x1 = __builtin_bit_cast(float, wv & 0xffff0000u);
; #pragma unroll
;                 for (int t = 0; t < 16; ++t) { const int k = r - t; if (k >= 0 && k <= 30) { a0[t] += w0[k] * x0; a1[t] += w1[k] * x1; } }
	v_lshlrev_b32_e32 v106, 16, v104
	v_and_b32_e32 v104, 0xffff0000, v104
	v_fmac_f32_e32 v71, v63, v104
	v_fmac_f32_e32 v72, v60, v106
	v_fmac_f32_e32 v70, v61, v104
	v_fmac_f32_e32 v75, v58, v106
	v_fmac_f32_e32 v73, v59, v104
	v_fmac_f32_e32 v77, v54, v106
	v_fmac_f32_e32 v76, v55, v104
	v_fmac_f32_e32 v80, v52, v106
	v_fmac_f32_e32 v79, v53, v104
	v_fmac_f32_e32 v82, v50, v106
	v_fmac_f32_e32 v81, v51, v104
	v_fmac_f32_e32 v84, v48, v106
	v_fmac_f32_e32 v83, v49, v104
	v_fmac_f32_e32 v86, v56, v106
	v_fmac_f32_e32 v85, v57, v104
	v_fmac_f32_e32 v88, v40, v106
	v_fmac_f32_e32 v87, v41, v104
	v_fmac_f32_e32 v90, v38, v106
	v_fmac_f32_e32 v89, v39, v104
	v_fmac_f32_e32 v92, v46, v106
	v_fmac_f32_e32 v91, v47, v104
	v_fmac_f32_e32 v94, v44, v106
	v_fmac_f32_e32 v93, v45, v104
	v_fmac_f32_e32 v97, v42, v106
	v_fmac_f32_e32 v96, v43, v104
	v_fmac_f32_e32 v99, v32, v106
	v_fmac_f32_e32 v98, v33, v104
	v_fmac_f32_e32 v101, v30, v106
	v_fmac_f32_e32 v100, v31, v104
	v_fmac_f32_e32 v103, v36, v106
	v_fmac_f32_e32 v102, v37, v104
	v_lshlrev_b32_e32 v104, 16, v105
	v_and_b32_e32 v105, 0xffff0000, v105
	v_fmac_f32_e32 v72, v62, v104
	v_fmac_f32_e32 v70, v63, v105
	v_fmac_f32_e32 v75, v60, v104
	v_fmac_f32_e32 v73, v61, v105
	v_fmac_f32_e32 v77, v58, v104
	v_fmac_f32_e32 v76, v59, v105
	v_fmac_f32_e32 v80, v54, v104
	v_fmac_f32_e32 v79, v55, v105
	v_fmac_f32_e32 v82, v52, v104
	v_fmac_f32_e32 v81, v53, v105
	v_fmac_f32_e32 v84, v50, v104
	v_fmac_f32_e32 v83, v51, v105
	v_fmac_f32_e32 v86, v48, v104
	v_fmac_f32_e32 v85, v49, v105
	v_fmac_f32_e32 v88, v56, v104
	v_fmac_f32_e32 v87, v57, v105
	v_fmac_f32_e32 v90, v40, v104
	v_fmac_f32_e32 v89, v41, v105
	v_fmac_f32_e32 v92, v38, v104
	v_fmac_f32_e32 v91, v39, v105
	v_fmac_f32_e32 v94, v46, v104
	v_fmac_f32_e32 v93, v47, v105
	v_fmac_f32_e32 v97, v44, v104
	v_fmac_f32_e32 v96, v45, v105
	v_fmac_f32_e32 v99, v42, v104
	v_fmac_f32_e32 v98, v43, v105
	v_fmac_f32_e32 v101, v32, v104
	v_fmac_f32_e32 v100, v33, v105
	v_fmac_f32_e32 v103, v30, v104
	v_fmac_f32_e32 v102, v31, v105
	ds_read2st64_b32 v[104:105], v78 offset0:64 offset1:66
	v_fmac_f32_e32 v74, v62, v106
	s_waitcnt lgkmcnt(0)
	v_lshlrev_b32_e32 v106, 16, v104
	v_and_b32_e32 v104, 0xffff0000, v104
	v_fmac_f32_e32 v73, v63, v104
	v_fmac_f32_e32 v77, v60, v106
	v_fmac_f32_e32 v76, v61, v104
	v_fmac_f32_e32 v80, v58, v106
	v_fmac_f32_e32 v79, v59, v104
	v_fmac_f32_e32 v82, v54, v106
	v_fmac_f32_e32 v81, v55, v104
	v_fmac_f32_e32 v84, v52, v106
	v_fmac_f32_e32 v83, v53, v104
	v_fmac_f32_e32 v86, v50, v106
	v_fmac_f32_e32 v85, v51, v104
	v_fmac_f32_e32 v88, v48, v106
	v_fmac_f32_e32 v87, v49, v104
	v_fmac_f32_e32 v90, v56, v106
	v_fmac_f32_e32 v89, v57, v104
	v_fmac_f32_e32 v92, v40, v106
	v_fmac_f32_e32 v91, v41, v104
	v_fmac_f32_e32 v94, v38, v106
	v_fmac_f32_e32 v93, v39, v104
	v_fmac_f32_e32 v97, v46, v106
	v_fmac_f32_e32 v96, v47, v104
	v_fmac_f32_e32 v99, v44, v106
	v_fmac_f32_e32 v98, v45, v104
	v_fmac_f32_e32 v101, v42, v106
	v_fmac_f32_e32 v100, v43, v104
	v_fmac_f32_e32 v103, v32, v106
	v_fmac_f32_e32 v102, v33, v104
	v_lshlrev_b32_e32 v104, 16, v105
	v_and_b32_e32 v105, 0xffff0000, v105
	v_fmac_f32_e32 v77, v62, v104
	v_fmac_f32_e32 v76, v63, v105
	v_fmac_f32_e32 v80, v60, v104
	v_fmac_f32_e32 v79, v61, v105
	v_fmac_f32_e32 v82, v58, v104
	v_fmac_f32_e32 v81, v59, v105
	v_fmac_f32_e32 v84, v54, v104
	v_fmac_f32_e32 v83, v55, v105
	v_fmac_f32_e32 v86, v52, v104
	v_fmac_f32_e32 v85, v53, v105
	v_fmac_f32_e32 v88, v50, v104
	v_fmac_f32_e32 v87, v51, v105
	v_fmac_f32_e32 v90, v48, v104
	v_fmac_f32_e32 v89, v49, v105
	v_fmac_f32_e32 v92, v56, v104
	v_fmac_f32_e32 v91, v57, v105
	v_fmac_f32_e32 v94, v40, v104
	v_fmac_f32_e32 v93, v41, v105
	v_fmac_f32_e32 v97, v38, v104
	v_fmac_f32_e32 v96, v39, v105
	v_fmac_f32_e32 v99, v46, v104
	v_fmac_f32_e32 v98, v47, v105
	v_fmac_f32_e32 v101, v44, v104
	v_fmac_f32_e32 v100, v45, v105
	v_fmac_f32_e32 v103, v42, v104
	v_fmac_f32_e32 v102, v43, v105
	ds_read2st64_b32 v[104:105], v78 offset0:68 offset1:70
	v_fmac_f32_e32 v75, v62, v106
	s_waitcnt lgkmcnt(0)
	v_lshlrev_b32_e32 v106, 16, v104
	v_and_b32_e32 v104, 0xffff0000, v104
	v_fmac_f32_e32 v79, v63, v104
	v_fmac_f32_e32 v82, v60, v106
	v_fmac_f32_e32 v81, v61, v104
	v_fmac_f32_e32 v84, v58, v106
	v_fmac_f32_e32 v83, v59, v104
	v_fmac_f32_e32 v86, v54, v106
	v_fmac_f32_e32 v85, v55, v104
	v_fmac_f32_e32 v88, v52, v106
	v_fmac_f32_e32 v87, v53, v104
	v_fmac_f32_e32 v90, v50, v106
	v_fmac_f32_e32 v89, v51, v104
	v_fmac_f32_e32 v92, v48, v106
	v_fmac_f32_e32 v91, v49, v104
	v_fmac_f32_e32 v94, v56, v106
	v_fmac_f32_e32 v93, v57, v104
	v_fmac_f32_e32 v97, v40, v106
	v_fmac_f32_e32 v96, v41, v104
	v_fmac_f32_e32 v99, v38, v106
	v_fmac_f32_e32 v98, v39, v104
	v_fmac_f32_e32 v101, v46, v106
	v_fmac_f32_e32 v100, v47, v104
	v_fmac_f32_e32 v103, v44, v106
	v_fmac_f32_e32 v102, v45, v104
	v_lshlrev_b32_e32 v104, 16, v105
	v_and_b32_e32 v105, 0xffff0000, v105
	v_fmac_f32_e32 v82, v62, v104
	v_fmac_f32_e32 v81, v63, v105
	v_fmac_f32_e32 v84, v60, v104
	v_fmac_f32_e32 v83, v61, v105
	v_fmac_f32_e32 v86, v58, v104
	v_fmac_f32_e32 v85, v59, v105
	v_fmac_f32_e32 v88, v54, v104
	v_fmac_f32_e32 v87, v55, v105
	v_fmac_f32_e32 v90, v52, v104
	v_fmac_f32_e32 v89, v53, v105
	v_fmac_f32_e32 v92, v50, v104
	v_fmac_f32_e32 v91, v51, v105
	v_fmac_f32_e32 v94, v48, v104
	v_fmac_f32_e32 v93, v49, v105
	v_fmac_f32_e32 v97, v56, v104
	v_fmac_f32_e32 v96, v57, v105
	v_fmac_f32_e32 v99, v40, v104
	v_fmac_f32_e32 v98, v41, v105
	v_fmac_f32_e32 v101, v38, v104
	v_fmac_f32_e32 v100, v39, v105
	v_fmac_f32_e32 v103, v46, v104
	v_fmac_f32_e32 v102, v47, v105
	ds_read2st64_b32 v[104:105], v78 offset0:72 offset1:74
	v_fmac_f32_e32 v80, v62, v106
	s_waitcnt lgkmcnt(0)
; #define LAS __attribute__((address_space(3)))
; __device__ __forceinline__ unsigned pk2(float lo, float hi) { return f2bf(lo) | (f2bf(hi) << 16); }
; __device__ __forceinline__ void conv_unit(const Args& a, LAS unsigned char* lds, int l, int tt) {
;     ...
;             for (int r = 0; r < 46; ++r) {
;                 const unsigned wv = Yu[(tb + r) * 128 + cp];
;                 const float x0 = bf2f(wv & 0xffffu), x1 = __builtin_bit_cast(float, wv & 0xffff0000u);
; #pragma unroll
;                 for (int t = 0; t < 16; ++t) { const int k = r - t; if (k >= 0 && k <= 30) { a0[t] += w0[k] * x0; a1[t] += w1[k] * x1; } }
;             }
; #pragma unroll
;             for (int t = 0; t < 16; ++t) *(LAS unsigned*)(O + (tb + t) * CXS + 2 * cp) = pk2(a0[t], a1[t]);
	v_lshlrev_b32_e32 v106, 16, v104
	v_and_b32_e32 v104, 0xffff0000, v104
	v_fmac_f32_e32 v83, v63, v104
	v_fmac_f32_e32 v86, v60, v106
	v_fmac_f32_e32 v85, v61, v104
	v_fmac_f32_e32 v88, v58, v106
	v_fmac_f32_e32 v87, v59, v104
	v_fmac_f32_e32 v90, v54, v106
	v_fmac_f32_e32 v89, v55, v104
	v_fmac_f32_e32 v92, v52, v106
	v_fmac_f32_e32 v91, v53, v104
	v_fmac_f32_e32 v94, v50, v106
	v_fmac_f32_e32 v93, v51, v104
	v_fmac_f32_e32 v97, v48, v106
	v_fmac_f32_e32 v96, v49, v104
	v_fmac_f32_e32 v99, v56, v106
	v_fmac_f32_e32 v98, v57, v104
	v_fmac_f32_e32 v101, v40, v106
	v_fmac_f32_e32 v100, v41, v104
	v_fmac_f32_e32 v103, v38, v106
	v_fmac_f32_e32 v102, v39, v104
	v_lshlrev_b32_e32 v104, 16, v105
	v_and_b32_e32 v105, 0xffff0000, v105
	v_fmac_f32_e32 v86, v62, v104
	v_fmac_f32_e32 v85, v63, v105
	v_fmac_f32_e32 v88, v60, v104
	v_fmac_f32_e32 v87, v61, v105
	v_fmac_f32_e32 v90, v58, v104
	v_fmac_f32_e32 v89, v59, v105
	v_fmac_f32_e32 v92, v54, v104
	v_fmac_f32_e32 v91, v55, v105
	v_fmac_f32_e32 v94, v52, v104
	v_fmac_f32_e32 v93, v53, v105
	v_fmac_f32_e32 v97, v50, v104
	v_fmac_f32_e32 v96, v51, v105
	v_fmac_f32_e32 v99, v48, v104
	v_fmac_f32_e32 v98, v49, v105
	v_fmac_f32_e32 v101, v56, v104
	v_fmac_f32_e32 v100, v57, v105
	v_fmac_f32_e32 v103, v40, v104
	v_fmac_f32_e32 v102, v41, v105
	ds_read2st64_b32 v[104:105], v78 offset0:76 offset1:78
	v_fmac_f32_e32 v84, v62, v106
	s_waitcnt lgkmcnt(0)
	v_lshlrev_b32_e32 v106, 16, v104
	v_and_b32_e32 v104, 0xffff0000, v104
	v_fmac_f32_e32 v87, v63, v104
	v_fmac_f32_e32 v90, v60, v106
	v_fmac_f32_e32 v89, v61, v104
	v_fmac_f32_e32 v92, v58, v106
	v_fmac_f32_e32 v91, v59, v104
	v_fmac_f32_e32 v94, v54, v106
	v_fmac_f32_e32 v93, v55, v104
	v_fmac_f32_e32 v97, v52, v106
	v_fmac_f32_e32 v96, v53, v104
	v_fmac_f32_e32 v99, v50, v106
	v_fmac_f32_e32 v98, v51, v104
	v_fmac_f32_e32 v101, v48, v106
	v_fmac_f32_e32 v100, v49, v104
	v_fmac_f32_e32 v103, v56, v106
	v_fmac_f32_e32 v102, v57, v104
	v_lshlrev_b32_e32 v104, 16, v105
	v_and_b32_e32 v105, 0xffff0000, v105
	v_fmac_f32_e32 v90, v62, v104
	v_fmac_f32_e32 v89, v63, v105
	v_fmac_f32_e32 v92, v60, v104
	v_fmac_f32_e32 v91, v61, v105
	v_fmac_f32_e32 v94, v58, v104
	v_fmac_f32_e32 v93, v59, v105
	v_fmac_f32_e32 v97, v54, v104
	v_fmac_f32_e32 v96, v55, v105
	v_fmac_f32_e32 v99, v52, v104
	v_fmac_f32_e32 v98, v53, v105
	v_fmac_f32_e32 v101, v50, v104
	v_fmac_f32_e32 v100, v51, v105
	v_fmac_f32_e32 v103, v48, v104
	v_fmac_f32_e32 v102, v49, v105
	ds_read2st64_b32 v[104:105], v78 offset0:80 offset1:82
	v_fmac_f32_e32 v88, v62, v106
	s_waitcnt lgkmcnt(0)
	v_lshlrev_b32_e32 v106, 16, v104
	v_and_b32_e32 v104, 0xffff0000, v104
	v_fmac_f32_e32 v91, v63, v104
	v_fmac_f32_e32 v94, v60, v106
	v_fmac_f32_e32 v93, v61, v104
	v_fmac_f32_e32 v97, v58, v106
	v_fmac_f32_e32 v96, v59, v104
	v_fmac_f32_e32 v99, v54, v106
	v_fmac_f32_e32 v98, v55, v104
	v_fmac_f32_e32 v101, v52, v106
	v_fmac_f32_e32 v100, v53, v104
	v_fmac_f32_e32 v103, v50, v106
	v_fmac_f32_e32 v102, v51, v104
	v_lshlrev_b32_e32 v104, 16, v105
	v_and_b32_e32 v105, 0xffff0000, v105
	v_fmac_f32_e32 v94, v62, v104
	v_fmac_f32_e32 v93, v63, v105
	v_fmac_f32_e32 v97, v60, v104
	v_fmac_f32_e32 v96, v61, v105
	v_fmac_f32_e32 v99, v58, v104
	v_fmac_f32_e32 v98, v59, v105
	v_fmac_f32_e32 v101, v54, v104
	v_fmac_f32_e32 v100, v55, v105
	v_fmac_f32_e32 v103, v52, v104
	v_fmac_f32_e32 v102, v53, v105
	ds_read2st64_b32 v[104:105], v78 offset0:84 offset1:86
	v_fmac_f32_e32 v92, v62, v106
	s_waitcnt lgkmcnt(0)
	v_lshlrev_b32_e32 v106, 16, v104
	v_and_b32_e32 v104, 0xffff0000, v104
	v_fmac_f32_e32 v96, v63, v104
	v_fmac_f32_e32 v99, v60, v106
	v_fmac_f32_e32 v98, v61, v104
	v_fmac_f32_e32 v101, v58, v106
	v_fmac_f32_e32 v100, v59, v104
	v_fmac_f32_e32 v103, v54, v106
	v_fmac_f32_e32 v102, v55, v104
	v_lshlrev_b32_e32 v104, 16, v105
	v_and_b32_e32 v105, 0xffff0000, v105
	v_fmac_f32_e32 v99, v62, v104
	v_fmac_f32_e32 v98, v63, v105
	v_fmac_f32_e32 v101, v60, v104
	v_fmac_f32_e32 v100, v61, v105
	v_fmac_f32_e32 v103, v58, v104
	v_fmac_f32_e32 v102, v59, v105
	ds_read2st64_b32 v[104:105], v78 offset0:88 offset1:90
	v_fmac_f32_e32 v97, v62, v106
	s_waitcnt lgkmcnt(0)
	v_lshlrev_b32_e32 v78, 16, v104
	v_and_b32_e32 v104, 0xffff0000, v104
	v_fmac_f32_e32 v101, v62, v78
	v_fmac_f32_e32 v100, v63, v104
	v_fmac_f32_e32 v103, v60, v78
	v_fmac_f32_e32 v102, v61, v104
	v_lshlrev_b32_e32 v78, 16, v105
	v_and_b32_e32 v104, 0xffff0000, v105
	v_fmac_f32_e32 v102, v63, v104
	v_fmac_f32_e32 v103, v62, v78
	v_bfe_u32 v78, v74, 16, 1
	v_mad_u64_u32 v[104:105], s[4:5], v69, s55, v[66:67]
	v_bfe_u32 v69, v72, 16, 1
	v_add3_u32 v74, v74, v78, s27
	v_bfe_u32 v78, v71, 16, 1
	v_add3_u32 v69, v72, v69, s27
	v_bfe_u32 v72, v70, 16, 1
	v_lshrrev_b32_e32 v74, 16, v74
	v_add3_u32 v71, v71, v78, s27
	v_lshrrev_b32_e32 v69, 16, v69
	v_add3_u32 v70, v70, v72, s27
	v_and_or_b32 v71, v71, s6, v74
	v_and_or_b32 v69, v70, s6, v69
	ds_write2_b32 v104, v71, v69 offset1:132
	v_bfe_u32 v69, v75, 16, 1
	v_add3_u32 v69, v75, v69, s27
	v_bfe_u32 v70, v73, 16, 1
	v_lshrrev_b32_e32 v69, 16, v69
	v_add3_u32 v70, v73, v70, s27
	v_and_or_b32 v69, v70, s6, v69
	v_bfe_u32 v70, v77, 16, 1
	v_add3_u32 v70, v77, v70, s27
	v_bfe_u32 v71, v76, 16, 1
	v_lshrrev_b32_e32 v70, 16, v70
	v_add3_u32 v71, v76, v71, s27
	v_and_or_b32 v70, v71, s6, v70
	v_add_u32_e32 v71, 0x400, v104
	ds_write2_b32 v71, v69, v70 offset0:8 offset1:140
	v_bfe_u32 v69, v80, 16, 1
	v_add3_u32 v69, v80, v69, s27
	v_bfe_u32 v70, v79, 16, 1
	v_lshrrev_b32_e32 v69, 16, v69
	v_add3_u32 v70, v79, v70, s27
	v_and_or_b32 v69, v70, s6, v69
	v_bfe_u32 v70, v82, 16, 1
	v_add3_u32 v70, v82, v70, s27
	v_bfe_u32 v71, v81, 16, 1
; #define LAS __attribute__((address_space(3)))
; __device__ __forceinline__ unsigned pk2(float lo, float hi) { return f2bf(lo) | (f2bf(hi) << 16); }
; __device__ __forceinline__ float sum8sq(const float (&d)[8]) { return (d[0] * d[0] + d[1] * d[1]) + (d[2] * d[2] + d[3] * d[3]) + (d[4] * d[4] + d[5] * d[5]) + (d[6] * d[6] + d[7] * d[7]); }
; __host__ __device__ __forceinline__ unsigned hl_off(unsigned r, unsigned c) { const unsigned st = (r >> 4) * 2u + (c >> 5), ob = (r & 15u) * 64u + (c & 31u) * 2u; return (st * 1024u + (ob ^ (((ob >> 9) & 1u) << 5))) >> 1; }
; __host__ __device__ __forceinline__ unsigned img_off(unsigned row, unsigned col, unsigned KT) { return (((row >> 8) * KT + (col >> 6)) << 14) + (((row >> 7) & 1u) << 13) + hl_off(row & 127u, col & 63u); }
; __device__ __forceinline__ void conv_unit(const Args& a, LAS unsigned char* lds, int l, int tt) {
;     ...
;             for (int t = 0; t < 16; ++t) *(LAS unsigned*)(O + (tb + t) * CXS + 2 * cp) = pk2(a0[t], a1[t]);
;         }
;     }
;     __syncthreads();
;     {
;         const int row = tid >> 2, seg = tid & 3;
;         float v[8][8]; float s = 0.f;
; #pragma unroll
;         for (int j = 0; j < 8; ++j) { unpack8(*(const LAS u32x4*)(O + row * CXS + 64 * seg + 8 * j), v[j]);
; #pragma unroll
;             for (int e = 0; e < 8; ++e) s += v[j][e]; }
;         s += __shfl_xor(s, 1); s += __shfl_xor(s, 2);
;         const float mu = s * (1.0f / 256.0f);
;         float q = 0.f;
; #pragma unroll
;         for (int j = 0; j < 8; ++j) {
; #pragma unroll
;             for (int e = 0; e < 8; ++e) v[j][e] -= mu;
;             q += sum8sq(v[j]); }
;         q += __shfl_xor(q, 1); q += __shfl_xor(q, 2);
;         const float rstd = __builtin_amdgcn_rsqf(q * (1.0f / 256.0f) + EPS);
;         const LAS float* lgp = lnp + 64 * seg; const LAS float* lbp = lnp + 256 + 64 * seg;
;         bf16_t* dst = MIX + img_off((unsigned)(T.rowbase + T.t0 + row), (unsigned)(768 + 64 * seg), 16u);
;         const unsigned rl_ = (unsigned)((T.t0 + row) & 127), h0_ = hl_off(rl_, 0u);
	v_lshrrev_b32_e32 v70, 16, v70
	v_add3_u32 v71, v81, v71, s27
	v_and_or_b32 v70, v71, s6, v70
	v_add_u32_e32 v71, 0x800, v104
	ds_write2_b32 v71, v69, v70 offset0:16 offset1:148
	v_bfe_u32 v69, v84, 16, 1
	v_add3_u32 v69, v84, v69, s27
	v_bfe_u32 v70, v83, 16, 1
	v_lshrrev_b32_e32 v69, 16, v69
	v_add3_u32 v70, v83, v70, s27
	v_and_or_b32 v69, v70, s6, v69
	v_bfe_u32 v70, v86, 16, 1
	v_add3_u32 v70, v86, v70, s27
	v_bfe_u32 v71, v85, 16, 1
	v_lshrrev_b32_e32 v70, 16, v70
	v_add3_u32 v71, v85, v71, s27
	v_and_or_b32 v70, v71, s6, v70
	v_add_u32_e32 v71, 0xc00, v104
	ds_write2_b32 v71, v69, v70 offset0:24 offset1:156
	v_bfe_u32 v69, v88, 16, 1
	v_add3_u32 v69, v88, v69, s27
	v_bfe_u32 v70, v87, 16, 1
	v_lshrrev_b32_e32 v69, 16, v69
	v_add3_u32 v70, v87, v70, s27
	v_and_or_b32 v69, v70, s6, v69
	v_bfe_u32 v70, v90, 16, 1
	v_add3_u32 v70, v90, v70, s27
	v_bfe_u32 v71, v89, 16, 1
	v_lshrrev_b32_e32 v70, 16, v70
	v_add3_u32 v71, v89, v71, s27
	v_and_or_b32 v70, v71, s6, v70
	v_add_u32_e32 v71, 0x1000, v104
	ds_write2_b32 v71, v69, v70 offset0:32 offset1:164
	v_bfe_u32 v69, v92, 16, 1
	v_add3_u32 v69, v92, v69, s27
	v_bfe_u32 v70, v91, 16, 1
	v_lshrrev_b32_e32 v69, 16, v69
	v_add3_u32 v70, v91, v70, s27
	v_and_or_b32 v69, v70, s6, v69
	v_bfe_u32 v70, v94, 16, 1
	v_add3_u32 v70, v94, v70, s27
	v_bfe_u32 v71, v93, 16, 1
	v_lshrrev_b32_e32 v70, 16, v70
	v_add3_u32 v71, v93, v71, s27
	v_and_or_b32 v70, v71, s6, v70
	v_add_u32_e32 v71, 0x1400, v104
	ds_write2_b32 v71, v69, v70 offset0:40 offset1:172
	v_bfe_u32 v69, v97, 16, 1
	v_add3_u32 v69, v97, v69, s27
	v_bfe_u32 v70, v96, 16, 1
	v_lshrrev_b32_e32 v69, 16, v69
	v_add3_u32 v70, v96, v70, s27
	v_and_or_b32 v69, v70, s6, v69
	v_bfe_u32 v70, v99, 16, 1
	v_add3_u32 v70, v99, v70, s27
	v_bfe_u32 v71, v98, 16, 1
	v_lshrrev_b32_e32 v70, 16, v70
	v_add3_u32 v71, v98, v71, s27
	v_and_or_b32 v70, v71, s6, v70
	v_add_u32_e32 v71, 0x1800, v104
	ds_write2_b32 v71, v69, v70 offset0:48 offset1:180
	v_bfe_u32 v69, v101, 16, 1
	v_add3_u32 v69, v101, v69, s27
	v_bfe_u32 v70, v100, 16, 1
	v_lshrrev_b32_e32 v69, 16, v69
	v_add3_u32 v70, v100, v70, s27
	v_and_or_b32 v69, v70, s6, v69
	v_bfe_u32 v70, v103, 16, 1
	v_add3_u32 v70, v103, v70, s27
	v_bfe_u32 v71, v102, 16, 1
	v_lshrrev_b32_e32 v70, 16, v70
	v_add3_u32 v71, v102, v71, s27
	v_and_or_b32 v70, v71, s6, v70
	v_add_u32_e32 v71, 0x1c00, v104
	s_mov_b32 s4, 64
	ds_write2_b32 v71, v69, v70 offset0:56 offset1:188
	s_cbranch_vccnz .LBB0_764
	v_ashrrev_i32_e32 v30, 2, v95
	v_and_b32_e32 v31, 3, v95
	v_mul_lo_u32 v2, v30, s55
	v_lshlrev_b32_e32 v3, 7, v31
	v_readlane_b32 s0, v254, 6
	s_waitcnt lgkmcnt(0)
	s_barrier
	v_add3_u32 v26, s0, v2, v3
	ds_read_b128 v[2:5], v26
	ds_read_b128 v[6:9], v26 offset:16
	ds_read_b128 v[10:13], v26 offset:32
	ds_read_b128 v[14:17], v26 offset:48
	s_add_i32 s38, s38, s39
	s_waitcnt lgkmcnt(3)
	v_lshlrev_b32_e32 v144, 16, v2
	s_waitcnt lgkmcnt(2)
	v_lshlrev_b32_e32 v212, 16, v9
	v_and_b32_e32 v211, 0xffff0000, v9
	v_xor_b32_e32 v9, 1, v227
	v_cmp_lt_i32_e32 vcc, v9, v229
	v_and_b32_e32 v142, 0xffff0000, v2
	v_lshlrev_b32_e32 v145, 16, v3
	v_cndmask_b32_e32 v9, v227, v9, vcc
	v_and_b32_e32 v143, 0xffff0000, v3
	v_lshlrev_b32_e32 v150, 16, v4
	v_and_b32_e32 v148, 0xffff0000, v4
	v_lshlrev_b32_e32 v151, 16, v5
	v_and_b32_e32 v149, 0xffff0000, v5
	ds_read_b128 v[2:5], v26 offset:64
	ds_read_b128 v[18:21], v26 offset:80
	v_lshlrev_b32_e32 v214, 2, v9
	v_xor_b32_e32 v9, 2, v227
	v_cmp_lt_i32_e32 vcc, v9, v229
	s_waitcnt lgkmcnt(2)
	v_lshlrev_b32_e32 v210, 16, v15
	v_and_b32_e32 v100, 0xffff0000, v15
	v_cndmask_b32_e32 v9, v227, v9, vcc
	v_lshlrev_b32_e32 v213, 2, v9
	v_lshl_add_u32 v9, v31, 8, 0
	v_add_u32_e32 v203, 0x24400, v9
	v_add_u32_e32 v202, 0x24800, v9
	v_add_u32_e32 v9, s38, v30
	v_lshlrev_b32_e32 v15, 6, v30
	v_lshlrev_b32_e32 v140, 16, v10
	v_and_b32_e32 v130, 0xffff0000, v10
	v_lshlrev_b32_e32 v141, 16, v11
	v_and_b32_e32 v131, 0xffff0000, v11
	v_lshlrev_b32_e32 v120, 16, v17
	v_and_b32_e32 v116, 0xffff0000, v17
	s_waitcnt lgkmcnt(0)
	v_lshlrev_b32_e32 v208, 16, v21
	v_and_b32_e32 v205, 0xffff0000, v21
	v_lshrrev_b32_e32 v10, 4, v9
	s_mov_b32 s0, 0x3fff0
	v_lshlrev_b32_e32 v9, 6, v9
	v_lshlrev_b32_e32 v11, 5, v30
	v_and_b32_e32 v17, 0x1c00, v15
	v_lshlrev_b32_e32 v21, 1, v30
	v_and_or_b32 v10, v10, s0, v31
	v_and_b32_e32 v9, 0x2000, v9
	v_and_b32_e32 v11, 0x1e0, v11
	v_and_or_b32 v17, v21, 16, v17
	v_lshlrev_b32_e32 v10, 14, v10
	v_or3_b32 v9, v17, v11, v9
	s_mov_b32 s0, 0x30000
	v_or3_b32 v206, v10, v9, s0
	v_and_b32_e32 v9, 0x3c0, v15
	v_lshlrev_b32_e32 v10, 7, v30
	v_and_b32_e32 v11, 32, v95
	v_and_b32_e32 v10, 0x3800, v10
	v_or_b32_e32 v15, v9, v11
	v_or_b32_e32 v17, v15, v10
	v_lshrrev_b32_e32 v200, 1, v17
	v_add_f32_e32 v17, 0, v144
	v_add_f32_e32 v17, v17, v142
	v_add_f32_e32 v17, v17, v145
	v_add_f32_e32 v17, v17, v143
	v_add_f32_e32 v17, v17, v150
	v_add_f32_e32 v17, v17, v148
	v_add_f32_e32 v17, v17, v151
	v_add_f32_e32 v17, v17, v149
	v_lshlrev_b32_e32 v165, 16, v6
	v_lshlrev_b32_e32 v177, 16, v2
	v_and_b32_e32 v181, 0xffff0000, v2
	v_and_b32_e32 v167, 0xffff0000, v6
	v_add_f32_e32 v2, v17, v165
	v_add_f32_e32 v2, v2, v167
	v_lshlrev_b32_e32 v188, 16, v7
	v_and_b32_e32 v189, 0xffff0000, v7
	v_add_f32_e32 v2, v2, v188
	v_lshlrev_b32_e32 v164, 16, v8
	v_add_f32_e32 v2, v2, v189
	v_and_b32_e32 v166, 0xffff0000, v8
	v_add_f32_e32 v2, v2, v164
	v_add_f32_e32 v2, v2, v166
	v_add_f32_e32 v2, v2, v212
	v_or_b32_e32 v215, 16, v15
	v_lshlrev_b32_e32 v176, 16, v4
	v_and_b32_e32 v180, 0xffff0000, v4
	v_add_f32_e32 v4, v2, v211
	v_or_b32_e32 v2, v215, v10
	v_readlane_b32 s0, v253, 18
	v_lshrrev_b32_e32 v2, 1, v2
	v_readlane_b32 s1, v253, 19
; #define LAS __attribute__((address_space(3)))
; __device__ __forceinline__ float sum8sq(const float (&d)[8]) { return (d[0] * d[0] + d[1] * d[1]) + (d[2] * d[2] + d[3] * d[3]) + (d[4] * d[4] + d[5] * d[5]) + (d[6] * d[6] + d[7] * d[7]); }
; __host__ __device__ __forceinline__ unsigned hl_off(unsigned r, unsigned c) { const unsigned st = (r >> 4) * 2u + (c >> 5), ob = (r & 15u) * 64u + (c & 31u) * 2u; return (st * 1024u + (ob ^ (((ob >> 9) & 1u) << 5))) >> 1; }
; __host__ __device__ __forceinline__ unsigned img_off(unsigned row, unsigned col, unsigned KT) { return (((row >> 8) * KT + (col >> 6)) << 14) + (((row >> 7) & 1u) << 13) + hl_off(row & 127u, col & 63u); }
; __device__ __forceinline__ void conv_unit(const Args& a, LAS unsigned char* lds, int l, int tt) {
;     ...
;         float v[8][8]; float s = 0.f;
; #pragma unroll
;         for (int j = 0; j < 8; ++j) { unpack8(*(const LAS u32x4*)(O + row * CXS + 64 * seg + 8 * j), v[j]);
; #pragma unroll
;             for (int e = 0; e < 8; ++e) s += v[j][e]; }
;         s += __shfl_xor(s, 1); s += __shfl_xor(s, 2);
;         const float mu = s * (1.0f / 256.0f);
;         float q = 0.f;
; #pragma unroll
;         for (int j = 0; j < 8; ++j) {
; #pragma unroll
;             for (int e = 0; e < 8; ++e) v[j][e] -= mu;
;             q += sum8sq(v[j]); }
;         q += __shfl_xor(q, 1); q += __shfl_xor(q, 2);
;         const float rstd = __builtin_amdgcn_rsqf(q * (1.0f / 256.0f) + EPS);
;         const LAS float* lgp = lnp + 64 * seg; const LAS float* lbp = lnp + 256 + 64 * seg;
;         bf16_t* dst = MIX + img_off((unsigned)(T.rowbase + T.t0 + row), (unsigned)(768 + 64 * seg), 16u);
;         const unsigned rl_ = (unsigned)((T.t0 + row) & 127), h0_ = hl_off(rl_, 0u);
; #pragma unroll
;         for (int j = 0; j < 8; ++j) {
;             const f32x4 g0 = *(const LAS f32x4*)(lgp + 8 * j), g1 = *(const LAS f32x4*)(lgp + 8 * j + 4), b0 = *(const LAS f32x4*)(lbp + 8 * j), b1 = *(const LAS f32x4*)(lbp + 8 * j + 4);
	v_sub_u32_e32 v2, v2, v200
	v_lshlrev_b32_e32 v184, 16, v3
	v_lshl_add_u64 v[96:97], v[206:207], 1, s[0:1]
	v_and_b32_e32 v185, 0xffff0000, v3
	v_ashrrev_i32_e32 v3, 31, v2
	v_lshl_add_u64 v[114:115], v[2:3], 1, v[96:97]
	v_add_f32_e32 v2, v4, v140
	v_add_f32_e32 v2, v2, v130
	v_add_f32_e32 v2, v2, v141
	v_lshlrev_b32_e32 v155, 16, v12
	v_add_f32_e32 v2, v2, v131
	v_and_b32_e32 v157, 0xffff0000, v12
	v_add_f32_e32 v2, v2, v155
	v_lshlrev_b32_e32 v163, 16, v13
	v_add_f32_e32 v2, v2, v157
	v_and_b32_e32 v187, 0xffff0000, v13
	v_add_f32_e32 v2, v2, v163
	v_lshlrev_b32_e32 v154, 16, v14
	v_add_f32_e32 v2, v2, v187
	v_and_b32_e32 v156, 0xffff0000, v14
	v_add_f32_e32 v2, v2, v154
	v_add_f32_e32 v2, v2, v156
	v_add_f32_e32 v2, v2, v210
	v_lshlrev_b32_e32 v162, 16, v16
	v_add_f32_e32 v2, v2, v100
	v_and_b32_e32 v186, 0xffff0000, v16
	v_add_f32_e32 v2, v2, v162
	v_add_f32_e32 v2, v2, v186
	v_add_f32_e32 v2, v2, v120
	v_add_f32_e32 v2, v2, v116
	v_add_f32_e32 v2, v2, v177
	v_add_f32_e32 v2, v2, v181
	v_add_f32_e32 v2, v2, v184
	v_add_f32_e32 v2, v2, v185
	v_add_f32_e32 v2, v2, v176
	v_lshlrev_b32_e32 v174, 16, v5
	v_add_f32_e32 v2, v2, v180
	v_and_b32_e32 v175, 0xffff0000, v5
	v_add_f32_e32 v2, v2, v174
	v_lshlrev_b32_e32 v169, 16, v18
	v_add_f32_e32 v2, v2, v175
	v_and_b32_e32 v171, 0xffff0000, v18
	v_add_f32_e32 v2, v2, v169
	v_lshlrev_b32_e32 v172, 16, v19
	v_add_f32_e32 v2, v2, v171
	v_and_b32_e32 v173, 0xffff0000, v19
	v_add_f32_e32 v2, v2, v172
	v_lshlrev_b32_e32 v168, 16, v20
	v_add_f32_e32 v2, v2, v173
	v_and_b32_e32 v170, 0xffff0000, v20
	v_add_f32_e32 v2, v2, v168
	v_add_f32_e32 v2, v2, v170
	v_add_f32_e32 v2, v2, v208
	v_bitop3_b32 v209, v9, v95, 32 bitop3:0x72
	v_add_f32_e32 v12, v2, v205
	v_or_b32_e32 v2, v209, v10
	v_lshrrev_b32_e32 v2, 1, v2
	v_sub_u32_e32 v2, v2, v200
	ds_read_b128 v[22:25], v26 offset:96
	ds_read_b128 v[76:79], v203
	ds_read_b128 v[26:29], v26 offset:112
	ds_read_b128 v[80:83], v203 offset:16
	ds_read_b128 v[44:47], v203 offset:32
	ds_read_b128 v[30:33], v203 offset:48
	ds_read_b128 v[88:91], v202
	ds_read_b128 v[84:87], v202 offset:16
	ds_read_b128 v[48:51], v202 offset:32
	ds_read_b128 v[34:37], v202 offset:48
	ds_read_b128 v[66:69], v203 offset:64
	ds_read_b128 v[52:55], v203 offset:80
	ds_read_b128 v[70:73], v202 offset:64
	ds_read_b128 v[56:59], v202 offset:80
	v_ashrrev_i32_e32 v3, 31, v2
	ds_read_b128 v[60:63], v203 offset:96
	v_bitop3_b32 v204, v9, v11, 48 bitop3:0x36
	v_lshl_add_u64 v[106:107], v[2:3], 1, v[96:97]
	v_or_b32_e32 v2, v204, v10
	v_lshrrev_b32_e32 v2, 1, v2
	v_sub_u32_e32 v2, v2, v200
	v_ashrrev_i32_e32 v3, 31, v2
	s_waitcnt lgkmcnt(14)
	v_lshlrev_b32_e32 v108, 16, v22
	v_and_b32_e32 v104, 0xffff0000, v22
	v_lshlrev_b32_e32 v109, 16, v23
	v_and_b32_e32 v105, 0xffff0000, v23
	s_waitcnt lgkmcnt(10)
	v_mov_b32_e32 v134, v44
	v_mov_b32_e32 v135, v46
	v_mov_b32_e32 v46, v45
	s_waitcnt lgkmcnt(4)
	v_mov_b32_e32 v124, v66
	v_mov_b32_e32 v125, v68
	v_mov_b32_e32 v68, v67
	ds_read_b128 v[64:67], v202 offset:96
	ds_read_b128 v[38:41], v203 offset:112
	ds_read_b128 v[42:45], v202 offset:112
	s_waitcnt lgkmcnt(3)
	v_mov_b32_e32 v110, v60
	v_mov_b32_e32 v111, v62
	v_mov_b32_e32 v62, v61
	ds_read_b128 v[16:19], v203 offset:128
	v_lshl_add_u64 v[60:61], v[2:3], 1, v[96:97]
	ds_read_b128 v[20:23], v202 offset:128
	ds_read_b128 v[2:5], v203 offset:144
	ds_read_b128 v[6:9], v202 offset:144
	v_mov_b32_e32 v137, v50
	v_mov_b32_e32 v50, v49
	v_mov_b32_e32 v75, v78
	s_waitcnt lgkmcnt(1)
	v_mov_b32_e32 v49, v4
	v_mov_b32_e32 v4, v3
	v_add_f32_e32 v3, v12, v108
	v_add_f32_e32 v3, v3, v104
	v_add_f32_e32 v3, v3, v109
	v_mov_b32_e32 v78, v77
	v_lshlrev_b32_e32 v77, 16, v24
	v_add_f32_e32 v3, v3, v105
	v_and_b32_e32 v159, 0xffff0000, v24
	v_add_f32_e32 v3, v3, v77
	v_lshlrev_b32_e32 v147, 16, v25
	v_add_f32_e32 v3, v3, v159
	v_and_b32_e32 v161, 0xffff0000, v25
	v_add_f32_e32 v3, v3, v147
	v_mov_b32_e32 v74, v76
	v_lshlrev_b32_e32 v76, 16, v26
	v_add_f32_e32 v3, v3, v161
	v_and_b32_e32 v158, 0xffff0000, v26
	v_add_f32_e32 v3, v3, v76
	v_lshlrev_b32_e32 v201, 16, v27
	v_add_f32_e32 v3, v3, v158
	v_and_b32_e32 v98, 0xffff0000, v27
	v_add_f32_e32 v3, v3, v201
	v_lshlrev_b32_e32 v146, 16, v28
	v_add_f32_e32 v3, v3, v98
	v_and_b32_e32 v160, 0xffff0000, v28
	v_add_f32_e32 v3, v3, v146
	v_lshlrev_b32_e32 v138, 16, v29
	v_add_f32_e32 v3, v3, v160
	v_and_b32_e32 v94, 0xffff0000, v29
	v_add_f32_e32 v3, v3, v138
	v_mov_b32_e32 v122, v56
	s_waitcnt lgkmcnt(0)
	v_mov_b32_e32 v56, v6
	v_add_f32_e32 v6, v3, v94
	v_mov_b32_e32 v123, v58
	v_mov_b32_e32 v58, v57
	v_mov_b32_e32 v57, v8
	v_mov_b32_e32 v8, v7
	v_or_b32_e32 v206, 0x400, v10
	ds_bpermute_b32 v7, v214, v6
	v_mov_b32_e32 v136, v48
	v_mov_b32_e32 v48, v2
	v_or_b32_e32 v2, v15, v206
	v_lshrrev_b32_e32 v2, 1, v2
	v_sub_u32_e32 v2, v2, v200
	v_ashrrev_i32_e32 v3, 31, v2
	v_mov_b32_e32 v118, v52
	v_mov_b32_e32 v119, v54
	v_mov_b32_e32 v54, v53
	v_lshl_add_u64 v[52:53], v[2:3], 1, v[96:97]
	s_waitcnt lgkmcnt(0)
	v_add_f32_e32 v2, v6, v7
	ds_bpermute_b32 v3, v213, v2
	v_mov_b32_e32 v92, v88
	v_mov_b32_e32 v93, v90
	v_mov_b32_e32 v90, v89
	v_mov_b32_e32 v88, v80
	s_waitcnt lgkmcnt(0)
; #define LAS __attribute__((address_space(3)))
; __device__ __forceinline__ float sum8sq(const float (&d)[8]) { return (d[0] * d[0] + d[1] * d[1]) + (d[2] * d[2] + d[3] * d[3]) + (d[4] * d[4] + d[5] * d[5]) + (d[6] * d[6] + d[7] * d[7]); }
; __host__ __device__ __forceinline__ unsigned hl_off(unsigned r, unsigned c) { const unsigned st = (r >> 4) * 2u + (c >> 5), ob = (r & 15u) * 64u + (c & 31u) * 2u; return (st * 1024u + (ob ^ (((ob >> 9) & 1u) << 5))) >> 1; }
; __host__ __device__ __forceinline__ unsigned img_off(unsigned row, unsigned col, unsigned KT) { return (((row >> 8) * KT + (col >> 6)) << 14) + (((row >> 7) & 1u) << 13) + hl_off(row & 127u, col & 63u); }
; __device__ __forceinline__ void conv_unit(const Args& a, LAS unsigned char* lds, int l, int tt) {
;     ...
;             for (int e = 0; e < 8; ++e) s += v[j][e]; }
;         s += __shfl_xor(s, 1); s += __shfl_xor(s, 2);
;         const float mu = s * (1.0f / 256.0f);
;         float q = 0.f;
; #pragma unroll
;         for (int j = 0; j < 8; ++j) {
; #pragma unroll
;             for (int e = 0; e < 8; ++e) v[j][e] -= mu;
;             q += sum8sq(v[j]); }
;         q += __shfl_xor(q, 1); q += __shfl_xor(q, 2);
;         const float rstd = __builtin_amdgcn_rsqf(q * (1.0f / 256.0f) + EPS);
;         const LAS float* lgp = lnp + 64 * seg; const LAS float* lbp = lnp + 256 + 64 * seg;
;         bf16_t* dst = MIX + img_off((unsigned)(T.rowbase + T.t0 + row), (unsigned)(768 + 64 * seg), 16u);
;         const unsigned rl_ = (unsigned)((T.t0 + row) & 127), h0_ = hl_off(rl_, 0u);
; #pragma unroll
;         for (int j = 0; j < 8; ++j) {
;             const f32x4 g0 = *(const LAS f32x4*)(lgp + 8 * j), g1 = *(const LAS f32x4*)(lgp + 8 * j + 4), b0 = *(const LAS f32x4*)(lbp + 8 * j), b1 = *(const LAS f32x4*)(lbp + 8 * j + 4);
	v_add_f32_e32 v218, v2, v3
	v_mul_f32_e32 v216, 0x3b800000, v218
	v_mov_b32_e32 v89, v82
	v_mov_b32_e32 v82, v81
	v_pk_add_f32 v[80:81], v[142:143], v[216:217] op_sel_hi:[1,0] neg_lo:[0,1] neg_hi:[0,1]
	v_pk_add_f32 v[194:195], v[148:149], v[216:217] op_sel_hi:[1,0] neg_lo:[0,1] neg_hi:[0,1]
	v_mov_b32_e32 v126, v70
	v_mov_b32_e32 v127, v72
	v_mov_b32_e32 v72, v71
	v_mov_b32_e32 v70, v20
	v_mov_b32_e32 v71, v22
	v_mov_b32_e32 v22, v21
	v_pk_add_f32 v[198:199], v[144:145], v[216:217] op_sel_hi:[1,0] neg_lo:[0,1] neg_hi:[0,1]
	v_pk_add_f32 v[196:197], v[150:151], v[216:217] op_sel_hi:[1,0] neg_lo:[0,1] neg_hi:[0,1]
	v_mov_b32_e32 v20, v194
	v_mov_b32_e32 v21, v80
	v_mov_b32_e32 v6, v196
	v_mov_b32_e32 v7, v198
	v_pk_mul_f32 v[20:21], v[20:21], v[20:21]
	v_pk_add_f32 v[182:183], v[140:141], v[216:217] op_sel_hi:[1,0] neg_lo:[0,1] neg_hi:[0,1]
	v_pk_add_f32 v[178:179], v[130:131], v[216:217] op_sel_hi:[1,0] neg_lo:[0,1] neg_hi:[0,1]
	v_mov_b32_e32 v152, v84
	v_mov_b32_e32 v153, v86
	v_mov_b32_e32 v86, v85
	v_mov_b32_e32 v132, v34
	v_mov_b32_e32 v133, v36
	v_mov_b32_e32 v36, v35
	v_mov_b32_e32 v84, v38
	v_mov_b32_e32 v85, v40
	v_mov_b32_e32 v40, v39
	v_pk_fma_f32 v[6:7], v[6:7], v[6:7], v[20:21]
	v_pk_mul_f32 v[20:21], v[196:197], v[196:197]
	v_pk_mul_f32 v[34:35], v[182:183], v[182:183]
	v_pk_mul_f32 v[38:39], v[178:179], v[178:179]
	v_fmac_f32_e32 v100, 0xbb800000, v218
	v_mov_b32_e32 v121, v21
	v_add_f32_e32 v21, v34, v38
	v_mov_b32_e32 v101, v35
	v_mov_b32_e32 v34, v100
	v_mov_b32_e32 v35, v39
	v_pk_mul_f32 v[34:35], v[100:101], v[34:35]
	v_pk_fma_f32 v[38:39], v[182:183], v[182:183], v[38:39]
	v_fmac_f32_e32 v210, 0xbb800000, v218
	v_mov_b32_e32 v35, v39
	v_pk_add_f32 v[190:191], v[164:165], v[216:217] op_sel_hi:[1,0] neg_lo:[0,1] neg_hi:[0,1]
	v_pk_add_f32 v[164:165], v[156:157], v[216:217] op_sel_hi:[1,0] neg_lo:[0,1] neg_hi:[0,1]
	v_mul_f32_e32 v20, v210, v210
	v_pk_add_f32 v[192:193], v[188:189], v[216:217] op_sel_hi:[1,0] neg_lo:[0,1] neg_hi:[0,1]
	v_pk_add_f32 v[188:189], v[166:167], v[216:217] op_sel_hi:[1,0] neg_lo:[0,1] neg_hi:[0,1]
	v_pk_add_f32 v[166:167], v[154:155], v[216:217] op_sel_hi:[1,0] neg_lo:[0,1] neg_hi:[0,1]
	v_pk_add_f32 v[20:21], v[20:21], v[34:35]
	v_pk_mul_f32 v[34:35], v[164:165], v[164:165]
	v_mov_b32_e32 v2, v199
	v_mov_b32_e32 v3, v81
	v_pk_add_f32 v[150:151], v[186:187], v[216:217] op_sel_hi:[1,0] neg_lo:[0,1] neg_hi:[0,1]
	v_pk_fma_f32 v[34:35], v[166:167], v[166:167], v[34:35]
	v_pk_mul_f32 v[2:3], v[2:3], v[2:3]
	v_pk_add_f32 v[154:155], v[162:163], v[216:217] op_sel_hi:[1,0] neg_lo:[0,1] neg_hi:[0,1]
	v_pk_add_f32 v[20:21], v[34:35], v[20:21]
	v_pk_mul_f32 v[34:35], v[150:151], v[150:151]
	v_pk_mul_f32 v[38:39], v[194:195], v[194:195]
	v_fmac_f32_e32 v211, 0xbb800000, v218
	v_pk_fma_f32 v[34:35], v[154:155], v[154:155], v[34:35]
	v_add_f32_e32 v2, v2, v3
	v_pk_add_f32 v[20:21], v[34:35], v[20:21]
	v_mul_f32_e32 v34, v211, v211
	v_mov_b32_e32 v217, v39
	v_add_f32_e32 v2, v7, v2
	v_pk_add_f32 v[156:157], v[120:121], v[216:217] neg_lo:[0,1] neg_hi:[0,1]
	v_mov_b32_e32 v217, v34
	v_pk_mul_f32 v[34:35], v[192:193], v[192:193]
	v_add_f32_e32 v2, v6, v2
	v_pk_mul_f32 v[6:7], v[188:189], v[188:189]
	v_fmac_f32_e32 v212, 0xbb800000, v218
	v_pk_fma_f32 v[6:7], v[190:191], v[190:191], v[6:7]
	v_pk_fma_f32 v[38:39], v[196:197], v[196:197], v[38:39]
	v_add_f32_e32 v34, v34, v35
	v_mul_f32_e32 v117, v212, v212
	v_pk_add_f32 v[2:3], v[38:39], v[2:3] op_sel_hi:[1,0]
	v_pk_mul_f32 v[38:39], v[156:157], v[156:157]
	v_add_f32_e32 v7, v7, v34
	v_mov_b32_e32 v39, v3
	v_pk_add_f32 v[162:163], v[116:117], v[216:217] neg_lo:[0,1] neg_hi:[0,1]
	v_pk_add_f32 v[2:3], v[116:117], v[216:217]
	v_add_f32_e32 v6, v6, v7
	v_pk_mul_f32 v[34:35], v[162:163], v[162:163]
	v_pk_add_f32 v[2:3], v[2:3], v[6:7] op_sel_hi:[1,0]
	v_fmac_f32_e32 v205, 0xbb800000, v218
	v_mov_b32_e32 v35, v3
	v_pk_add_f32 v[2:3], v[38:39], v[34:35]
	v_pk_add_f32 v[148:149], v[184:185], v[216:217] op_sel_hi:[1,0] neg_lo:[0,1] neg_hi:[0,1]
	v_pk_add_f32 v[144:145], v[176:177], v[216:217] op_sel_hi:[1,0] neg_lo:[0,1] neg_hi:[0,1]
	v_pk_add_f32 v[140:141], v[180:181], v[216:217] op_sel_hi:[1,0] neg_lo:[0,1] neg_hi:[0,1]
	v_pk_add_f32 v[142:143], v[174:175], v[216:217] op_sel_hi:[1,0] neg_lo:[0,1] neg_hi:[0,1]
	v_pk_add_f32 v[130:131], v[172:173], v[216:217] op_sel_hi:[1,0] neg_lo:[0,1] neg_hi:[0,1]
	v_pk_add_f32 v[120:121], v[168:169], v[216:217] op_sel_hi:[1,0] neg_lo:[0,1] neg_hi:[0,1]
	v_pk_add_f32 v[116:117], v[170:171], v[216:217] op_sel_hi:[1,0] neg_lo:[0,1] neg_hi:[0,1]
	v_fmac_f32_e32 v208, 0xbb800000, v218
	v_mul_f32_e32 v217, v205, v205
	v_pk_add_f32 v[186:187], v[20:21], v[2:3]
	v_mul_f32_e32 v2, v149, v149
	v_pk_mul_f32 v[6:7], v[140:141], v[140:141]
	v_mul_f32_e32 v139, v208, v208
	v_pk_add_f32 v[108:109], v[108:109], v[216:217] op_sel_hi:[1,0] neg_lo:[0,1] neg_hi:[0,1]
	v_pk_add_f32 v[104:105], v[104:105], v[216:217] op_sel_hi:[1,0] neg_lo:[0,1] neg_hi:[0,1]
	v_mov_b32_e32 v102, v42
	v_mov_b32_e32 v103, v44
	v_mov_b32_e32 v44, v43
	v_pk_fma_f32 v[2:3], v[148:149], v[148:149], v[2:3] op_sel_hi:[1,1,0]
	v_pk_fma_f32 v[6:7], v[144:145], v[144:145], v[6:7]
	v_pk_mul_f32 v[168:169], v[108:109], v[108:109]
	v_pk_add_f32 v[42:43], v[76:77], v[216:217] op_sel_hi:[1,0] neg_lo:[0,1] neg_hi:[0,1]
	v_fmac_f32_e32 v98, 0xbb800000, v218
	v_pk_add_f32 v[34:35], v[138:139], v[216:217] neg_lo:[0,1] neg_hi:[0,1]
	v_pk_add_f32 v[76:77], v[138:139], v[216:217]
	v_pk_mul_f32 v[138:139], v[104:105], v[104:105]
	v_pk_add_f32 v[2:3], v[6:7], v[2:3] op_sel:[1,0] op_sel_hi:[0,1]
	v_pk_add_f32 v[38:39], v[158:159], v[216:217] op_sel_hi:[1,0] neg_lo:[0,1] neg_hi:[0,1]
	v_mov_b32_e32 v99, v169
	v_mov_b32_e32 v158, v98
	v_mov_b32_e32 v159, v139
	v_pk_add_f32 v[20:21], v[6:7], v[2:3]
	v_pk_add_f32 v[6:7], v[146:147], v[216:217] op_sel_hi:[1,0] neg_lo:[0,1] neg_hi:[0,1]
	v_add_f32_e32 v147, v168, v138
	v_pk_mul_f32 v[158:159], v[98:99], v[158:159]
	v_pk_fma_f32 v[138:139], v[108:109], v[108:109], v[138:139]
	v_fmac_f32_e32 v201, 0xbb800000, v218
	v_mov_b32_e32 v159, v139
	v_mul_f32_e32 v146, v201, v201
	v_mul_f32_e32 v2, v142, v142
	v_pk_add_f32 v[146:147], v[146:147], v[158:159]
	v_pk_mul_f32 v[158:159], v[38:39], v[38:39]
	v_pk_fma_f32 v[174:175], v[142:143], v[142:143], v[2:3] op_sel_hi:[1,1,0]
	v_pk_add_f32 v[2:3], v[160:161], v[216:217] op_sel_hi:[1,0] neg_lo:[0,1] neg_hi:[0,1]
	v_pk_fma_f32 v[158:159], v[42:43], v[42:43], v[158:159]
	v_mov_b32_e32 v128, v30
	v_pk_add_f32 v[146:147], v[158:159], v[146:147]
	v_pk_mul_f32 v[158:159], v[2:3], v[2:3]
	v_mov_b32_e32 v129, v32
	v_mov_b32_e32 v32, v31
	v_mov_b32_e32 v112, v64
	v_mov_b32_e32 v113, v66
	v_mov_b32_e32 v66, v65
	v_mov_b32_e32 v64, v16
	v_mov_b32_e32 v65, v18
	v_mov_b32_e32 v18, v17
	ds_read_b128 v[24:27], v203 offset:160
	ds_read_b128 v[10:13], v203 offset:176
	ds_read_b128 v[28:31], v202 offset:160
	ds_read_b128 v[14:17], v202 offset:176
	v_pk_fma_f32 v[158:159], v[6:7], v[6:7], v[158:159]
	s_waitcnt lgkmcnt(3)
; #define LAS __attribute__((address_space(3)))
; __device__ __forceinline__ u32x4 pack8(const float (&f)[8]) { u32x4 o; o.x = pk2(f[0], f[1]); o.y = pk2(f[2], f[3]); o.z = pk2(f[4], f[5]); o.w = pk2(f[6], f[7]); return o; }
; __host__ __device__ __forceinline__ unsigned hl_off(unsigned r, unsigned c) { const unsigned st = (r >> 4) * 2u + (c >> 5), ob = (r & 15u) * 64u + (c & 31u) * 2u; return (st * 1024u + (ob ^ (((ob >> 9) & 1u) << 5))) >> 1; }
; __host__ __device__ __forceinline__ unsigned img_off(unsigned row, unsigned col, unsigned KT) { return (((row >> 8) * KT + (col >> 6)) << 14) + (((row >> 7) & 1u) << 13) + hl_off(row & 127u, col & 63u); }
; __device__ __forceinline__ float fsig(float x) { return frcp(1.0f + __expf(-x)); }
; __device__ __forceinline__ void conv_unit(const Args& a, LAS unsigned char* lds, int l, int tt) {
;     ...
;         q += __shfl_xor(q, 1); q += __shfl_xor(q, 2);
;         const float rstd = __builtin_amdgcn_rsqf(q * (1.0f / 256.0f) + EPS);
;         const LAS float* lgp = lnp + 64 * seg; const LAS float* lbp = lnp + 256 + 64 * seg;
;         bf16_t* dst = MIX + img_off((unsigned)(T.rowbase + T.t0 + row), (unsigned)(768 + 64 * seg), 16u);
;         const unsigned rl_ = (unsigned)((T.t0 + row) & 127), h0_ = hl_off(rl_, 0u);
; #pragma unroll
;         for (int j = 0; j < 8; ++j) {
;             const f32x4 g0 = *(const LAS f32x4*)(lgp + 8 * j), g1 = *(const LAS f32x4*)(lgp + 8 * j + 4), b0 = *(const LAS f32x4*)(lbp + 8 * j), b1 = *(const LAS f32x4*)(lbp + 8 * j + 4);
;             float y[8];
; #pragma unroll
;             for (int e = 0; e < 4; ++e) { y[e] = v[j][e] * rstd * g0[e] + b0[e]; y[4 + e] = v[j][4 + e] * rstd * g1[e] + b1[e]; }
; #pragma unroll
;             for (int e = 0; e < 8; ++e) y[e] = y[e] * fsig(y[e]);
;             *(u32x4*)(dst + ((int)hl_off(rl_, 8u * j) - (int)h0_)) = pack8(y);
	v_mov_b32_e32 v138, v24
	v_pk_add_f32 v[158:159], v[158:159], v[146:147]
	v_pk_mul_f32 v[146:147], v[130:131], v[130:131]
	v_mov_b32_e32 v217, v20
	v_add_f32_e32 v24, v146, v147
	v_pk_mul_f32 v[146:147], v[116:117], v[116:117]
	v_mov_b32_e32 v95, v175
	v_pk_fma_f32 v[146:147], v[120:121], v[120:121], v[146:147]
	v_pk_add_f32 v[20:21], v[94:95], v[216:217] neg_lo:[0,1] neg_hi:[0,1]
	v_add_f32_e32 v24, v147, v24
	v_add_f32_e32 v24, v146, v24
	v_pk_add_f32 v[94:95], v[174:175], v[216:217]
	v_mov_b32_e32 v139, v26
	v_pk_add_f32 v[76:77], v[76:77], v[24:25] op_sel_hi:[1,0]
	v_mov_b32_e32 v26, v25
	v_pk_add_f32 v[24:25], v[186:187], v[186:187] op_sel_hi:[0,1]
	v_pk_mul_f32 v[160:161], v[34:35], v[34:35]
	s_waitcnt lgkmcnt(1)
	v_mov_b32_e32 v146, v28
	v_mov_b32_e32 v147, v30
	v_mov_b32_e32 v30, v29
	v_pk_add_f32 v[24:25], v[94:95], v[24:25]
	v_pk_mul_f32 v[28:29], v[20:21], v[20:21]
	v_mov_b32_e32 v161, v77
	v_mov_b32_e32 v29, v25
	v_pk_add_f32 v[24:25], v[160:161], v[28:29]
	s_waitcnt lgkmcnt(0)
	v_mov_b32_e32 v28, v14
	v_pk_add_f32 v[24:25], v[158:159], v[24:25]
	v_mov_b32_e32 v29, v16
	v_add_f32_e32 v21, v24, v25
	ds_bpermute_b32 v35, v214, v21
	v_mov_b32_e32 v24, v10
	v_mov_b32_e32 v25, v12
	v_mov_b32_e32 v12, v11
	v_or_b32_e32 v11, v215, v206
	s_waitcnt lgkmcnt(0)
	v_add_f32_e32 v10, v21, v35
	ds_bpermute_b32 v14, v213, v10
	v_lshrrev_b32_e32 v11, 1, v11
	v_mov_b32_e32 v16, v15
	s_mov_b64 s[0:1], 0
	s_waitcnt lgkmcnt(0)
	v_add_f32_e32 v10, v10, v14
	v_fmamk_f32 v10, v10, 0x3b800000, v222
	v_rsq_f32_e32 v10, v10
	v_sub_u32_e32 v14, v11, v200
	v_ashrrev_i32_e32 v15, 31, v14
	v_lshl_add_u64 v[14:15], v[14:15], 1, v[96:97]
	v_pk_mul_f32 v[76:77], v[198:199], v[10:11] op_sel_hi:[1,0]
	v_pk_mul_f32 v[160:161], v[196:197], v[10:11] op_sel_hi:[1,0]
	v_pk_fma_f32 v[158:159], v[74:75], v[76:77], v[92:93]
	v_pk_mul_f32 v[80:81], v[80:81], v[10:11] op_sel_hi:[1,0]
	v_pk_fma_f32 v[152:153], v[88:89], v[160:161], v[152:153]
	v_pk_fma_f32 v[160:161], v[78:79], v[80:81], v[90:91]
	v_pk_mul_f32 v[168:169], v[194:195], v[10:11] op_sel_hi:[1,0]
	v_mul_f32_e32 v11, 0xbfb8aa3b, v158
	v_exp_f32_e32 v11, v11
	v_mul_f32_e32 v21, 0xbfb8aa3b, v160
	v_exp_f32_e32 v21, v21
	v_pk_fma_f32 v[82:83], v[82:83], v[168:169], v[86:87]
	v_add_f32_e32 v11, 1.0, v11
	v_rcp_f32_e32 v86, v11
	v_add_f32_e32 v11, 1.0, v21
	v_mul_f32_e32 v21, 0xbfb8aa3b, v159
	v_exp_f32_e32 v21, v21
	v_mul_f32_e32 v35, 0xbfb8aa3b, v161
	v_exp_f32_e32 v35, v35
	v_rcp_f32_e32 v168, v11
	v_add_f32_e32 v11, 1.0, v21
	v_mul_f32_e32 v21, 0xbfb8aa3b, v152
	v_rcp_f32_e32 v87, v11
	v_add_f32_e32 v11, 1.0, v35
	v_exp_f32_e32 v21, v21
	v_mul_f32_e32 v35, 0xbfb8aa3b, v82
	v_exp_f32_e32 v35, v35
	v_rcp_f32_e32 v169, v11
	v_add_f32_e32 v11, 1.0, v21
	v_mul_f32_e32 v21, 0xbfb8aa3b, v153
	v_rcp_f32_e32 v170, v11
	v_add_f32_e32 v11, 1.0, v35
	v_exp_f32_e32 v21, v21
	v_mul_f32_e32 v35, 0xbfb8aa3b, v83
	v_exp_f32_e32 v35, v35
	v_rcp_f32_e32 v172, v11
	v_add_f32_e32 v11, 1.0, v21
	v_rcp_f32_e32 v171, v11
	v_add_f32_e32 v11, 1.0, v35
	v_rcp_f32_e32 v173, v11
	v_pk_mul_f32 v[86:87], v[158:159], v[86:87]
	v_pk_mul_f32 v[158:159], v[160:161], v[168:169]
	v_pk_mul_f32 v[152:153], v[152:153], v[170:171]
	v_pk_mul_f32 v[82:83], v[82:83], v[172:173]
	v_bfe_u32 v35, v159, 16, 1
	v_bfe_u32 v11, v83, 16, 1
	v_bfe_u32 v21, v82, 16, 1
	v_add3_u32 v21, v82, v21, s27
	v_add3_u32 v11, v83, v11, s27
	v_bfe_u32 v82, v86, 16, 1
	v_bfe_u32 v83, v87, 16, 1
	v_bfe_u32 v99, v158, 16, 1
	v_add3_u32 v83, v87, v83, s27
	v_add3_u32 v82, v86, v82, s27
	v_add3_u32 v99, v158, v99, s27
	v_add3_u32 v35, v159, v35, s27
	v_bfe_u32 v101, v152, 16, 1
	v_bfe_u32 v157, v153, 16, 1
	v_lshrrev_b32_e32 v82, 16, v82
	v_lshrrev_b32_e32 v83, 16, v83
	v_add3_u32 v153, v153, v157, s27
	v_add3_u32 v101, v152, v101, s27
	v_and_or_b32 v159, v35, s6, v83
	v_and_or_b32 v158, v99, s6, v82
	v_pk_mov_b32 v[82:83], v[190:191], v[192:193] op_sel:[1,0]
	v_lshrrev_b32_e32 v86, 16, v101
	v_lshrrev_b32_e32 v87, 16, v153
	v_pk_mul_f32 v[82:83], v[82:83], v[10:11] op_sel_hi:[1,0]
	v_mov_b32_e32 v192, v189
	v_and_or_b32 v161, v11, s6, v87
	v_and_or_b32 v160, v21, s6, v86
	v_pk_fma_f32 v[82:83], v[134:135], v[82:83], v[136:137]
	v_pk_mul_f32 v[86:87], v[192:193], v[10:11] op_sel_hi:[1,0]
	v_mul_f32_e32 v11, 0xbfb8aa3b, v82
	v_pk_fma_f32 v[46:47], v[46:47], v[86:87], v[50:51]
	v_exp_f32_e32 v11, v11
	v_mul_f32_e32 v21, 0xbfb8aa3b, v46
	v_exp_f32_e32 v21, v21
	v_mul_f32_e32 v35, 0xbfb8aa3b, v47
	v_add_f32_e32 v11, 1.0, v11
	v_rcp_f32_e32 v50, v11
	v_add_f32_e32 v11, 1.0, v21
	v_mul_f32_e32 v21, 0xbfb8aa3b, v83
	v_exp_f32_e32 v21, v21
	v_exp_f32_e32 v35, v35
	v_rcp_f32_e32 v86, v11
	v_mov_b32_e32 v191, v212
	v_add_f32_e32 v11, 1.0, v21
	v_rcp_f32_e32 v51, v11
	v_add_f32_e32 v11, 1.0, v35
	v_pk_mul_f32 v[134:135], v[190:191], v[10:11] op_sel_hi:[1,0]
	v_mov_b32_e32 v189, v211
	v_pk_fma_f32 v[128:129], v[128:129], v[134:135], v[132:133]
	v_pk_mul_f32 v[132:133], v[188:189], v[10:11] op_sel_hi:[1,0]
	v_mul_f32_e32 v21, 0xbfb8aa3b, v128
	v_pk_fma_f32 v[32:33], v[32:33], v[132:133], v[36:37]
	v_exp_f32_e32 v21, v21
	v_mul_f32_e32 v35, 0xbfb8aa3b, v32
	v_exp_f32_e32 v35, v35
	v_rcp_f32_e32 v87, v11
	v_add_f32_e32 v11, 1.0, v21
	v_mul_f32_e32 v21, 0xbfb8aa3b, v129
	v_rcp_f32_e32 v36, v11
	v_add_f32_e32 v11, 1.0, v35
	v_exp_f32_e32 v21, v21
	v_mul_f32_e32 v35, 0xbfb8aa3b, v33
	v_exp_f32_e32 v35, v35
	v_rcp_f32_e32 v132, v11
	v_add_f32_e32 v11, 1.0, v21
	v_rcp_f32_e32 v37, v11
	v_add_f32_e32 v11, 1.0, v35
	v_rcp_f32_e32 v133, v11
	v_pk_mul_f32 v[50:51], v[82:83], v[50:51]
	v_pk_mul_f32 v[46:47], v[46:47], v[86:87]
	v_pk_mul_f32 v[36:37], v[128:129], v[36:37]
	v_pk_mul_f32 v[32:33], v[32:33], v[132:133]
; #define LAS __attribute__((address_space(3)))
; __device__ __forceinline__ u32x4 pack8(const float (&f)[8]) { u32x4 o; o.x = pk2(f[0], f[1]); o.y = pk2(f[2], f[3]); o.z = pk2(f[4], f[5]); o.w = pk2(f[6], f[7]); return o; }
; __host__ __device__ __forceinline__ unsigned hl_off(unsigned r, unsigned c) { const unsigned st = (r >> 4) * 2u + (c >> 5), ob = (r & 15u) * 64u + (c & 31u) * 2u; return (st * 1024u + (ob ^ (((ob >> 9) & 1u) << 5))) >> 1; }
; __device__ __forceinline__ float fsig(float x) { return frcp(1.0f + __expf(-x)); }
; __device__ __forceinline__ void conv_unit(const Args& a, LAS unsigned char* lds, int l, int tt) {
;     ...
;         for (int j = 0; j < 8; ++j) {
;             const f32x4 g0 = *(const LAS f32x4*)(lgp + 8 * j), g1 = *(const LAS f32x4*)(lgp + 8 * j + 4), b0 = *(const LAS f32x4*)(lbp + 8 * j), b1 = *(const LAS f32x4*)(lbp + 8 * j + 4);
;             float y[8];
; #pragma unroll
;             for (int e = 0; e < 4; ++e) { y[e] = v[j][e] * rstd * g0[e] + b0[e]; y[4 + e] = v[j][4 + e] * rstd * g1[e] + b1[e]; }
; #pragma unroll
;             for (int e = 0; e < 8; ++e) y[e] = y[e] * fsig(y[e]);
;             *(u32x4*)(dst + ((int)hl_off(rl_, 8u * j) - (int)h0_)) = pack8(y);
	v_bfe_u32 v35, v47, 16, 1
	v_bfe_u32 v11, v33, 16, 1
	v_bfe_u32 v21, v32, 16, 1
	v_bfe_u32 v82, v46, 16, 1
	v_add3_u32 v21, v32, v21, s27
	v_add3_u32 v11, v33, v11, s27
	v_bfe_u32 v32, v50, 16, 1
	v_bfe_u32 v33, v51, 16, 1
	v_add3_u32 v46, v46, v82, s27
	v_add3_u32 v35, v47, v35, s27
	v_bfe_u32 v47, v36, 16, 1
	v_bfe_u32 v82, v37, 16, 1
	v_add3_u32 v33, v51, v33, s27
	v_add3_u32 v32, v50, v32, s27
	v_add3_u32 v37, v37, v82, s27
	v_add3_u32 v36, v36, v47, s27
	v_lshrrev_b32_e32 v32, 16, v32
	v_lshrrev_b32_e32 v33, 16, v33
	v_lshrrev_b32_e32 v36, 16, v36
	v_lshrrev_b32_e32 v37, 16, v37
	v_and_or_b32 v133, v35, s6, v33
	v_and_or_b32 v132, v46, s6, v32
	v_pk_mul_f32 v[32:33], v[182:183], v[10:11] op_sel_hi:[1,0]
	v_and_or_b32 v135, v11, s6, v37
	v_and_or_b32 v134, v21, s6, v36
	v_pk_fma_f32 v[32:33], v[124:125], v[32:33], v[126:127]
	v_pk_mul_f32 v[36:37], v[178:179], v[10:11] op_sel_hi:[1,0]
	v_mul_f32_e32 v11, 0xbfb8aa3b, v32
	v_pk_fma_f32 v[36:37], v[68:69], v[36:37], v[72:73]
	v_exp_f32_e32 v11, v11
	v_mul_f32_e32 v21, 0xbfb8aa3b, v36
	v_exp_f32_e32 v21, v21
	v_mul_f32_e32 v35, 0xbfb8aa3b, v37
	v_add_f32_e32 v11, 1.0, v11
	v_rcp_f32_e32 v46, v11
	v_add_f32_e32 v11, 1.0, v21
	v_mul_f32_e32 v21, 0xbfb8aa3b, v33
	v_exp_f32_e32 v21, v21
	v_exp_f32_e32 v35, v35
	v_rcp_f32_e32 v50, v11
	v_mov_b32_e32 v68, v167
	v_add_f32_e32 v11, 1.0, v21
	v_rcp_f32_e32 v47, v11
	v_add_f32_e32 v11, 1.0, v35
	v_mov_b32_e32 v69, v155
	v_pk_mul_f32 v[68:69], v[68:69], v[10:11] op_sel_hi:[1,0]
	v_mov_b32_e32 v72, v165
	v_mov_b32_e32 v73, v151
	v_pk_fma_f32 v[68:69], v[118:119], v[68:69], v[122:123]
	v_pk_mul_f32 v[72:73], v[72:73], v[10:11] op_sel_hi:[1,0]
	v_mul_f32_e32 v21, 0xbfb8aa3b, v68
	v_pk_fma_f32 v[54:55], v[54:55], v[72:73], v[58:59]
	v_exp_f32_e32 v21, v21
	v_mul_f32_e32 v35, 0xbfb8aa3b, v54
	v_exp_f32_e32 v35, v35
	v_rcp_f32_e32 v51, v11
	v_add_f32_e32 v11, 1.0, v21
	v_mul_f32_e32 v21, 0xbfb8aa3b, v69
	v_rcp_f32_e32 v58, v11
	v_add_f32_e32 v11, 1.0, v35
	v_exp_f32_e32 v21, v21
	v_mul_f32_e32 v35, 0xbfb8aa3b, v55
	v_exp_f32_e32 v35, v35
	v_rcp_f32_e32 v72, v11
	v_add_f32_e32 v11, 1.0, v21
	v_rcp_f32_e32 v59, v11
	v_add_f32_e32 v11, 1.0, v35
	v_rcp_f32_e32 v73, v11
	v_pk_mul_f32 v[36:37], v[36:37], v[50:51]
	v_pk_mul_f32 v[32:33], v[32:33], v[46:47]
	v_bfe_u32 v35, v37, 16, 1
	v_pk_mul_f32 v[50:51], v[54:55], v[72:73]
	v_pk_mul_f32 v[46:47], v[68:69], v[58:59]
	v_bfe_u32 v21, v50, 16, 1
	v_bfe_u32 v11, v51, 16, 1
	v_add3_u32 v35, v37, v35, s27
	v_add3_u32 v21, v50, v21, s27
	v_bfe_u32 v37, v32, 16, 1
	v_bfe_u32 v50, v33, 16, 1
	v_bfe_u32 v54, v36, 16, 1
	v_add3_u32 v11, v51, v11, s27
	v_bfe_u32 v51, v46, 16, 1
	v_add3_u32 v33, v33, v50, s27
	v_add3_u32 v32, v32, v37, s27
	v_add3_u32 v36, v36, v54, s27
	v_bfe_u32 v54, v47, 16, 1
	v_add3_u32 v46, v46, v51, s27
	v_lshrrev_b32_e32 v32, 16, v32
	v_lshrrev_b32_e32 v33, 16, v33
	v_mov_b32_e32 v167, v210
	v_add3_u32 v47, v47, v54, s27
	v_lshrrev_b32_e32 v37, 16, v46
	v_and_or_b32 v123, v35, s6, v33
	v_and_or_b32 v122, v36, s6, v32
	v_pk_mul_f32 v[32:33], v[166:167], v[10:11] op_sel_hi:[1,0]
	v_mov_b32_e32 v165, v100
	v_lshrrev_b32_e32 v46, 16, v47
	v_and_or_b32 v124, v21, s6, v37
	v_pk_fma_f32 v[32:33], v[110:111], v[32:33], v[112:113]
	v_pk_mul_f32 v[36:37], v[164:165], v[10:11] op_sel_hi:[1,0]
	v_and_or_b32 v125, v11, s6, v46
	v_pk_fma_f32 v[36:37], v[62:63], v[36:37], v[66:67]
	v_mul_f32_e32 v11, 0xbfb8aa3b, v32
	v_exp_f32_e32 v11, v11
	v_mul_f32_e32 v21, 0xbfb8aa3b, v36
	v_exp_f32_e32 v21, v21
	v_mul_f32_e32 v35, 0xbfb8aa3b, v37
	v_add_f32_e32 v11, 1.0, v11
	v_rcp_f32_e32 v46, v11
	v_add_f32_e32 v11, 1.0, v21
	v_mul_f32_e32 v21, 0xbfb8aa3b, v33
	v_exp_f32_e32 v21, v21
	v_exp_f32_e32 v35, v35
	v_rcp_f32_e32 v50, v11
	v_mov_b32_e32 v155, v156
	v_add_f32_e32 v11, 1.0, v21
	v_rcp_f32_e32 v47, v11
	v_add_f32_e32 v11, 1.0, v35
	v_pk_mul_f32 v[54:55], v[154:155], v[10:11] op_sel_hi:[1,0]
	v_mov_b32_e32 v151, v162
	v_pk_fma_f32 v[54:55], v[84:85], v[54:55], v[102:103]
	v_pk_mul_f32 v[58:59], v[150:151], v[10:11] op_sel_hi:[1,0]
	v_mul_f32_e32 v21, 0xbfb8aa3b, v54
	v_pk_fma_f32 v[40:41], v[40:41], v[58:59], v[44:45]
	v_exp_f32_e32 v21, v21
	v_mul_f32_e32 v35, 0xbfb8aa3b, v40
	v_exp_f32_e32 v35, v35
	v_rcp_f32_e32 v51, v11
	v_add_f32_e32 v11, 1.0, v21
	v_mul_f32_e32 v21, 0xbfb8aa3b, v55
	v_rcp_f32_e32 v44, v11
	v_add_f32_e32 v11, 1.0, v35
	v_exp_f32_e32 v21, v21
	v_mul_f32_e32 v35, 0xbfb8aa3b, v41
	v_exp_f32_e32 v35, v35
	v_rcp_f32_e32 v58, v11
	v_add_f32_e32 v11, 1.0, v21
	v_rcp_f32_e32 v45, v11
	v_add_f32_e32 v11, 1.0, v35
	v_rcp_f32_e32 v59, v11
	v_pk_mul_f32 v[36:37], v[36:37], v[50:51]
	v_pk_mul_f32 v[32:33], v[32:33], v[46:47]
	v_bfe_u32 v35, v37, 16, 1
	v_pk_mul_f32 v[40:41], v[40:41], v[58:59]
	v_pk_mul_f32 v[44:45], v[54:55], v[44:45]
	v_bfe_u32 v21, v40, 16, 1
	v_bfe_u32 v46, v36, 16, 1
	v_add3_u32 v35, v37, v35, s27
	v_add3_u32 v21, v40, v21, s27
	v_bfe_u32 v37, v32, 16, 1
	v_bfe_u32 v40, v33, 16, 1
	v_bfe_u32 v11, v41, 16, 1
	v_add3_u32 v36, v36, v46, s27
	v_bfe_u32 v46, v45, 16, 1
	v_add3_u32 v33, v33, v40, s27
	v_add3_u32 v32, v32, v37, s27
	v_add3_u32 v11, v41, v11, s27
	v_bfe_u32 v41, v44, 16, 1
	v_add3_u32 v45, v45, v46, s27
	v_lshrrev_b32_e32 v32, 16, v32
	v_lshrrev_b32_e32 v33, 16, v33
	v_add3_u32 v41, v44, v41, s27
	v_lshrrev_b32_e32 v40, 16, v45
	v_and_or_b32 v45, v35, s6, v33
	v_and_or_b32 v44, v36, s6, v32
	v_pk_mov_b32 v[32:33], v[144:145], v[148:149] op_sel:[1,0]
	v_lshrrev_b32_e32 v37, 16, v41
	v_pk_mul_f32 v[32:33], v[32:33], v[10:11] op_sel_hi:[1,0]
	v_mov_b32_e32 v148, v141
	v_and_or_b32 v46, v21, s6, v37
	v_pk_fma_f32 v[32:33], v[64:65], v[32:33], v[70:71]
; #define LAS __attribute__((address_space(3)))
; __device__ __forceinline__ u32x4 pack8(const float (&f)[8]) { u32x4 o; o.x = pk2(f[0], f[1]); o.y = pk2(f[2], f[3]); o.z = pk2(f[4], f[5]); o.w = pk2(f[6], f[7]); return o; }
; __host__ __device__ __forceinline__ unsigned hl_off(unsigned r, unsigned c) { const unsigned st = (r >> 4) * 2u + (c >> 5), ob = (r & 15u) * 64u + (c & 31u) * 2u; return (st * 1024u + (ob ^ (((ob >> 9) & 1u) << 5))) >> 1; }
; __device__ __forceinline__ float fsig(float x) { return frcp(1.0f + __expf(-x)); }
; __device__ __forceinline__ void conv_unit(const Args& a, LAS unsigned char* lds, int l, int tt) {
;     ...
;         for (int j = 0; j < 8; ++j) {
;             const f32x4 g0 = *(const LAS f32x4*)(lgp + 8 * j), g1 = *(const LAS f32x4*)(lgp + 8 * j + 4), b0 = *(const LAS f32x4*)(lbp + 8 * j), b1 = *(const LAS f32x4*)(lbp + 8 * j + 4);
;             float y[8];
; #pragma unroll
;             for (int e = 0; e < 4; ++e) { y[e] = v[j][e] * rstd * g0[e] + b0[e]; y[4 + e] = v[j][4 + e] * rstd * g1[e] + b1[e]; }
; #pragma unroll
;             for (int e = 0; e < 8; ++e) y[e] = y[e] * fsig(y[e]);
;             *(u32x4*)(dst + ((int)hl_off(rl_, 8u * j) - (int)h0_)) = pack8(y);
;         }
;     }
;     __syncthreads();
	v_pk_mul_f32 v[36:37], v[148:149], v[10:11] op_sel_hi:[1,0]
	v_and_or_b32 v47, v11, s6, v40
	v_pk_fma_f32 v[18:19], v[18:19], v[36:37], v[22:23]
	v_mul_f32_e32 v11, 0xbfb8aa3b, v32
	v_exp_f32_e32 v11, v11
	v_mul_f32_e32 v21, 0xbfb8aa3b, v18
	v_exp_f32_e32 v21, v21
	v_mul_f32_e32 v23, 0xbfb8aa3b, v19
	v_add_f32_e32 v11, 1.0, v11
	v_rcp_f32_e32 v22, v11
	v_add_f32_e32 v11, 1.0, v21
	v_mul_f32_e32 v21, 0xbfb8aa3b, v33
	v_exp_f32_e32 v21, v21
	v_exp_f32_e32 v35, v23
	v_rcp_f32_e32 v36, v11
	v_mov_b32_e32 v141, v143
	v_add_f32_e32 v11, 1.0, v21
	v_rcp_f32_e32 v23, v11
	v_add_f32_e32 v11, 1.0, v35
	ds_read_b128 v[92:95], v203 offset:192
	ds_read_b128 v[74:77], v203 offset:208
	ds_read_b128 v[88:91], v202 offset:192
	ds_read_b128 v[78:81], v202 offset:208
	global_store_dwordx4 v[96:97], v[158:161], off sc0 sc1
	global_store_dwordx4 v[114:115], v[132:135], off sc0 sc1
	global_store_dwordx4 v[106:107], v[122:125], off sc0 sc1
	global_store_dwordx4 v[60:61], v[44:47], off sc0 sc1
	v_mov_b32_e32 v145, v142
	v_pk_mul_f32 v[40:41], v[144:145], v[10:11] op_sel_hi:[1,0]
	v_pk_mul_f32 v[44:45], v[140:141], v[10:11] op_sel_hi:[1,0]
	v_pk_fma_f32 v[40:41], v[48:49], v[40:41], v[56:57]
	v_pk_fma_f32 v[4:5], v[4:5], v[44:45], v[8:9]
	v_mul_f32_e32 v8, 0xbfb8aa3b, v40
	v_mul_f32_e32 v9, 0xbfb8aa3b, v4
	v_exp_f32_e32 v9, v9
	v_rcp_f32_e32 v37, v11
	v_mul_f32_e32 v11, 0xbfb8aa3b, v41
	v_mul_f32_e32 v21, 0xbfb8aa3b, v5
	v_exp_f32_e32 v8, v8
	v_exp_f32_e32 v11, v11
	v_exp_f32_e32 v21, v21
	v_add_f32_e32 v9, 1.0, v9
	v_add_f32_e32 v8, 1.0, v8
	v_rcp_f32_e32 v44, v9
	v_add_f32_e32 v9, 1.0, v11
	v_add_f32_e32 v11, 1.0, v21
	v_rcp_f32_e32 v8, v8
	v_rcp_f32_e32 v9, v9
	v_rcp_f32_e32 v45, v11
	v_pk_mul_f32 v[18:19], v[18:19], v[36:37]
	v_pk_mul_f32 v[22:23], v[32:33], v[22:23]
	v_pk_mul_f32 v[8:9], v[40:41], v[8:9]
	v_pk_mul_f32 v[4:5], v[4:5], v[44:45]
	v_bfe_u32 v32, v19, 16, 1
	v_bfe_u32 v33, v18, 16, 1
	v_bfe_u32 v11, v5, 16, 1
	v_add3_u32 v18, v18, v33, s27
	v_add3_u32 v19, v19, v32, s27
	v_bfe_u32 v32, v8, 16, 1
	v_bfe_u32 v33, v9, 16, 1
	v_bfe_u32 v21, v4, 16, 1
	v_add3_u32 v5, v5, v11, s27
	v_bfe_u32 v11, v22, 16, 1
	v_add3_u32 v9, v9, v33, s27
	v_add3_u32 v8, v8, v32, s27
	v_add3_u32 v4, v4, v21, s27
	v_add3_u32 v11, v22, v11, s27
	v_lshrrev_b32_e32 v8, 16, v8
	v_lshrrev_b32_e32 v9, 16, v9
	v_lshrrev_b32_e32 v11, 16, v11
	v_and_or_b32 v47, v5, s6, v9
	v_and_or_b32 v46, v4, s6, v8
	v_pk_mov_b32 v[4:5], v[120:121], v[130:131] op_sel:[1,0]
	v_mov_b32_e32 v130, v117
	v_pk_mul_f32 v[4:5], v[4:5], v[10:11] op_sel_hi:[1,0]
	v_bfe_u32 v21, v23, 16, 1
	v_pk_fma_f32 v[4:5], v[138:139], v[4:5], v[146:147]
	v_pk_mul_f32 v[8:9], v[130:131], v[10:11] op_sel_hi:[1,0]
	v_add3_u32 v21, v23, v21, s27
	v_and_or_b32 v44, v18, s6, v11
	v_pk_fma_f32 v[8:9], v[26:27], v[8:9], v[30:31]
	v_mul_f32_e32 v11, 0xbfb8aa3b, v4
	v_lshrrev_b32_e32 v21, 16, v21
	v_exp_f32_e32 v11, v11
	v_mul_f32_e32 v18, 0xbfb8aa3b, v8
	v_and_or_b32 v45, v19, s6, v21
	v_exp_f32_e32 v19, v18
	v_add_f32_e32 v11, 1.0, v11
	v_rcp_f32_e32 v18, v11
	v_mul_f32_e32 v21, 0xbfb8aa3b, v9
	v_add_f32_e32 v11, 1.0, v19
	v_mul_f32_e32 v19, 0xbfb8aa3b, v5
	v_exp_f32_e32 v19, v19
	v_exp_f32_e32 v21, v21
	v_rcp_f32_e32 v22, v11
	v_mov_b32_e32 v121, v208
	v_add_f32_e32 v11, 1.0, v19
	v_rcp_f32_e32 v19, v11
	v_add_f32_e32 v11, 1.0, v21
	v_pk_mul_f32 v[26:27], v[120:121], v[10:11] op_sel_hi:[1,0]
	v_mov_b32_e32 v117, v205
	v_pk_fma_f32 v[24:25], v[24:25], v[26:27], v[28:29]
	v_pk_mul_f32 v[26:27], v[116:117], v[10:11] op_sel_hi:[1,0]
	v_rcp_f32_e32 v23, v11
	v_pk_fma_f32 v[12:13], v[12:13], v[26:27], v[16:17]
	v_mul_f32_e32 v16, 0xbfb8aa3b, v24
	v_exp_f32_e32 v16, v16
	v_mul_f32_e32 v17, 0xbfb8aa3b, v12
	v_exp_f32_e32 v17, v17
	v_mul_f32_e32 v21, 0xbfb8aa3b, v13
	v_add_f32_e32 v11, 1.0, v16
	v_rcp_f32_e32 v16, v11
	v_add_f32_e32 v11, 1.0, v17
	v_mul_f32_e32 v17, 0xbfb8aa3b, v25
	v_exp_f32_e32 v17, v17
	v_exp_f32_e32 v21, v21
	v_rcp_f32_e32 v26, v11
	v_pk_mul_f32 v[8:9], v[8:9], v[22:23]
	v_add_f32_e32 v11, 1.0, v17
	v_rcp_f32_e32 v17, v11
	v_add_f32_e32 v11, 1.0, v21
	v_rcp_f32_e32 v27, v11
	v_pk_mul_f32 v[4:5], v[4:5], v[18:19]
	v_pk_mul_f32 v[16:17], v[24:25], v[16:17]
	v_bfe_u32 v19, v9, 16, 1
	v_pk_mul_f32 v[12:13], v[12:13], v[26:27]
	v_bfe_u32 v21, v8, 16, 1
	v_bfe_u32 v11, v13, 16, 1
	v_bfe_u32 v18, v12, 16, 1
	v_add3_u32 v8, v8, v21, s27
	v_add3_u32 v9, v9, v19, s27
	v_add3_u32 v12, v12, v18, s27
	v_add3_u32 v11, v13, v11, s27
	v_bfe_u32 v13, v4, 16, 1
	v_bfe_u32 v18, v5, 16, 1
	v_bfe_u32 v19, v16, 16, 1
	v_bfe_u32 v21, v17, 16, 1
	v_add3_u32 v17, v17, v21, s27
	v_add3_u32 v16, v16, v19, s27
	v_add3_u32 v5, v5, v18, s27
	v_add3_u32 v4, v4, v13, s27
	v_lshrrev_b32_e32 v4, 16, v4
	v_lshrrev_b32_e32 v5, 16, v5
	v_lshrrev_b32_e32 v13, 16, v16
	v_lshrrev_b32_e32 v16, 16, v17
	v_and_or_b32 v19, v11, s6, v16
	v_and_or_b32 v18, v12, s6, v13
	v_and_or_b32 v17, v9, s6, v5
	v_and_or_b32 v16, v8, s6, v4
	v_pk_mul_f32 v[4:5], v[108:109], v[10:11] op_sel_hi:[1,0]
	s_waitcnt lgkmcnt(3)
	v_mov_b32_e32 v8, v92
	v_mov_b32_e32 v9, v94
	s_waitcnt lgkmcnt(1)
; #define LAS __attribute__((address_space(3)))
; __device__ __forceinline__ u32x4 pack8(const float (&f)[8]) { u32x4 o; o.x = pk2(f[0], f[1]); o.y = pk2(f[2], f[3]); o.z = pk2(f[4], f[5]); o.w = pk2(f[6], f[7]); return o; }
; __host__ __device__ __forceinline__ unsigned hl_off(unsigned r, unsigned c) { const unsigned st = (r >> 4) * 2u + (c >> 5), ob = (r & 15u) * 64u + (c & 31u) * 2u; return (st * 1024u + (ob ^ (((ob >> 9) & 1u) << 5))) >> 1; }
; __device__ __forceinline__ float fsig(float x) { return frcp(1.0f + __expf(-x)); }
; __device__ __forceinline__ void conv_unit(const Args& a, LAS unsigned char* lds, int l, int tt) {
;     ...
;         for (int j = 0; j < 8; ++j) {
;             const f32x4 g0 = *(const LAS f32x4*)(lgp + 8 * j), g1 = *(const LAS f32x4*)(lgp + 8 * j + 4), b0 = *(const LAS f32x4*)(lbp + 8 * j), b1 = *(const LAS f32x4*)(lbp + 8 * j + 4);
;             float y[8];
; #pragma unroll
;             for (int e = 0; e < 4; ++e) { y[e] = v[j][e] * rstd * g0[e] + b0[e]; y[4 + e] = v[j][4 + e] * rstd * g1[e] + b1[e]; }
; #pragma unroll
;             for (int e = 0; e < 8; ++e) y[e] = y[e] * fsig(y[e]);
;             *(u32x4*)(dst + ((int)hl_off(rl_, 8u * j) - (int)h0_)) = pack8(y);
;         }
;     }
;     __syncthreads();
	v_mov_b32_e32 v12, v88
	v_mov_b32_e32 v13, v90
	v_pk_fma_f32 v[4:5], v[8:9], v[4:5], v[12:13]
	v_pk_mul_f32 v[8:9], v[104:105], v[10:11] op_sel_hi:[1,0]
	v_mov_b32_e32 v94, v93
	v_mov_b32_e32 v90, v89
	v_pk_fma_f32 v[8:9], v[94:95], v[8:9], v[90:91]
	v_mul_f32_e32 v11, 0xbfb8aa3b, v4
	v_exp_f32_e32 v11, v11
	v_mul_f32_e32 v12, 0xbfb8aa3b, v8
	v_exp_f32_e32 v13, v12
	global_store_dwordx4 v[52:53], v[44:47], off sc0 sc1
	v_add_f32_e32 v11, 1.0, v11
	v_rcp_f32_e32 v12, v11
	v_add_f32_e32 v11, 1.0, v13
	v_mul_f32_e32 v13, 0xbfb8aa3b, v5
	global_store_dwordx4 v[14:15], v[16:19], off sc0 sc1
	v_exp_f32_e32 v13, v13
	v_mul_f32_e32 v14, 0xbfb8aa3b, v9
	v_exp_f32_e32 v15, v14
	v_rcp_f32_e32 v14, v11
	v_add_f32_e32 v11, 1.0, v13
	v_rcp_f32_e32 v13, v11
	v_add_f32_e32 v11, 1.0, v15
	v_mov_b32_e32 v16, v43
	v_mov_b32_e32 v17, v7
	v_pk_mul_f32 v[16:17], v[16:17], v[10:11] op_sel_hi:[1,0]
	v_mov_b32_e32 v18, v74
	v_mov_b32_e32 v19, v76
	s_waitcnt lgkmcnt(0)
	v_mov_b32_e32 v22, v78
	v_mov_b32_e32 v23, v80
	v_pk_fma_f32 v[16:17], v[18:19], v[16:17], v[22:23]
	v_mov_b32_e32 v18, v39
	v_mov_b32_e32 v19, v3
	v_pk_mul_f32 v[18:19], v[18:19], v[10:11] op_sel_hi:[1,0]
	v_mov_b32_e32 v76, v75
	v_mov_b32_e32 v80, v79
	v_pk_fma_f32 v[18:19], v[76:77], v[18:19], v[80:81]
	v_mul_f32_e32 v3, 0xbfb8aa3b, v16
	v_exp_f32_e32 v3, v3
	v_mul_f32_e32 v7, 0xbfb8aa3b, v18
	v_exp_f32_e32 v7, v7
	v_rcp_f32_e32 v15, v11
	v_add_f32_e32 v3, 1.0, v3
	v_rcp_f32_e32 v22, v3
	v_add_f32_e32 v3, 1.0, v7
	v_mul_f32_e32 v7, 0xbfb8aa3b, v17
	v_exp_f32_e32 v7, v7
	v_mul_f32_e32 v11, 0xbfb8aa3b, v19
	v_exp_f32_e32 v11, v11
	v_rcp_f32_e32 v24, v3
	v_add_f32_e32 v3, 1.0, v7
	v_rcp_f32_e32 v23, v3
	v_add_f32_e32 v3, 1.0, v11
	v_rcp_f32_e32 v25, v3
	v_pk_mul_f32 v[8:9], v[8:9], v[14:15]
	v_pk_mul_f32 v[4:5], v[4:5], v[12:13]
	v_pk_mul_f32 v[12:13], v[16:17], v[22:23]
	v_bfe_u32 v16, v8, 16, 1
	v_pk_mul_f32 v[14:15], v[18:19], v[24:25]
	v_add3_u32 v8, v8, v16, s27
	v_bfe_u32 v16, v13, 16, 1
	v_bfe_u32 v3, v15, 16, 1
	v_bfe_u32 v7, v14, 16, 1
	v_bfe_u32 v11, v9, 16, 1
	v_add3_u32 v13, v13, v16, s27
	ds_read_b128 v[16:19], v203 offset:224
	ds_read_b128 v[22:25], v203 offset:240
	ds_read_b128 v[26:29], v202 offset:224
	ds_read_b128 v[30:33], v202 offset:240
	v_add3_u32 v9, v9, v11, s27
	v_add3_u32 v7, v14, v7, s27
	v_add3_u32 v3, v15, v3, s27
	v_bfe_u32 v11, v4, 16, 1
	v_bfe_u32 v14, v5, 16, 1
	v_bfe_u32 v15, v12, 16, 1
	v_add3_u32 v12, v12, v15, s27
	v_add3_u32 v5, v5, v14, s27
	v_add3_u32 v4, v4, v11, s27
	v_lshrrev_b32_e32 v4, 16, v4
	v_lshrrev_b32_e32 v5, 16, v5
	v_lshrrev_b32_e32 v11, 16, v12
	v_lshrrev_b32_e32 v12, 16, v13
	v_mov_b32_e32 v43, v201
	v_and_or_b32 v15, v3, s6, v12
	v_and_or_b32 v13, v9, s6, v5
	v_and_or_b32 v12, v8, s6, v4
	v_or_b32_e32 v3, v209, v206
	v_pk_mul_f32 v[8:9], v[42:43], v[10:11] op_sel_hi:[1,0]
	s_waitcnt lgkmcnt(3)
	v_mov_b32_e32 v36, v16
	v_mov_b32_e32 v37, v18
	s_waitcnt lgkmcnt(1)
	v_mov_b32_e32 v40, v26
	v_mov_b32_e32 v41, v28
	v_mov_b32_e32 v39, v98
	v_lshrrev_b32_e32 v3, 1, v3
	v_pk_fma_f32 v[8:9], v[36:37], v[8:9], v[40:41]
	v_pk_mul_f32 v[36:37], v[38:39], v[10:11] op_sel_hi:[1,0]
	v_mov_b32_e32 v18, v17
	v_mov_b32_e32 v28, v27
	v_sub_u32_e32 v4, v3, v200
	v_pk_fma_f32 v[16:17], v[18:19], v[36:37], v[28:29]
	v_mul_f32_e32 v3, 0xbfb8aa3b, v8
	v_and_or_b32 v14, v7, s6, v11
	v_exp_f32_e32 v3, v3
	v_mul_f32_e32 v7, 0xbfb8aa3b, v16
	v_exp_f32_e32 v7, v7
	v_ashrrev_i32_e32 v5, 31, v4
	v_lshl_add_u64 v[4:5], v[4:5], 1, v[96:97]
	global_store_dwordx4 v[4:5], v[12:15], off sc0 sc1
	v_add_f32_e32 v3, 1.0, v3
	v_mul_f32_e32 v5, 0xbfb8aa3b, v9
	v_rcp_f32_e32 v4, v3
	v_add_f32_e32 v3, 1.0, v7
	v_exp_f32_e32 v5, v5
	v_mul_f32_e32 v7, 0xbfb8aa3b, v17
	v_exp_f32_e32 v7, v7
	v_rcp_f32_e32 v12, v3
	v_add_f32_e32 v3, 1.0, v5
	v_rcp_f32_e32 v5, v3
	v_add_f32_e32 v11, 1.0, v7
	v_mov_b32_e32 v3, v20
	v_mov_b32_e32 v15, v24
	s_waitcnt lgkmcnt(0)
	v_mov_b32_e32 v19, v32
	v_pk_mul_f32 v[2:3], v[2:3], v[10:11] op_sel_hi:[1,0]
	v_mov_b32_e32 v24, v23
	v_mov_b32_e32 v32, v31
	v_mov_b32_e32 v7, v34
	v_pk_fma_f32 v[2:3], v[24:25], v[2:3], v[32:33]
	v_pk_mul_f32 v[6:7], v[6:7], v[10:11] op_sel_hi:[1,0]
	v_mov_b32_e32 v14, v22
	v_mov_b32_e32 v18, v30
	v_mul_f32_e32 v13, 0xbfb8aa3b, v2
	v_pk_fma_f32 v[6:7], v[14:15], v[6:7], v[18:19]
	v_exp_f32_e32 v14, v13
	v_rcp_f32_e32 v13, v11
	v_mul_f32_e32 v10, 0xbfb8aa3b, v6
	v_exp_f32_e32 v10, v10
	v_add_f32_e32 v11, 1.0, v14
	v_mul_f32_e32 v14, 0xbfb8aa3b, v7
	v_exp_f32_e32 v15, v14
	v_mul_f32_e32 v14, 0xbfb8aa3b, v3
	v_exp_f32_e32 v18, v14
	v_rcp_f32_e32 v14, v11
	v_add_f32_e32 v11, 1.0, v15
	v_add_f32_e32 v10, 1.0, v10
	v_add_f32_e32 v15, 1.0, v18
	v_rcp_f32_e32 v15, v15
	v_rcp_f32_e32 v10, v10
	v_rcp_f32_e32 v11, v11
	v_pk_mul_f32 v[4:5], v[8:9], v[4:5]
	v_pk_mul_f32 v[8:9], v[16:17], v[12:13]
	v_pk_mul_f32 v[2:3], v[2:3], v[14:15]
	v_pk_mul_f32 v[6:7], v[6:7], v[10:11]
	v_bfe_u32 v10, v3, 16, 1
	v_bfe_u32 v12, v9, 16, 1
	v_add3_u32 v9, v9, v12, s27
	v_add3_u32 v3, v3, v10, s27
	v_bfe_u32 v10, v4, 16, 1
	v_bfe_u32 v12, v6, 16, 1
	v_add3_u32 v6, v6, v12, s27
	v_add3_u32 v4, v4, v10, s27
	v_bfe_u32 v11, v2, 16, 1
	v_bfe_u32 v13, v8, 16, 1
	v_lshrrev_b32_e32 v10, 16, v4
	v_lshrrev_b32_e32 v4, 16, v6
	v_or_b32_e32 v6, v204, v206
	v_add3_u32 v8, v8, v13, s27
	v_add3_u32 v2, v2, v11, s27
	v_bfe_u32 v11, v5, 16, 1
	v_bfe_u32 v13, v7, 16, 1
	v_lshrrev_b32_e32 v6, 1, v6
	v_add3_u32 v7, v7, v13, s27
	v_add3_u32 v5, v5, v11, s27
	v_sub_u32_e32 v6, v6, v200
	v_lshrrev_b32_e32 v11, 16, v5
	v_lshrrev_b32_e32 v5, 16, v7
	v_ashrrev_i32_e32 v7, 31, v6
	v_and_or_b32 v5, v3, s6, v5
	v_and_or_b32 v4, v2, s6, v4
	v_and_or_b32 v3, v9, s6, v11
	v_and_or_b32 v2, v8, s6, v10
	v_lshl_add_u64 v[6:7], v[6:7], 1, v[96:97]
	global_store_dwordx4 v[6:7], v[2:5], off sc0 sc1
	s_barrier

; #define LAS __attribute__((address_space(3)))
; __host__ __device__ __forceinline__ unsigned img_off(unsigned row, unsigned col, unsigned KT) { return (((row >> 8) * KT + (col >> 6)) << 14) + (((row >> 7) & 1u) << 13) + hl_off(row & 127u, col & 63u); }
; __device__ __forceinline__ unsigned cvt_pk_bf16(float lo, float hi) { unsigned r; asm volatile("v_cvt_pk_bf16_f32 %0, %1, %2" : "=v"(r) : "v"(lo), "v"(hi)); return r; }
;     __device__ __forceinline__ void operator()(const f32x4 (&acc)[2][2][4][2], const Unit& u, int wr, int wc, int fr, int fq, const LAS float* pre) const {
;         const int col0 = u.pn * BM + wc * 32 + 8 * fq;
;         f32x4 sv[2][2];
; #pragma unroll
;         for (int bj = 0; bj < 2; ++bj)
; #pragma unroll
;             for (int n = 0; n < 2; ++n) sv[bj][n] = *(const LAS f32x4*)(pre + 256 + wc * 32 + 8 * fq + bj * HALF + 4 * n);
;         float rsv[2][4];
; #pragma unroll
;         for (int ai = 0; ai < 2; ++ai)
; #pragma unroll
;             for (int m = 0; m < 4; ++m) rsv[ai][m] = pre[ai * HALF + wr * 64 + m * 16 + fr];
;     __device__ __forceinline__ void store(const f32x4 (&acc)[2][2][4][2], const Unit& u, int wr, int wc, int fr, int fq, int col0, const f32x4 (&sv)[2][2], const float (&rsv)[2][4]) const {
; #pragma unroll
;         for (int ai = 0; ai < 2; ++ai)
; #pragma unroll
;             for (int m = 0; m < 4; ++m) {
;                 const int row = u.pm * BM + ai * HALF + wr * 64 + m * 16 + fr;
;                 const float rs = rsv[ai][m];
;                 bf16_t* rowp = TILED ? O + img_off((unsigned)row, (unsigned)col0, (unsigned)(ldc >> 6)) : O + (size_t)row * ldc + col0;
; #pragma unroll
;                 for (int bj = 0; bj < 2; ++bj) {
;                     f32x4 v0 = acc[ai][bj][m][0] * rs + sv[bj][0], v1 = acc[ai][bj][m][1] * rs + sv[bj][1];
;                     if (ACT == 1) {
; #pragma unroll
;                         for (int e = 0; e < 4; ++e) { const float a0 = fmaxf(v0[e], 0.f), a1 = fmaxf(v1[e], 0.f); v0[e] = a0 * a0; v1[e] = a1 * a1; }
;                     }
;                     u32x4 w; w.x = cvt_pk_bf16(v0[0], v0[1]); w.y = cvt_pk_bf16(v0[2], v0[3]); w.z = cvt_pk_bf16(v1[0], v1[1]); w.w = cvt_pk_bf16(v1[2], v1[3]);
;                     *(u32x4*)(rowp + (TILED ? bj * 2 * (256 * 64) : bj * HALF)) = w;
.LBB0_897:
	s_lshl_b32 s34, s78, 11
	s_add_i32 s34, s34, 0
	s_add_i32 s34, s34, 0x20000
	s_lshl_b32 s35, s74, 2
	s_add_i32 s35, s34, s35
	s_add_i32 s34, s34, s77
	v_readlane_b32 s28, v254, 59
	v_lshl_add_u32 v130, v171, 2, s35
	v_lshl_add_u32 v146, v167, 2, s34
	s_lshl_b32 s34, s38, 8
	v_readlane_b32 s29, v254, 60
	ds_read_b128 v[142:145], v130 offset:1024
	ds_read_b128 v[138:141], v130 offset:1040
	ds_read_b128 v[134:137], v130 offset:1536
	ds_read_b128 v[130:133], v130 offset:1552
	ds_read2_b32 v[164:165], v146 offset1:16
	ds_read2_b32 v[184:185], v146 offset0:32 offset1:48
	ds_read2_b32 v[152:153], v146 offset0:128 offset1:144
	ds_read2_b32 v[146:147], v146 offset0:160 offset1:176
	v_ashrrev_i32_e32 v163, 31, v162
	v_add_u32_e32 v150, s34, v169
	v_mov_b64_e32 v[148:149], s[28:29]
	v_mad_i64_i32 v[154:155], s[52:53], v150, s24, v[148:149]
	v_lshlrev_b64 v[150:151], 1, v[162:163]
	v_lshl_add_u64 v[162:163], v[154:155], 0, v[150:151]
	s_waitcnt lgkmcnt(0)
	v_pk_fma_f32 v[154:155], v[126:127], v[164:165], v[142:143] op_sel_hi:[1,0,1]
	v_pk_fma_f32 v[156:157], v[128:129], v[164:165], v[144:145] op_sel_hi:[1,0,1]
	v_cvt_pk_bf16_f32 v154, v154, v155
	v_pk_fma_f32 v[186:187], v[124:125], v[164:165], v[140:141] op_sel_hi:[1,0,1]
	v_cvt_pk_bf16_f32 v155, v156, v157
	v_pk_fma_f32 v[188:189], v[122:123], v[164:165], v[138:139] op_sel_hi:[1,0,1]
	s_nop 0
	v_cvt_pk_bf16_f32 v156, v188, v189
	v_cvt_pk_bf16_f32 v157, v186, v187
	global_store_dwordx4 v[162:163], v[154:157], off sc0 sc1
	v_pk_fma_f32 v[186:187], v[92:93], v[164:165], v[132:133] op_sel_hi:[1,0,1]
	v_pk_fma_f32 v[188:189], v[90:91], v[164:165], v[130:131] op_sel_hi:[1,0,1]
	v_pk_fma_f32 v[154:155], v[94:95], v[164:165], v[134:135] op_sel_hi:[1,0,1]
	v_pk_fma_f32 v[156:157], v[96:97], v[164:165], v[136:137] op_sel_hi:[1,0,1]
	v_cvt_pk_bf16_f32 v154, v154, v155
	v_mov_b32_e32 v164, v165
	v_cvt_pk_bf16_f32 v155, v156, v157
	v_cvt_pk_bf16_f32 v156, v188, v189
	v_cvt_pk_bf16_f32 v157, v186, v187
	global_store_dwordx4 v[162:163], v[154:157], off offset:256 sc0 sc1
	v_pk_fma_f32 v[186:187], v[116:117], v[164:165], v[140:141] op_sel_hi:[1,0,1]
	v_pk_fma_f32 v[188:189], v[114:115], v[164:165], v[138:139] op_sel_hi:[1,0,1]
	v_add_u32_e32 v154, s34, v175
	v_mad_i64_i32 v[154:155], s[52:53], v154, s24, v[148:149]
	v_lshl_add_u64 v[162:163], v[154:155], 0, v[150:151]
	v_pk_fma_f32 v[154:155], v[118:119], v[164:165], v[142:143] op_sel_hi:[1,0,1]
	v_pk_fma_f32 v[156:157], v[120:121], v[164:165], v[144:145] op_sel_hi:[1,0,1]
	v_cvt_pk_bf16_f32 v154, v154, v155
	s_nop 0
	v_cvt_pk_bf16_f32 v155, v156, v157
	v_cvt_pk_bf16_f32 v156, v188, v189
	v_cvt_pk_bf16_f32 v157, v186, v187
	global_store_dwordx4 v[162:163], v[154:157], off sc0 sc1
	v_pk_fma_f32 v[186:187], v[84:85], v[164:165], v[132:133] op_sel_hi:[1,0,1]
	s_nop 0
	v_pk_fma_f32 v[154:155], v[86:87], v[164:165], v[134:135] op_sel_hi:[1,0,1]
	v_pk_fma_f32 v[156:157], v[88:89], v[164:165], v[136:137] op_sel_hi:[1,0,1]
	v_cvt_pk_bf16_f32 v154, v154, v155
	v_pk_fma_f32 v[164:165], v[82:83], v[164:165], v[130:131] op_sel_hi:[1,0,1]
	v_cvt_pk_bf16_f32 v155, v156, v157
	s_nop 0
	v_cvt_pk_bf16_f32 v156, v164, v165
	v_cvt_pk_bf16_f32 v157, v186, v187
	global_store_dwordx4 v[162:163], v[154:157], off offset:256 sc0 sc1
	v_pk_fma_f32 v[164:165], v[108:109], v[184:185], v[140:141] op_sel_hi:[1,0,1]
	v_pk_fma_f32 v[186:187], v[106:107], v[184:185], v[138:139] op_sel_hi:[1,0,1]
	v_add_u32_e32 v154, s34, v176
	v_mad_i64_i32 v[154:155], s[52:53], v154, s24, v[148:149]
	v_lshl_add_u64 v[162:163], v[154:155], 0, v[150:151]
	v_pk_fma_f32 v[154:155], v[110:111], v[184:185], v[142:143] op_sel_hi:[1,0,1]
	v_pk_fma_f32 v[156:157], v[112:113], v[184:185], v[144:145] op_sel_hi:[1,0,1]
	v_cvt_pk_bf16_f32 v154, v154, v155
	s_nop 0
	v_cvt_pk_bf16_f32 v155, v156, v157
	v_cvt_pk_bf16_f32 v156, v186, v187
	v_cvt_pk_bf16_f32 v157, v164, v165
	global_store_dwordx4 v[162:163], v[154:157], off sc0 sc1
	v_pk_fma_f32 v[164:165], v[76:77], v[184:185], v[132:133] op_sel_hi:[1,0,1]
	v_pk_fma_f32 v[186:187], v[74:75], v[184:185], v[130:131] op_sel_hi:[1,0,1]
	v_pk_fma_f32 v[154:155], v[78:79], v[184:185], v[134:135] op_sel_hi:[1,0,1]
	v_pk_fma_f32 v[156:157], v[80:81], v[184:185], v[136:137] op_sel_hi:[1,0,1]
	v_cvt_pk_bf16_f32 v154, v154, v155
	s_nop 0
	v_cvt_pk_bf16_f32 v155, v156, v157
	v_cvt_pk_bf16_f32 v156, v186, v187
	v_cvt_pk_bf16_f32 v157, v164, v165
	global_store_dwordx4 v[162:163], v[154:157], off offset:256 sc0 sc1
	v_mov_b32_e32 v164, v185
	v_pk_fma_f32 v[184:185], v[100:101], v[164:165], v[140:141] op_sel_hi:[1,0,1]
	v_add_u32_e32 v154, s34, v177
	v_mad_i64_i32 v[154:155], s[52:53], v154, s24, v[148:149]
	v_lshl_add_u64 v[162:163], v[154:155], 0, v[150:151]
	v_pk_fma_f32 v[154:155], v[102:103], v[164:165], v[142:143] op_sel_hi:[1,0,1]
	v_pk_fma_f32 v[156:157], v[104:105], v[164:165], v[144:145] op_sel_hi:[1,0,1]
	v_cvt_pk_bf16_f32 v154, v154, v155
	v_pk_fma_f32 v[186:187], v[98:99], v[164:165], v[138:139] op_sel_hi:[1,0,1]
	v_cvt_pk_bf16_f32 v155, v156, v157
	s_nop 0
	v_cvt_pk_bf16_f32 v156, v186, v187
	v_cvt_pk_bf16_f32 v157, v184, v185
	global_store_dwordx4 v[162:163], v[154:157], off sc0 sc1
	v_pk_fma_f32 v[184:185], v[68:69], v[164:165], v[132:133] op_sel_hi:[1,0,1]
	s_nop 0
	v_pk_fma_f32 v[154:155], v[70:71], v[164:165], v[134:135] op_sel_hi:[1,0,1]
; __host__ __device__ __forceinline__ unsigned img_off(unsigned row, unsigned col, unsigned KT) { return (((row >> 8) * KT + (col >> 6)) << 14) + (((row >> 7) & 1u) << 13) + hl_off(row & 127u, col & 63u); }
; __device__ __forceinline__ unsigned cvt_pk_bf16(float lo, float hi) { unsigned r; asm volatile("v_cvt_pk_bf16_f32 %0, %1, %2" : "=v"(r) : "v"(lo), "v"(hi)); return r; }
;     __device__ __forceinline__ void store(const f32x4 (&acc)[2][2][4][2], const Unit& u, int wr, int wc, int fr, int fq, int col0, const f32x4 (&sv)[2][2], const float (&rsv)[2][4]) const {
; #pragma unroll
;         for (int ai = 0; ai < 2; ++ai)
; #pragma unroll
;             for (int m = 0; m < 4; ++m) {
;                 const int row = u.pm * BM + ai * HALF + wr * 64 + m * 16 + fr;
;                 const float rs = rsv[ai][m];
;                 bf16_t* rowp = TILED ? O + img_off((unsigned)row, (unsigned)col0, (unsigned)(ldc >> 6)) : O + (size_t)row * ldc + col0;
; #pragma unroll
;                 for (int bj = 0; bj < 2; ++bj) {
;                     f32x4 v0 = acc[ai][bj][m][0] * rs + sv[bj][0], v1 = acc[ai][bj][m][1] * rs + sv[bj][1];
;                     if (ACT == 1) {
; #pragma unroll
;                         for (int e = 0; e < 4; ++e) { const float a0 = fmaxf(v0[e], 0.f), a1 = fmaxf(v1[e], 0.f); v0[e] = a0 * a0; v1[e] = a1 * a1; }
;                     }
;                     u32x4 w; w.x = cvt_pk_bf16(v0[0], v0[1]); w.y = cvt_pk_bf16(v0[2], v0[3]); w.z = cvt_pk_bf16(v1[0], v1[1]); w.w = cvt_pk_bf16(v1[2], v1[3]);
;                     *(u32x4*)(rowp + (TILED ? bj * 2 * (256 * 64) : bj * HALF)) = w;
;                 }
;             }
	v_pk_fma_f32 v[156:157], v[72:73], v[164:165], v[136:137] op_sel_hi:[1,0,1]
	v_cvt_pk_bf16_f32 v154, v154, v155
	v_pk_fma_f32 v[164:165], v[66:67], v[164:165], v[130:131] op_sel_hi:[1,0,1]
	v_cvt_pk_bf16_f32 v155, v156, v157
	s_nop 0
	v_cvt_pk_bf16_f32 v156, v164, v165
	v_cvt_pk_bf16_f32 v157, v184, v185
	global_store_dwordx4 v[162:163], v[154:157], off offset:256 sc0 sc1
	v_pk_fma_f32 v[164:165], v[60:61], v[152:153], v[140:141] op_sel_hi:[1,0,1]
	v_pk_fma_f32 v[184:185], v[58:59], v[152:153], v[138:139] op_sel_hi:[1,0,1]
	v_add_u32_e32 v154, s34, v178
	v_mad_i64_i32 v[154:155], s[52:53], v154, s24, v[148:149]
	v_lshl_add_u64 v[162:163], v[154:155], 0, v[150:151]
	v_pk_fma_f32 v[156:157], v[64:65], v[152:153], v[144:145] op_sel_hi:[1,0,1]
	v_pk_fma_f32 v[154:155], v[62:63], v[152:153], v[142:143] op_sel_hi:[1,0,1]
	s_nop 0
	v_cvt_pk_bf16_f32 v154, v154, v155
	v_cvt_pk_bf16_f32 v155, v156, v157
	v_cvt_pk_bf16_f32 v156, v184, v185
	v_cvt_pk_bf16_f32 v157, v164, v165
	global_store_dwordx4 v[162:163], v[154:157], off sc0 sc1
	v_pk_fma_f32 v[164:165], v[28:29], v[152:153], v[132:133] op_sel_hi:[1,0,1]
	v_pk_fma_f32 v[184:185], v[26:27], v[152:153], v[130:131] op_sel_hi:[1,0,1]
	v_pk_fma_f32 v[156:157], v[32:33], v[152:153], v[136:137] op_sel_hi:[1,0,1]
	v_pk_fma_f32 v[154:155], v[30:31], v[152:153], v[134:135] op_sel_hi:[1,0,1]
	v_add_u32_e32 v152, s34, v179
	v_cvt_pk_bf16_f32 v154, v154, v155
	v_cvt_pk_bf16_f32 v155, v156, v157
	v_cvt_pk_bf16_f32 v156, v184, v185
	v_cvt_pk_bf16_f32 v157, v164, v165
	global_store_dwordx4 v[162:163], v[154:157], off offset:256 sc0 sc1
	v_mov_b32_e32 v162, v153
	v_pk_fma_f32 v[164:165], v[52:53], v[162:163], v[140:141] op_sel_hi:[1,0,1]
	v_mad_i64_i32 v[154:155], s[52:53], v152, s24, v[148:149]
	v_pk_fma_f32 v[152:153], v[54:55], v[162:163], v[142:143] op_sel_hi:[1,0,1]
	v_lshl_add_u64 v[156:157], v[154:155], 0, v[150:151]
	v_pk_fma_f32 v[154:155], v[56:57], v[162:163], v[144:145] op_sel_hi:[1,0,1]
	v_cvt_pk_bf16_f32 v152, v152, v153
	v_pk_fma_f32 v[184:185], v[50:51], v[162:163], v[138:139] op_sel_hi:[1,0,1]
	v_cvt_pk_bf16_f32 v153, v154, v155
	s_nop 0
	v_cvt_pk_bf16_f32 v154, v184, v185
	v_cvt_pk_bf16_f32 v155, v164, v165
	global_store_dwordx4 v[156:157], v[152:155], off sc0 sc1
	v_pk_fma_f32 v[164:165], v[20:21], v[162:163], v[132:133] op_sel_hi:[1,0,1]
	s_nop 0
	v_pk_fma_f32 v[152:153], v[22:23], v[162:163], v[134:135] op_sel_hi:[1,0,1]
	v_pk_fma_f32 v[154:155], v[24:25], v[162:163], v[136:137] op_sel_hi:[1,0,1]
	v_cvt_pk_bf16_f32 v152, v152, v153
	v_pk_fma_f32 v[162:163], v[18:19], v[162:163], v[130:131] op_sel_hi:[1,0,1]
	v_cvt_pk_bf16_f32 v153, v154, v155
	s_nop 0
	v_cvt_pk_bf16_f32 v154, v162, v163
	v_cvt_pk_bf16_f32 v155, v164, v165
	global_store_dwordx4 v[156:157], v[152:155], off offset:256 sc0 sc1
	v_pk_fma_f32 v[162:163], v[44:45], v[146:147], v[140:141] op_sel_hi:[1,0,1]
	v_pk_fma_f32 v[164:165], v[42:43], v[146:147], v[138:139] op_sel_hi:[1,0,1]
	v_add_u32_e32 v152, s34, v180
	v_mad_i64_i32 v[152:153], s[52:53], v152, s24, v[148:149]
	v_lshl_add_u64 v[156:157], v[152:153], 0, v[150:151]
	v_pk_fma_f32 v[154:155], v[48:49], v[146:147], v[144:145] op_sel_hi:[1,0,1]
	v_pk_fma_f32 v[152:153], v[46:47], v[146:147], v[142:143] op_sel_hi:[1,0,1]
	s_nop 0
	v_cvt_pk_bf16_f32 v152, v152, v153
	v_cvt_pk_bf16_f32 v153, v154, v155
	v_cvt_pk_bf16_f32 v154, v164, v165
	v_cvt_pk_bf16_f32 v155, v162, v163
	global_store_dwordx4 v[156:157], v[152:155], off sc0 sc1
	v_pk_fma_f32 v[162:163], v[12:13], v[146:147], v[132:133] op_sel_hi:[1,0,1]
	v_pk_fma_f32 v[164:165], v[10:11], v[146:147], v[130:131] op_sel_hi:[1,0,1]
	v_pk_fma_f32 v[154:155], v[16:17], v[146:147], v[136:137] op_sel_hi:[1,0,1]
	v_pk_fma_f32 v[152:153], v[14:15], v[146:147], v[134:135] op_sel_hi:[1,0,1]
	v_add_u32_e32 v146, s34, v181
	v_mad_i64_i32 v[148:149], s[34:35], v146, s24, v[148:149]
	v_mov_b32_e32 v146, v147
	v_cvt_pk_bf16_f32 v152, v152, v153
	v_cvt_pk_bf16_f32 v153, v154, v155
	v_cvt_pk_bf16_f32 v154, v164, v165
	v_cvt_pk_bf16_f32 v155, v162, v163
	global_store_dwordx4 v[156:157], v[152:155], off offset:256 sc0 sc1
	v_lshl_add_u64 v[148:149], v[148:149], 0, v[150:151]
	v_pk_fma_f32 v[144:145], v[40:41], v[146:147], v[144:145] op_sel_hi:[1,0,1]
	v_pk_fma_f32 v[142:143], v[38:39], v[146:147], v[142:143] op_sel_hi:[1,0,1]
	v_pk_fma_f32 v[150:151], v[36:37], v[146:147], v[140:141] op_sel_hi:[1,0,1]
	v_pk_fma_f32 v[140:141], v[34:35], v[146:147], v[138:139] op_sel_hi:[1,0,1]
	v_cvt_pk_bf16_f32 v138, v142, v143
	v_cvt_pk_bf16_f32 v139, v144, v145
	v_pk_fma_f32 v[136:137], v[8:9], v[146:147], v[136:137] op_sel_hi:[1,0,1]
	v_cvt_pk_bf16_f32 v140, v140, v141
	v_cvt_pk_bf16_f32 v141, v150, v151
	global_store_dwordx4 v[148:149], v[138:141], off sc0 sc1
	v_pk_fma_f32 v[134:135], v[6:7], v[146:147], v[134:135] op_sel_hi:[1,0,1]
	s_nop 0
	v_pk_fma_f32 v[138:139], v[4:5], v[146:147], v[132:133] op_sel_hi:[1,0,1]
	v_pk_fma_f32 v[132:133], v[2:3], v[146:147], v[130:131] op_sel_hi:[1,0,1]
	v_cvt_pk_bf16_f32 v130, v134, v135
	v_cvt_pk_bf16_f32 v131, v136, v137
	s_nop 0
	v_cvt_pk_bf16_f32 v132, v132, v133
	v_cvt_pk_bf16_f32 v133, v138, v139
	global_store_dwordx4 v[148:149], v[130:133], off offset:256 sc0 sc1
	s_add_u32 s52, s80, 0xffff0000
	s_addc_u32 s53, s81, -1
	s_andn2_b64 vcc, exec, s[56:57]
	s_cbranch_vccz .LBB0_902

;     __device__ __forceinline__ void operator()(const f32x4 (&acc)[2][2][4][2], const Unit& u, int wr, int wc, int fr, int fq) const {
;         const int bb = row_bb(u.pm);
;         const int col0 = u.pn * BM + wc * 32 + 8 * fq;
;         const float* swb = sw + (size_t)bb * ldsw + col0;
;         f32x4 sv[2][2];
; #pragma unroll
;         for (int bj = 0; bj < 2; ++bj)
; #pragma unroll
;             for (int n = 0; n < 2; ++n) sv[bj][n] = *(const f32x4*)(swb + bj * HALF + 4 * n);
;         f32x4 sl[2][4];
; #pragma unroll
;         for (int ai = 0; ai < 2; ++ai)
; #pragma unroll
;             for (int m = 0; m < 4; ++m) sl[ai][m] = *(const f32x4*)(ss + (size_t)(u.pm * BM + ai * HALF + wr * 64 + m * 16 + fr) * 16 + 4 * fq);
;         float rsv[2][4];
; #pragma unroll
;         for (int ai = 0; ai < 2; ++ai)
; #pragma unroll
;             for (int m = 0; m < 4; ++m) { float t = (sl[ai][m][0] + sl[ai][m][1]) + (sl[ai][m][2] + sl[ai][m][3]); t += __shfl_xor(t, 16); t += __shfl_xor(t, 32); rsv[ai][m] = __builtin_amdgcn_rsqf(t * (1.0f / DM) + EPS); }
;         store(acc, u, wr, wc, fr, fq, col0, sv, rsv);
;     }
;     __device__ __forceinline__ void store(const f32x4 (&acc)[2][2][4][2], const Unit& u, int wr, int wc, int fr, int fq, int col0, const f32x4 (&sv)[2][2], const float (&rsv)[2][4]) const {
; #pragma unroll
;         for (int ai = 0; ai < 2; ++ai)
; #pragma unroll
;             for (int m = 0; m < 4; ++m) {
;                 const int row = u.pm * BM + ai * HALF + wr * 64 + m * 16 + fr;
;                 const float rs = rsv[ai][m];
;                 bf16_t* rowp = TILED ? O + img_off((unsigned)row, (unsigned)col0, (unsigned)(ldc >> 6)) : O + (size_t)row * ldc + col0;
; #pragma unroll
;                 for (int bj = 0; bj < 2; ++bj) {
;                     f32x4 v0 = acc[ai][bj][m][0] * rs + sv[bj][0], v1 = acc[ai][bj][m][1] * rs + sv[bj][1];
;                     if (ACT == 1) {
; #pragma unroll
;                         for (int e = 0; e < 4; ++e) { const float a0 = fmaxf(v0[e], 0.f), a1 = fmaxf(v1[e], 0.f); v0[e] = a0 * a0; v1[e] = a1 * a1; }
;                     }
;                     u32x4 w; w.x = cvt_pk_bf16(v0[0], v0[1]); w.y = cvt_pk_bf16(v0[2], v0[3]); w.z = cvt_pk_bf16(v1[0], v1[1]); w.w = cvt_pk_bf16(v1[2], v1[3]);
;                     *(u32x4*)(rowp + (TILED ? bj * 2 * (256 * 64) : bj * HALF)) = w;
.LBB0_900:
	s_min_i32 s34, s38, 64
	s_ashr_i32 s34, s34, 4
	s_mul_hi_i32 s35, s34, 0x1c00
	s_mulk_i32 s34, 0x1c00
	s_add_u32 s34, s72, s34
	s_addc_u32 s35, s73, s35
	v_ashrrev_i32_e32 v163, 31, v162
	v_lshl_add_u64 v[134:135], v[162:163], 2, s[34:35]
	s_lshl_b32 s34, s38, 8
	v_add_u32_e32 v164, s34, v169
	v_ashrrev_i32_e32 v165, 31, v164
	v_lshlrev_b64 v[146:147], 6, v[164:165]
	v_lshl_add_u64 v[146:147], v[160:161], 0, v[146:147]
	global_load_dwordx4 v[138:141], v[134:135], off offset:16
	global_load_dwordx4 v[142:145], v[134:135], off
	global_load_dwordx4 v[130:133], v[134:135], off offset:528
	s_nop 0
	global_load_dwordx4 v[134:137], v[134:135], off offset:512
	v_add_u32_e32 v150, 0xb0, v164
	global_load_dwordx4 v[184:187], v[146:147], off
	v_ashrrev_i32_e32 v151, 31, v150
	v_lshlrev_b64 v[150:151], 6, v[150:151]
	v_lshl_add_u64 v[150:151], v[160:161], 0, v[150:151]
	global_load_dwordx4 v[150:153], v[150:151], off
	v_or_b32_e32 v146, 16, v164
	v_ashrrev_i32_e32 v147, 31, v146
	v_lshlrev_b64 v[146:147], 6, v[146:147]
	v_lshl_add_u64 v[146:147], v[160:161], 0, v[146:147]
	global_load_dwordx4 v[188:191], v[146:147], off
	v_or_b32_e32 v146, 32, v164
	v_ashrrev_i32_e32 v147, 31, v146
	v_lshlrev_b64 v[146:147], 6, v[146:147]
	v_lshl_add_u64 v[146:147], v[160:161], 0, v[146:147]
	global_load_dwordx4 v[192:195], v[146:147], off
	v_or_b32_e32 v146, 48, v164
	v_ashrrev_i32_e32 v147, 31, v146
	v_lshlrev_b64 v[146:147], 6, v[146:147]
	v_lshl_add_u64 v[146:147], v[160:161], 0, v[146:147]
	global_load_dwordx4 v[196:199], v[146:147], off
	v_add_u32_e32 v146, 0x80, v164
	v_ashrrev_i32_e32 v147, 31, v146
	v_lshlrev_b64 v[146:147], 6, v[146:147]
	v_lshl_add_u64 v[146:147], v[160:161], 0, v[146:147]
	global_load_dwordx4 v[200:203], v[146:147], off
	v_add_u32_e32 v146, 0x90, v164
	v_ashrrev_i32_e32 v147, 31, v146
	v_lshlrev_b64 v[146:147], 6, v[146:147]
	v_lshl_add_u64 v[146:147], v[160:161], 0, v[146:147]
	global_load_dwordx4 v[154:157], v[146:147], off
	v_add_u32_e32 v146, 0xa0, v164
	v_ashrrev_i32_e32 v147, 31, v146
	v_lshlrev_b64 v[146:147], 6, v[146:147]
	v_lshl_add_u64 v[146:147], v[160:161], 0, v[146:147]
	global_load_dwordx4 v[146:149], v[146:147], off
	v_cmp_lt_i32_e32 vcc, v234, v229
	v_xor_b32_e32 v166, 32, v227
	v_readlane_b32 s28, v254, 59
	v_cndmask_b32_e32 v165, v227, v234, vcc
	v_cmp_lt_i32_e32 vcc, v166, v229
	v_lshlrev_b32_e32 v165, 2, v165
	v_readlane_b32 s29, v254, 60
	v_cndmask_b32_e32 v166, v227, v166, vcc
	v_lshlrev_b32_e32 v204, 2, v166
	s_waitcnt vmcnt(0)
	v_add_f32_e32 v166, v184, v185
	v_add_f32_e32 v168, v186, v187
	v_add_f32_e32 v166, v166, v168
	ds_bpermute_b32 v168, v165, v166
	s_waitcnt lgkmcnt(0)
	v_add_f32_e32 v166, v166, v168
	ds_bpermute_b32 v168, v204, v166
	s_waitcnt lgkmcnt(0)
	v_add_f32_e32 v166, v166, v168
	v_fmamk_f32 v166, v166, 0x3a800000, v222
	v_rsq_f32_e32 v174, v166
	v_add_f32_e32 v166, v188, v189
	v_add_f32_e32 v168, v190, v191
	v_add_f32_e32 v166, v166, v168
	ds_bpermute_b32 v168, v165, v166
	v_pk_fma_f32 v[186:187], v[122:123], v[174:175], v[138:139] op_sel_hi:[1,0,1]
	v_pk_fma_f32 v[188:189], v[124:125], v[174:175], v[140:141] op_sel_hi:[1,0,1]
	v_add_f32_e32 v184, v202, v203
	s_waitcnt lgkmcnt(0)
	v_add_f32_e32 v166, v166, v168
	ds_bpermute_b32 v168, v204, v166
	v_add_f32_e32 v154, v154, v155
	v_add_f32_e32 v155, v156, v157
	s_waitcnt lgkmcnt(0)
	v_add_f32_e32 v166, v166, v168
	v_fmamk_f32 v166, v166, 0x3a800000, v222
	v_rsq_f32_e32 v172, v166
	v_add_f32_e32 v166, v192, v193
	v_add_f32_e32 v168, v194, v195
	v_add_f32_e32 v166, v166, v168
	ds_bpermute_b32 v168, v165, v166
	v_add_f32_e32 v146, v146, v147
	v_add_f32_e32 v147, v148, v149
	v_add_f32_e32 v146, v146, v147
	ds_bpermute_b32 v147, v165, v146
	s_waitcnt lgkmcnt(1)
	v_add_f32_e32 v166, v166, v168
	ds_bpermute_b32 v168, v204, v166
	v_add_f32_e32 v148, v152, v153
	v_add_f32_e32 v154, v154, v155
	s_waitcnt lgkmcnt(1)
	v_add_f32_e32 v146, v146, v147
	ds_bpermute_b32 v147, v204, v146
	s_waitcnt lgkmcnt(1)
	v_add_f32_e32 v166, v166, v168
	v_fmamk_f32 v166, v166, 0x3a800000, v222
	v_rsq_f32_e32 v170, v166
	v_add_f32_e32 v166, v196, v197
	v_add_f32_e32 v168, v198, v199
	v_add_f32_e32 v166, v166, v168
	ds_bpermute_b32 v168, v165, v166
	s_waitcnt lgkmcnt(1)
	v_add_f32_e32 v146, v146, v147
	v_add_f32_e32 v147, v150, v151
	v_add_f32_e32 v147, v147, v148
	ds_bpermute_b32 v148, v165, v147
	s_waitcnt lgkmcnt(1)
	v_add_f32_e32 v166, v166, v168
	ds_bpermute_b32 v168, v204, v166
	v_mov_b64_e32 v[150:151], s[28:29]
	v_mad_i64_i32 v[156:157], s[52:53], v164, s24, v[150:151]
	s_waitcnt lgkmcnt(1)
	v_add_f32_e32 v147, v147, v148
	s_waitcnt lgkmcnt(0)
	v_add_f32_e32 v166, v166, v168
	v_fmamk_f32 v166, v166, 0x3a800000, v222
	v_rsq_f32_e32 v168, v166
	v_add_f32_e32 v166, v200, v201
	v_add_f32_e32 v166, v166, v184
	ds_bpermute_b32 v184, v165, v166
	ds_bpermute_b32 v148, v204, v147
	v_lshlrev_b64 v[152:153], 1, v[162:163]
	ds_bpermute_b32 v155, v165, v154
	v_lshl_add_u64 v[156:157], v[156:157], 0, v[152:153]
	s_waitcnt lgkmcnt(2)
	v_add_f32_e32 v166, v166, v184
	ds_bpermute_b32 v184, v204, v166
	s_waitcnt lgkmcnt(2)
	v_add_f32_e32 v147, v147, v148
	v_pk_fma_f32 v[164:165], v[128:129], v[174:175], v[144:145] op_sel_hi:[1,0,1]
	v_fmamk_f32 v147, v147, 0x3a800000, v222
	v_rsq_f32_e32 v148, v147
	s_waitcnt lgkmcnt(0)
; __host__ __device__ __forceinline__ unsigned img_off(unsigned row, unsigned col, unsigned KT) { return (((row >> 8) * KT + (col >> 6)) << 14) + (((row >> 7) & 1u) << 13) + hl_off(row & 127u, col & 63u); }
; __device__ __forceinline__ unsigned cvt_pk_bf16(float lo, float hi) { unsigned r; asm volatile("v_cvt_pk_bf16_f32 %0, %1, %2" : "=v"(r) : "v"(lo), "v"(hi)); return r; }
;     __device__ __forceinline__ void operator()(const f32x4 (&acc)[2][2][4][2], const Unit& u, int wr, int wc, int fr, int fq) const {
;     ...
;             for (int m = 0; m < 4; ++m) { float t = (sl[ai][m][0] + sl[ai][m][1]) + (sl[ai][m][2] + sl[ai][m][3]); t += __shfl_xor(t, 16); t += __shfl_xor(t, 32); rsv[ai][m] = __builtin_amdgcn_rsqf(t * (1.0f / DM) + EPS); }
;         store(acc, u, wr, wc, fr, fq, col0, sv, rsv);
;     }
;     __device__ __forceinline__ void store(const f32x4 (&acc)[2][2][4][2], const Unit& u, int wr, int wc, int fr, int fq, int col0, const f32x4 (&sv)[2][2], const float (&rsv)[2][4]) const {
; #pragma unroll
;         for (int ai = 0; ai < 2; ++ai)
; #pragma unroll
;             for (int m = 0; m < 4; ++m) {
;                 const int row = u.pm * BM + ai * HALF + wr * 64 + m * 16 + fr;
;                 const float rs = rsv[ai][m];
;                 bf16_t* rowp = TILED ? O + img_off((unsigned)row, (unsigned)col0, (unsigned)(ldc >> 6)) : O + (size_t)row * ldc + col0;
; #pragma unroll
;                 for (int bj = 0; bj < 2; ++bj) {
;                     f32x4 v0 = acc[ai][bj][m][0] * rs + sv[bj][0], v1 = acc[ai][bj][m][1] * rs + sv[bj][1];
;                     if (ACT == 1) {
; #pragma unroll
;                         for (int e = 0; e < 4; ++e) { const float a0 = fmaxf(v0[e], 0.f), a1 = fmaxf(v1[e], 0.f); v0[e] = a0 * a0; v1[e] = a1 * a1; }
;                     }
;                     u32x4 w; w.x = cvt_pk_bf16(v0[0], v0[1]); w.y = cvt_pk_bf16(v0[2], v0[3]); w.z = cvt_pk_bf16(v1[0], v1[1]); w.w = cvt_pk_bf16(v1[2], v1[3]);
;                     *(u32x4*)(rowp + (TILED ? bj * 2 * (256 * 64) : bj * HALF)) = w;
	v_add_f32_e32 v166, v166, v184
	v_pk_fma_f32 v[184:185], v[126:127], v[174:175], v[142:143] op_sel_hi:[1,0,1]
	v_add_u32_e32 v147, s34, v175
	v_cvt_pk_bf16_f32 v184, v184, v185
	v_cvt_pk_bf16_f32 v185, v164, v165
	v_cvt_pk_bf16_f32 v186, v186, v187
	v_cvt_pk_bf16_f32 v187, v188, v189
	global_store_dwordx4 v[156:157], v[184:187], off sc0 sc1
	v_pk_fma_f32 v[164:165], v[96:97], v[174:175], v[136:137] op_sel_hi:[1,0,1]
	v_pk_fma_f32 v[188:189], v[92:93], v[174:175], v[132:133] op_sel_hi:[1,0,1]
	v_pk_fma_f32 v[184:185], v[94:95], v[174:175], v[134:135] op_sel_hi:[1,0,1]
	v_pk_fma_f32 v[186:187], v[90:91], v[174:175], v[130:131] op_sel_hi:[1,0,1]
	v_cvt_pk_bf16_f32 v184, v184, v185
	v_cvt_pk_bf16_f32 v185, v164, v165
	v_pk_fma_f32 v[164:165], v[120:121], v[172:173], v[144:145] op_sel_hi:[1,0,1]
	v_cvt_pk_bf16_f32 v186, v186, v187
	v_cvt_pk_bf16_f32 v187, v188, v189
	global_store_dwordx4 v[156:157], v[184:187], off offset:256 sc0 sc1
	v_mad_i64_i32 v[156:157], s[52:53], v147, s24, v[150:151]
	s_nop 0
	v_pk_fma_f32 v[184:185], v[118:119], v[172:173], v[142:143] op_sel_hi:[1,0,1]
	v_pk_fma_f32 v[186:187], v[114:115], v[172:173], v[138:139] op_sel_hi:[1,0,1]
	v_lshl_add_u64 v[156:157], v[156:157], 0, v[152:153]
	v_pk_fma_f32 v[188:189], v[116:117], v[172:173], v[140:141] op_sel_hi:[1,0,1]
	v_cvt_pk_bf16_f32 v184, v184, v185
	v_cvt_pk_bf16_f32 v185, v164, v165
	v_cvt_pk_bf16_f32 v186, v186, v187
	v_pk_fma_f32 v[164:165], v[88:89], v[172:173], v[136:137] op_sel_hi:[1,0,1]
	v_cvt_pk_bf16_f32 v187, v188, v189
	global_store_dwordx4 v[156:157], v[184:187], off sc0 sc1
	v_pk_fma_f32 v[188:189], v[84:85], v[172:173], v[132:133] op_sel_hi:[1,0,1]
	v_add_u32_e32 v147, s34, v176
	v_pk_fma_f32 v[184:185], v[86:87], v[172:173], v[134:135] op_sel_hi:[1,0,1]
	v_pk_fma_f32 v[186:187], v[82:83], v[172:173], v[130:131] op_sel_hi:[1,0,1]
	v_cvt_pk_bf16_f32 v184, v184, v185
	v_cvt_pk_bf16_f32 v185, v164, v165
	v_add_f32_e32 v154, v154, v155
	v_cvt_pk_bf16_f32 v186, v186, v187
	v_cvt_pk_bf16_f32 v187, v188, v189
	global_store_dwordx4 v[156:157], v[184:187], off offset:256 sc0 sc1
	v_mad_i64_i32 v[156:157], s[52:53], v147, s24, v[150:151]
	s_nop 0
	v_pk_fma_f32 v[184:185], v[110:111], v[170:171], v[142:143] op_sel_hi:[1,0,1]
	v_pk_fma_f32 v[186:187], v[106:107], v[170:171], v[138:139] op_sel_hi:[1,0,1]
	ds_bpermute_b32 v155, v204, v154
	v_lshl_add_u64 v[156:157], v[156:157], 0, v[152:153]
	v_pk_fma_f32 v[164:165], v[112:113], v[170:171], v[144:145] op_sel_hi:[1,0,1]
	v_pk_fma_f32 v[188:189], v[108:109], v[170:171], v[140:141] op_sel_hi:[1,0,1]
	v_cvt_pk_bf16_f32 v184, v184, v185
	v_cvt_pk_bf16_f32 v185, v164, v165
	v_cvt_pk_bf16_f32 v186, v186, v187
	v_fmamk_f32 v166, v166, 0x3a800000, v222
	v_cvt_pk_bf16_f32 v187, v188, v189
	global_store_dwordx4 v[156:157], v[184:187], off sc0 sc1
	v_pk_fma_f32 v[164:165], v[80:81], v[170:171], v[136:137] op_sel_hi:[1,0,1]
	v_pk_fma_f32 v[188:189], v[76:77], v[170:171], v[132:133] op_sel_hi:[1,0,1]
	v_pk_fma_f32 v[184:185], v[78:79], v[170:171], v[134:135] op_sel_hi:[1,0,1]
	v_pk_fma_f32 v[186:187], v[74:75], v[170:171], v[130:131] op_sel_hi:[1,0,1]
	v_cvt_pk_bf16_f32 v184, v184, v185
	v_cvt_pk_bf16_f32 v185, v164, v165
	v_add_u32_e32 v147, s34, v177
	v_cvt_pk_bf16_f32 v186, v186, v187
	v_cvt_pk_bf16_f32 v187, v188, v189
	v_rsq_f32_e32 v166, v166
	global_store_dwordx4 v[156:157], v[184:187], off offset:256 sc0 sc1
	v_mad_i64_i32 v[156:157], s[52:53], v147, s24, v[150:151]
	s_nop 0
	v_pk_fma_f32 v[184:185], v[102:103], v[168:169], v[142:143] op_sel_hi:[1,0,1]
	v_pk_fma_f32 v[186:187], v[98:99], v[168:169], v[138:139] op_sel_hi:[1,0,1]
	v_lshl_add_u64 v[156:157], v[156:157], 0, v[152:153]
	v_pk_fma_f32 v[164:165], v[104:105], v[168:169], v[144:145] op_sel_hi:[1,0,1]
	v_pk_fma_f32 v[188:189], v[100:101], v[168:169], v[140:141] op_sel_hi:[1,0,1]
	v_cvt_pk_bf16_f32 v184, v184, v185
	v_cvt_pk_bf16_f32 v185, v164, v165
	v_cvt_pk_bf16_f32 v186, v186, v187
	s_waitcnt lgkmcnt(0)
; __host__ __device__ __forceinline__ unsigned img_off(unsigned row, unsigned col, unsigned KT) { return (((row >> 8) * KT + (col >> 6)) << 14) + (((row >> 7) & 1u) << 13) + hl_off(row & 127u, col & 63u); }
; __device__ __forceinline__ unsigned cvt_pk_bf16(float lo, float hi) { unsigned r; asm volatile("v_cvt_pk_bf16_f32 %0, %1, %2" : "=v"(r) : "v"(lo), "v"(hi)); return r; }
;     __device__ __forceinline__ void operator()(const f32x4 (&acc)[2][2][4][2], const Unit& u, int wr, int wc, int fr, int fq) const {
;     ...
;             for (int m = 0; m < 4; ++m) { float t = (sl[ai][m][0] + sl[ai][m][1]) + (sl[ai][m][2] + sl[ai][m][3]); t += __shfl_xor(t, 16); t += __shfl_xor(t, 32); rsv[ai][m] = __builtin_amdgcn_rsqf(t * (1.0f / DM) + EPS); }
;         store(acc, u, wr, wc, fr, fq, col0, sv, rsv);
;     }
;     __device__ __forceinline__ void store(const f32x4 (&acc)[2][2][4][2], const Unit& u, int wr, int wc, int fr, int fq, int col0, const f32x4 (&sv)[2][2], const float (&rsv)[2][4]) const {
; #pragma unroll
;         for (int ai = 0; ai < 2; ++ai)
; #pragma unroll
;             for (int m = 0; m < 4; ++m) {
;                 const int row = u.pm * BM + ai * HALF + wr * 64 + m * 16 + fr;
;                 const float rs = rsv[ai][m];
;                 bf16_t* rowp = TILED ? O + img_off((unsigned)row, (unsigned)col0, (unsigned)(ldc >> 6)) : O + (size_t)row * ldc + col0;
; #pragma unroll
;                 for (int bj = 0; bj < 2; ++bj) {
;                     f32x4 v0 = acc[ai][bj][m][0] * rs + sv[bj][0], v1 = acc[ai][bj][m][1] * rs + sv[bj][1];
;                     if (ACT == 1) {
; #pragma unroll
;                         for (int e = 0; e < 4; ++e) { const float a0 = fmaxf(v0[e], 0.f), a1 = fmaxf(v1[e], 0.f); v0[e] = a0 * a0; v1[e] = a1 * a1; }
;                     }
;                     u32x4 w; w.x = cvt_pk_bf16(v0[0], v0[1]); w.y = cvt_pk_bf16(v0[2], v0[3]); w.z = cvt_pk_bf16(v1[0], v1[1]); w.w = cvt_pk_bf16(v1[2], v1[3]);
;                     *(u32x4*)(rowp + (TILED ? bj * 2 * (256 * 64) : bj * HALF)) = w;
	v_add_f32_e32 v154, v154, v155
	v_cvt_pk_bf16_f32 v187, v188, v189
	global_store_dwordx4 v[156:157], v[184:187], off sc0 sc1
	v_fmamk_f32 v154, v154, 0x3a800000, v222
	v_pk_fma_f32 v[164:165], v[72:73], v[168:169], v[136:137] op_sel_hi:[1,0,1]
	v_pk_fma_f32 v[184:185], v[70:71], v[168:169], v[134:135] op_sel_hi:[1,0,1]
	v_pk_fma_f32 v[186:187], v[66:67], v[168:169], v[130:131] op_sel_hi:[1,0,1]
	v_pk_fma_f32 v[188:189], v[68:69], v[168:169], v[132:133] op_sel_hi:[1,0,1]
	v_cvt_pk_bf16_f32 v184, v184, v185
	v_cvt_pk_bf16_f32 v185, v164, v165
	v_cvt_pk_bf16_f32 v186, v186, v187
	v_add_u32_e32 v147, s34, v178
	v_cvt_pk_bf16_f32 v187, v188, v189
	v_rsq_f32_e32 v154, v154
	global_store_dwordx4 v[156:157], v[184:187], off offset:256 sc0 sc1
	v_mad_i64_i32 v[156:157], s[52:53], v147, s24, v[150:151]
	s_nop 0
	v_pk_fma_f32 v[184:185], v[62:63], v[166:167], v[142:143] op_sel_hi:[1,0,1]
	v_pk_fma_f32 v[186:187], v[58:59], v[166:167], v[138:139] op_sel_hi:[1,0,1]
	v_lshl_add_u64 v[156:157], v[156:157], 0, v[152:153]
	v_pk_fma_f32 v[164:165], v[64:65], v[166:167], v[144:145] op_sel_hi:[1,0,1]
	v_pk_fma_f32 v[188:189], v[60:61], v[166:167], v[140:141] op_sel_hi:[1,0,1]
	v_cvt_pk_bf16_f32 v184, v184, v185
	v_cvt_pk_bf16_f32 v185, v164, v165
	v_cvt_pk_bf16_f32 v186, v186, v187
	v_fmamk_f32 v146, v146, 0x3a800000, v222
	v_cvt_pk_bf16_f32 v187, v188, v189
	global_store_dwordx4 v[156:157], v[184:187], off sc0 sc1
	v_pk_fma_f32 v[164:165], v[32:33], v[166:167], v[136:137] op_sel_hi:[1,0,1]
	v_pk_fma_f32 v[188:189], v[28:29], v[166:167], v[132:133] op_sel_hi:[1,0,1]
	v_pk_fma_f32 v[184:185], v[30:31], v[166:167], v[134:135] op_sel_hi:[1,0,1]
	v_pk_fma_f32 v[186:187], v[26:27], v[166:167], v[130:131] op_sel_hi:[1,0,1]
	v_cvt_pk_bf16_f32 v184, v184, v185
	v_cvt_pk_bf16_f32 v185, v164, v165
	v_add_u32_e32 v147, s34, v179
	v_cvt_pk_bf16_f32 v186, v186, v187
	v_cvt_pk_bf16_f32 v187, v188, v189
	v_rsq_f32_e32 v146, v146
	global_store_dwordx4 v[156:157], v[184:187], off offset:256 sc0 sc1
	v_mad_i64_i32 v[156:157], s[52:53], v147, s24, v[150:151]
	s_nop 0
	v_pk_fma_f32 v[184:185], v[54:55], v[154:155], v[142:143] op_sel_hi:[1,0,1]
	v_pk_fma_f32 v[186:187], v[50:51], v[154:155], v[138:139] op_sel_hi:[1,0,1]
	v_lshl_add_u64 v[164:165], v[156:157], 0, v[152:153]
	v_pk_fma_f32 v[156:157], v[56:57], v[154:155], v[144:145] op_sel_hi:[1,0,1]
	v_pk_fma_f32 v[188:189], v[52:53], v[154:155], v[140:141] op_sel_hi:[1,0,1]
	v_cvt_pk_bf16_f32 v184, v184, v185
	v_cvt_pk_bf16_f32 v185, v156, v157
	v_cvt_pk_bf16_f32 v186, v186, v187
	v_pk_fma_f32 v[156:157], v[24:25], v[154:155], v[136:137] op_sel_hi:[1,0,1]
	v_cvt_pk_bf16_f32 v187, v188, v189
	global_store_dwordx4 v[164:165], v[184:187], off sc0 sc1
	v_pk_fma_f32 v[188:189], v[18:19], v[154:155], v[130:131] op_sel_hi:[1,0,1]
	v_add_u32_e32 v147, s34, v180
	v_pk_fma_f32 v[184:185], v[22:23], v[154:155], v[134:135] op_sel_hi:[1,0,1]
	v_pk_fma_f32 v[186:187], v[20:21], v[154:155], v[132:133] op_sel_hi:[1,0,1]
	v_cvt_pk_bf16_f32 v154, v184, v185
	v_cvt_pk_bf16_f32 v155, v156, v157
	v_cvt_pk_bf16_f32 v156, v188, v189
	v_pk_fma_f32 v[184:185], v[44:45], v[146:147], v[140:141] op_sel_hi:[1,0,1]
	v_cvt_pk_bf16_f32 v157, v186, v187
	global_store_dwordx4 v[164:165], v[154:157], off offset:256 sc0 sc1
	v_pk_fma_f32 v[186:187], v[42:43], v[146:147], v[138:139] op_sel_hi:[1,0,1]
	s_nop 0
	v_mad_i64_i32 v[154:155], s[52:53], v147, s24, v[150:151]
	v_lshl_add_u64 v[164:165], v[154:155], 0, v[152:153]
	v_pk_fma_f32 v[156:157], v[48:49], v[146:147], v[144:145] op_sel_hi:[1,0,1]
	v_pk_fma_f32 v[154:155], v[46:47], v[146:147], v[142:143] op_sel_hi:[1,0,1]
	v_pk_fma_f32 v[144:145], v[40:41], v[148:149], v[144:145] op_sel_hi:[1,0,1]
	v_cvt_pk_bf16_f32 v154, v154, v155
	v_cvt_pk_bf16_f32 v155, v156, v157
	v_cvt_pk_bf16_f32 v156, v186, v187
	v_cvt_pk_bf16_f32 v157, v184, v185
	global_store_dwordx4 v[164:165], v[154:157], off sc0 sc1
	v_pk_fma_f32 v[184:185], v[12:13], v[146:147], v[132:133] op_sel_hi:[1,0,1]
	v_pk_fma_f32 v[142:143], v[38:39], v[148:149], v[142:143] op_sel_hi:[1,0,1]
	v_pk_fma_f32 v[156:157], v[16:17], v[146:147], v[136:137] op_sel_hi:[1,0,1]
	v_pk_fma_f32 v[154:155], v[14:15], v[146:147], v[134:135] op_sel_hi:[1,0,1]
	v_pk_fma_f32 v[146:147], v[10:11], v[146:147], v[130:131] op_sel_hi:[1,0,1]
	v_cvt_pk_bf16_f32 v154, v154, v155
	v_cvt_pk_bf16_f32 v155, v156, v157
	v_pk_fma_f32 v[136:137], v[8:9], v[148:149], v[136:137] op_sel_hi:[1,0,1]
	v_cvt_pk_bf16_f32 v156, v146, v147
	v_add_u32_e32 v146, s34, v181
	v_mad_i64_i32 v[146:147], s[34:35], v146, s24, v[150:151]
	v_cvt_pk_bf16_f32 v157, v184, v185
	global_store_dwordx4 v[164:165], v[154:157], off offset:256 sc0 sc1
	v_lshl_add_u64 v[146:147], v[146:147], 0, v[152:153]
	v_pk_fma_f32 v[150:151], v[36:37], v[148:149], v[140:141] op_sel_hi:[1,0,1]
	v_pk_fma_f32 v[140:141], v[34:35], v[148:149], v[138:139] op_sel_hi:[1,0,1]
	v_cvt_pk_bf16_f32 v138, v142, v143
	v_cvt_pk_bf16_f32 v139, v144, v145
	v_pk_fma_f32 v[134:135], v[6:7], v[148:149], v[134:135] op_sel_hi:[1,0,1]
	v_cvt_pk_bf16_f32 v140, v140, v141
	v_cvt_pk_bf16_f32 v141, v150, v151
	global_store_dwordx4 v[146:147], v[138:141], off sc0 sc1
	s_nop 1
	v_pk_fma_f32 v[138:139], v[4:5], v[148:149], v[132:133] op_sel_hi:[1,0,1]
	v_pk_fma_f32 v[132:133], v[2:3], v[148:149], v[130:131] op_sel_hi:[1,0,1]
	v_cvt_pk_bf16_f32 v130, v134, v135
	v_cvt_pk_bf16_f32 v131, v136, v137
	s_nop 0
	v_cvt_pk_bf16_f32 v132, v132, v133
	v_cvt_pk_bf16_f32 v133, v138, v139
	global_store_dwordx4 v[146:147], v[130:133], off offset:256 sc0 sc1
	s_cbranch_execz .LBB0_897
